# pool_item_x: all row loads issued up front (scalar address chain replayed, SGPR state saved/restored) instead of one load at a time
# speedup vs baseline: 1.0006x; 1.0006x over previous
.LBB0_294:
	v_writelane_b32 v244, s5, 0
	v_writelane_b32 v244, vcc_lo, 1
	v_writelane_b32 v244, vcc_hi, 2
	v_writelane_b32 v244, s2, 3
	v_writelane_b32 v244, s3, 4
	v_writelane_b32 v244, s16, 5
	v_writelane_b32 v244, s17, 6
	v_writelane_b32 v244, s7, 7
	v_writelane_b32 v244, s86, 8
	v_writelane_b32 v244, s18, 9
	v_writelane_b32 v244, s19, 10
	v_writelane_b32 v244, s85, 11
	v_writelane_b32 v244, s84, 12
	v_writelane_b32 v244, s83, 13
	v_writelane_b32 v244, s82, 14
	v_writelane_b32 v244, s81, 15
	v_writelane_b32 v244, s80, 16
	v_writelane_b32 v244, s79, 17
	v_writelane_b32 v244, s78, 18
	v_writelane_b32 v244, s77, 19
	v_writelane_b32 v244, s76, 20
	v_writelane_b32 v244, s74, 21
	v_writelane_b32 v244, s35, 22
	v_writelane_b32 v244, s75, 23
	v_writelane_b32 v244, s73, 24
	v_writelane_b32 v244, s72, 25
	v_writelane_b32 v244, s71, 26
	v_writelane_b32 v244, s70, 27
	v_writelane_b32 v244, s69, 28
	v_writelane_b32 v244, s68, 29
	v_writelane_b32 v244, s67, 30
	v_writelane_b32 v244, s66, 31
	v_writelane_b32 v244, s34, 32
	v_writelane_b32 v244, s63, 33
	v_writelane_b32 v244, s62, 34
	v_writelane_b32 v244, s21, 35
	v_writelane_b32 v244, s20, 36
	v_writelane_b32 v244, s88, 37
	v_writelane_b32 v244, s89, 38
	v_writelane_b32 v244, s15, 39
	v_writelane_b32 v244, s6, 40
	v_writelane_b32 v244, s14, 41
	s_add_i32 s5, s4, -1
	s_cmp_lt_u32 s5, s23
	s_cselect_b64 vcc, -1, 0
	v_lshl_add_u64 v[248:249], s[2:3], 0, v[96:97]
	s_and_b64 s[2:3], vcc, exec
	s_cselect_b32 s2, s5, s4
	s_ashr_i32 s3, s2, 31
	s_lshl_b64 s[16:17], s[2:3], 11
	v_lshl_add_u64 v[246:247], v[248:249], 0, s[16:17]
	global_load_dwordx2 v[120:121], v[246:247], off
	s_add_i32 s2, s2, s14
	s_ashr_i32 s3, s2, 31
	s_lshl_b64 s[2:3], s[2:3], 2
	s_add_u32 s2, s26, s2
	s_addc_u32 s3, s27, s3
	s_cmp_lt_u32 s4, s23
	s_cselect_b64 vcc, -1, 0
	s_ashr_i32 s5, s4, 31
	s_lshl_b64 s[2:3], s[4:5], 11
	v_lshl_add_u64 v[246:247], v[248:249], 0, s[2:3]
	global_load_dword v104, v[246:247], off offset:0
	global_load_dword v103, v[246:247], off offset:4
	s_ashr_i32 s7, s6, 31
	s_lshl_b64 s[2:3], s[6:7], 2
	s_add_u32 s2, s26, s2
	s_addc_u32 s3, s27, s3
	s_or_b32 s86, s4, 1
	s_cmp_lt_u32 s86, s23
	global_load_dword v70, v97, s[2:3]
	s_cselect_b64 s[2:3], -1, 0
	s_and_b64 s[16:17], s[2:3], exec
	s_cselect_b32 s16, s86, s4
	s_ashr_i32 s17, s16, 31
	s_lshl_b64 s[18:19], s[16:17], 11
	s_add_i32 s16, s16, s14
	s_ashr_i32 s17, s16, 31
	s_lshl_b64 s[16:17], s[16:17], 2
	s_add_u32 s16, s26, s16
	s_addc_u32 s17, s27, s17
	s_or_b32 s85, s4, 2
	s_cmp_lt_u32 s85, s23
	global_load_dword v68, v97, s[16:17]
	v_lshl_add_u64 v[246:247], v[248:249], 0, s[18:19]
	s_cselect_b64 vcc, -1, 0
	global_load_dwordx2 v[66:67], v[246:247], off
	s_and_b64 s[16:17], vcc, exec
	s_cselect_b32 s16, s85, s4
	s_ashr_i32 s17, s16, 31
	s_lshl_b64 s[18:19], s[16:17], 11
	v_lshl_add_u64 v[246:247], v[248:249], 0, s[18:19]
	global_load_dword v101, v[246:247], off offset:0
	global_load_dword v65, v[246:247], off offset:4
	s_add_i32 s16, s16, s14
	s_ashr_i32 s17, s16, 31
	s_lshl_b64 s[16:17], s[16:17], 2
	s_add_u32 s16, s26, s16
	s_addc_u32 s17, s27, s17
	s_or_b32 s84, s4, 3
	s_cmp_lt_u32 s84, s23
	global_load_dword v64, v97, s[16:17]
	s_cselect_b64 vcc, -1, 0
	s_and_b64 s[16:17], vcc, exec
	s_cselect_b32 s16, s84, s4
	s_ashr_i32 s17, s16, 31
	s_lshl_b64 s[18:19], s[16:17], 11
	v_lshl_add_u64 v[246:247], v[248:249], 0, s[18:19]
	global_load_dword v100, v[246:247], off offset:0
	global_load_dword v99, v[246:247], off offset:4
	s_add_i32 s16, s16, s14
	s_ashr_i32 s17, s16, 31
	s_lshl_b64 s[16:17], s[16:17], 2
	s_add_u32 s16, s26, s16
	s_addc_u32 s17, s27, s17
	s_or_b32 s83, s4, 4
	s_cmp_lt_u32 s83, s23
	global_load_dword v62, v97, s[16:17]
	s_cselect_b64 vcc, -1, 0
	s_and_b64 s[16:17], vcc, exec
	s_cselect_b32 s16, s83, s4
	s_ashr_i32 s17, s16, 31
	s_lshl_b64 s[18:19], s[16:17], 11
	v_lshl_add_u64 v[246:247], v[248:249], 0, s[18:19]
	global_load_dword v98, v[246:247], off offset:0
	global_load_dword v95, v[246:247], off offset:4
	s_add_i32 s16, s16, s14
	s_ashr_i32 s17, s16, 31
	s_lshl_b64 s[16:17], s[16:17], 2
	s_add_u32 s16, s26, s16
	s_addc_u32 s17, s27, s17
	s_or_b32 s82, s4, 5
	s_cmp_lt_u32 s82, s23
	global_load_dword v60, v97, s[16:17]
	s_cselect_b64 vcc, -1, 0
	s_and_b64 s[16:17], vcc, exec
	s_cselect_b32 s16, s82, s4
	s_ashr_i32 s17, s16, 31
	s_lshl_b64 s[18:19], s[16:17], 11
	v_lshl_add_u64 v[246:247], v[248:249], 0, s[18:19]
	global_load_dword v94, v[246:247], off offset:0
	global_load_dword v93, v[246:247], off offset:4
	s_add_i32 s16, s16, s14
	s_ashr_i32 s17, s16, 31
	s_lshl_b64 s[16:17], s[16:17], 2
	s_add_u32 s16, s26, s16
	s_addc_u32 s17, s27, s17
	s_or_b32 s81, s4, 6
	s_cmp_lt_u32 s81, s23
	global_load_dword v58, v97, s[16:17]
	s_cselect_b64 vcc, -1, 0
	s_and_b64 s[16:17], vcc, exec
	s_cselect_b32 s16, s81, s4
	s_ashr_i32 s17, s16, 31
	s_lshl_b64 s[18:19], s[16:17], 11
	v_lshl_add_u64 v[246:247], v[248:249], 0, s[18:19]
	global_load_dword v92, v[246:247], off offset:0
	global_load_dword v57, v[246:247], off offset:4
	s_add_i32 s16, s16, s14
	s_ashr_i32 s17, s16, 31
	s_lshl_b64 s[16:17], s[16:17], 2
	s_add_u32 s16, s26, s16
	s_addc_u32 s17, s27, s17
	s_or_b32 s80, s4, 7
	s_cmp_lt_u32 s80, s23
	global_load_dword v56, v97, s[16:17]
	s_cselect_b64 vcc, -1, 0
	s_and_b64 s[16:17], vcc, exec
	s_cselect_b32 s16, s80, s4
	s_ashr_i32 s17, s16, 31
	s_lshl_b64 s[18:19], s[16:17], 11
	v_lshl_add_u64 v[246:247], v[248:249], 0, s[18:19]
	global_load_dword v91, v[246:247], off offset:0
	global_load_dword v90, v[246:247], off offset:4
	s_add_i32 s16, s16, s14
	s_ashr_i32 s17, s16, 31
	s_lshl_b64 s[16:17], s[16:17], 2
	s_add_u32 s16, s26, s16
	s_addc_u32 s17, s27, s17
	s_or_b32 s79, s4, 8
	s_cmp_lt_u32 s79, s23
	global_load_dword v54, v97, s[16:17]
	s_cselect_b64 vcc, -1, 0
	s_and_b64 s[16:17], vcc, exec
	s_cselect_b32 s16, s79, s4
	s_ashr_i32 s17, s16, 31
	s_lshl_b64 s[18:19], s[16:17], 11
	v_lshl_add_u64 v[246:247], v[248:249], 0, s[18:19]
	global_load_dword v89, v[246:247], off offset:0
	global_load_dword v88, v[246:247], off offset:4
	s_add_i32 s16, s16, s14
	s_ashr_i32 s17, s16, 31
	s_lshl_b64 s[16:17], s[16:17], 2
	s_add_u32 s16, s26, s16
	s_addc_u32 s17, s27, s17
	s_or_b32 s78, s4, 9
	s_cmp_lt_u32 s78, s23
	global_load_dword v52, v97, s[16:17]
	s_cselect_b64 vcc, -1, 0
	s_and_b64 s[16:17], vcc, exec
	s_cselect_b32 s16, s78, s4
	s_ashr_i32 s17, s16, 31
	s_lshl_b64 s[18:19], s[16:17], 11
	v_lshl_add_u64 v[246:247], v[248:249], 0, s[18:19]
	global_load_dword v87, v[246:247], off offset:0
	global_load_dword v86, v[246:247], off offset:4
	s_add_i32 s16, s16, s14
	s_ashr_i32 s17, s16, 31
	s_lshl_b64 s[16:17], s[16:17], 2
	s_add_u32 s16, s26, s16
	s_addc_u32 s17, s27, s17
	s_or_b32 s77, s4, 10
	s_cmp_lt_u32 s77, s23
	global_load_dword v50, v97, s[16:17]
	s_cselect_b64 vcc, -1, 0
	s_and_b64 s[16:17], vcc, exec
	s_cselect_b32 s16, s77, s4
	s_ashr_i32 s17, s16, 31
	s_lshl_b64 s[18:19], s[16:17], 11
	v_lshl_add_u64 v[246:247], v[248:249], 0, s[18:19]
	global_load_dword v85, v[246:247], off offset:0
	global_load_dword v49, v[246:247], off offset:4
	s_add_i32 s16, s16, s14
	s_ashr_i32 s17, s16, 31
	s_lshl_b64 s[16:17], s[16:17], 2
	s_add_u32 s16, s26, s16
	s_addc_u32 s17, s27, s17
	s_or_b32 s76, s4, 11
	s_cmp_lt_u32 s76, s23
	global_load_dword v48, v97, s[16:17]
	s_cselect_b64 vcc, -1, 0
	s_and_b64 s[16:17], vcc, exec
	s_cselect_b32 s16, s76, s4
	s_ashr_i32 s17, s16, 31
	s_lshl_b64 s[18:19], s[16:17], 11
	v_lshl_add_u64 v[246:247], v[248:249], 0, s[18:19]
	global_load_dword v84, v[246:247], off offset:0
	global_load_dword v83, v[246:247], off offset:4
	s_add_i32 s16, s16, s14
	s_ashr_i32 s17, s16, 31
	s_lshl_b64 s[16:17], s[16:17], 2
	s_add_u32 s16, s26, s16
	s_addc_u32 s17, s27, s17
	s_or_b32 s74, s4, 12
	s_cmp_lt_u32 s74, s23
	global_load_dword v44, v97, s[16:17]
	s_cselect_b64 vcc, -1, 0
	s_and_b64 s[16:17], vcc, exec
	s_cselect_b32 s16, s74, s4
	s_ashr_i32 s17, s16, 31
	s_lshl_b64 s[18:19], s[16:17], 11
	v_lshl_add_u64 v[246:247], v[248:249], 0, s[18:19]
	global_load_dword v80, v[246:247], off offset:0
	global_load_dword v79, v[246:247], off offset:4
	s_add_i32 s16, s16, s14
	s_ashr_i32 s17, s16, 31
	s_lshl_b64 s[16:17], s[16:17], 2
	s_add_u32 s16, s26, s16
	s_addc_u32 s17, s27, s17
	s_or_b32 s35, s4, 13
	s_cmp_lt_u32 s35, s23
	global_load_dword v38, v97, s[16:17]
	s_cselect_b64 vcc, -1, 0
	s_and_b64 s[16:17], vcc, exec
	s_cselect_b32 s16, s35, s4
	s_ashr_i32 s17, s16, 31
	s_lshl_b64 s[18:19], s[16:17], 11
	v_lshl_add_u64 v[246:247], v[248:249], 0, s[18:19]
	global_load_dword v76, v[246:247], off offset:0
	global_load_dword v39, v[246:247], off offset:4
	s_add_i32 s16, s16, s14
	s_ashr_i32 s17, s16, 31
	s_lshl_b64 s[16:17], s[16:17], 2
	s_add_u32 s16, s26, s16
	s_addc_u32 s17, s27, s17
	s_or_b32 s75, s4, 14
	s_cmp_lt_u32 s75, s23
	global_load_dword v46, v97, s[16:17]
	s_cselect_b64 vcc, -1, 0
	s_and_b64 s[16:17], vcc, exec
	s_cselect_b32 s16, s75, s4
	s_ashr_i32 s17, s16, 31
	s_lshl_b64 s[18:19], s[16:17], 11
	v_lshl_add_u64 v[246:247], v[248:249], 0, s[18:19]
	global_load_dword v82, v[246:247], off offset:0
	global_load_dword v81, v[246:247], off offset:4
	s_add_i32 s16, s16, s14
	s_ashr_i32 s17, s16, 31
	s_lshl_b64 s[16:17], s[16:17], 2
	s_add_u32 s16, s26, s16
	s_addc_u32 s17, s27, s17
	s_or_b32 s73, s4, 15
	s_cmp_lt_u32 s73, s23
	global_load_dword v42, v97, s[16:17]
	s_cselect_b64 vcc, -1, 0
	s_and_b64 s[16:17], vcc, exec
	s_cselect_b32 s16, s73, s4
	s_ashr_i32 s17, s16, 31
	s_lshl_b64 s[18:19], s[16:17], 11
	v_lshl_add_u64 v[246:247], v[248:249], 0, s[18:19]
	global_load_dword v78, v[246:247], off offset:0
	global_load_dword v77, v[246:247], off offset:4
	s_add_i32 s16, s16, s14
	s_ashr_i32 s17, s16, 31
	s_lshl_b64 s[16:17], s[16:17], 2
	s_add_u32 s16, s26, s16
	s_addc_u32 s17, s27, s17
	s_or_b32 s72, s4, 16
	s_cmp_lt_u32 s72, s23
	global_load_dword v40, v97, s[16:17]
	s_cselect_b64 vcc, -1, 0
	s_and_b64 s[16:17], vcc, exec
	s_cselect_b32 s16, s72, s4
	s_ashr_i32 s17, s16, 31
	s_lshl_b64 s[18:19], s[16:17], 11
	v_lshl_add_u64 v[246:247], v[248:249], 0, s[18:19]
	global_load_dword v75, v[246:247], off offset:0
	global_load_dword v74, v[246:247], off offset:4
	s_add_i32 s16, s16, s14
	s_ashr_i32 s17, s16, 31
	s_lshl_b64 s[16:17], s[16:17], 2
	s_add_u32 s16, s26, s16
	s_addc_u32 s17, s27, s17
	s_or_b32 s71, s4, 17
	s_cmp_lt_u32 s71, s23
	global_load_dword v36, v97, s[16:17]
	s_cselect_b64 vcc, -1, 0
	s_and_b64 s[16:17], vcc, exec
	s_cselect_b32 s16, s71, s4
	s_ashr_i32 s17, s16, 31
	s_lshl_b64 s[18:19], s[16:17], 11
	v_lshl_add_u64 v[246:247], v[248:249], 0, s[18:19]
	global_load_dword v73, v[246:247], off offset:0
	global_load_dword v72, v[246:247], off offset:4
	s_add_i32 s16, s16, s14
	s_ashr_i32 s17, s16, 31
	s_lshl_b64 s[16:17], s[16:17], 2
	s_add_u32 s16, s26, s16
	s_addc_u32 s17, s27, s17
	s_or_b32 s70, s4, 18
	s_cmp_lt_u32 s70, s23
	global_load_dword v34, v97, s[16:17]
	s_cselect_b64 vcc, -1, 0
	s_and_b64 s[16:17], vcc, exec
	s_cselect_b32 s16, s70, s4
	s_ashr_i32 s17, s16, 31
	s_lshl_b64 s[18:19], s[16:17], 11
	v_lshl_add_u64 v[246:247], v[248:249], 0, s[18:19]
	global_load_dword v71, v[246:247], off offset:0
	global_load_dword v33, v[246:247], off offset:4
	s_add_i32 s16, s16, s14
	s_ashr_i32 s17, s16, 31
	s_lshl_b64 s[16:17], s[16:17], 2
	s_add_u32 s16, s26, s16
	s_addc_u32 s17, s27, s17
	s_or_b32 s69, s4, 19
	s_cmp_lt_u32 s69, s23
	global_load_dword v32, v97, s[16:17]
	s_cselect_b64 vcc, -1, 0
	s_and_b64 s[16:17], vcc, exec
	s_cselect_b32 s16, s69, s4
	s_ashr_i32 s17, s16, 31
	s_lshl_b64 s[18:19], s[16:17], 11
	v_lshl_add_u64 v[246:247], v[248:249], 0, s[18:19]
	global_load_dword v69, v[246:247], off offset:0
	global_load_dword v63, v[246:247], off offset:4
	s_add_i32 s16, s16, s14
	s_ashr_i32 s17, s16, 31
	s_lshl_b64 s[16:17], s[16:17], 2
	s_add_u32 s16, s26, s16
	s_addc_u32 s17, s27, s17
	s_or_b32 s68, s4, 20
	s_cmp_lt_u32 s68, s23
	global_load_dword v30, v97, s[16:17]
	s_cselect_b64 vcc, -1, 0
	s_and_b64 s[16:17], vcc, exec
	s_cselect_b32 s16, s68, s4
	s_ashr_i32 s17, s16, 31
	s_lshl_b64 s[18:19], s[16:17], 11
	v_lshl_add_u64 v[246:247], v[248:249], 0, s[18:19]
	global_load_dword v61, v[246:247], off offset:0
	global_load_dword v59, v[246:247], off offset:4
	s_add_i32 s16, s16, s14
	s_ashr_i32 s17, s16, 31
	s_lshl_b64 s[16:17], s[16:17], 2
	s_add_u32 s16, s26, s16
	s_addc_u32 s17, s27, s17
	s_or_b32 s67, s4, 21
	s_cmp_lt_u32 s67, s23
	global_load_dword v28, v97, s[16:17]
	s_cselect_b64 vcc, -1, 0
	s_and_b64 s[16:17], vcc, exec
	s_cselect_b32 s16, s67, s4
	s_ashr_i32 s17, s16, 31
	s_lshl_b64 s[18:19], s[16:17], 11
	v_lshl_add_u64 v[246:247], v[248:249], 0, s[18:19]
	global_load_dword v55, v[246:247], off offset:0
	global_load_dword v53, v[246:247], off offset:4
	s_add_i32 s16, s16, s14
	s_ashr_i32 s17, s16, 31
	s_lshl_b64 s[16:17], s[16:17], 2
	s_add_u32 s16, s26, s16
	s_addc_u32 s17, s27, s17
	s_or_b32 s66, s4, 22
	s_cmp_lt_u32 s66, s23
	global_load_dword v26, v97, s[16:17]
	s_cselect_b64 vcc, -1, 0
	s_and_b64 s[16:17], vcc, exec
	s_cselect_b32 s16, s66, s4
	s_ashr_i32 s17, s16, 31
	s_lshl_b64 s[18:19], s[16:17], 11
	v_lshl_add_u64 v[246:247], v[248:249], 0, s[18:19]
	global_load_dword v51, v[246:247], off offset:0
	global_load_dword v21, v[246:247], off offset:4
	s_add_i32 s16, s16, s14
	s_ashr_i32 s17, s16, 31
	s_lshl_b64 s[16:17], s[16:17], 2
	s_add_u32 s16, s26, s16
	s_addc_u32 s17, s27, s17
	s_or_b32 s34, s4, 23
	s_cmp_lt_u32 s34, s23
	global_load_dword v20, v97, s[16:17]
	s_cselect_b64 vcc, -1, 0
	s_and_b64 s[16:17], vcc, exec
	s_cselect_b32 s16, s34, s4
	s_ashr_i32 s17, s16, 31
	s_lshl_b64 s[18:19], s[16:17], 11
	v_lshl_add_u64 v[246:247], v[248:249], 0, s[18:19]
	global_load_dword v37, v[246:247], off offset:0
	global_load_dword v35, v[246:247], off offset:4
	s_add_i32 s16, s16, s14
	s_ashr_i32 s17, s16, 31
	s_lshl_b64 s[16:17], s[16:17], 2
	s_add_u32 s16, s26, s16
	s_addc_u32 s17, s27, s17
	s_or_b32 s63, s4, 24
	s_cmp_lt_u32 s63, s23
	global_load_dword v24, v97, s[16:17]
	s_cselect_b64 vcc, -1, 0
	s_and_b64 s[16:17], vcc, exec
	s_cselect_b32 s16, s63, s4
	s_ashr_i32 s17, s16, 31
	s_lshl_b64 s[18:19], s[16:17], 11
	v_lshl_add_u64 v[246:247], v[248:249], 0, s[18:19]
	global_load_dword v47, v[246:247], off offset:0
	global_load_dword v45, v[246:247], off offset:4
	s_add_i32 s16, s16, s14
	s_ashr_i32 s17, s16, 31
	s_lshl_b64 s[16:17], s[16:17], 2
	s_add_u32 s16, s26, s16
	s_addc_u32 s17, s27, s17
	s_or_b32 s62, s4, 25
	s_cmp_lt_u32 s62, s23
	global_load_dword v22, v97, s[16:17]
	s_cselect_b64 vcc, -1, 0
	s_and_b64 s[16:17], vcc, exec
	s_cselect_b32 s16, s62, s4
	s_ashr_i32 s17, s16, 31
	s_lshl_b64 s[18:19], s[16:17], 11
	v_lshl_add_u64 v[246:247], v[248:249], 0, s[18:19]
	global_load_dword v43, v[246:247], off offset:0
	global_load_dword v41, v[246:247], off offset:4
	s_add_i32 s16, s16, s14
	s_ashr_i32 s17, s16, 31
	s_lshl_b64 s[16:17], s[16:17], 2
	s_add_u32 s16, s26, s16
	s_addc_u32 s17, s27, s17
	s_or_b32 s21, s4, 26
	s_cmp_lt_u32 s21, s23
	global_load_dword v18, v97, s[16:17]
	s_cselect_b64 vcc, -1, 0
	s_and_b64 s[16:17], vcc, exec
	s_cselect_b32 s16, s21, s4
	s_ashr_i32 s17, s16, 31
	s_lshl_b64 s[18:19], s[16:17], 11
	v_lshl_add_u64 v[246:247], v[248:249], 0, s[18:19]
	global_load_dword v31, v[246:247], off offset:0
	global_load_dword v17, v[246:247], off offset:4
	s_add_i32 s16, s16, s14
	s_ashr_i32 s17, s16, 31
	s_lshl_b64 s[16:17], s[16:17], 2
	s_add_u32 s16, s26, s16
	s_addc_u32 s17, s27, s17
	s_or_b32 s20, s4, 27
	s_cmp_lt_u32 s20, s23
	global_load_dword v16, v97, s[16:17]
	s_cselect_b64 vcc, -1, 0
	s_and_b64 s[16:17], vcc, exec
	s_cselect_b32 s16, s20, s4
	s_ashr_i32 s17, s16, 31
	s_lshl_b64 s[18:19], s[16:17], 11
	v_lshl_add_u64 v[246:247], v[248:249], 0, s[18:19]
	global_load_dword v29, v[246:247], off offset:0
	global_load_dword v27, v[246:247], off offset:4
	s_add_i32 s16, s16, s14
	s_ashr_i32 s17, s16, 31
	s_lshl_b64 s[16:17], s[16:17], 2
	s_add_u32 s16, s26, s16
	s_addc_u32 s17, s27, s17
	s_or_b32 s19, s4, 28
	s_cmp_lt_u32 s19, s23
	global_load_dword v14, v97, s[16:17]
	s_cselect_b64 vcc, -1, 0
	s_and_b64 s[16:17], vcc, exec
	s_cselect_b32 s16, s19, s4
	s_ashr_i32 s17, s16, 31
	s_lshl_b64 s[88:89], s[16:17], 11
	v_lshl_add_u64 v[246:247], v[248:249], 0, s[88:89]
	global_load_dword v25, v[246:247], off offset:0
	global_load_dword v23, v[246:247], off offset:4
	s_add_i32 s16, s16, s14
	s_ashr_i32 s17, s16, 31
	s_lshl_b64 s[16:17], s[16:17], 2
	s_add_u32 s16, s26, s16
	s_addc_u32 s17, s27, s17
	s_or_b32 s18, s4, 29
	s_cmp_lt_u32 s18, s23
	global_load_dword v12, v97, s[16:17]
	s_cselect_b64 vcc, -1, 0
	s_and_b64 s[16:17], vcc, exec
	s_cselect_b32 s16, s18, s4
	s_ashr_i32 s17, s16, 31
	s_lshl_b64 s[88:89], s[16:17], 11
	v_lshl_add_u64 v[246:247], v[248:249], 0, s[88:89]
	global_load_dword v15, v[246:247], off offset:0
	global_load_dword v13, v[246:247], off offset:4
	s_add_i32 s16, s16, s14
	s_ashr_i32 s17, s16, 31
	s_lshl_b64 s[16:17], s[16:17], 2
	s_add_u32 s16, s26, s16
	s_addc_u32 s17, s27, s17
	s_or_b32 s15, s4, 30
	s_cmp_lt_u32 s15, s23
	global_load_dword v10, v97, s[16:17]
	s_cselect_b64 vcc, -1, 0
	s_and_b64 s[16:17], vcc, exec
	s_cselect_b32 s16, s15, s4
	s_ashr_i32 s17, s16, 31
	s_lshl_b64 s[88:89], s[16:17], 11
	v_lshl_add_u64 v[246:247], v[248:249], 0, s[88:89]
	global_load_dwordx2 v[122:123], v[246:247], off
	s_add_i32 s16, s16, s14
	s_ashr_i32 s17, s16, 31
	s_lshl_b64 s[16:17], s[16:17], 2
	s_add_u32 s16, s26, s16
	s_addc_u32 s17, s27, s17
	s_or_b32 s5, s4, 31
	s_cmp_lt_u32 s5, s23
	s_cselect_b64 vcc, -1, 0
	s_and_b64 s[16:17], vcc, exec
	s_cselect_b32 s16, s5, s4
	s_ashr_i32 s17, s16, 31
	s_lshl_b64 s[88:89], s[16:17], 11
	v_lshl_add_u64 v[246:247], v[248:249], 0, s[88:89]
	global_load_dwordx2 v[124:125], v[246:247], off
	s_add_i32 s16, s16, s14
	s_ashr_i32 s17, s16, 31
	s_lshl_b64 s[16:17], s[16:17], 2
	s_add_u32 s16, s26, s16
	s_addc_u32 s17, s27, s17
	s_lshl_b64 s[6:7], s[6:7], 11
	s_add_u32 s6, s24, s6
	s_addc_u32 s7, s25, s7
	s_max_i32 s14, s4, 1
	v_readlane_b32 s5, v244, 0
	v_readlane_b32 vcc_lo, v244, 1
	v_readlane_b32 vcc_hi, v244, 2
	v_readlane_b32 s2, v244, 3
	v_readlane_b32 s3, v244, 4
	v_readlane_b32 s16, v244, 5
	v_readlane_b32 s17, v244, 6
	v_readlane_b32 s7, v244, 7
	v_readlane_b32 s86, v244, 8
	v_readlane_b32 s18, v244, 9
	v_readlane_b32 s19, v244, 10
	v_readlane_b32 s85, v244, 11
	v_readlane_b32 s84, v244, 12
	v_readlane_b32 s83, v244, 13
	v_readlane_b32 s82, v244, 14
	v_readlane_b32 s81, v244, 15
	v_readlane_b32 s80, v244, 16
	v_readlane_b32 s79, v244, 17
	v_readlane_b32 s78, v244, 18
	v_readlane_b32 s77, v244, 19
	v_readlane_b32 s76, v244, 20
	v_readlane_b32 s74, v244, 21
	v_readlane_b32 s35, v244, 22
	v_readlane_b32 s75, v244, 23
	v_readlane_b32 s73, v244, 24
	v_readlane_b32 s72, v244, 25
	v_readlane_b32 s71, v244, 26
	v_readlane_b32 s70, v244, 27
	v_readlane_b32 s69, v244, 28
	v_readlane_b32 s68, v244, 29
	v_readlane_b32 s67, v244, 30
	v_readlane_b32 s66, v244, 31
	v_readlane_b32 s34, v244, 32
	v_readlane_b32 s63, v244, 33
	v_readlane_b32 s62, v244, 34
	v_readlane_b32 s21, v244, 35
	v_readlane_b32 s20, v244, 36
	v_readlane_b32 s88, v244, 37
	v_readlane_b32 s89, v244, 38
	v_readlane_b32 s15, v244, 39
	v_readlane_b32 s6, v244, 40
	v_readlane_b32 s14, v244, 41
	s_nop 4
	s_waitcnt vmcnt(0)
	s_add_i32 s5, s4, -1
	s_cmp_lt_u32 s5, s23
	s_cselect_b64 vcc, -1, 0
	v_lshl_add_u64 v[8:9], s[2:3], 0, v[96:97]
	s_and_b64 s[2:3], vcc, exec
	s_cselect_b32 s2, s5, s4
	s_ashr_i32 s3, s2, 31
	s_lshl_b64 s[16:17], s[2:3], 11
	v_lshl_add_u64 v[4:5], v[8:9], 0, s[16:17]
	s_add_i32 s2, s2, s14
	s_ashr_i32 s3, s2, 31
	s_lshl_b64 s[2:3], s[2:3], 2
	s_add_u32 s2, s26, s2
	s_addc_u32 s3, s27, s3
	s_cmp_lt_u32 s4, s23
	s_waitcnt vmcnt(0)
	v_cndmask_b32_e32 v102, 0, v120, vcc
	v_cndmask_b32_e32 v5, 0, v121, vcc
	s_cselect_b64 vcc, -1, 0
	s_ashr_i32 s5, s4, 31
	global_load_dword v4, v97, s[2:3]
	s_waitcnt vmcnt(0)
	s_lshl_b64 s[2:3], s[4:5], 11
	v_lshl_add_u64 v[6:7], v[8:9], 0, s[2:3]
	s_ashr_i32 s7, s6, 31
	s_lshl_b64 s[2:3], s[6:7], 2
	s_add_u32 s2, s26, s2
	s_addc_u32 s3, s27, s3
	s_or_b32 s86, s4, 1
	s_cmp_lt_u32 s86, s23
	s_cselect_b64 s[2:3], -1, 0
	s_and_b64 s[16:17], s[2:3], exec
	s_cselect_b32 s16, s86, s4
	s_ashr_i32 s17, s16, 31
	s_lshl_b64 s[18:19], s[16:17], 11
	s_add_i32 s16, s16, s14
	s_ashr_i32 s17, s16, 31
	s_lshl_b64 s[16:17], s[16:17], 2
	s_add_u32 s16, s26, s16
	s_addc_u32 s17, s27, s17
	s_or_b32 s85, s4, 2
	s_cmp_lt_u32 s85, s23
	v_lshlrev_b32_e32 v106, 16, v102
	v_and_b32_e32 v107, 0xffff0000, v102
	v_lshlrev_b32_e32 v108, 16, v5
	v_and_b32_e32 v109, 0xffff0000, v5
	s_waitcnt vmcnt(3)
	v_pk_mul_f32 v[110:111], v[4:5], v[108:109] op_sel_hi:[0,1]
	v_pk_mul_f32 v[112:113], v[4:5], v[106:107] op_sel_hi:[0,1]
	v_pk_fma_f32 v[106:107], v[4:5], v[106:107], 0 op_sel_hi:[0,1,0]
	s_waitcnt vmcnt(2)
	v_cndmask_b32_e32 v104, 0, v104, vcc
	v_cndmask_b32_e32 v103, 0, v103, vcc
	v_lshl_add_u64 v[6:7], v[8:9], 0, s[18:19]
	s_cselect_b64 vcc, -1, 0
	s_and_b64 s[16:17], vcc, exec
	s_cselect_b32 s16, s85, s4
	s_ashr_i32 s17, s16, 31
	s_lshl_b64 s[18:19], s[16:17], 11
	v_lshl_add_u64 v[6:7], v[8:9], 0, s[18:19]
	s_add_i32 s16, s16, s14
	s_ashr_i32 s17, s16, 31
	s_lshl_b64 s[16:17], s[16:17], 2
	s_add_u32 s16, s26, s16
	s_addc_u32 s17, s27, s17
	s_or_b32 s84, s4, 3
	s_cmp_lt_u32 s84, s23
	v_pk_fma_f32 v[4:5], v[4:5], v[108:109], 0 op_sel_hi:[0,1,0]
	v_lshlrev_b32_e32 v108, 16, v104
	v_and_b32_e32 v109, 0xffff0000, v104
	v_lshlrev_b32_e32 v102, 16, v103
	v_and_b32_e32 v103, 0xffff0000, v103
	s_waitcnt vmcnt(1)
	v_cndmask_b32_e32 v101, 0, v101, vcc
	v_cndmask_b32_e32 v65, 0, v65, vcc
	s_cselect_b64 vcc, -1, 0
	s_and_b64 s[16:17], vcc, exec
	s_cselect_b32 s16, s84, s4
	s_ashr_i32 s17, s16, 31
	s_lshl_b64 s[18:19], s[16:17], 11
	v_lshl_add_u64 v[6:7], v[8:9], 0, s[18:19]
	s_add_i32 s16, s16, s14
	s_ashr_i32 s17, s16, 31
	s_lshl_b64 s[16:17], s[16:17], 2
	s_add_u32 s16, s26, s16
	s_addc_u32 s17, s27, s17
	s_or_b32 s83, s4, 4
	s_cmp_lt_u32 s83, s23
	s_waitcnt vmcnt(1)
	v_cndmask_b32_e32 v100, 0, v100, vcc
	v_cndmask_b32_e32 v99, 0, v99, vcc
	s_cselect_b64 vcc, -1, 0
	s_and_b64 s[16:17], vcc, exec
	s_cselect_b32 s16, s83, s4
	s_ashr_i32 s17, s16, 31
	s_lshl_b64 s[18:19], s[16:17], 11
	v_lshl_add_u64 v[6:7], v[8:9], 0, s[18:19]
	s_add_i32 s16, s16, s14
	s_ashr_i32 s17, s16, 31
	s_lshl_b64 s[16:17], s[16:17], 2
	s_add_u32 s16, s26, s16
	s_addc_u32 s17, s27, s17
	s_or_b32 s82, s4, 5
	s_cmp_lt_u32 s82, s23
	s_waitcnt vmcnt(1)
	v_cndmask_b32_e32 v98, 0, v98, vcc
	v_cndmask_b32_e32 v95, 0, v95, vcc
	s_cselect_b64 vcc, -1, 0
	s_and_b64 s[16:17], vcc, exec
	s_cselect_b32 s16, s82, s4
	s_ashr_i32 s17, s16, 31
	s_lshl_b64 s[18:19], s[16:17], 11
	v_lshl_add_u64 v[6:7], v[8:9], 0, s[18:19]
	s_add_i32 s16, s16, s14
	s_ashr_i32 s17, s16, 31
	s_lshl_b64 s[16:17], s[16:17], 2
	s_add_u32 s16, s26, s16
	s_addc_u32 s17, s27, s17
	s_or_b32 s81, s4, 6
	s_cmp_lt_u32 s81, s23
	s_waitcnt vmcnt(1)
	v_cndmask_b32_e32 v94, 0, v94, vcc
	v_cndmask_b32_e32 v93, 0, v93, vcc
	s_cselect_b64 vcc, -1, 0
	s_and_b64 s[16:17], vcc, exec
	s_cselect_b32 s16, s81, s4
	s_ashr_i32 s17, s16, 31
	s_lshl_b64 s[18:19], s[16:17], 11
	v_lshl_add_u64 v[6:7], v[8:9], 0, s[18:19]
	s_add_i32 s16, s16, s14
	s_ashr_i32 s17, s16, 31
	s_lshl_b64 s[16:17], s[16:17], 2
	s_add_u32 s16, s26, s16
	s_addc_u32 s17, s27, s17
	s_or_b32 s80, s4, 7
	s_cmp_lt_u32 s80, s23
	s_waitcnt vmcnt(1)
	v_cndmask_b32_e32 v92, 0, v92, vcc
	v_cndmask_b32_e32 v57, 0, v57, vcc
	s_cselect_b64 vcc, -1, 0
	s_and_b64 s[16:17], vcc, exec
	s_cselect_b32 s16, s80, s4
	s_ashr_i32 s17, s16, 31
	s_lshl_b64 s[18:19], s[16:17], 11
	v_lshl_add_u64 v[6:7], v[8:9], 0, s[18:19]
	s_add_i32 s16, s16, s14
	s_ashr_i32 s17, s16, 31
	s_lshl_b64 s[16:17], s[16:17], 2
	s_add_u32 s16, s26, s16
	s_addc_u32 s17, s27, s17
	s_or_b32 s79, s4, 8
	s_cmp_lt_u32 s79, s23
	s_waitcnt vmcnt(1)
	v_cndmask_b32_e32 v91, 0, v91, vcc
	v_cndmask_b32_e32 v90, 0, v90, vcc
	s_cselect_b64 vcc, -1, 0
	s_and_b64 s[16:17], vcc, exec
	s_cselect_b32 s16, s79, s4
	s_ashr_i32 s17, s16, 31
	s_lshl_b64 s[18:19], s[16:17], 11
	v_lshl_add_u64 v[6:7], v[8:9], 0, s[18:19]
	s_add_i32 s16, s16, s14
	s_ashr_i32 s17, s16, 31
	s_lshl_b64 s[16:17], s[16:17], 2
	s_add_u32 s16, s26, s16
	s_addc_u32 s17, s27, s17
	s_or_b32 s78, s4, 9
	s_cmp_lt_u32 s78, s23
	s_waitcnt vmcnt(1)
	v_cndmask_b32_e32 v89, 0, v89, vcc
	v_cndmask_b32_e32 v88, 0, v88, vcc
	s_cselect_b64 vcc, -1, 0
	s_and_b64 s[16:17], vcc, exec
	s_cselect_b32 s16, s78, s4
	s_ashr_i32 s17, s16, 31
	s_lshl_b64 s[18:19], s[16:17], 11
	v_lshl_add_u64 v[6:7], v[8:9], 0, s[18:19]
	s_add_i32 s16, s16, s14
	s_ashr_i32 s17, s16, 31
	s_lshl_b64 s[16:17], s[16:17], 2
	s_add_u32 s16, s26, s16
	s_addc_u32 s17, s27, s17
	s_or_b32 s77, s4, 10
	s_cmp_lt_u32 s77, s23
	s_waitcnt vmcnt(1)
	v_cndmask_b32_e32 v87, 0, v87, vcc
	v_cndmask_b32_e32 v86, 0, v86, vcc
	s_cselect_b64 vcc, -1, 0
	s_and_b64 s[16:17], vcc, exec
	s_cselect_b32 s16, s77, s4
	s_ashr_i32 s17, s16, 31
	s_lshl_b64 s[18:19], s[16:17], 11
	v_lshl_add_u64 v[6:7], v[8:9], 0, s[18:19]
	s_add_i32 s16, s16, s14
	s_ashr_i32 s17, s16, 31
	s_lshl_b64 s[16:17], s[16:17], 2
	s_add_u32 s16, s26, s16
	s_addc_u32 s17, s27, s17
	s_or_b32 s76, s4, 11
	s_cmp_lt_u32 s76, s23
	s_waitcnt vmcnt(1)
	v_cndmask_b32_e32 v85, 0, v85, vcc
	v_cndmask_b32_e32 v49, 0, v49, vcc
	s_cselect_b64 vcc, -1, 0
	s_and_b64 s[16:17], vcc, exec
	s_cselect_b32 s16, s76, s4
	s_ashr_i32 s17, s16, 31
	s_lshl_b64 s[18:19], s[16:17], 11
	v_lshl_add_u64 v[6:7], v[8:9], 0, s[18:19]
	s_add_i32 s16, s16, s14
	s_ashr_i32 s17, s16, 31
	s_lshl_b64 s[16:17], s[16:17], 2
	s_add_u32 s16, s26, s16
	s_addc_u32 s17, s27, s17
	s_or_b32 s74, s4, 12
	s_cmp_lt_u32 s74, s23
	s_waitcnt vmcnt(1)
	v_cndmask_b32_e32 v84, 0, v84, vcc
	v_cndmask_b32_e32 v83, 0, v83, vcc
	s_cselect_b64 vcc, -1, 0
	s_and_b64 s[16:17], vcc, exec
	s_cselect_b32 s16, s74, s4
	s_ashr_i32 s17, s16, 31
	s_lshl_b64 s[18:19], s[16:17], 11
	v_lshl_add_u64 v[6:7], v[8:9], 0, s[18:19]
	s_add_i32 s16, s16, s14
	s_ashr_i32 s17, s16, 31
	s_lshl_b64 s[16:17], s[16:17], 2
	s_add_u32 s16, s26, s16
	s_addc_u32 s17, s27, s17
	s_or_b32 s35, s4, 13
	s_cmp_lt_u32 s35, s23
	s_waitcnt vmcnt(1)
	v_cndmask_b32_e32 v80, 0, v80, vcc
	v_cndmask_b32_e32 v79, 0, v79, vcc
	s_cselect_b64 vcc, -1, 0
	s_and_b64 s[16:17], vcc, exec
	s_cselect_b32 s16, s35, s4
	s_ashr_i32 s17, s16, 31
	s_lshl_b64 s[18:19], s[16:17], 11
	v_lshl_add_u64 v[6:7], v[8:9], 0, s[18:19]
	s_add_i32 s16, s16, s14
	s_ashr_i32 s17, s16, 31
	s_lshl_b64 s[16:17], s[16:17], 2
	s_add_u32 s16, s26, s16
	s_addc_u32 s17, s27, s17
	s_or_b32 s75, s4, 14
	s_cmp_lt_u32 s75, s23
	s_waitcnt vmcnt(1)
	v_cndmask_b32_e32 v76, 0, v76, vcc
	v_cndmask_b32_e32 v39, 0, v39, vcc
	s_cselect_b64 vcc, -1, 0
	s_and_b64 s[16:17], vcc, exec
	s_cselect_b32 s16, s75, s4
	s_ashr_i32 s17, s16, 31
	s_lshl_b64 s[18:19], s[16:17], 11
	v_lshl_add_u64 v[6:7], v[8:9], 0, s[18:19]
	s_add_i32 s16, s16, s14
	s_ashr_i32 s17, s16, 31
	s_lshl_b64 s[16:17], s[16:17], 2
	s_add_u32 s16, s26, s16
	s_addc_u32 s17, s27, s17
	s_or_b32 s73, s4, 15
	s_cmp_lt_u32 s73, s23
	s_waitcnt vmcnt(1)
	v_cndmask_b32_e32 v82, 0, v82, vcc
	v_cndmask_b32_e32 v81, 0, v81, vcc
	s_cselect_b64 vcc, -1, 0
	s_and_b64 s[16:17], vcc, exec
	s_cselect_b32 s16, s73, s4
	s_ashr_i32 s17, s16, 31
	s_lshl_b64 s[18:19], s[16:17], 11
	v_lshl_add_u64 v[6:7], v[8:9], 0, s[18:19]
	s_add_i32 s16, s16, s14
	s_ashr_i32 s17, s16, 31
	s_lshl_b64 s[16:17], s[16:17], 2
	s_add_u32 s16, s26, s16
	s_addc_u32 s17, s27, s17
	s_or_b32 s72, s4, 16
	s_cmp_lt_u32 s72, s23
	s_waitcnt vmcnt(1)
	v_cndmask_b32_e32 v78, 0, v78, vcc
	v_cndmask_b32_e32 v77, 0, v77, vcc
	s_cselect_b64 vcc, -1, 0
	s_and_b64 s[16:17], vcc, exec
	s_cselect_b32 s16, s72, s4
	s_ashr_i32 s17, s16, 31
	s_lshl_b64 s[18:19], s[16:17], 11
	v_lshl_add_u64 v[6:7], v[8:9], 0, s[18:19]
	s_add_i32 s16, s16, s14
	s_ashr_i32 s17, s16, 31
	s_lshl_b64 s[16:17], s[16:17], 2
	s_add_u32 s16, s26, s16
	s_addc_u32 s17, s27, s17
	s_or_b32 s71, s4, 17
	s_cmp_lt_u32 s71, s23
	s_waitcnt vmcnt(1)
	v_cndmask_b32_e32 v75, 0, v75, vcc
	v_cndmask_b32_e32 v74, 0, v74, vcc
	s_cselect_b64 vcc, -1, 0
	s_and_b64 s[16:17], vcc, exec
	s_cselect_b32 s16, s71, s4
	s_ashr_i32 s17, s16, 31
	s_lshl_b64 s[18:19], s[16:17], 11
	v_lshl_add_u64 v[6:7], v[8:9], 0, s[18:19]
	s_add_i32 s16, s16, s14
	s_ashr_i32 s17, s16, 31
	s_lshl_b64 s[16:17], s[16:17], 2
	s_add_u32 s16, s26, s16
	s_addc_u32 s17, s27, s17
	s_or_b32 s70, s4, 18
	s_cmp_lt_u32 s70, s23
	s_waitcnt vmcnt(1)
	v_cndmask_b32_e32 v73, 0, v73, vcc
	v_cndmask_b32_e32 v72, 0, v72, vcc
	s_cselect_b64 vcc, -1, 0
	s_and_b64 s[16:17], vcc, exec
	s_cselect_b32 s16, s70, s4
	s_ashr_i32 s17, s16, 31
	s_lshl_b64 s[18:19], s[16:17], 11
	v_lshl_add_u64 v[6:7], v[8:9], 0, s[18:19]
	s_add_i32 s16, s16, s14
	s_ashr_i32 s17, s16, 31
	s_lshl_b64 s[16:17], s[16:17], 2
	s_add_u32 s16, s26, s16
	s_addc_u32 s17, s27, s17
	s_or_b32 s69, s4, 19
	s_cmp_lt_u32 s69, s23
	s_waitcnt vmcnt(1)
	v_cndmask_b32_e32 v71, 0, v71, vcc
	v_cndmask_b32_e32 v33, 0, v33, vcc
	s_cselect_b64 vcc, -1, 0
	s_and_b64 s[16:17], vcc, exec
	s_cselect_b32 s16, s69, s4
	s_ashr_i32 s17, s16, 31
	s_lshl_b64 s[18:19], s[16:17], 11
	v_lshl_add_u64 v[6:7], v[8:9], 0, s[18:19]
	s_add_i32 s16, s16, s14
	s_ashr_i32 s17, s16, 31
	s_lshl_b64 s[16:17], s[16:17], 2
	s_add_u32 s16, s26, s16
	s_addc_u32 s17, s27, s17
	s_or_b32 s68, s4, 20
	s_cmp_lt_u32 s68, s23
	v_pk_mul_f32 v[104:105], v[70:71], v[102:103] op_sel_hi:[0,1]
	v_pk_mul_f32 v[114:115], v[70:71], v[108:109] op_sel_hi:[0,1]
	v_pk_fma_f32 v[102:103], v[70:71], v[102:103], v[4:5] op_sel_hi:[0,1,1]
	v_pk_fma_f32 v[106:107], v[70:71], v[108:109], v[106:107] op_sel_hi:[0,1,1]
	s_waitcnt vmcnt(1)
	v_cndmask_b32_e32 v69, 0, v69, vcc
	v_cndmask_b32_e32 v63, 0, v63, vcc
	s_cselect_b64 vcc, -1, 0
	s_and_b64 s[16:17], vcc, exec
	s_cselect_b32 s16, s68, s4
	s_ashr_i32 s17, s16, 31
	s_lshl_b64 s[18:19], s[16:17], 11
	v_lshl_add_u64 v[6:7], v[8:9], 0, s[18:19]
	s_add_i32 s16, s16, s14
	s_ashr_i32 s17, s16, 31
	s_lshl_b64 s[16:17], s[16:17], 2
	s_add_u32 s16, s26, s16
	s_addc_u32 s17, s27, s17
	s_or_b32 s67, s4, 21
	s_cmp_lt_u32 s67, s23
	s_waitcnt vmcnt(1)
	v_cndmask_b32_e32 v61, 0, v61, vcc
	v_cndmask_b32_e32 v59, 0, v59, vcc
	s_cselect_b64 vcc, -1, 0
	s_and_b64 s[16:17], vcc, exec
	s_cselect_b32 s16, s67, s4
	s_ashr_i32 s17, s16, 31
	s_lshl_b64 s[18:19], s[16:17], 11
	v_lshl_add_u64 v[6:7], v[8:9], 0, s[18:19]
	s_add_i32 s16, s16, s14
	s_ashr_i32 s17, s16, 31
	s_lshl_b64 s[16:17], s[16:17], 2
	s_add_u32 s16, s26, s16
	s_addc_u32 s17, s27, s17
	s_or_b32 s66, s4, 22
	s_cmp_lt_u32 s66, s23
	s_waitcnt vmcnt(1)
	v_cndmask_b32_e32 v55, 0, v55, vcc
	v_cndmask_b32_e32 v53, 0, v53, vcc
	s_cselect_b64 vcc, -1, 0
	s_and_b64 s[16:17], vcc, exec
	s_cselect_b32 s16, s66, s4
	s_ashr_i32 s17, s16, 31
	s_lshl_b64 s[18:19], s[16:17], 11
	v_lshl_add_u64 v[6:7], v[8:9], 0, s[18:19]
	s_add_i32 s16, s16, s14
	s_ashr_i32 s17, s16, 31
	s_lshl_b64 s[16:17], s[16:17], 2
	s_add_u32 s16, s26, s16
	s_addc_u32 s17, s27, s17
	s_or_b32 s34, s4, 23
	s_cmp_lt_u32 s34, s23
	s_waitcnt vmcnt(1)
	v_cndmask_b32_e32 v51, 0, v51, vcc
	v_cndmask_b32_e32 v21, 0, v21, vcc
	s_cselect_b64 vcc, -1, 0
	s_and_b64 s[16:17], vcc, exec
	s_cselect_b32 s16, s34, s4
	s_ashr_i32 s17, s16, 31
	s_lshl_b64 s[18:19], s[16:17], 11
	v_lshl_add_u64 v[6:7], v[8:9], 0, s[18:19]
	s_add_i32 s16, s16, s14
	s_ashr_i32 s17, s16, 31
	s_lshl_b64 s[16:17], s[16:17], 2
	s_add_u32 s16, s26, s16
	s_addc_u32 s17, s27, s17
	s_or_b32 s63, s4, 24
	s_cmp_lt_u32 s63, s23
	s_waitcnt vmcnt(1)
	v_cndmask_b32_e32 v37, 0, v37, vcc
	v_cndmask_b32_e32 v35, 0, v35, vcc
	s_cselect_b64 vcc, -1, 0
	s_and_b64 s[16:17], vcc, exec
	s_cselect_b32 s16, s63, s4
	s_ashr_i32 s17, s16, 31
	s_lshl_b64 s[18:19], s[16:17], 11
	v_lshl_add_u64 v[6:7], v[8:9], 0, s[18:19]
	s_add_i32 s16, s16, s14
	s_ashr_i32 s17, s16, 31
	s_lshl_b64 s[16:17], s[16:17], 2
	s_add_u32 s16, s26, s16
	s_addc_u32 s17, s27, s17
	s_or_b32 s62, s4, 25
	s_cmp_lt_u32 s62, s23
	s_waitcnt vmcnt(1)
	v_cndmask_b32_e32 v47, 0, v47, vcc
	v_cndmask_b32_e32 v45, 0, v45, vcc
	s_cselect_b64 vcc, -1, 0
	s_and_b64 s[16:17], vcc, exec
	s_cselect_b32 s16, s62, s4
	s_ashr_i32 s17, s16, 31
	s_lshl_b64 s[18:19], s[16:17], 11
	v_lshl_add_u64 v[6:7], v[8:9], 0, s[18:19]
	s_add_i32 s16, s16, s14
	s_ashr_i32 s17, s16, 31
	s_lshl_b64 s[16:17], s[16:17], 2
	s_add_u32 s16, s26, s16
	s_addc_u32 s17, s27, s17
	s_or_b32 s21, s4, 26
	s_cmp_lt_u32 s21, s23
	s_waitcnt vmcnt(1)
	v_cndmask_b32_e32 v43, 0, v43, vcc
	v_cndmask_b32_e32 v41, 0, v41, vcc
	s_cselect_b64 vcc, -1, 0
	s_and_b64 s[16:17], vcc, exec
	s_cselect_b32 s16, s21, s4
	s_ashr_i32 s17, s16, 31
	s_lshl_b64 s[18:19], s[16:17], 11
	v_lshl_add_u64 v[6:7], v[8:9], 0, s[18:19]
	s_add_i32 s16, s16, s14
	s_ashr_i32 s17, s16, 31
	s_lshl_b64 s[16:17], s[16:17], 2
	s_add_u32 s16, s26, s16
	s_addc_u32 s17, s27, s17
	s_or_b32 s20, s4, 27
	s_cmp_lt_u32 s20, s23
	s_waitcnt vmcnt(1)
	v_cndmask_b32_e32 v31, 0, v31, vcc
	v_cndmask_b32_e32 v17, 0, v17, vcc
	s_cselect_b64 vcc, -1, 0
	s_and_b64 s[16:17], vcc, exec
	s_cselect_b32 s16, s20, s4
	s_ashr_i32 s17, s16, 31
	s_lshl_b64 s[18:19], s[16:17], 11
	v_lshl_add_u64 v[6:7], v[8:9], 0, s[18:19]
	s_add_i32 s16, s16, s14
	s_ashr_i32 s17, s16, 31
	s_lshl_b64 s[16:17], s[16:17], 2
	s_add_u32 s16, s26, s16
	s_addc_u32 s17, s27, s17
	s_or_b32 s19, s4, 28
	s_cmp_lt_u32 s19, s23
	s_waitcnt vmcnt(1)
	v_cndmask_b32_e32 v29, 0, v29, vcc
	v_cndmask_b32_e32 v27, 0, v27, vcc
	s_cselect_b64 vcc, -1, 0
	s_and_b64 s[16:17], vcc, exec
	s_cselect_b32 s16, s19, s4
	s_ashr_i32 s17, s16, 31
	s_lshl_b64 s[88:89], s[16:17], 11
	v_lshl_add_u64 v[6:7], v[8:9], 0, s[88:89]
	s_add_i32 s16, s16, s14
	s_ashr_i32 s17, s16, 31
	s_lshl_b64 s[16:17], s[16:17], 2
	s_add_u32 s16, s26, s16
	s_addc_u32 s17, s27, s17
	s_or_b32 s18, s4, 29
	s_cmp_lt_u32 s18, s23
	s_waitcnt vmcnt(1)
	v_cndmask_b32_e32 v25, 0, v25, vcc
	v_cndmask_b32_e32 v23, 0, v23, vcc
	s_cselect_b64 vcc, -1, 0
	s_and_b64 s[16:17], vcc, exec
	s_cselect_b32 s16, s18, s4
	s_ashr_i32 s17, s16, 31
	s_lshl_b64 s[88:89], s[16:17], 11
	v_lshl_add_u64 v[6:7], v[8:9], 0, s[88:89]
	s_add_i32 s16, s16, s14
	s_ashr_i32 s17, s16, 31
	s_lshl_b64 s[16:17], s[16:17], 2
	s_add_u32 s16, s26, s16
	s_addc_u32 s17, s27, s17
	s_or_b32 s15, s4, 30
	s_cmp_lt_u32 s15, s23
	s_waitcnt vmcnt(1)
	v_cndmask_b32_e32 v15, 0, v15, vcc
	v_cndmask_b32_e32 v13, 0, v13, vcc
	s_cselect_b64 vcc, -1, 0
	s_and_b64 s[16:17], vcc, exec
	s_cselect_b32 s16, s15, s4
	s_ashr_i32 s17, s16, 31
	s_lshl_b64 s[88:89], s[16:17], 11
	v_lshl_add_u64 v[6:7], v[8:9], 0, s[88:89]
	s_add_i32 s16, s16, s14
	s_ashr_i32 s17, s16, 31
	s_lshl_b64 s[16:17], s[16:17], 2
	s_add_u32 s16, s26, s16
	s_addc_u32 s17, s27, s17
	s_or_b32 s5, s4, 31
	s_cmp_lt_u32 s5, s23
	s_waitcnt vmcnt(0)
	v_cndmask_b32_e32 v11, 0, v122, vcc
	v_cndmask_b32_e32 v7, 0, v123, vcc
	s_cselect_b64 vcc, -1, 0
	global_load_dword v6, v97, s[16:17]
	s_waitcnt vmcnt(0)
	s_and_b64 s[16:17], vcc, exec
	s_cselect_b32 s16, s5, s4
	s_ashr_i32 s17, s16, 31
	s_lshl_b64 s[88:89], s[16:17], 11
	v_lshl_add_u64 v[8:9], v[8:9], 0, s[88:89]
	s_add_i32 s16, s16, s14
	s_ashr_i32 s17, s16, 31
	s_lshl_b64 s[16:17], s[16:17], 2
	s_add_u32 s16, s26, s16
	s_addc_u32 s17, s27, s17
	s_lshl_b64 s[6:7], s[6:7], 11
	s_add_u32 s6, s24, s6
	s_addc_u32 s7, s25, s7
	s_max_i32 s14, s4, 1
	v_lshl_add_u64 v[4:5], s[6:7], 0, v[96:97]
	s_waitcnt vmcnt(0)
	v_cndmask_b32_e32 v19, 0, v124, vcc
	global_load_dword v8, v97, s[16:17]
	s_waitcnt vmcnt(0)
	s_min_i32 s16, s86, s23
	s_sub_i32 s14, s16, s14
	s_add_i32 s14, s14, 1
	v_cvt_f32_i32_e32 v70, s14
	v_cndmask_b32_e32 v9, 0, v125, vcc
	v_div_scale_f32 v108, s[16:17], v70, v70, 1.0
	v_rcp_f32_e32 v109, v108
	s_nop 0
	v_fma_f32 v116, -v108, v109, 1.0
	v_fmac_f32_e32 v109, v116, v109
	v_div_scale_f32 v116, vcc, 1.0, v70, 1.0
	v_mul_f32_e32 v117, v116, v109
	v_fma_f32 v118, -v108, v117, v116
	v_fmac_f32_e32 v117, v118, v109
	v_fma_f32 v108, -v108, v117, v116
	v_div_fmas_f32 v108, v108, v109, v117
	v_div_fixup_f32 v70, v108, v70, 1.0
	v_pk_fma_f32 v[108:109], v[70:71], v[106:107], v[114:115] op_sel_hi:[0,1,1] neg_lo:[0,0,1] neg_hi:[0,0,1]
	v_pk_fma_f32 v[116:117], v[70:71], v[102:103], v[104:105] op_sel_hi:[0,1,1] neg_lo:[0,0,1] neg_hi:[0,0,1]
	v_pk_mul_f32 v[108:109], v[0:1], v[108:109]
	v_cndmask_b32_e64 v70, 0, v67, s[2:3]
	v_cndmask_b32_e64 v67, 0, v66, s[2:3]
	s_max_i32 s2, s86, 1
	s_min_i32 s3, s85, s23
	v_pk_mul_f32 v[116:117], v[2:3], v[116:117]
	v_cvt_pk_bf16_f32 v108, v108, v109
	s_sub_i32 s2, s3, s2
	v_cvt_pk_bf16_f32 v109, v116, v117
	global_store_dwordx2 v96, v[108:109], s[6:7]
	v_lshlrev_b32_e32 v66, 16, v67
	v_and_b32_e32 v67, 0xffff0000, v67
	v_lshlrev_b32_e32 v108, 16, v70
	v_and_b32_e32 v109, 0xffff0000, v70
	s_add_i32 s2, s2, 1
	v_pk_mul_f32 v[116:117], v[68:69], v[108:109] op_sel_hi:[0,1]
	v_pk_mul_f32 v[118:119], v[68:69], v[66:67] op_sel_hi:[0,1]
	v_pk_fma_f32 v[66:67], v[68:69], v[66:67], v[112:113] op_sel_hi:[0,1,1] neg_lo:[0,0,1] neg_hi:[0,0,1]
	v_pk_fma_f32 v[108:109], v[68:69], v[108:109], v[110:111] op_sel_hi:[0,1,1] neg_lo:[0,0,1] neg_hi:[0,0,1]
	v_cvt_f32_i32_e32 v68, s2
	v_pk_add_f32 v[66:67], v[106:107], v[66:67]
	v_pk_add_f32 v[102:103], v[102:103], v[108:109]
	v_div_scale_f32 v70, s[2:3], v68, v68, 1.0
	v_rcp_f32_e32 v106, v70
	s_max_i32 s2, s85, 1
	s_min_i32 s3, s84, s23
	s_sub_i32 s2, s3, s2
	v_fma_f32 v107, -v70, v106, 1.0
	v_fmac_f32_e32 v106, v107, v106
	v_div_scale_f32 v107, vcc, 1.0, v68, 1.0
	v_mul_f32_e32 v108, v107, v106
	v_fma_f32 v109, -v70, v108, v107
	v_fmac_f32_e32 v108, v109, v106
	v_fma_f32 v70, -v70, v108, v107
	v_div_fmas_f32 v70, v70, v106, v108
	v_div_fixup_f32 v68, v70, v68, 1.0
	v_pk_fma_f32 v[106:107], v[68:69], v[66:67], v[118:119] op_sel_hi:[0,1,1] neg_lo:[0,0,1] neg_hi:[0,0,1]
	v_pk_fma_f32 v[108:109], v[68:69], v[102:103], v[116:117] op_sel_hi:[0,1,1] neg_lo:[0,0,1] neg_hi:[0,0,1]
	v_pk_mul_f32 v[106:107], v[0:1], v[106:107]
	v_pk_mul_f32 v[108:109], v[2:3], v[108:109]
	v_cvt_pk_bf16_f32 v106, v106, v107
	s_add_i32 s2, s2, 1
	v_cvt_pk_bf16_f32 v107, v108, v109
	global_store_dwordx2 v96, v[106:107], s[6:7] offset:2048
	v_lshlrev_b32_e32 v106, 16, v101
	v_and_b32_e32 v107, 0xffff0000, v101
	v_lshlrev_b32_e32 v108, 16, v65
	v_and_b32_e32 v109, 0xffff0000, v65
	v_pk_mul_f32 v[110:111], v[64:65], v[108:109] op_sel_hi:[0,1]
	v_pk_mul_f32 v[112:113], v[64:65], v[106:107] op_sel_hi:[0,1]
	v_pk_fma_f32 v[106:107], v[64:65], v[106:107], v[114:115] op_sel_hi:[0,1,1] neg_lo:[0,0,1] neg_hi:[0,0,1]
	v_pk_fma_f32 v[64:65], v[64:65], v[108:109], v[104:105] op_sel_hi:[0,1,1] neg_lo:[0,0,1] neg_hi:[0,0,1]
	v_pk_add_f32 v[102:103], v[102:103], v[64:65]
	v_cvt_f32_i32_e32 v64, s2
	v_pk_add_f32 v[66:67], v[66:67], v[106:107]
	v_div_scale_f32 v65, s[2:3], v64, v64, 1.0
	v_rcp_f32_e32 v68, v65
	s_max_i32 s2, s84, 1
	s_min_i32 s3, s83, s23
	s_sub_i32 s2, s3, s2
	v_fma_f32 v70, -v65, v68, 1.0
	v_fmac_f32_e32 v68, v70, v68
	v_div_scale_f32 v70, vcc, 1.0, v64, 1.0
	v_mul_f32_e32 v96, v70, v68
	v_fma_f32 v101, -v65, v96, v70
	v_fmac_f32_e32 v96, v101, v68
	v_fma_f32 v65, -v65, v96, v70
	v_div_fmas_f32 v65, v65, v68, v96
	v_div_fixup_f32 v64, v65, v64, 1.0
	v_pk_fma_f32 v[104:105], v[64:65], v[66:67], v[112:113] op_sel_hi:[0,1,1] neg_lo:[0,0,1] neg_hi:[0,0,1]
	v_pk_fma_f32 v[64:65], v[64:65], v[102:103], v[110:111] op_sel_hi:[0,1,1] neg_lo:[0,0,1] neg_hi:[0,0,1]
	v_add_co_u32_e32 v106, vcc, s92, v4
	v_pk_mul_f32 v[64:65], v[2:3], v[64:65]
	v_pk_mul_f32 v[104:105], v[0:1], v[104:105]
	v_addc_co_u32_e32 v107, vcc, 0, v5, vcc
	v_cvt_pk_bf16_f32 v104, v104, v105
	v_cvt_pk_bf16_f32 v105, v64, v65
	v_add_co_u32_e32 v64, vcc, s91, v4
	v_and_b32_e32 v101, 0xffff0000, v99
	s_nop 0
	v_addc_co_u32_e32 v65, vcc, 0, v5, vcc
	global_store_dwordx2 v[64:65], v[104:105], off offset:-4096
	v_lshlrev_b32_e32 v104, 16, v100
	v_and_b32_e32 v105, 0xffff0000, v100
	v_lshlrev_b32_e32 v100, 16, v99
	s_add_i32 s2, s2, 1
	v_pk_mul_f32 v[108:109], v[62:63], v[100:101] op_sel_hi:[0,1]
	v_pk_mul_f32 v[114:115], v[62:63], v[104:105] op_sel_hi:[0,1]
	v_pk_fma_f32 v[104:105], v[62:63], v[104:105], v[118:119] op_sel_hi:[0,1,1] neg_lo:[0,0,1] neg_hi:[0,0,1]
	v_pk_fma_f32 v[100:101], v[62:63], v[100:101], v[116:117] op_sel_hi:[0,1,1] neg_lo:[0,0,1] neg_hi:[0,0,1]
	v_cvt_f32_i32_e32 v62, s2
	v_pk_add_f32 v[100:101], v[102:103], v[100:101]
	v_pk_add_f32 v[66:67], v[66:67], v[104:105]
	v_div_scale_f32 v68, s[2:3], v62, v62, 1.0
	v_rcp_f32_e32 v70, v68
	s_max_i32 s2, s83, 1
	s_min_i32 s3, s82, s23
	s_sub_i32 s2, s3, s2
	v_fma_f32 v96, -v68, v70, 1.0
	v_fmac_f32_e32 v70, v96, v70
	v_div_scale_f32 v96, vcc, 1.0, v62, 1.0
	v_mul_f32_e32 v99, v96, v70
	v_fma_f32 v102, -v68, v99, v96
	v_fmac_f32_e32 v99, v102, v70
	v_fma_f32 v68, -v68, v99, v96
	v_div_fmas_f32 v68, v68, v70, v99
	v_div_fixup_f32 v62, v68, v62, 1.0
	v_pk_fma_f32 v[102:103], v[62:63], v[66:67], v[114:115] op_sel_hi:[0,1,1] neg_lo:[0,0,1] neg_hi:[0,0,1]
	v_pk_fma_f32 v[104:105], v[62:63], v[100:101], v[108:109] op_sel_hi:[0,1,1] neg_lo:[0,0,1] neg_hi:[0,0,1]
	v_pk_mul_f32 v[102:103], v[0:1], v[102:103]
	v_pk_mul_f32 v[104:105], v[2:3], v[104:105]
	v_cvt_pk_bf16_f32 v102, v102, v103
	v_and_b32_e32 v99, 0xffff0000, v95
	v_cvt_pk_bf16_f32 v103, v104, v105
	global_store_dwordx2 v[106:107], v[102:103], off offset:2048
	v_lshlrev_b32_e32 v102, 16, v98
	v_and_b32_e32 v103, 0xffff0000, v98
	v_lshlrev_b32_e32 v98, 16, v95
	s_add_i32 s2, s2, 1
	v_pk_mul_f32 v[104:105], v[60:61], v[98:99] op_sel_hi:[0,1]
	v_pk_mul_f32 v[106:107], v[60:61], v[102:103] op_sel_hi:[0,1]
	v_pk_fma_f32 v[102:103], v[60:61], v[102:103], v[112:113] op_sel_hi:[0,1,1] neg_lo:[0,0,1] neg_hi:[0,0,1]
	v_pk_fma_f32 v[98:99], v[60:61], v[98:99], v[110:111] op_sel_hi:[0,1,1] neg_lo:[0,0,1] neg_hi:[0,0,1]
	v_cvt_f32_i32_e32 v60, s2
	v_pk_add_f32 v[66:67], v[66:67], v[102:103]
	v_pk_add_f32 v[98:99], v[100:101], v[98:99]
	v_div_scale_f32 v62, s[2:3], v60, v60, 1.0
	v_rcp_f32_e32 v68, v62
	s_max_i32 s2, s82, 1
	s_min_i32 s3, s81, s23
	s_sub_i32 s2, s3, s2
	v_fma_f32 v70, -v62, v68, 1.0
	v_fmac_f32_e32 v68, v70, v68
	v_div_scale_f32 v70, vcc, 1.0, v60, 1.0
	v_mul_f32_e32 v95, v70, v68
	v_fma_f32 v96, -v62, v95, v70
	v_fmac_f32_e32 v95, v96, v68
	v_fma_f32 v62, -v62, v95, v70
	v_div_fmas_f32 v62, v62, v68, v95
	v_div_fixup_f32 v60, v62, v60, 1.0
	v_pk_fma_f32 v[100:101], v[60:61], v[66:67], v[106:107] op_sel_hi:[0,1,1] neg_lo:[0,0,1] neg_hi:[0,0,1]
	v_pk_fma_f32 v[102:103], v[60:61], v[98:99], v[104:105] op_sel_hi:[0,1,1] neg_lo:[0,0,1] neg_hi:[0,0,1]
	v_pk_mul_f32 v[100:101], v[0:1], v[100:101]
	v_pk_mul_f32 v[102:103], v[2:3], v[102:103]
	v_cvt_pk_bf16_f32 v100, v100, v101
	v_and_b32_e32 v95, 0xffff0000, v93
	v_cvt_pk_bf16_f32 v101, v102, v103
	global_store_dwordx2 v[64:65], v[100:101], off
	v_lshlrev_b32_e32 v100, 16, v94
	v_and_b32_e32 v101, 0xffff0000, v94
	v_lshlrev_b32_e32 v94, 16, v93
	s_add_i32 s2, s2, 1
	v_pk_mul_f32 v[102:103], v[58:59], v[94:95] op_sel_hi:[0,1]
	v_pk_mul_f32 v[110:111], v[58:59], v[100:101] op_sel_hi:[0,1]
	v_pk_fma_f32 v[100:101], v[58:59], v[100:101], v[114:115] op_sel_hi:[0,1,1] neg_lo:[0,0,1] neg_hi:[0,0,1]
	v_pk_fma_f32 v[94:95], v[58:59], v[94:95], v[108:109] op_sel_hi:[0,1,1] neg_lo:[0,0,1] neg_hi:[0,0,1]
	v_cvt_f32_i32_e32 v58, s2
	v_pk_add_f32 v[66:67], v[66:67], v[100:101]
	v_pk_add_f32 v[94:95], v[98:99], v[94:95]
	v_div_scale_f32 v60, s[2:3], v58, v58, 1.0
	v_rcp_f32_e32 v62, v60
	s_max_i32 s2, s81, 1
	s_min_i32 s3, s80, s23
	s_sub_i32 s2, s3, s2
	v_fma_f32 v68, -v60, v62, 1.0
	v_fmac_f32_e32 v62, v68, v62
	v_div_scale_f32 v68, vcc, 1.0, v58, 1.0
	v_mul_f32_e32 v70, v68, v62
	v_fma_f32 v93, -v60, v70, v68
	v_fmac_f32_e32 v70, v93, v62
	v_fma_f32 v60, -v60, v70, v68
	v_div_fmas_f32 v60, v60, v62, v70
	v_div_fixup_f32 v58, v60, v58, 1.0
	v_pk_fma_f32 v[98:99], v[58:59], v[66:67], v[110:111] op_sel_hi:[0,1,1] neg_lo:[0,0,1] neg_hi:[0,0,1]
	v_pk_fma_f32 v[100:101], v[58:59], v[94:95], v[102:103] op_sel_hi:[0,1,1] neg_lo:[0,0,1] neg_hi:[0,0,1]
	v_pk_mul_f32 v[98:99], v[0:1], v[98:99]
	v_pk_mul_f32 v[100:101], v[2:3], v[100:101]
	v_cvt_pk_bf16_f32 v98, v98, v99
	v_and_b32_e32 v93, 0xffff0000, v57
	v_cvt_pk_bf16_f32 v99, v100, v101
	global_store_dwordx2 v[64:65], v[98:99], off offset:2048
	v_lshlrev_b32_e32 v64, 16, v92
	v_and_b32_e32 v65, 0xffff0000, v92
	v_lshlrev_b32_e32 v92, 16, v57
	v_pk_mul_f32 v[98:99], v[56:57], v[92:93] op_sel_hi:[0,1]
	v_pk_mul_f32 v[100:101], v[56:57], v[64:65] op_sel_hi:[0,1]
	v_pk_fma_f32 v[64:65], v[56:57], v[64:65], v[106:107] op_sel_hi:[0,1,1] neg_lo:[0,0,1] neg_hi:[0,0,1]
	v_pk_fma_f32 v[56:57], v[56:57], v[92:93], v[104:105] op_sel_hi:[0,1,1] neg_lo:[0,0,1] neg_hi:[0,0,1]
	s_add_i32 s2, s2, 1
	v_pk_add_f32 v[92:93], v[94:95], v[56:57]
	v_cvt_f32_i32_e32 v56, s2
	v_pk_add_f32 v[64:65], v[66:67], v[64:65]
	v_lshlrev_b32_e32 v104, 16, v90
	v_and_b32_e32 v105, 0xffff0000, v90
	v_div_scale_f32 v57, s[2:3], v56, v56, 1.0
	v_rcp_f32_e32 v58, v57
	s_movk_i32 s2, 0x3000
	s_min_i32 s3, s79, s23
	v_pk_fma_f32 v[102:103], v[54:55], v[104:105], v[102:103] op_sel_hi:[0,1,1] neg_lo:[0,0,1] neg_hi:[0,0,1]
	v_fma_f32 v60, -v57, v58, 1.0
	v_fmac_f32_e32 v58, v60, v58
	v_div_scale_f32 v60, vcc, 1.0, v56, 1.0
	v_mul_f32_e32 v62, v60, v58
	v_fma_f32 v66, -v57, v62, v60
	v_fmac_f32_e32 v62, v66, v58
	v_fma_f32 v57, -v57, v62, v60
	v_div_fmas_f32 v57, v57, v58, v62
	v_div_fixup_f32 v56, v57, v56, 1.0
	v_pk_fma_f32 v[66:67], v[56:57], v[64:65], v[100:101] op_sel_hi:[0,1,1] neg_lo:[0,0,1] neg_hi:[0,0,1]
	v_pk_fma_f32 v[56:57], v[56:57], v[92:93], v[98:99] op_sel_hi:[0,1,1] neg_lo:[0,0,1] neg_hi:[0,0,1]
	v_add_co_u32_e32 v94, vcc, s2, v4
	v_pk_mul_f32 v[56:57], v[2:3], v[56:57]
	v_pk_mul_f32 v[66:67], v[0:1], v[66:67]
	v_addc_co_u32_e32 v95, vcc, 0, v5, vcc
	v_cvt_pk_bf16_f32 v66, v66, v67
	v_cvt_pk_bf16_f32 v67, v56, v57
	v_add_co_u32_e32 v56, vcc, s9, v4
	s_max_i32 s2, s80, 1
	s_nop 0
	v_addc_co_u32_e32 v57, vcc, 0, v5, vcc
	s_sub_i32 s2, s3, s2
	global_store_dwordx2 v[56:57], v[66:67], off offset:-4096
	v_lshlrev_b32_e32 v66, 16, v91
	v_and_b32_e32 v67, 0xffff0000, v91
	s_add_i32 s2, s2, 1
	v_pk_mul_f32 v[90:91], v[54:55], v[104:105] op_sel_hi:[0,1]
	v_pk_mul_f32 v[106:107], v[54:55], v[66:67] op_sel_hi:[0,1]
	v_pk_fma_f32 v[66:67], v[54:55], v[66:67], v[110:111] op_sel_hi:[0,1,1] neg_lo:[0,0,1] neg_hi:[0,0,1]
	v_cvt_f32_i32_e32 v54, s2
	v_pk_add_f32 v[64:65], v[64:65], v[66:67]
	v_pk_add_f32 v[92:93], v[92:93], v[102:103]
	v_div_scale_f32 v58, s[2:3], v54, v54, 1.0
	v_rcp_f32_e32 v60, v58
	s_max_i32 s2, s79, 1
	s_min_i32 s3, s78, s23
	s_sub_i32 s2, s3, s2
	v_fma_f32 v62, -v58, v60, 1.0
	v_fmac_f32_e32 v60, v62, v60
	v_div_scale_f32 v62, vcc, 1.0, v54, 1.0
	v_mul_f32_e32 v66, v62, v60
	v_fma_f32 v67, -v58, v66, v62
	v_fmac_f32_e32 v66, v67, v60
	v_fma_f32 v58, -v58, v66, v62
	v_div_fmas_f32 v58, v58, v60, v66
	v_div_fixup_f32 v54, v58, v54, 1.0
	v_pk_fma_f32 v[66:67], v[54:55], v[64:65], v[106:107] op_sel_hi:[0,1,1] neg_lo:[0,0,1] neg_hi:[0,0,1]
	v_pk_fma_f32 v[102:103], v[54:55], v[92:93], v[90:91] op_sel_hi:[0,1,1] neg_lo:[0,0,1] neg_hi:[0,0,1]
	v_pk_mul_f32 v[66:67], v[0:1], v[66:67]
	v_pk_mul_f32 v[102:103], v[2:3], v[102:103]
	v_cvt_pk_bf16_f32 v66, v66, v67
	s_add_i32 s2, s2, 1
	v_cvt_pk_bf16_f32 v67, v102, v103
	global_store_dwordx2 v[94:95], v[66:67], off offset:2048
	v_lshlrev_b32_e32 v66, 16, v89
	v_and_b32_e32 v67, 0xffff0000, v89
	v_lshlrev_b32_e32 v94, 16, v88
	v_and_b32_e32 v95, 0xffff0000, v88
	v_pk_mul_f32 v[88:89], v[52:53], v[94:95] op_sel_hi:[0,1]
	v_pk_mul_f32 v[102:103], v[52:53], v[66:67] op_sel_hi:[0,1]
	v_pk_fma_f32 v[66:67], v[52:53], v[66:67], v[100:101] op_sel_hi:[0,1,1] neg_lo:[0,0,1] neg_hi:[0,0,1]
	v_pk_fma_f32 v[94:95], v[52:53], v[94:95], v[98:99] op_sel_hi:[0,1,1] neg_lo:[0,0,1] neg_hi:[0,0,1]
	v_cvt_f32_i32_e32 v52, s2
	v_pk_add_f32 v[64:65], v[64:65], v[66:67]
	v_pk_add_f32 v[92:93], v[92:93], v[94:95]
	v_div_scale_f32 v54, s[2:3], v52, v52, 1.0
	v_rcp_f32_e32 v58, v54
	s_max_i32 s2, s78, 1
	s_min_i32 s3, s77, s23
	s_sub_i32 s2, s3, s2
	v_fma_f32 v60, -v54, v58, 1.0
	v_fmac_f32_e32 v58, v60, v58
	v_div_scale_f32 v60, vcc, 1.0, v52, 1.0
	v_mul_f32_e32 v62, v60, v58
	v_fma_f32 v66, -v54, v62, v60
	v_fmac_f32_e32 v62, v66, v58
	v_fma_f32 v54, -v54, v62, v60
	v_div_fmas_f32 v54, v54, v58, v62
	v_div_fixup_f32 v52, v54, v52, 1.0
	v_pk_fma_f32 v[66:67], v[52:53], v[64:65], v[102:103] op_sel_hi:[0,1,1] neg_lo:[0,0,1] neg_hi:[0,0,1]
	v_pk_fma_f32 v[94:95], v[52:53], v[92:93], v[88:89] op_sel_hi:[0,1,1] neg_lo:[0,0,1] neg_hi:[0,0,1]
	v_pk_mul_f32 v[66:67], v[0:1], v[66:67]
	v_pk_mul_f32 v[94:95], v[2:3], v[94:95]
	v_cvt_pk_bf16_f32 v66, v66, v67
	s_add_i32 s2, s2, 1
	v_cvt_pk_bf16_f32 v67, v94, v95
	global_store_dwordx2 v[56:57], v[66:67], off
	v_lshlrev_b32_e32 v66, 16, v87
	v_and_b32_e32 v67, 0xffff0000, v87
	v_lshlrev_b32_e32 v94, 16, v86
	v_and_b32_e32 v95, 0xffff0000, v86
	v_pk_mul_f32 v[86:87], v[50:51], v[94:95] op_sel_hi:[0,1]
	v_pk_mul_f32 v[98:99], v[50:51], v[66:67] op_sel_hi:[0,1]
	v_pk_fma_f32 v[66:67], v[50:51], v[66:67], v[106:107] op_sel_hi:[0,1,1] neg_lo:[0,0,1] neg_hi:[0,0,1]
	v_pk_fma_f32 v[90:91], v[50:51], v[94:95], v[90:91] op_sel_hi:[0,1,1] neg_lo:[0,0,1] neg_hi:[0,0,1]
	v_cvt_f32_i32_e32 v50, s2
	v_pk_add_f32 v[64:65], v[64:65], v[66:67]
	v_pk_add_f32 v[90:91], v[92:93], v[90:91]
	v_div_scale_f32 v52, s[2:3], v50, v50, 1.0
	v_rcp_f32_e32 v54, v52
	s_max_i32 s2, s77, 1
	s_min_i32 s3, s76, s23
	s_sub_i32 s2, s3, s2
	v_fma_f32 v58, -v52, v54, 1.0
	v_fmac_f32_e32 v54, v58, v54
	v_div_scale_f32 v58, vcc, 1.0, v50, 1.0
	v_mul_f32_e32 v60, v58, v54
	v_fma_f32 v62, -v52, v60, v58
	v_fmac_f32_e32 v60, v62, v54
	v_fma_f32 v52, -v52, v60, v58
	v_div_fmas_f32 v52, v52, v54, v60
	v_div_fixup_f32 v50, v52, v50, 1.0
	v_pk_fma_f32 v[66:67], v[50:51], v[64:65], v[98:99] op_sel_hi:[0,1,1] neg_lo:[0,0,1] neg_hi:[0,0,1]
	v_pk_fma_f32 v[92:93], v[50:51], v[90:91], v[86:87] op_sel_hi:[0,1,1] neg_lo:[0,0,1] neg_hi:[0,0,1]
	v_pk_mul_f32 v[66:67], v[0:1], v[66:67]
	v_pk_mul_f32 v[92:93], v[2:3], v[92:93]
	v_cvt_pk_bf16_f32 v66, v66, v67
	s_add_i32 s2, s2, 1
	v_cvt_pk_bf16_f32 v67, v92, v93
	global_store_dwordx2 v[56:57], v[66:67], off offset:2048
	v_lshlrev_b32_e32 v56, 16, v85
	v_and_b32_e32 v57, 0xffff0000, v85
	v_lshlrev_b32_e32 v66, 16, v49
	v_and_b32_e32 v67, 0xffff0000, v49
	v_pk_mul_f32 v[92:93], v[48:49], v[66:67] op_sel_hi:[0,1]
	v_pk_mul_f32 v[94:95], v[48:49], v[56:57] op_sel_hi:[0,1]
	v_pk_fma_f32 v[56:57], v[48:49], v[56:57], v[102:103] op_sel_hi:[0,1,1] neg_lo:[0,0,1] neg_hi:[0,0,1]
	v_pk_fma_f32 v[48:49], v[48:49], v[66:67], v[88:89] op_sel_hi:[0,1,1] neg_lo:[0,0,1] neg_hi:[0,0,1]
	v_pk_add_f32 v[66:67], v[90:91], v[48:49]
	v_cvt_f32_i32_e32 v48, s2
	v_pk_add_f32 v[56:57], v[64:65], v[56:57]
	v_and_b32_e32 v85, 0xffff0000, v83
	v_lshlrev_b32_e32 v62, 16, v63
	v_div_scale_f32 v49, s[2:3], v48, v48, 1.0
	v_rcp_f32_e32 v50, v49
	s_max_i32 s2, s76, 1
	s_min_i32 s3, s74, s23
	s_sub_i32 s2, s3, s2
	v_fma_f32 v52, -v49, v50, 1.0
	v_fmac_f32_e32 v50, v52, v50
	v_div_scale_f32 v52, vcc, 1.0, v48, 1.0
	v_mul_f32_e32 v54, v52, v50
	v_fma_f32 v58, -v49, v54, v52
	v_fmac_f32_e32 v54, v58, v50
	v_fma_f32 v49, -v49, v54, v52
	v_div_fmas_f32 v49, v49, v50, v54
	v_div_fixup_f32 v48, v49, v48, 1.0
	v_pk_fma_f32 v[64:65], v[48:49], v[56:57], v[94:95] op_sel_hi:[0,1,1] neg_lo:[0,0,1] neg_hi:[0,0,1]
	v_pk_fma_f32 v[48:49], v[48:49], v[66:67], v[92:93] op_sel_hi:[0,1,1] neg_lo:[0,0,1] neg_hi:[0,0,1]
	v_add_co_u32_e32 v88, vcc, s38, v4
	v_pk_mul_f32 v[48:49], v[2:3], v[48:49]
	v_pk_mul_f32 v[64:65], v[0:1], v[64:65]
	v_addc_co_u32_e32 v89, vcc, 0, v5, vcc
	v_cvt_pk_bf16_f32 v64, v64, v65
	v_cvt_pk_bf16_f32 v65, v48, v49
	v_add_co_u32_e32 v48, vcc, s39, v4
	s_add_i32 s2, s2, 1
	s_nop 0
	v_addc_co_u32_e32 v49, vcc, 0, v5, vcc
	global_store_dwordx2 v[48:49], v[64:65], off offset:-4096
	v_lshlrev_b32_e32 v64, 16, v84
	v_and_b32_e32 v65, 0xffff0000, v84
	v_lshlrev_b32_e32 v84, 16, v83
	v_pk_mul_f32 v[90:91], v[44:45], v[84:85] op_sel_hi:[0,1]
	v_pk_mul_f32 v[100:101], v[44:45], v[64:65] op_sel_hi:[0,1]
	v_pk_fma_f32 v[64:65], v[44:45], v[64:65], v[98:99] op_sel_hi:[0,1,1] neg_lo:[0,0,1] neg_hi:[0,0,1]
	v_pk_fma_f32 v[84:85], v[44:45], v[84:85], v[86:87] op_sel_hi:[0,1,1] neg_lo:[0,0,1] neg_hi:[0,0,1]
	v_cvt_f32_i32_e32 v44, s2
	v_pk_add_f32 v[56:57], v[56:57], v[64:65]
	v_pk_add_f32 v[66:67], v[66:67], v[84:85]
	v_and_b32_e32 v63, 0xffff0000, v63
	v_div_scale_f32 v50, s[2:3], v44, v44, 1.0
	v_rcp_f32_e32 v52, v50
	s_max_i32 s2, s74, 1
	s_min_i32 s3, s35, s23
	s_sub_i32 s2, s3, s2
	v_fma_f32 v54, -v50, v52, 1.0
	v_fmac_f32_e32 v52, v54, v52
	v_div_scale_f32 v54, vcc, 1.0, v44, 1.0
	v_mul_f32_e32 v58, v54, v52
	v_fma_f32 v60, -v50, v58, v54
	v_fmac_f32_e32 v58, v60, v52
	v_fma_f32 v50, -v50, v58, v54
	v_div_fmas_f32 v50, v50, v52, v58
	v_div_fixup_f32 v44, v50, v44, 1.0
	v_pk_fma_f32 v[64:65], v[44:45], v[56:57], v[100:101] op_sel_hi:[0,1,1] neg_lo:[0,0,1] neg_hi:[0,0,1]
	v_pk_fma_f32 v[84:85], v[44:45], v[66:67], v[90:91] op_sel_hi:[0,1,1] neg_lo:[0,0,1] neg_hi:[0,0,1]
	v_pk_mul_f32 v[64:65], v[0:1], v[64:65]
	v_pk_mul_f32 v[84:85], v[2:3], v[84:85]
	v_cvt_pk_bf16_f32 v64, v64, v65
	s_add_i32 s2, s2, 1
	v_cvt_pk_bf16_f32 v65, v84, v85
	global_store_dwordx2 v[88:89], v[64:65], off offset:2048
	v_lshlrev_b32_e32 v64, 16, v80
	v_and_b32_e32 v65, 0xffff0000, v80
	v_lshlrev_b32_e32 v84, 16, v79
	v_and_b32_e32 v85, 0xffff0000, v79
	v_pk_mul_f32 v[86:87], v[38:39], v[84:85] op_sel_hi:[0,1]
	v_pk_mul_f32 v[88:89], v[38:39], v[64:65] op_sel_hi:[0,1]
	v_pk_fma_f32 v[64:65], v[38:39], v[64:65], v[94:95] op_sel_hi:[0,1,1] neg_lo:[0,0,1] neg_hi:[0,0,1]
	v_pk_fma_f32 v[84:85], v[38:39], v[84:85], v[92:93] op_sel_hi:[0,1,1] neg_lo:[0,0,1] neg_hi:[0,0,1]
	v_cvt_f32_i32_e32 v38, s2
	v_pk_add_f32 v[56:57], v[56:57], v[64:65]
	v_pk_add_f32 v[66:67], v[66:67], v[84:85]
	v_div_scale_f32 v44, s[2:3], v38, v38, 1.0
	v_rcp_f32_e32 v50, v44
	s_max_i32 s2, s35, 1
	s_min_i32 s3, s75, s23
	s_sub_i32 s2, s3, s2
	v_fma_f32 v52, -v44, v50, 1.0
	v_fmac_f32_e32 v50, v52, v50
	v_div_scale_f32 v52, vcc, 1.0, v38, 1.0
	v_mul_f32_e32 v54, v52, v50
	v_fma_f32 v58, -v44, v54, v52
	v_fmac_f32_e32 v54, v58, v50
	v_fma_f32 v44, -v44, v54, v52
	v_div_fmas_f32 v44, v44, v50, v54
	v_div_fixup_f32 v38, v44, v38, 1.0
	s_add_i32 s2, s2, 1
	v_pk_fma_f32 v[64:65], v[38:39], v[56:57], v[88:89] op_sel_hi:[0,1,1] neg_lo:[0,0,1] neg_hi:[0,0,1]
	v_cvt_f32_i32_e32 v44, s2
	v_pk_fma_f32 v[84:85], v[38:39], v[66:67], v[86:87] op_sel_hi:[0,1,1] neg_lo:[0,0,1] neg_hi:[0,0,1]
	v_pk_mul_f32 v[64:65], v[0:1], v[64:65]
	v_pk_mul_f32 v[84:85], v[2:3], v[84:85]
	v_cvt_pk_bf16_f32 v64, v64, v65
	v_lshlrev_b32_e32 v38, 16, v39
	v_cvt_pk_bf16_f32 v65, v84, v85
	global_store_dwordx2 v[48:49], v[64:65], off
	v_lshlrev_b32_e32 v64, 16, v76
	v_and_b32_e32 v65, 0xffff0000, v76
	v_and_b32_e32 v39, 0xffff0000, v39
	v_pk_mul_f32 v[84:85], v[46:47], v[38:39] op_sel_hi:[0,1]
	v_pk_mul_f32 v[92:93], v[46:47], v[64:65] op_sel_hi:[0,1]
	v_pk_fma_f32 v[64:65], v[46:47], v[64:65], v[100:101] op_sel_hi:[0,1,1] neg_lo:[0,0,1] neg_hi:[0,0,1]
	v_pk_fma_f32 v[38:39], v[46:47], v[38:39], v[90:91] op_sel_hi:[0,1,1] neg_lo:[0,0,1] neg_hi:[0,0,1]
	v_div_scale_f32 v46, s[2:3], v44, v44, 1.0
	v_rcp_f32_e32 v50, v46
	v_pk_add_f32 v[56:57], v[56:57], v[64:65]
	v_pk_add_f32 v[38:39], v[66:67], v[38:39]
	s_max_i32 s2, s75, 1
	v_fma_f32 v52, -v46, v50, 1.0
	v_fmac_f32_e32 v50, v52, v50
	v_div_scale_f32 v52, vcc, 1.0, v44, 1.0
	v_mul_f32_e32 v54, v52, v50
	v_fma_f32 v58, -v46, v54, v52
	v_fmac_f32_e32 v54, v58, v50
	v_fma_f32 v46, -v46, v54, v52
	v_div_fmas_f32 v46, v46, v50, v54
	v_div_fixup_f32 v44, v46, v44, 1.0
	v_pk_fma_f32 v[64:65], v[44:45], v[56:57], v[92:93] op_sel_hi:[0,1,1] neg_lo:[0,0,1] neg_hi:[0,0,1]
	v_pk_fma_f32 v[66:67], v[44:45], v[38:39], v[84:85] op_sel_hi:[0,1,1] neg_lo:[0,0,1] neg_hi:[0,0,1]
	v_pk_mul_f32 v[64:65], v[0:1], v[64:65]
	v_pk_mul_f32 v[66:67], v[2:3], v[66:67]
	v_cvt_pk_bf16_f32 v64, v64, v65
	s_min_i32 s3, s73, s23
	v_cvt_pk_bf16_f32 v65, v66, v67
	global_store_dwordx2 v[48:49], v[64:65], off offset:2048
	v_lshlrev_b32_e32 v64, 16, v81
	v_and_b32_e32 v65, 0xffff0000, v81
	s_sub_i32 s2, s3, s2
	v_pk_mul_f32 v[66:67], v[42:43], v[64:65] op_sel_hi:[0,1]
	v_pk_fma_f32 v[64:65], v[42:43], v[64:65], v[86:87] op_sel_hi:[0,1,1] neg_lo:[0,0,1] neg_hi:[0,0,1]
	s_add_i32 s2, s2, 1
	v_pk_add_f32 v[64:65], v[38:39], v[64:65]
	v_cvt_f32_i32_e32 v38, s2
	v_lshlrev_b32_e32 v48, 16, v82
	v_and_b32_e32 v49, 0xffff0000, v82
	v_pk_mul_f32 v[80:81], v[42:43], v[48:49] op_sel_hi:[0,1]
	v_div_scale_f32 v39, s[2:3], v38, v38, 1.0
	v_pk_fma_f32 v[48:49], v[42:43], v[48:49], v[88:89] op_sel_hi:[0,1,1] neg_lo:[0,0,1] neg_hi:[0,0,1]
	v_rcp_f32_e32 v42, v39
	v_pk_add_f32 v[48:49], v[56:57], v[48:49]
	s_movk_i32 s2, 0x7000
	s_min_i32 s3, s72, s23
	v_fma_f32 v44, -v39, v42, 1.0
	v_fmac_f32_e32 v42, v44, v42
	v_div_scale_f32 v44, vcc, 1.0, v38, 1.0
	v_mul_f32_e32 v46, v44, v42
	v_fma_f32 v50, -v39, v46, v44
	v_fmac_f32_e32 v46, v50, v42
	v_fma_f32 v39, -v39, v46, v44
	v_div_fmas_f32 v39, v39, v42, v46
	v_div_fixup_f32 v38, v39, v38, 1.0
	v_pk_fma_f32 v[56:57], v[38:39], v[48:49], v[80:81] op_sel_hi:[0,1,1] neg_lo:[0,0,1] neg_hi:[0,0,1]
	v_pk_fma_f32 v[38:39], v[38:39], v[64:65], v[66:67] op_sel_hi:[0,1,1] neg_lo:[0,0,1] neg_hi:[0,0,1]
	v_add_co_u32_e32 v82, vcc, s2, v4
	v_pk_mul_f32 v[38:39], v[2:3], v[38:39]
	v_pk_mul_f32 v[56:57], v[0:1], v[56:57]
	v_addc_co_u32_e32 v83, vcc, 0, v5, vcc
	v_cvt_pk_bf16_f32 v56, v56, v57
	v_cvt_pk_bf16_f32 v57, v38, v39
	v_add_co_u32_e32 v38, vcc, s61, v4
	s_max_i32 s2, s73, 1
	s_nop 0
	v_addc_co_u32_e32 v39, vcc, 0, v5, vcc
	s_sub_i32 s2, s3, s2
	global_store_dwordx2 v[38:39], v[56:57], off offset:-4096
	v_lshlrev_b32_e32 v56, 16, v78
	v_and_b32_e32 v57, 0xffff0000, v78
	v_lshlrev_b32_e32 v76, 16, v77
	v_and_b32_e32 v77, 0xffff0000, v77
	s_add_i32 s2, s2, 1
	v_pk_mul_f32 v[78:79], v[40:41], v[76:77] op_sel_hi:[0,1]
	v_pk_mul_f32 v[86:87], v[40:41], v[56:57] op_sel_hi:[0,1]
	v_pk_fma_f32 v[56:57], v[40:41], v[56:57], v[92:93] op_sel_hi:[0,1,1] neg_lo:[0,0,1] neg_hi:[0,0,1]
	v_pk_fma_f32 v[76:77], v[40:41], v[76:77], v[84:85] op_sel_hi:[0,1,1] neg_lo:[0,0,1] neg_hi:[0,0,1]
	v_cvt_f32_i32_e32 v40, s2
	v_pk_add_f32 v[48:49], v[48:49], v[56:57]
	v_pk_add_f32 v[64:65], v[64:65], v[76:77]
	v_lshlrev_b32_e32 v58, 16, v59
	v_div_scale_f32 v42, s[2:3], v40, v40, 1.0
	v_rcp_f32_e32 v44, v42
	s_max_i32 s2, s72, 1
	s_min_i32 s3, s71, s23
	s_sub_i32 s2, s3, s2
	v_fma_f32 v46, -v42, v44, 1.0
	v_fmac_f32_e32 v44, v46, v44
	v_div_scale_f32 v46, vcc, 1.0, v40, 1.0
	v_mul_f32_e32 v50, v46, v44
	v_fma_f32 v52, -v42, v50, v46
	v_fmac_f32_e32 v50, v52, v44
	v_fma_f32 v42, -v42, v50, v46
	v_div_fmas_f32 v42, v42, v44, v50
	v_div_fixup_f32 v40, v42, v40, 1.0
	v_pk_fma_f32 v[56:57], v[40:41], v[48:49], v[86:87] op_sel_hi:[0,1,1] neg_lo:[0,0,1] neg_hi:[0,0,1]
	v_pk_fma_f32 v[76:77], v[40:41], v[64:65], v[78:79] op_sel_hi:[0,1,1] neg_lo:[0,0,1] neg_hi:[0,0,1]
	v_pk_mul_f32 v[56:57], v[0:1], v[56:57]
	v_pk_mul_f32 v[76:77], v[2:3], v[76:77]
	v_cvt_pk_bf16_f32 v56, v56, v57
	s_add_i32 s2, s2, 1
	v_cvt_pk_bf16_f32 v57, v76, v77
	global_store_dwordx2 v[82:83], v[56:57], off offset:2048
	v_lshlrev_b32_e32 v56, 16, v75
	v_and_b32_e32 v57, 0xffff0000, v75
	v_lshlrev_b32_e32 v76, 16, v74
	v_and_b32_e32 v77, 0xffff0000, v74
	v_pk_mul_f32 v[74:75], v[36:37], v[76:77] op_sel_hi:[0,1]
	v_pk_mul_f32 v[82:83], v[36:37], v[56:57] op_sel_hi:[0,1]
	v_pk_fma_f32 v[56:57], v[36:37], v[56:57], v[80:81] op_sel_hi:[0,1,1] neg_lo:[0,0,1] neg_hi:[0,0,1]
	v_pk_fma_f32 v[66:67], v[36:37], v[76:77], v[66:67] op_sel_hi:[0,1,1] neg_lo:[0,0,1] neg_hi:[0,0,1]
	v_cvt_f32_i32_e32 v36, s2
	v_pk_add_f32 v[48:49], v[48:49], v[56:57]
	v_pk_add_f32 v[64:65], v[64:65], v[66:67]
	v_and_b32_e32 v59, 0xffff0000, v59
	v_div_scale_f32 v40, s[2:3], v36, v36, 1.0
	v_rcp_f32_e32 v42, v40
	s_max_i32 s2, s71, 1
	s_min_i32 s3, s70, s23
	s_sub_i32 s2, s3, s2
	v_fma_f32 v44, -v40, v42, 1.0
	v_fmac_f32_e32 v42, v44, v42
	v_div_scale_f32 v44, vcc, 1.0, v36, 1.0
	v_mul_f32_e32 v46, v44, v42
	v_fma_f32 v50, -v40, v46, v44
	v_fmac_f32_e32 v46, v50, v42
	v_fma_f32 v40, -v40, v46, v44
	v_div_fmas_f32 v40, v40, v42, v46
	v_div_fixup_f32 v36, v40, v36, 1.0
	v_pk_fma_f32 v[56:57], v[36:37], v[48:49], v[82:83] op_sel_hi:[0,1,1] neg_lo:[0,0,1] neg_hi:[0,0,1]
	v_pk_fma_f32 v[66:67], v[36:37], v[64:65], v[74:75] op_sel_hi:[0,1,1] neg_lo:[0,0,1] neg_hi:[0,0,1]
	v_pk_mul_f32 v[56:57], v[0:1], v[56:57]
	v_pk_mul_f32 v[66:67], v[2:3], v[66:67]
	v_cvt_pk_bf16_f32 v56, v56, v57
	s_add_i32 s2, s2, 1
	v_cvt_pk_bf16_f32 v57, v66, v67
	global_store_dwordx2 v[38:39], v[56:57], off
	v_lshlrev_b32_e32 v56, 16, v73
	v_and_b32_e32 v57, 0xffff0000, v73
	v_lshlrev_b32_e32 v66, 16, v72
	v_and_b32_e32 v67, 0xffff0000, v72
	v_pk_mul_f32 v[72:73], v[34:35], v[66:67] op_sel_hi:[0,1]
	v_pk_mul_f32 v[76:77], v[34:35], v[56:57] op_sel_hi:[0,1]
	v_pk_fma_f32 v[56:57], v[34:35], v[56:57], v[86:87] op_sel_hi:[0,1,1] neg_lo:[0,0,1] neg_hi:[0,0,1]
	v_pk_fma_f32 v[66:67], v[34:35], v[66:67], v[78:79] op_sel_hi:[0,1,1] neg_lo:[0,0,1] neg_hi:[0,0,1]
	v_cvt_f32_i32_e32 v34, s2
	v_pk_add_f32 v[48:49], v[48:49], v[56:57]
	v_pk_add_f32 v[64:65], v[64:65], v[66:67]
	v_lshlrev_b32_e32 v52, 16, v53
	v_div_scale_f32 v36, s[2:3], v34, v34, 1.0
	v_rcp_f32_e32 v40, v36
	s_max_i32 s2, s70, 1
	s_min_i32 s3, s69, s23
	s_sub_i32 s2, s3, s2
	v_fma_f32 v42, -v36, v40, 1.0
	v_fmac_f32_e32 v40, v42, v40
	v_div_scale_f32 v42, vcc, 1.0, v34, 1.0
	v_mul_f32_e32 v44, v42, v40
	v_fma_f32 v46, -v36, v44, v42
	v_fmac_f32_e32 v44, v46, v40
	v_fma_f32 v36, -v36, v44, v42
	v_div_fmas_f32 v36, v36, v40, v44
	v_div_fixup_f32 v34, v36, v34, 1.0
	v_pk_fma_f32 v[56:57], v[34:35], v[48:49], v[76:77] op_sel_hi:[0,1,1] neg_lo:[0,0,1] neg_hi:[0,0,1]
	v_pk_fma_f32 v[66:67], v[34:35], v[64:65], v[72:73] op_sel_hi:[0,1,1] neg_lo:[0,0,1] neg_hi:[0,0,1]
	v_pk_mul_f32 v[56:57], v[0:1], v[56:57]
	v_pk_mul_f32 v[66:67], v[2:3], v[66:67]
	v_cvt_pk_bf16_f32 v56, v56, v57
	s_add_i32 s2, s2, 1
	v_cvt_pk_bf16_f32 v57, v66, v67
	global_store_dwordx2 v[38:39], v[56:57], off offset:2048
	v_lshlrev_b32_e32 v38, 16, v71
	v_and_b32_e32 v39, 0xffff0000, v71
	v_lshlrev_b32_e32 v56, 16, v33
	v_and_b32_e32 v57, 0xffff0000, v33
	v_pk_mul_f32 v[66:67], v[32:33], v[56:57] op_sel_hi:[0,1]
	v_pk_mul_f32 v[70:71], v[32:33], v[38:39] op_sel_hi:[0,1]
	v_pk_fma_f32 v[38:39], v[32:33], v[38:39], v[82:83] op_sel_hi:[0,1,1] neg_lo:[0,0,1] neg_hi:[0,0,1]
	v_pk_fma_f32 v[32:33], v[32:33], v[56:57], v[74:75] op_sel_hi:[0,1,1] neg_lo:[0,0,1] neg_hi:[0,0,1]
	v_pk_add_f32 v[56:57], v[64:65], v[32:33]
	v_cvt_f32_i32_e32 v32, s2
	v_pk_add_f32 v[38:39], v[48:49], v[38:39]
	v_and_b32_e32 v53, 0xffff0000, v53
	v_div_scale_f32 v33, s[2:3], v32, v32, 1.0
	v_rcp_f32_e32 v34, v33
	s_mov_b32 s2, 0xa000
	s_min_i32 s3, s68, s23
	v_fma_f32 v36, -v33, v34, 1.0
	v_fmac_f32_e32 v34, v36, v34
	v_div_scale_f32 v36, vcc, 1.0, v32, 1.0
	v_mul_f32_e32 v40, v36, v34
	v_fma_f32 v42, -v33, v40, v36
	v_fmac_f32_e32 v40, v42, v34
	v_fma_f32 v33, -v33, v40, v36
	v_div_fmas_f32 v33, v33, v34, v40
	v_div_fixup_f32 v32, v33, v32, 1.0
	v_pk_fma_f32 v[48:49], v[32:33], v[38:39], v[70:71] op_sel_hi:[0,1,1] neg_lo:[0,0,1] neg_hi:[0,0,1]
	v_pk_fma_f32 v[32:33], v[32:33], v[56:57], v[66:67] op_sel_hi:[0,1,1] neg_lo:[0,0,1] neg_hi:[0,0,1]
	v_add_co_u32_e32 v64, vcc, s94, v4
	v_pk_mul_f32 v[32:33], v[2:3], v[32:33]
	v_pk_mul_f32 v[48:49], v[0:1], v[48:49]
	v_addc_co_u32_e32 v65, vcc, 0, v5, vcc
	v_cvt_pk_bf16_f32 v48, v48, v49
	v_cvt_pk_bf16_f32 v49, v32, v33
	v_add_co_u32_e32 v32, vcc, s2, v4
	s_max_i32 s2, s69, 1
	s_nop 0
	v_addc_co_u32_e32 v33, vcc, 0, v5, vcc
	s_sub_i32 s2, s3, s2
	global_store_dwordx2 v[32:33], v[48:49], off offset:-4096
	v_lshlrev_b32_e32 v48, 16, v69
	v_and_b32_e32 v49, 0xffff0000, v69
	s_add_i32 s2, s2, 1
	v_pk_mul_f32 v[68:69], v[30:31], v[62:63] op_sel_hi:[0,1]
	v_pk_mul_f32 v[74:75], v[30:31], v[48:49] op_sel_hi:[0,1]
	v_pk_fma_f32 v[48:49], v[30:31], v[48:49], v[76:77] op_sel_hi:[0,1,1] neg_lo:[0,0,1] neg_hi:[0,0,1]
	v_pk_fma_f32 v[62:63], v[30:31], v[62:63], v[72:73] op_sel_hi:[0,1,1] neg_lo:[0,0,1] neg_hi:[0,0,1]
	v_cvt_f32_i32_e32 v30, s2
	v_pk_add_f32 v[38:39], v[38:39], v[48:49]
	v_pk_add_f32 v[56:57], v[56:57], v[62:63]
	v_div_scale_f32 v34, s[2:3], v30, v30, 1.0
	v_rcp_f32_e32 v36, v34
	s_max_i32 s2, s68, 1
	s_min_i32 s3, s67, s23
	s_sub_i32 s2, s3, s2
	v_fma_f32 v40, -v34, v36, 1.0
	v_fmac_f32_e32 v36, v40, v36
	v_div_scale_f32 v40, vcc, 1.0, v30, 1.0
	v_mul_f32_e32 v42, v40, v36
	v_fma_f32 v44, -v34, v42, v40
	v_fmac_f32_e32 v42, v44, v36
	v_fma_f32 v34, -v34, v42, v40
	v_div_fmas_f32 v34, v34, v36, v42
	v_div_fixup_f32 v30, v34, v30, 1.0
	v_pk_fma_f32 v[48:49], v[30:31], v[38:39], v[74:75] op_sel_hi:[0,1,1] neg_lo:[0,0,1] neg_hi:[0,0,1]
	v_pk_fma_f32 v[62:63], v[30:31], v[56:57], v[68:69] op_sel_hi:[0,1,1] neg_lo:[0,0,1] neg_hi:[0,0,1]
	v_pk_mul_f32 v[48:49], v[0:1], v[48:49]
	v_pk_mul_f32 v[62:63], v[2:3], v[62:63]
	v_cvt_pk_bf16_f32 v48, v48, v49
	s_add_i32 s2, s2, 1
	v_cvt_pk_bf16_f32 v49, v62, v63
	global_store_dwordx2 v[64:65], v[48:49], off offset:2048
	v_lshlrev_b32_e32 v48, 16, v61
	v_and_b32_e32 v49, 0xffff0000, v61
	v_pk_mul_f32 v[60:61], v[28:29], v[58:59] op_sel_hi:[0,1]
	v_pk_mul_f32 v[62:63], v[28:29], v[48:49] op_sel_hi:[0,1]
	v_pk_fma_f32 v[48:49], v[28:29], v[48:49], v[70:71] op_sel_hi:[0,1,1] neg_lo:[0,0,1] neg_hi:[0,0,1]
	v_pk_fma_f32 v[58:59], v[28:29], v[58:59], v[66:67] op_sel_hi:[0,1,1] neg_lo:[0,0,1] neg_hi:[0,0,1]
	v_cvt_f32_i32_e32 v28, s2
	v_pk_add_f32 v[38:39], v[38:39], v[48:49]
	v_pk_add_f32 v[56:57], v[56:57], v[58:59]
	v_lshlrev_b32_e32 v44, 16, v45
	v_div_scale_f32 v30, s[2:3], v28, v28, 1.0
	v_rcp_f32_e32 v34, v30
	s_max_i32 s2, s67, 1
	s_min_i32 s3, s66, s23
	s_sub_i32 s2, s3, s2
	v_fma_f32 v36, -v30, v34, 1.0
	v_fmac_f32_e32 v34, v36, v34
	v_div_scale_f32 v36, vcc, 1.0, v28, 1.0
	v_mul_f32_e32 v40, v36, v34
	v_fma_f32 v42, -v30, v40, v36
	v_fmac_f32_e32 v40, v42, v34
	v_fma_f32 v30, -v30, v40, v36
	v_div_fmas_f32 v30, v30, v34, v40
	v_div_fixup_f32 v28, v30, v28, 1.0
	v_pk_fma_f32 v[48:49], v[28:29], v[38:39], v[62:63] op_sel_hi:[0,1,1] neg_lo:[0,0,1] neg_hi:[0,0,1]
	v_pk_fma_f32 v[58:59], v[28:29], v[56:57], v[60:61] op_sel_hi:[0,1,1] neg_lo:[0,0,1] neg_hi:[0,0,1]
	v_pk_mul_f32 v[48:49], v[0:1], v[48:49]
	v_pk_mul_f32 v[58:59], v[2:3], v[58:59]
	v_cvt_pk_bf16_f32 v48, v48, v49
	s_add_i32 s2, s2, 1
	v_cvt_pk_bf16_f32 v49, v58, v59
	global_store_dwordx2 v[32:33], v[48:49], off
	v_lshlrev_b32_e32 v48, 16, v55
	v_and_b32_e32 v49, 0xffff0000, v55
	v_pk_mul_f32 v[54:55], v[26:27], v[52:53] op_sel_hi:[0,1]
	v_pk_mul_f32 v[58:59], v[26:27], v[48:49] op_sel_hi:[0,1]
	v_pk_fma_f32 v[48:49], v[26:27], v[48:49], v[74:75] op_sel_hi:[0,1,1] neg_lo:[0,0,1] neg_hi:[0,0,1]
	v_pk_fma_f32 v[52:53], v[26:27], v[52:53], v[68:69] op_sel_hi:[0,1,1] neg_lo:[0,0,1] neg_hi:[0,0,1]
	v_cvt_f32_i32_e32 v26, s2
	v_pk_add_f32 v[38:39], v[38:39], v[48:49]
	v_pk_add_f32 v[52:53], v[56:57], v[52:53]
	v_and_b32_e32 v45, 0xffff0000, v45
	v_div_scale_f32 v28, s[2:3], v26, v26, 1.0
	v_rcp_f32_e32 v30, v28
	s_max_i32 s2, s66, 1
	s_min_i32 s3, s34, s23
	s_sub_i32 s2, s3, s2
	v_fma_f32 v34, -v28, v30, 1.0
	v_fmac_f32_e32 v30, v34, v30
	v_div_scale_f32 v34, vcc, 1.0, v26, 1.0
	v_mul_f32_e32 v36, v34, v30
	v_fma_f32 v40, -v28, v36, v34
	v_fmac_f32_e32 v36, v40, v30
	v_fma_f32 v28, -v28, v36, v34
	v_div_fmas_f32 v28, v28, v30, v36
	v_div_fixup_f32 v26, v28, v26, 1.0
	v_pk_fma_f32 v[48:49], v[26:27], v[38:39], v[58:59] op_sel_hi:[0,1,1] neg_lo:[0,0,1] neg_hi:[0,0,1]
	v_pk_fma_f32 v[56:57], v[26:27], v[52:53], v[54:55] op_sel_hi:[0,1,1] neg_lo:[0,0,1] neg_hi:[0,0,1]
	v_pk_mul_f32 v[48:49], v[0:1], v[48:49]
	v_pk_mul_f32 v[56:57], v[2:3], v[56:57]
	v_cvt_pk_bf16_f32 v48, v48, v49
	s_add_i32 s2, s2, 1
	v_cvt_pk_bf16_f32 v49, v56, v57
	global_store_dwordx2 v[32:33], v[48:49], off offset:2048
	v_lshlrev_b32_e32 v32, 16, v51
	v_and_b32_e32 v33, 0xffff0000, v51
	v_lshlrev_b32_e32 v48, 16, v21
	v_and_b32_e32 v49, 0xffff0000, v21
	v_pk_mul_f32 v[50:51], v[20:21], v[48:49] op_sel_hi:[0,1]
	v_pk_mul_f32 v[56:57], v[20:21], v[32:33] op_sel_hi:[0,1]
	v_pk_fma_f32 v[32:33], v[20:21], v[32:33], v[62:63] op_sel_hi:[0,1,1] neg_lo:[0,0,1] neg_hi:[0,0,1]
	v_pk_fma_f32 v[20:21], v[20:21], v[48:49], v[60:61] op_sel_hi:[0,1,1] neg_lo:[0,0,1] neg_hi:[0,0,1]
	v_pk_add_f32 v[48:49], v[52:53], v[20:21]
	v_cvt_f32_i32_e32 v20, s2
	v_pk_add_f32 v[32:33], v[38:39], v[32:33]
	v_lshlrev_b32_e32 v36, 16, v37
	v_and_b32_e32 v37, 0xffff0000, v37
	v_div_scale_f32 v21, s[2:3], v20, v20, 1.0
	v_rcp_f32_e32 v26, v21
	s_max_i32 s2, s34, 1
	s_min_i32 s3, s63, s23
	s_sub_i32 s2, s3, s2
	v_fma_f32 v28, -v21, v26, 1.0
	v_fmac_f32_e32 v26, v28, v26
	v_div_scale_f32 v28, vcc, 1.0, v20, 1.0
	v_mul_f32_e32 v30, v28, v26
	v_fma_f32 v34, -v21, v30, v28
	v_fmac_f32_e32 v30, v34, v26
	v_fma_f32 v21, -v21, v30, v28
	v_div_fmas_f32 v21, v21, v26, v30
	v_div_fixup_f32 v20, v21, v20, 1.0
	v_pk_fma_f32 v[38:39], v[20:21], v[32:33], v[56:57] op_sel_hi:[0,1,1] neg_lo:[0,0,1] neg_hi:[0,0,1]
	v_pk_fma_f32 v[20:21], v[20:21], v[48:49], v[50:51] op_sel_hi:[0,1,1] neg_lo:[0,0,1] neg_hi:[0,0,1]
	v_add_co_u32_e32 v52, vcc, s51, v4
	v_pk_mul_f32 v[20:21], v[2:3], v[20:21]
	v_pk_mul_f32 v[38:39], v[0:1], v[38:39]
	v_addc_co_u32_e32 v53, vcc, 0, v5, vcc
	v_cvt_pk_bf16_f32 v38, v38, v39
	v_cvt_pk_bf16_f32 v39, v20, v21
	v_add_co_u32_e32 v20, vcc, s58, v4
	v_lshlrev_b32_e32 v34, 16, v35
	s_nop 0
	v_addc_co_u32_e32 v21, vcc, 0, v5, vcc
	v_and_b32_e32 v35, 0xffff0000, v35
	s_add_i32 s2, s2, 1
	global_store_dwordx2 v[20:21], v[38:39], off offset:-4096
	v_pk_mul_f32 v[38:39], v[24:25], v[34:35] op_sel_hi:[0,1]
	v_pk_mul_f32 v[60:61], v[24:25], v[36:37] op_sel_hi:[0,1]
	v_pk_fma_f32 v[36:37], v[24:25], v[36:37], v[58:59] op_sel_hi:[0,1,1] neg_lo:[0,0,1] neg_hi:[0,0,1]
	v_pk_fma_f32 v[34:35], v[24:25], v[34:35], v[54:55] op_sel_hi:[0,1,1] neg_lo:[0,0,1] neg_hi:[0,0,1]
	v_cvt_f32_i32_e32 v24, s2
	v_pk_add_f32 v[32:33], v[32:33], v[36:37]
	v_pk_add_f32 v[34:35], v[48:49], v[34:35]
	v_lshlrev_b32_e32 v40, 16, v41
	v_div_scale_f32 v26, s[2:3], v24, v24, 1.0
	v_rcp_f32_e32 v28, v26
	s_max_i32 s2, s63, 1
	s_min_i32 s3, s62, s23
	s_sub_i32 s2, s3, s2
	v_fma_f32 v30, -v26, v28, 1.0
	v_fmac_f32_e32 v28, v30, v28
	v_div_scale_f32 v30, vcc, 1.0, v24, 1.0
	v_mul_f32_e32 v36, v30, v28
	v_fma_f32 v37, -v26, v36, v30
	v_fmac_f32_e32 v36, v37, v28
	v_fma_f32 v26, -v26, v36, v30
	v_div_fmas_f32 v26, v26, v28, v36
	v_div_fixup_f32 v24, v26, v24, 1.0
	v_pk_fma_f32 v[36:37], v[24:25], v[32:33], v[60:61] op_sel_hi:[0,1,1] neg_lo:[0,0,1] neg_hi:[0,0,1]
	v_pk_fma_f32 v[48:49], v[24:25], v[34:35], v[38:39] op_sel_hi:[0,1,1] neg_lo:[0,0,1] neg_hi:[0,0,1]
	v_pk_mul_f32 v[36:37], v[0:1], v[36:37]
	v_pk_mul_f32 v[48:49], v[2:3], v[48:49]
	v_cvt_pk_bf16_f32 v36, v36, v37
	s_add_i32 s2, s2, 1
	v_cvt_pk_bf16_f32 v37, v48, v49
	global_store_dwordx2 v[52:53], v[36:37], off offset:2048
	v_lshlrev_b32_e32 v36, 16, v47
	v_and_b32_e32 v37, 0xffff0000, v47
	v_pk_mul_f32 v[46:47], v[22:23], v[44:45] op_sel_hi:[0,1]
	v_pk_mul_f32 v[48:49], v[22:23], v[36:37] op_sel_hi:[0,1]
	v_pk_fma_f32 v[36:37], v[22:23], v[36:37], v[56:57] op_sel_hi:[0,1,1] neg_lo:[0,0,1] neg_hi:[0,0,1]
	v_pk_fma_f32 v[44:45], v[22:23], v[44:45], v[50:51] op_sel_hi:[0,1,1] neg_lo:[0,0,1] neg_hi:[0,0,1]
	v_cvt_f32_i32_e32 v22, s2
	v_pk_add_f32 v[32:33], v[32:33], v[36:37]
	v_pk_add_f32 v[34:35], v[34:35], v[44:45]
	v_and_b32_e32 v41, 0xffff0000, v41
	v_div_scale_f32 v24, s[2:3], v22, v22, 1.0
	v_rcp_f32_e32 v26, v24
	s_max_i32 s2, s62, 1
	s_min_i32 s3, s21, s23
	s_sub_i32 s2, s3, s2
	v_fma_f32 v28, -v24, v26, 1.0
	v_fmac_f32_e32 v26, v28, v26
	v_div_scale_f32 v28, vcc, 1.0, v22, 1.0
	v_mul_f32_e32 v30, v28, v26
	v_fma_f32 v36, -v24, v30, v28
	v_fmac_f32_e32 v30, v36, v26
	v_fma_f32 v24, -v24, v30, v28
	v_div_fmas_f32 v24, v24, v26, v30
	v_div_fixup_f32 v22, v24, v22, 1.0
	v_pk_fma_f32 v[36:37], v[22:23], v[32:33], v[48:49] op_sel_hi:[0,1,1] neg_lo:[0,0,1] neg_hi:[0,0,1]
	v_pk_fma_f32 v[44:45], v[22:23], v[34:35], v[46:47] op_sel_hi:[0,1,1] neg_lo:[0,0,1] neg_hi:[0,0,1]
	v_pk_mul_f32 v[36:37], v[0:1], v[36:37]
	v_pk_mul_f32 v[44:45], v[2:3], v[44:45]
	v_cvt_pk_bf16_f32 v36, v36, v37
	s_add_i32 s2, s2, 1
	v_cvt_pk_bf16_f32 v37, v44, v45
	global_store_dwordx2 v[20:21], v[36:37], off
	v_lshlrev_b32_e32 v36, 16, v43
	v_and_b32_e32 v37, 0xffff0000, v43
	v_pk_mul_f32 v[42:43], v[18:19], v[40:41] op_sel_hi:[0,1]
	v_pk_mul_f32 v[44:45], v[18:19], v[36:37] op_sel_hi:[0,1]
	v_pk_fma_f32 v[36:37], v[18:19], v[36:37], v[60:61] op_sel_hi:[0,1,1] neg_lo:[0,0,1] neg_hi:[0,0,1]
	v_pk_fma_f32 v[38:39], v[18:19], v[40:41], v[38:39] op_sel_hi:[0,1,1] neg_lo:[0,0,1] neg_hi:[0,0,1]
	v_cvt_f32_i32_e32 v18, s2
	v_pk_add_f32 v[32:33], v[32:33], v[36:37]
	v_pk_add_f32 v[34:35], v[34:35], v[38:39]
	v_div_scale_f32 v22, s[2:3], v18, v18, 1.0
	v_rcp_f32_e32 v24, v22
	s_max_i32 s2, s21, 1
	s_min_i32 s3, s20, s23
	s_sub_i32 s2, s3, s2
	v_fma_f32 v26, -v22, v24, 1.0
	v_fmac_f32_e32 v24, v26, v24
	v_div_scale_f32 v26, vcc, 1.0, v18, 1.0
	v_mul_f32_e32 v28, v26, v24
	v_fma_f32 v30, -v22, v28, v26
	v_fmac_f32_e32 v28, v30, v24
	v_fma_f32 v22, -v22, v28, v26
	v_div_fmas_f32 v22, v22, v24, v28
	v_div_fixup_f32 v18, v22, v18, 1.0
	v_pk_fma_f32 v[36:37], v[18:19], v[32:33], v[44:45] op_sel_hi:[0,1,1] neg_lo:[0,0,1] neg_hi:[0,0,1]
	v_pk_fma_f32 v[38:39], v[18:19], v[34:35], v[42:43] op_sel_hi:[0,1,1] neg_lo:[0,0,1] neg_hi:[0,0,1]
	v_pk_mul_f32 v[36:37], v[0:1], v[36:37]
	v_pk_mul_f32 v[38:39], v[2:3], v[38:39]
	v_cvt_pk_bf16_f32 v36, v36, v37
	v_lshlrev_b32_e32 v30, 16, v17
	v_cvt_pk_bf16_f32 v37, v38, v39
	global_store_dwordx2 v[20:21], v[36:37], off offset:2048
	v_lshlrev_b32_e32 v20, 16, v31
	v_and_b32_e32 v21, 0xffff0000, v31
	v_and_b32_e32 v31, 0xffff0000, v17
	v_pk_mul_f32 v[36:37], v[16:17], v[30:31] op_sel_hi:[0,1]
	v_pk_mul_f32 v[38:39], v[16:17], v[20:21] op_sel_hi:[0,1]
	v_pk_fma_f32 v[20:21], v[16:17], v[20:21], v[48:49] op_sel_hi:[0,1,1] neg_lo:[0,0,1] neg_hi:[0,0,1]
	v_pk_fma_f32 v[16:17], v[16:17], v[30:31], v[46:47] op_sel_hi:[0,1,1] neg_lo:[0,0,1] neg_hi:[0,0,1]
	s_add_i32 s2, s2, 1
	v_pk_add_f32 v[30:31], v[34:35], v[16:17]
	v_cvt_f32_i32_e32 v16, s2
	v_pk_add_f32 v[20:21], v[32:33], v[20:21]
	v_lshlrev_b32_e32 v28, 16, v29
	v_and_b32_e32 v29, 0xffff0000, v29
	v_div_scale_f32 v17, s[2:3], v16, v16, 1.0
	v_rcp_f32_e32 v18, v17
	s_max_i32 s2, s20, 1
	s_min_i32 s3, s19, s23
	s_sub_i32 s2, s3, s2
	v_fma_f32 v22, -v17, v18, 1.0
	v_fmac_f32_e32 v18, v22, v18
	v_div_scale_f32 v22, vcc, 1.0, v16, 1.0
	v_mul_f32_e32 v24, v22, v18
	v_fma_f32 v26, -v17, v24, v22
	v_fmac_f32_e32 v24, v26, v18
	v_fma_f32 v17, -v17, v24, v22
	v_div_fmas_f32 v17, v17, v18, v24
	v_div_fixup_f32 v16, v17, v16, 1.0
	v_pk_fma_f32 v[32:33], v[16:17], v[20:21], v[38:39] op_sel_hi:[0,1,1] neg_lo:[0,0,1] neg_hi:[0,0,1]
	v_pk_fma_f32 v[16:17], v[16:17], v[30:31], v[36:37] op_sel_hi:[0,1,1] neg_lo:[0,0,1] neg_hi:[0,0,1]
	v_add_co_u32_e32 v34, vcc, s59, v4
	v_pk_mul_f32 v[16:17], v[2:3], v[16:17]
	v_pk_mul_f32 v[32:33], v[0:1], v[32:33]
	v_addc_co_u32_e32 v35, vcc, 0, v5, vcc
	v_cvt_pk_bf16_f32 v32, v32, v33
	v_cvt_pk_bf16_f32 v33, v16, v17
	v_add_co_u32_e32 v16, vcc, s60, v4
	v_lshlrev_b32_e32 v26, 16, v27
	s_nop 0
	v_addc_co_u32_e32 v17, vcc, 0, v5, vcc
	v_and_b32_e32 v27, 0xffff0000, v27
	s_add_i32 s2, s2, 1
	global_store_dwordx2 v[16:17], v[32:33], off offset:-4096
	v_pk_mul_f32 v[32:33], v[14:15], v[26:27] op_sel_hi:[0,1]
	v_pk_mul_f32 v[40:41], v[14:15], v[28:29] op_sel_hi:[0,1]
	v_pk_fma_f32 v[28:29], v[14:15], v[28:29], v[44:45] op_sel_hi:[0,1,1] neg_lo:[0,0,1] neg_hi:[0,0,1]
	v_pk_fma_f32 v[26:27], v[14:15], v[26:27], v[42:43] op_sel_hi:[0,1,1] neg_lo:[0,0,1] neg_hi:[0,0,1]
	v_cvt_f32_i32_e32 v14, s2
	v_pk_add_f32 v[20:21], v[20:21], v[28:29]
	v_pk_add_f32 v[26:27], v[30:31], v[26:27]
	v_div_scale_f32 v18, s[2:3], v14, v14, 1.0
	v_rcp_f32_e32 v22, v18
	s_max_i32 s2, s19, 1
	s_min_i32 s3, s18, s23
	s_sub_i32 s2, s3, s2
	v_fma_f32 v24, -v18, v22, 1.0
	v_fmac_f32_e32 v22, v24, v22
	v_div_scale_f32 v24, vcc, 1.0, v14, 1.0
	v_mul_f32_e32 v28, v24, v22
	v_fma_f32 v29, -v18, v28, v24
	v_fmac_f32_e32 v28, v29, v22
	v_fma_f32 v18, -v18, v28, v24
	v_div_fmas_f32 v18, v18, v22, v28
	v_div_fixup_f32 v14, v18, v14, 1.0
	v_pk_fma_f32 v[28:29], v[14:15], v[20:21], v[40:41] op_sel_hi:[0,1,1] neg_lo:[0,0,1] neg_hi:[0,0,1]
	v_pk_fma_f32 v[30:31], v[14:15], v[26:27], v[32:33] op_sel_hi:[0,1,1] neg_lo:[0,0,1] neg_hi:[0,0,1]
	v_pk_mul_f32 v[28:29], v[0:1], v[28:29]
	v_pk_mul_f32 v[30:31], v[2:3], v[30:31]
	v_cvt_pk_bf16_f32 v28, v28, v29
	v_lshlrev_b32_e32 v24, 16, v25
	v_cvt_pk_bf16_f32 v29, v30, v31
	v_and_b32_e32 v25, 0xffff0000, v25
	v_lshlrev_b32_e32 v22, 16, v23
	v_and_b32_e32 v23, 0xffff0000, v23
	s_add_i32 s2, s2, 1
	global_store_dwordx2 v[34:35], v[28:29], off offset:2048
	v_pk_mul_f32 v[28:29], v[12:13], v[22:23] op_sel_hi:[0,1]
	v_pk_mul_f32 v[30:31], v[12:13], v[24:25] op_sel_hi:[0,1]
	v_pk_fma_f32 v[24:25], v[12:13], v[24:25], v[38:39] op_sel_hi:[0,1,1] neg_lo:[0,0,1] neg_hi:[0,0,1]
	v_pk_fma_f32 v[22:23], v[12:13], v[22:23], v[36:37] op_sel_hi:[0,1,1] neg_lo:[0,0,1] neg_hi:[0,0,1]
	v_cvt_f32_i32_e32 v12, s2
	v_pk_add_f32 v[20:21], v[20:21], v[24:25]
	v_pk_add_f32 v[22:23], v[26:27], v[22:23]
	v_div_scale_f32 v14, s[2:3], v12, v12, 1.0
	v_rcp_f32_e32 v18, v14
	s_max_i32 s2, s18, 1
	s_min_i32 s3, s15, s23
	s_sub_i32 s2, s3, s2
	v_fma_f32 v24, -v14, v18, 1.0
	v_fmac_f32_e32 v18, v24, v18
	v_div_scale_f32 v24, vcc, 1.0, v12, 1.0
	v_mul_f32_e32 v25, v24, v18
	v_fma_f32 v26, -v14, v25, v24
	v_fmac_f32_e32 v25, v26, v18
	v_fma_f32 v14, -v14, v25, v24
	v_div_fmas_f32 v14, v14, v18, v25
	v_div_fixup_f32 v12, v14, v12, 1.0
	v_pk_fma_f32 v[24:25], v[12:13], v[20:21], v[30:31] op_sel_hi:[0,1,1] neg_lo:[0,0,1] neg_hi:[0,0,1]
	v_pk_fma_f32 v[26:27], v[12:13], v[22:23], v[28:29] op_sel_hi:[0,1,1] neg_lo:[0,0,1] neg_hi:[0,0,1]
	v_pk_mul_f32 v[24:25], v[0:1], v[24:25]
	v_pk_mul_f32 v[26:27], v[2:3], v[26:27]
	v_cvt_pk_bf16_f32 v24, v24, v25
	v_lshlrev_b32_e32 v14, 16, v15
	v_cvt_pk_bf16_f32 v25, v26, v27
	v_and_b32_e32 v15, 0xffff0000, v15
	v_lshlrev_b32_e32 v12, 16, v13
	v_and_b32_e32 v13, 0xffff0000, v13
	s_add_i32 s2, s2, 1
	global_store_dwordx2 v[16:17], v[24:25], off
	v_pk_mul_f32 v[24:25], v[10:11], v[12:13] op_sel_hi:[0,1]
	v_pk_mul_f32 v[26:27], v[10:11], v[14:15] op_sel_hi:[0,1]
	v_pk_fma_f32 v[14:15], v[10:11], v[14:15], v[40:41] op_sel_hi:[0,1,1] neg_lo:[0,0,1] neg_hi:[0,0,1]
	v_pk_fma_f32 v[12:13], v[10:11], v[12:13], v[32:33] op_sel_hi:[0,1,1] neg_lo:[0,0,1] neg_hi:[0,0,1]
	v_cvt_f32_i32_e32 v10, s2
	v_pk_add_f32 v[14:15], v[20:21], v[14:15]
	v_pk_add_f32 v[12:13], v[22:23], v[12:13]
	v_div_scale_f32 v18, s[2:3], v10, v10, 1.0
	v_rcp_f32_e32 v20, v18
	s_max_i32 s2, s15, 1
	s_min_i32 s3, s5, s23
	s_sub_i32 s2, s3, s2
	v_fma_f32 v21, -v18, v20, 1.0
	v_fmac_f32_e32 v20, v21, v20
	v_div_scale_f32 v21, vcc, 1.0, v10, 1.0
	v_mul_f32_e32 v22, v21, v20
	v_fma_f32 v23, -v18, v22, v21
	v_fmac_f32_e32 v22, v23, v20
	v_fma_f32 v18, -v18, v22, v21
	v_div_fmas_f32 v18, v18, v20, v22
	v_div_fixup_f32 v10, v18, v10, 1.0
	v_pk_fma_f32 v[20:21], v[10:11], v[14:15], v[26:27] op_sel_hi:[0,1,1] neg_lo:[0,0,1] neg_hi:[0,0,1]
	v_pk_fma_f32 v[22:23], v[10:11], v[12:13], v[24:25] op_sel_hi:[0,1,1] neg_lo:[0,0,1] neg_hi:[0,0,1]
	v_pk_mul_f32 v[20:21], v[0:1], v[20:21]
	v_pk_mul_f32 v[22:23], v[2:3], v[22:23]
	v_cvt_pk_bf16_f32 v20, v20, v21
	v_lshlrev_b32_e32 v10, 16, v11
	v_cvt_pk_bf16_f32 v21, v22, v23
	global_store_dwordx2 v[16:17], v[20:21], off offset:2048
	v_and_b32_e32 v11, 0xffff0000, v11
	v_lshlrev_b32_e32 v16, 16, v7
	v_and_b32_e32 v17, 0xffff0000, v7
	v_pk_mul_f32 v[20:21], v[6:7], v[16:17] op_sel_hi:[0,1]
	v_pk_mul_f32 v[22:23], v[6:7], v[10:11] op_sel_hi:[0,1]
	v_pk_fma_f32 v[10:11], v[6:7], v[10:11], v[30:31] op_sel_hi:[0,1,1] neg_lo:[0,0,1] neg_hi:[0,0,1]
	v_pk_fma_f32 v[6:7], v[6:7], v[16:17], v[28:29] op_sel_hi:[0,1,1] neg_lo:[0,0,1] neg_hi:[0,0,1]
	s_add_i32 s2, s2, 1
	v_pk_add_f32 v[6:7], v[12:13], v[6:7]
	v_cvt_f32_i32_e32 v12, s2
	v_pk_add_f32 v[10:11], v[14:15], v[10:11]
	v_div_scale_f32 v13, s[2:3], v12, v12, 1.0
	v_rcp_f32_e32 v14, v13
	s_add_i32 s3, s4, 32
	s_max_i32 s2, s5, 1
	s_min_i32 s3, s3, s23
	v_fma_f32 v15, -v13, v14, 1.0
	v_fmac_f32_e32 v14, v15, v14
	v_div_scale_f32 v15, vcc, 1.0, v12, 1.0
	v_mul_f32_e32 v16, v15, v14
	v_fma_f32 v17, -v13, v16, v15
	v_fmac_f32_e32 v16, v17, v14
	v_fma_f32 v13, -v13, v16, v15
	v_div_fmas_f32 v13, v13, v14, v16
	v_div_fixup_f32 v12, v13, v12, 1.0
	v_pk_fma_f32 v[14:15], v[12:13], v[10:11], v[22:23] op_sel_hi:[0,1,1] neg_lo:[0,0,1] neg_hi:[0,0,1]
	v_pk_fma_f32 v[12:13], v[12:13], v[6:7], v[20:21] op_sel_hi:[0,1,1] neg_lo:[0,0,1] neg_hi:[0,0,1]
	v_pk_mul_f32 v[12:13], v[2:3], v[12:13]
	v_pk_mul_f32 v[14:15], v[0:1], v[14:15]
	s_sub_i32 s2, s3, s2
	v_cvt_pk_bf16_f32 v14, v14, v15
	v_cvt_pk_bf16_f32 v15, v12, v13
	v_add_co_u32_e32 v12, vcc, s50, v4
	s_add_i32 s2, s2, 1
	s_nop 0
	v_addc_co_u32_e32 v13, vcc, 0, v5, vcc
	global_store_dwordx2 v[12:13], v[14:15], off
	v_lshlrev_b32_e32 v12, 16, v19
	v_and_b32_e32 v13, 0xffff0000, v19
	v_lshlrev_b32_e32 v14, 16, v9
	v_and_b32_e32 v15, 0xffff0000, v9
	s_waitcnt vmcnt(31)
	v_pk_mul_f32 v[16:17], v[8:9], v[14:15] op_sel_hi:[0,1]
	v_pk_mul_f32 v[18:19], v[8:9], v[12:13] op_sel_hi:[0,1]
	v_pk_fma_f32 v[12:13], v[8:9], v[12:13], v[26:27] op_sel_hi:[0,1,1] neg_lo:[0,0,1] neg_hi:[0,0,1]
	v_pk_fma_f32 v[8:9], v[8:9], v[14:15], v[24:25] op_sel_hi:[0,1,1] neg_lo:[0,0,1] neg_hi:[0,0,1]
	v_pk_add_f32 v[6:7], v[6:7], v[8:9]
	v_pk_add_f32 v[8:9], v[10:11], v[12:13]
	v_cvt_f32_i32_e32 v10, s2
	v_div_scale_f32 v11, s[2:3], v10, v10, 1.0
	v_rcp_f32_e32 v12, v11
	s_nop 0
	v_fma_f32 v13, -v11, v12, 1.0
	v_fmac_f32_e32 v12, v13, v12
	v_div_scale_f32 v13, vcc, 1.0, v10, 1.0
	v_mul_f32_e32 v14, v13, v12
	v_fma_f32 v15, -v11, v14, v13
	v_fmac_f32_e32 v14, v15, v12
	v_fma_f32 v11, -v11, v14, v13
	v_div_fmas_f32 v11, v11, v12, v14
	v_div_fixup_f32 v10, v11, v10, 1.0
	v_pk_fma_f32 v[8:9], v[10:11], v[8:9], v[18:19] op_sel_hi:[0,1,1] neg_lo:[0,0,1] neg_hi:[0,0,1]
	v_pk_fma_f32 v[6:7], v[10:11], v[6:7], v[16:17] op_sel_hi:[0,1,1] neg_lo:[0,0,1] neg_hi:[0,0,1]
	v_pk_mul_f32 v[2:3], v[2:3], v[6:7]
	v_pk_mul_f32 v[0:1], v[0:1], v[8:9]
	s_nop 0
	v_cvt_pk_bf16_f32 v6, v0, v1
	v_cvt_pk_bf16_f32 v7, v2, v3

.LBB0_381:
	s_cmp_gt_i32 s13, 1
	s_cbranch_scc0 .LBB0_400
	s_cmp_eq_u32 s13, 2
	s_mov_b64 s[18:19], -1
	s_cbranch_scc0 .LBB0_384
	v_writelane_b32 v244, s5, 0
	v_writelane_b32 v244, vcc_lo, 1
	v_writelane_b32 v244, vcc_hi, 2
	v_writelane_b32 v244, s18, 3
	v_writelane_b32 v244, s19, 4
	v_writelane_b32 v244, s20, 5
	v_writelane_b32 v244, s21, 6
	v_writelane_b32 v244, s30, 7
	v_writelane_b32 v244, s31, 8
	v_writelane_b32 v244, s7, 9
	v_writelane_b32 v244, s91, 10
	v_writelane_b32 v244, s90, 11
	v_writelane_b32 v244, s89, 12
	v_writelane_b32 v244, s88, 13
	v_writelane_b32 v244, s86, 14
	v_writelane_b32 v244, s87, 15
	v_writelane_b32 v244, s85, 16
	v_writelane_b32 v244, s35, 17
	v_writelane_b32 v244, s84, 18
	v_writelane_b32 v244, s83, 19
	v_writelane_b32 v244, s81, 20
	v_writelane_b32 v244, s79, 21
	v_writelane_b32 v244, s82, 22
	v_writelane_b32 v244, s80, 23
	v_writelane_b32 v244, s78, 24
	v_writelane_b32 v244, s77, 25
	v_writelane_b32 v244, s76, 26
	v_writelane_b32 v244, s75, 27
	v_writelane_b32 v244, s74, 28
	v_writelane_b32 v244, s71, 29
	v_writelane_b32 v244, s73, 30
	v_writelane_b32 v244, s72, 31
	v_writelane_b32 v244, s69, 32
	v_writelane_b32 v244, s68, 33
	v_writelane_b32 v244, s63, 34
	v_writelane_b32 v244, s62, 35
	v_writelane_b32 v244, s34, 36
	v_writelane_b32 v244, s66, 37
	v_writelane_b32 v244, s67, 38
	v_writelane_b32 v244, s15, 39
	v_writelane_b32 v244, s70, 40
	v_writelane_b32 v244, s96, 41
	v_writelane_b32 v244, s97, 42
	s_add_i32 s5, s4, -4
	s_cmp_lt_u32 s5, s23
	s_cselect_b64 vcc, -1, 0
	s_and_b64 s[18:19], vcc, exec
	s_cselect_b32 s18, s5, s4
	v_lshlrev_b32_e32 v96, 1, v11
	s_ashr_i32 s19, s18, 31
	v_lshl_add_u64 v[248:249], s[2:3], 0, v[96:97]
	s_lshl_b64 s[20:21], s[18:19], 11
	v_lshl_add_u64 v[246:247], v[248:249], 0, s[20:21]
	global_load_dwordx2 v[152:153], v[246:247], off offset:1024
	s_add_i32 s18, s18, s14
	s_ashr_i32 s19, s18, 31
	s_lshl_b64 s[18:19], s[18:19], 2
	s_add_u32 s18, s26, s18
	s_addc_u32 s19, s27, s19
	s_add_i32 s5, s4, -3
	s_cmp_lt_u32 s5, s23
	s_mov_b64 s[30:31], 0x400
	s_cselect_b64 vcc, -1, 0
	s_and_b64 s[18:19], vcc, exec
	s_cselect_b32 s18, s5, s4
	s_ashr_i32 s19, s18, 31
	s_lshl_b64 s[20:21], s[18:19], 11
	v_lshl_add_u64 v[246:247], v[248:249], 0, s[20:21]
	global_load_dword v67, v[246:247], off offset:1024
	global_load_dword v63, v[246:247], off offset:1028
	s_add_i32 s18, s18, s14
	s_ashr_i32 s19, s18, 31
	s_lshl_b64 s[18:19], s[18:19], 2
	s_add_u32 s18, s26, s18
	s_addc_u32 s19, s27, s19
	s_add_i32 s5, s4, -2
	s_cmp_lt_u32 s5, s23
	global_load_dword v16, v97, s[18:19]
	s_cselect_b64 vcc, -1, 0
	s_and_b64 s[18:19], vcc, exec
	s_cselect_b32 s18, s5, s4
	s_ashr_i32 s19, s18, 31
	s_lshl_b64 s[20:21], s[18:19], 11
	v_lshl_add_u64 v[246:247], v[248:249], 0, s[20:21]
	global_load_dword v71, v[246:247], off offset:1024
	global_load_dword v69, v[246:247], off offset:1028
	s_add_i32 s18, s18, s14
	s_ashr_i32 s19, s18, 31
	s_lshl_b64 s[18:19], s[18:19], 2
	s_add_u32 s18, s26, s18
	s_addc_u32 s19, s27, s19
	s_add_i32 s5, s4, -1
	s_cmp_lt_u32 s5, s23
	global_load_dword v62, v97, s[18:19]
	s_cselect_b64 vcc, -1, 0
	s_and_b64 s[18:19], vcc, exec
	s_cselect_b32 s18, s5, s4
	s_ashr_i32 s19, s18, 31
	s_lshl_b64 s[20:21], s[18:19], 11
	v_lshl_add_u64 v[246:247], v[248:249], 0, s[20:21]
	global_load_dword v75, v[246:247], off offset:1024
	global_load_dword v73, v[246:247], off offset:1028
	s_add_i32 s18, s18, s14
	s_ashr_i32 s19, s18, 31
	s_lshl_b64 s[18:19], s[18:19], 2
	s_add_u32 s18, s26, s18
	s_addc_u32 s19, s27, s19
	s_cmp_lt_u32 s4, s23
	global_load_dword v66, v97, s[18:19]
	s_cselect_b64 vcc, -1, 0
	s_ashr_i32 s5, s4, 31
	s_lshl_b64 s[18:19], s[4:5], 11
	v_lshl_add_u64 v[246:247], v[248:249], 0, s[18:19]
	global_load_dword v79, v[246:247], off offset:1024
	global_load_dword v77, v[246:247], off offset:1028
	s_ashr_i32 s7, s6, 31
	s_lshl_b64 s[18:19], s[6:7], 2
	s_add_u32 s18, s26, s18
	s_addc_u32 s19, s27, s19
	s_or_b32 s91, s4, 1
	s_cmp_lt_u32 s91, s23
	global_load_dword v68, v97, s[18:19]
	s_cselect_b64 vcc, -1, 0
	s_and_b64 s[18:19], vcc, exec
	s_cselect_b32 s18, s91, s4
	s_ashr_i32 s19, s18, 31
	s_lshl_b64 s[20:21], s[18:19], 11
	v_lshl_add_u64 v[246:247], v[248:249], 0, s[20:21]
	global_load_dword v89, v[246:247], off offset:1024
	global_load_dword v88, v[246:247], off offset:1028
	s_add_i32 s18, s18, s14
	s_ashr_i32 s19, s18, 31
	s_lshl_b64 s[18:19], s[18:19], 2
	s_add_u32 s18, s26, s18
	s_addc_u32 s19, s27, s19
	s_or_b32 s90, s4, 2
	s_cmp_lt_u32 s90, s23
	global_load_dword v72, v97, s[18:19]
	s_cselect_b64 vcc, -1, 0
	s_and_b64 s[18:19], vcc, exec
	s_cselect_b32 s18, s90, s4
	s_ashr_i32 s19, s18, 31
	s_lshl_b64 s[20:21], s[18:19], 11
	v_lshl_add_u64 v[246:247], v[248:249], 0, s[20:21]
	global_load_dword v91, v[246:247], off offset:1024
	global_load_dword v90, v[246:247], off offset:1028
	s_add_i32 s18, s18, s14
	s_ashr_i32 s19, s18, 31
	s_lshl_b64 s[18:19], s[18:19], 2
	s_add_u32 s18, s26, s18
	s_addc_u32 s19, s27, s19
	s_or_b32 s89, s4, 3
	s_cmp_lt_u32 s89, s23
	global_load_dword v76, v97, s[18:19]
	s_cselect_b64 vcc, -1, 0
	s_and_b64 s[18:19], vcc, exec
	s_cselect_b32 s18, s89, s4
	s_ashr_i32 s19, s18, 31
	s_lshl_b64 s[20:21], s[18:19], 11
	v_lshl_add_u64 v[246:247], v[248:249], 0, s[20:21]
	global_load_dword v143, v[246:247], off offset:1024
	global_load_dword v142, v[246:247], off offset:1028
	s_add_i32 s18, s18, s14
	s_ashr_i32 s19, s18, 31
	s_lshl_b64 s[18:19], s[18:19], 2
	s_add_u32 s18, s26, s18
	s_addc_u32 s19, s27, s19
	s_or_b32 s88, s4, 4
	s_cmp_lt_u32 s88, s23
	global_load_dword v80, v97, s[18:19]
	s_cselect_b64 vcc, -1, 0
	s_and_b64 s[18:19], vcc, exec
	s_cselect_b32 s18, s88, s4
	s_ashr_i32 s19, s18, 31
	s_lshl_b64 s[20:21], s[18:19], 11
	v_lshl_add_u64 v[246:247], v[248:249], 0, s[20:21]
	global_load_dword v141, v[246:247], off offset:1024
	global_load_dword v140, v[246:247], off offset:1028
	s_add_i32 s18, s18, s14
	s_ashr_i32 s19, s18, 31
	s_lshl_b64 s[18:19], s[18:19], 2
	s_add_u32 s18, s26, s18
	s_addc_u32 s19, s27, s19
	s_or_b32 s86, s4, 5
	s_cmp_lt_u32 s86, s23
	global_load_dword v74, v97, s[18:19]
	s_cselect_b64 vcc, -1, 0
	s_and_b64 s[18:19], vcc, exec
	s_cselect_b32 s18, s86, s4
	s_ashr_i32 s19, s18, 31
	s_lshl_b64 s[20:21], s[18:19], 11
	v_lshl_add_u64 v[246:247], v[248:249], 0, s[20:21]
	global_load_dword v137, v[246:247], off offset:1024
	global_load_dword v81, v[246:247], off offset:1028
	s_add_i32 s18, s18, s14
	s_ashr_i32 s19, s18, 31
	s_lshl_b64 s[18:19], s[18:19], 2
	s_add_u32 s18, s26, s18
	s_addc_u32 s19, s27, s19
	s_or_b32 s87, s4, 6
	s_cmp_lt_u32 s87, s23
	global_load_dword v78, v97, s[18:19]
	s_cselect_b64 vcc, -1, 0
	s_and_b64 s[18:19], vcc, exec
	s_cselect_b32 s18, s87, s4
	s_ashr_i32 s19, s18, 31
	s_lshl_b64 s[20:21], s[18:19], 11
	v_lshl_add_u64 v[246:247], v[248:249], 0, s[20:21]
	global_load_dword v139, v[246:247], off offset:1024
	global_load_dword v138, v[246:247], off offset:1028
	s_add_i32 s18, s18, s14
	s_ashr_i32 s19, s18, 31
	s_lshl_b64 s[18:19], s[18:19], 2
	s_add_u32 s18, s26, s18
	s_addc_u32 s19, s27, s19
	s_or_b32 s85, s4, 7
	s_cmp_lt_u32 s85, s23
	global_load_dword v70, v97, s[18:19]
	s_cselect_b64 vcc, -1, 0
	s_and_b64 s[18:19], vcc, exec
	s_cselect_b32 s18, s85, s4
	s_ashr_i32 s19, s18, 31
	s_lshl_b64 s[20:21], s[18:19], 11
	v_lshl_add_u64 v[246:247], v[248:249], 0, s[20:21]
	global_load_dword v136, v[246:247], off offset:1024
	global_load_dword v135, v[246:247], off offset:1028
	s_add_i32 s18, s18, s14
	s_ashr_i32 s19, s18, 31
	s_lshl_b64 s[18:19], s[18:19], 2
	s_add_u32 s18, s26, s18
	s_addc_u32 s19, s27, s19
	s_or_b32 s35, s4, 8
	s_cmp_lt_u32 s35, s23
	global_load_dword v64, v97, s[18:19]
	s_cselect_b64 vcc, -1, 0
	s_and_b64 s[18:19], vcc, exec
	s_cselect_b32 s18, s35, s4
	s_ashr_i32 s19, s18, 31
	s_lshl_b64 s[20:21], s[18:19], 11
	v_lshl_add_u64 v[246:247], v[248:249], 0, s[20:21]
	global_load_dword v134, v[246:247], off offset:1024
	global_load_dword v65, v[246:247], off offset:1028
	s_add_i32 s18, s18, s14
	s_ashr_i32 s19, s18, 31
	s_lshl_b64 s[18:19], s[18:19], 2
	s_add_u32 s18, s26, s18
	s_addc_u32 s19, s27, s19
	s_or_b32 s84, s4, 9
	s_cmp_lt_u32 s84, s23
	global_load_dword v60, v97, s[18:19]
	s_cselect_b64 vcc, -1, 0
	s_and_b64 s[18:19], vcc, exec
	s_cselect_b32 s18, s84, s4
	s_ashr_i32 s19, s18, 31
	s_lshl_b64 s[20:21], s[18:19], 11
	v_lshl_add_u64 v[246:247], v[248:249], 0, s[20:21]
	global_load_dword v133, v[246:247], off offset:1024
	global_load_dword v61, v[246:247], off offset:1028
	s_add_i32 s18, s18, s14
	s_ashr_i32 s19, s18, 31
	s_lshl_b64 s[18:19], s[18:19], 2
	s_add_u32 s18, s26, s18
	s_addc_u32 s19, s27, s19
	s_or_b32 s83, s4, 10
	s_cmp_lt_u32 s83, s23
	global_load_dword v58, v97, s[18:19]
	s_cselect_b64 vcc, -1, 0
	s_and_b64 s[18:19], vcc, exec
	s_cselect_b32 s18, s83, s4
	s_ashr_i32 s19, s18, 31
	s_lshl_b64 s[20:21], s[18:19], 11
	v_lshl_add_u64 v[246:247], v[248:249], 0, s[20:21]
	global_load_dword v132, v[246:247], off offset:1024
	global_load_dword v59, v[246:247], off offset:1028
	s_add_i32 s18, s18, s14
	s_ashr_i32 s19, s18, 31
	s_lshl_b64 s[18:19], s[18:19], 2
	s_add_u32 s18, s26, s18
	s_addc_u32 s19, s27, s19
	s_or_b32 s81, s4, 11
	s_cmp_lt_u32 s81, s23
	global_load_dword v54, v97, s[18:19]
	s_cselect_b64 vcc, -1, 0
	s_and_b64 s[18:19], vcc, exec
	s_cselect_b32 s18, s81, s4
	s_ashr_i32 s19, s18, 31
	s_lshl_b64 s[20:21], s[18:19], 11
	v_lshl_add_u64 v[246:247], v[248:249], 0, s[20:21]
	global_load_dword v57, v[246:247], off offset:1024
	global_load_dword v55, v[246:247], off offset:1028
	s_add_i32 s18, s18, s14
	s_ashr_i32 s19, s18, 31
	s_lshl_b64 s[18:19], s[18:19], 2
	s_add_u32 s18, s26, s18
	s_addc_u32 s19, s27, s19
	s_or_b32 s79, s4, 12
	s_cmp_lt_u32 s79, s23
	global_load_dword v50, v97, s[18:19]
	s_cselect_b64 vcc, -1, 0
	s_and_b64 s[18:19], vcc, exec
	s_cselect_b32 s18, s79, s4
	s_ashr_i32 s19, s18, 31
	s_lshl_b64 s[20:21], s[18:19], 11
	v_lshl_add_u64 v[246:247], v[248:249], 0, s[20:21]
	global_load_dword v53, v[246:247], off offset:1024
	global_load_dword v51, v[246:247], off offset:1028
	s_add_i32 s18, s18, s14
	s_ashr_i32 s19, s18, 31
	s_lshl_b64 s[18:19], s[18:19], 2
	s_add_u32 s18, s26, s18
	s_addc_u32 s19, s27, s19
	s_or_b32 s82, s4, 13
	s_cmp_lt_u32 s82, s23
	global_load_dword v56, v97, s[18:19]
	s_cselect_b64 vcc, -1, 0
	s_and_b64 s[18:19], vcc, exec
	s_cselect_b32 s18, s82, s4
	s_ashr_i32 s19, s18, 31
	s_lshl_b64 s[20:21], s[18:19], 11
	v_lshl_add_u64 v[246:247], v[248:249], 0, s[20:21]
	global_load_dword v131, v[246:247], off offset:1024
	global_load_dword v130, v[246:247], off offset:1028
	s_add_i32 s18, s18, s14
	s_ashr_i32 s19, s18, 31
	s_lshl_b64 s[18:19], s[18:19], 2
	s_add_u32 s18, s26, s18
	s_addc_u32 s19, s27, s19
	s_or_b32 s80, s4, 14
	s_cmp_lt_u32 s80, s23
	global_load_dword v52, v97, s[18:19]
	s_cselect_b64 vcc, -1, 0
	s_and_b64 s[18:19], vcc, exec
	s_cselect_b32 s18, s80, s4
	s_ashr_i32 s19, s18, 31
	s_lshl_b64 s[20:21], s[18:19], 11
	v_lshl_add_u64 v[246:247], v[248:249], 0, s[20:21]
	global_load_dword v129, v[246:247], off offset:1024
	global_load_dword v128, v[246:247], off offset:1028
	s_add_i32 s18, s18, s14
	s_ashr_i32 s19, s18, 31
	s_lshl_b64 s[18:19], s[18:19], 2
	s_add_u32 s18, s26, s18
	s_addc_u32 s19, s27, s19
	s_or_b32 s78, s4, 15
	s_cmp_lt_u32 s78, s23
	global_load_dword v48, v97, s[18:19]
	s_cselect_b64 vcc, -1, 0
	s_and_b64 s[18:19], vcc, exec
	s_cselect_b32 s18, s78, s4
	s_ashr_i32 s19, s18, 31
	s_lshl_b64 s[20:21], s[18:19], 11
	v_lshl_add_u64 v[246:247], v[248:249], 0, s[20:21]
	global_load_dword v127, v[246:247], off offset:1024
	global_load_dword v49, v[246:247], off offset:1028
	s_add_i32 s18, s18, s14
	s_ashr_i32 s19, s18, 31
	s_lshl_b64 s[18:19], s[18:19], 2
	s_add_u32 s18, s26, s18
	s_addc_u32 s19, s27, s19
	s_or_b32 s77, s4, 16
	s_cmp_lt_u32 s77, s23
	global_load_dword v46, v97, s[18:19]
	s_cselect_b64 vcc, -1, 0
	s_and_b64 s[18:19], vcc, exec
	s_cselect_b32 s18, s77, s4
	s_ashr_i32 s19, s18, 31
	s_lshl_b64 s[20:21], s[18:19], 11
	v_lshl_add_u64 v[246:247], v[248:249], 0, s[20:21]
	global_load_dword v126, v[246:247], off offset:1024
	global_load_dword v47, v[246:247], off offset:1028
	s_add_i32 s18, s18, s14
	s_ashr_i32 s19, s18, 31
	s_lshl_b64 s[18:19], s[18:19], 2
	s_add_u32 s18, s26, s18
	s_addc_u32 s19, s27, s19
	s_or_b32 s76, s4, 17
	s_cmp_lt_u32 s76, s23
	global_load_dword v44, v97, s[18:19]
	s_cselect_b64 vcc, -1, 0
	s_and_b64 s[18:19], vcc, exec
	s_cselect_b32 s18, s76, s4
	s_ashr_i32 s19, s18, 31
	s_lshl_b64 s[20:21], s[18:19], 11
	v_lshl_add_u64 v[246:247], v[248:249], 0, s[20:21]
	global_load_dword v125, v[246:247], off offset:1024
	global_load_dword v45, v[246:247], off offset:1028
	s_add_i32 s18, s18, s14
	s_ashr_i32 s19, s18, 31
	s_lshl_b64 s[18:19], s[18:19], 2
	s_add_u32 s18, s26, s18
	s_addc_u32 s19, s27, s19
	s_or_b32 s75, s4, 18
	s_cmp_lt_u32 s75, s23
	global_load_dword v42, v97, s[18:19]
	s_cselect_b64 vcc, -1, 0
	s_and_b64 s[18:19], vcc, exec
	s_cselect_b32 s18, s75, s4
	s_ashr_i32 s19, s18, 31
	s_lshl_b64 s[20:21], s[18:19], 11
	v_lshl_add_u64 v[246:247], v[248:249], 0, s[20:21]
	global_load_dword v124, v[246:247], off offset:1024
	global_load_dword v43, v[246:247], off offset:1028
	s_add_i32 s18, s18, s14
	s_ashr_i32 s19, s18, 31
	s_lshl_b64 s[18:19], s[18:19], 2
	s_add_u32 s18, s26, s18
	s_addc_u32 s19, s27, s19
	s_or_b32 s74, s4, 19
	s_cmp_lt_u32 s74, s23
	global_load_dword v40, v97, s[18:19]
	s_cselect_b64 vcc, -1, 0
	s_and_b64 s[18:19], vcc, exec
	s_cselect_b32 s18, s74, s4
	s_ashr_i32 s19, s18, 31
	s_lshl_b64 s[20:21], s[18:19], 11
	v_lshl_add_u64 v[246:247], v[248:249], 0, s[20:21]
	global_load_dword v123, v[246:247], off offset:1024
	global_load_dword v41, v[246:247], off offset:1028
	s_add_i32 s18, s18, s14
	s_ashr_i32 s19, s18, 31
	s_lshl_b64 s[18:19], s[18:19], 2
	s_add_u32 s18, s26, s18
	s_addc_u32 s19, s27, s19
	s_or_b32 s71, s4, 20
	s_cmp_lt_u32 s71, s23
	global_load_dword v34, v97, s[18:19]
	s_cselect_b64 vcc, -1, 0
	s_and_b64 s[18:19], vcc, exec
	s_cselect_b32 s18, s71, s4
	s_ashr_i32 s19, s18, 31
	s_lshl_b64 s[20:21], s[18:19], 11
	v_lshl_add_u64 v[246:247], v[248:249], 0, s[20:21]
	global_load_dword v37, v[246:247], off offset:1024
	global_load_dword v35, v[246:247], off offset:1028
	s_add_i32 s18, s18, s14
	s_ashr_i32 s19, s18, 31
	s_lshl_b64 s[18:19], s[18:19], 2
	s_add_u32 s18, s26, s18
	s_addc_u32 s19, s27, s19
	s_or_b32 s73, s4, 21
	s_cmp_lt_u32 s73, s23
	global_load_dword v38, v97, s[18:19]
	s_cselect_b64 vcc, -1, 0
	s_and_b64 s[18:19], vcc, exec
	s_cselect_b32 s18, s73, s4
	s_ashr_i32 s19, s18, 31
	s_lshl_b64 s[20:21], s[18:19], 11
	v_lshl_add_u64 v[246:247], v[248:249], 0, s[20:21]
	global_load_dword v122, v[246:247], off offset:1024
	global_load_dword v39, v[246:247], off offset:1028
	s_add_i32 s18, s18, s14
	s_ashr_i32 s19, s18, 31
	s_lshl_b64 s[18:19], s[18:19], 2
	s_add_u32 s18, s26, s18
	s_addc_u32 s19, s27, s19
	s_or_b32 s72, s4, 22
	s_cmp_lt_u32 s72, s23
	global_load_dword v36, v97, s[18:19]
	s_cselect_b64 vcc, -1, 0
	s_and_b64 s[18:19], vcc, exec
	s_cselect_b32 s18, s72, s4
	s_ashr_i32 s19, s18, 31
	s_lshl_b64 s[20:21], s[18:19], 11
	v_lshl_add_u64 v[246:247], v[248:249], 0, s[20:21]
	global_load_dword v121, v[246:247], off offset:1024
	global_load_dword v120, v[246:247], off offset:1028
	s_add_i32 s18, s18, s14
	s_ashr_i32 s19, s18, 31
	s_lshl_b64 s[18:19], s[18:19], 2
	s_add_u32 s18, s26, s18
	s_addc_u32 s19, s27, s19
	s_or_b32 s69, s4, 23
	s_cmp_lt_u32 s69, s23
	global_load_dword v32, v97, s[18:19]
	s_cselect_b64 vcc, -1, 0
	s_and_b64 s[18:19], vcc, exec
	s_cselect_b32 s18, s69, s4
	s_ashr_i32 s19, s18, 31
	s_lshl_b64 s[20:21], s[18:19], 11
	v_lshl_add_u64 v[246:247], v[248:249], 0, s[20:21]
	global_load_dword v119, v[246:247], off offset:1024
	global_load_dword v33, v[246:247], off offset:1028
	s_add_i32 s18, s18, s14
	s_ashr_i32 s19, s18, 31
	s_lshl_b64 s[18:19], s[18:19], 2
	s_add_u32 s18, s26, s18
	s_addc_u32 s19, s27, s19
	s_or_b32 s68, s4, 24
	s_cmp_lt_u32 s68, s23
	global_load_dword v30, v97, s[18:19]
	s_cselect_b64 vcc, -1, 0
	s_and_b64 s[18:19], vcc, exec
	s_cselect_b32 s18, s68, s4
	s_ashr_i32 s19, s18, 31
	s_lshl_b64 s[20:21], s[18:19], 11
	v_lshl_add_u64 v[246:247], v[248:249], 0, s[20:21]
	global_load_dword v118, v[246:247], off offset:1024
	global_load_dword v31, v[246:247], off offset:1028
	s_add_i32 s18, s18, s14
	s_ashr_i32 s19, s18, 31
	s_lshl_b64 s[18:19], s[18:19], 2
	s_add_u32 s18, s26, s18
	s_addc_u32 s19, s27, s19
	s_or_b32 s63, s4, 25
	s_cmp_lt_u32 s63, s23
	global_load_dword v28, v97, s[18:19]
	s_cselect_b64 vcc, -1, 0
	s_and_b64 s[18:19], vcc, exec
	s_cselect_b32 s18, s63, s4
	s_ashr_i32 s19, s18, 31
	s_lshl_b64 s[20:21], s[18:19], 11
	v_lshl_add_u64 v[246:247], v[248:249], 0, s[20:21]
	global_load_dword v117, v[246:247], off offset:1024
	global_load_dword v29, v[246:247], off offset:1028
	s_add_i32 s18, s18, s14
	s_ashr_i32 s19, s18, 31
	s_lshl_b64 s[18:19], s[18:19], 2
	s_add_u32 s18, s26, s18
	s_addc_u32 s19, s27, s19
	s_or_b32 s62, s4, 26
	s_cmp_lt_u32 s62, s23
	global_load_dword v26, v97, s[18:19]
	s_cselect_b64 vcc, -1, 0
	s_and_b64 s[18:19], vcc, exec
	s_cselect_b32 s18, s62, s4
	s_ashr_i32 s19, s18, 31
	s_lshl_b64 s[20:21], s[18:19], 11
	v_lshl_add_u64 v[246:247], v[248:249], 0, s[20:21]
	global_load_dword v116, v[246:247], off offset:1024
	global_load_dword v27, v[246:247], off offset:1028
	s_add_i32 s18, s18, s14
	s_ashr_i32 s19, s18, 31
	s_lshl_b64 s[18:19], s[18:19], 2
	s_add_u32 s18, s26, s18
	s_addc_u32 s19, s27, s19
	s_or_b32 s34, s4, 27
	s_cmp_lt_u32 s34, s23
	global_load_dword v24, v97, s[18:19]
	s_cselect_b64 vcc, -1, 0
	s_and_b64 s[18:19], vcc, exec
	s_cselect_b32 s18, s34, s4
	s_ashr_i32 s19, s18, 31
	s_lshl_b64 s[20:21], s[18:19], 11
	v_lshl_add_u64 v[246:247], v[248:249], 0, s[20:21]
	global_load_dword v115, v[246:247], off offset:1024
	global_load_dword v25, v[246:247], off offset:1028
	s_add_i32 s18, s18, s14
	s_ashr_i32 s19, s18, 31
	s_lshl_b64 s[18:19], s[18:19], 2
	s_add_u32 s18, s26, s18
	s_addc_u32 s19, s27, s19
	s_or_b32 s20, s4, 28
	s_cmp_lt_u32 s20, s23
	global_load_dword v20, v97, s[18:19]
	s_cselect_b64 vcc, -1, 0
	s_and_b64 s[18:19], vcc, exec
	s_cselect_b32 s18, s20, s4
	s_ashr_i32 s19, s18, 31
	s_lshl_b64 s[66:67], s[18:19], 11
	v_lshl_add_u64 v[246:247], v[248:249], 0, s[66:67]
	global_load_dword v23, v[246:247], off offset:1024
	global_load_dword v21, v[246:247], off offset:1028
	s_add_i32 s18, s18, s14
	s_ashr_i32 s19, s18, 31
	s_lshl_b64 s[18:19], s[18:19], 2
	s_add_u32 s18, s26, s18
	s_addc_u32 s19, s27, s19
	s_or_b32 s21, s4, 29
	s_cmp_lt_u32 s21, s23
	global_load_dword v22, v97, s[18:19]
	s_cselect_b64 vcc, -1, 0
	s_and_b64 s[18:19], vcc, exec
	s_cselect_b32 s18, s21, s4
	s_ashr_i32 s19, s18, 31
	s_lshl_b64 s[66:67], s[18:19], 11
	v_lshl_add_u64 v[246:247], v[248:249], 0, s[66:67]
	global_load_dword v114, v[246:247], off offset:1024
	global_load_dword v113, v[246:247], off offset:1028
	s_add_i32 s18, s18, s14
	s_ashr_i32 s19, s18, 31
	s_lshl_b64 s[18:19], s[18:19], 2
	s_add_u32 s18, s26, s18
	s_addc_u32 s19, s27, s19
	s_or_b32 s15, s4, 30
	s_cmp_lt_u32 s15, s23
	global_load_dword v18, v97, s[18:19]
	s_cselect_b64 vcc, -1, 0
	s_and_b64 s[18:19], vcc, exec
	s_cselect_b32 s18, s15, s4
	s_ashr_i32 s19, s18, 31
	s_lshl_b64 s[66:67], s[18:19], 11
	v_lshl_add_u64 v[246:247], v[248:249], 0, s[66:67]
	global_load_dword v112, v[246:247], off offset:1024
	global_load_dword v111, v[246:247], off offset:1028
	s_add_i32 s18, s18, s14
	s_ashr_i32 s19, s18, 31
	s_lshl_b64 s[18:19], s[18:19], 2
	s_add_u32 s18, s26, s18
	s_addc_u32 s19, s27, s19
	s_or_b32 s5, s4, 31
	s_cmp_lt_u32 s5, s23
	global_load_dword v14, v97, s[18:19]
	s_cselect_b64 vcc, -1, 0
	s_and_b64 s[18:19], vcc, exec
	s_cselect_b32 s18, s5, s4
	s_ashr_i32 s19, s18, 31
	s_lshl_b64 s[66:67], s[18:19], 11
	v_lshl_add_u64 v[246:247], v[248:249], 0, s[66:67]
	global_load_dword v19, v[246:247], off offset:1024
	global_load_dword v15, v[246:247], off offset:1028
	s_add_i32 s18, s18, s14
	s_ashr_i32 s19, s18, 31
	s_lshl_b64 s[18:19], s[18:19], 2
	s_add_u32 s18, s26, s18
	s_addc_u32 s19, s27, s19
	s_add_i32 s70, s4, 32
	s_cmp_lt_u32 s70, s23
	global_load_dword v12, v97, s[18:19]
	s_cselect_b64 vcc, -1, 0
	s_and_b64 s[18:19], vcc, exec
	s_cselect_b32 s18, s70, s4
	s_ashr_i32 s19, s18, 31
	s_lshl_b64 s[66:67], s[18:19], 11
	v_lshl_add_u64 v[246:247], v[248:249], 0, s[66:67]
	global_load_dword v110, v[246:247], off offset:1024
	global_load_dword v109, v[246:247], off offset:1028
	s_add_i32 s18, s18, s14
	s_ashr_i32 s19, s18, 31
	s_lshl_b64 s[18:19], s[18:19], 2
	s_add_u32 s18, s26, s18
	s_addc_u32 s19, s27, s19
	s_add_i32 s67, s4, 33
	s_cmp_lt_u32 s67, s23
	global_load_dword v10, v97, s[18:19]
	s_cselect_b64 vcc, -1, 0
	s_and_b64 s[18:19], vcc, exec
	s_cselect_b32 s18, s67, s4
	s_ashr_i32 s19, s18, 31
	s_lshl_b64 s[96:97], s[18:19], 11
	v_lshl_add_u64 v[246:247], v[248:249], 0, s[96:97]
	global_load_dwordx2 v[154:155], v[246:247], off offset:1024
	s_add_i32 s18, s18, s14
	s_ashr_i32 s19, s18, 31
	s_lshl_b64 s[18:19], s[18:19], 2
	s_add_u32 s18, s26, s18
	s_addc_u32 s19, s27, s19
	s_add_i32 s66, s4, 34
	s_cmp_lt_u32 s66, s23
	s_cselect_b64 vcc, -1, 0
	s_and_b64 s[18:19], vcc, exec
	s_cselect_b32 s18, s66, s4
	s_ashr_i32 s19, s18, 31
	s_lshl_b64 s[96:97], s[18:19], 11
	v_lshl_add_u64 v[246:247], v[248:249], 0, s[96:97]
	global_load_dwordx2 v[156:157], v[246:247], off offset:1024
	s_add_i32 s18, s18, s14
	s_ashr_i32 s19, s18, 31
	s_lshl_b64 s[18:19], s[18:19], 2
	s_add_u32 s18, s26, s18
	s_addc_u32 s19, s27, s19
	v_readlane_b32 s5, v244, 0
	v_readlane_b32 vcc_lo, v244, 1
	v_readlane_b32 vcc_hi, v244, 2
	v_readlane_b32 s18, v244, 3
	v_readlane_b32 s19, v244, 4
	v_readlane_b32 s20, v244, 5
	v_readlane_b32 s21, v244, 6
	v_readlane_b32 s30, v244, 7
	v_readlane_b32 s31, v244, 8
	v_readlane_b32 s7, v244, 9
	v_readlane_b32 s91, v244, 10
	v_readlane_b32 s90, v244, 11
	v_readlane_b32 s89, v244, 12
	v_readlane_b32 s88, v244, 13
	v_readlane_b32 s86, v244, 14
	v_readlane_b32 s87, v244, 15
	v_readlane_b32 s85, v244, 16
	v_readlane_b32 s35, v244, 17
	v_readlane_b32 s84, v244, 18
	v_readlane_b32 s83, v244, 19
	v_readlane_b32 s81, v244, 20
	v_readlane_b32 s79, v244, 21
	v_readlane_b32 s82, v244, 22
	v_readlane_b32 s80, v244, 23
	v_readlane_b32 s78, v244, 24
	v_readlane_b32 s77, v244, 25
	v_readlane_b32 s76, v244, 26
	v_readlane_b32 s75, v244, 27
	v_readlane_b32 s74, v244, 28
	v_readlane_b32 s71, v244, 29
	v_readlane_b32 s73, v244, 30
	v_readlane_b32 s72, v244, 31
	v_readlane_b32 s69, v244, 32
	v_readlane_b32 s68, v244, 33
	v_readlane_b32 s63, v244, 34
	v_readlane_b32 s62, v244, 35
	v_readlane_b32 s34, v244, 36
	v_readlane_b32 s66, v244, 37
	v_readlane_b32 s67, v244, 38
	v_readlane_b32 s15, v244, 39
	v_readlane_b32 s70, v244, 40
	v_readlane_b32 s96, v244, 41
	v_readlane_b32 s97, v244, 42
	s_nop 4
	s_waitcnt vmcnt(0)
	s_add_i32 s5, s4, -4
	s_cmp_lt_u32 s5, s23
	s_cselect_b64 vcc, -1, 0
	s_and_b64 s[18:19], vcc, exec
	s_cselect_b32 s18, s5, s4
	v_lshlrev_b32_e32 v96, 1, v11
	s_ashr_i32 s19, s18, 31
	v_lshl_add_u64 v[8:9], s[2:3], 0, v[96:97]
	s_lshl_b64 s[20:21], s[18:19], 11
	v_lshl_add_u64 v[4:5], v[8:9], 0, s[20:21]
	s_add_i32 s18, s18, s14
	s_ashr_i32 s19, s18, 31
	s_lshl_b64 s[18:19], s[18:19], 2
	s_add_u32 s18, s26, s18
	s_addc_u32 s19, s27, s19
	s_add_i32 s5, s4, -3
	s_cmp_lt_u32 s5, s23
	s_mov_b64 s[30:31], 0x400
	s_waitcnt vmcnt(0)
	v_cndmask_b32_e32 v17, 0, v152, vcc
	v_cndmask_b32_e32 v5, 0, v153, vcc
	s_cselect_b64 vcc, -1, 0
	global_load_dword v4, v97, s[18:19]
	s_waitcnt vmcnt(0)
	s_and_b64 s[18:19], vcc, exec
	s_cselect_b32 s18, s5, s4
	s_ashr_i32 s19, s18, 31
	s_lshl_b64 s[20:21], s[18:19], 11
	v_lshl_add_u64 v[6:7], v[8:9], 0, s[20:21]
	s_add_i32 s18, s18, s14
	s_ashr_i32 s19, s18, 31
	s_lshl_b64 s[18:19], s[18:19], 2
	s_add_u32 s18, s26, s18
	s_addc_u32 s19, s27, s19
	s_add_i32 s5, s4, -2
	s_cmp_lt_u32 s5, s23
	v_lshlrev_b32_e32 v82, 16, v17
	v_and_b32_e32 v83, 0xffff0000, v17
	v_lshlrev_b32_e32 v84, 16, v5
	v_and_b32_e32 v85, 0xffff0000, v5
	s_waitcnt vmcnt(2)
	v_pk_mul_f32 v[144:145], v[4:5], v[84:85] op_sel_hi:[0,1]
	v_pk_mul_f32 v[146:147], v[4:5], v[82:83] op_sel_hi:[0,1]
	v_pk_fma_f32 v[82:83], v[4:5], v[82:83], 0 op_sel_hi:[0,1,0]
	v_pk_fma_f32 v[4:5], v[4:5], v[84:85], 0 op_sel_hi:[0,1,0]
	s_waitcnt vmcnt(1)
	v_cndmask_b32_e32 v67, 0, v67, vcc
	v_cndmask_b32_e32 v63, 0, v63, vcc
	s_cselect_b64 vcc, -1, 0
	s_and_b64 s[18:19], vcc, exec
	s_cselect_b32 s18, s5, s4
	s_ashr_i32 s19, s18, 31
	s_lshl_b64 s[20:21], s[18:19], 11
	v_lshl_add_u64 v[6:7], v[8:9], 0, s[20:21]
	s_add_i32 s18, s18, s14
	s_ashr_i32 s19, s18, 31
	s_lshl_b64 s[18:19], s[18:19], 2
	s_add_u32 s18, s26, s18
	s_addc_u32 s19, s27, s19
	s_add_i32 s5, s4, -1
	s_cmp_lt_u32 s5, s23
	v_lshlrev_b32_e32 v84, 16, v67
	v_and_b32_e32 v85, 0xffff0000, v67
	v_lshlrev_b32_e32 v86, 16, v63
	v_and_b32_e32 v87, 0xffff0000, v63
	s_waitcnt vmcnt(2)
	v_pk_mul_f32 v[104:105], v[16:17], v[86:87] op_sel_hi:[0,1]
	v_pk_mul_f32 v[106:107], v[16:17], v[84:85] op_sel_hi:[0,1]
	v_pk_fma_f32 v[4:5], v[16:17], v[86:87], v[4:5] op_sel_hi:[0,1,1]
	v_pk_fma_f32 v[16:17], v[16:17], v[84:85], v[82:83] op_sel_hi:[0,1,1]
	s_waitcnt vmcnt(1)
	v_cndmask_b32_e32 v71, 0, v71, vcc
	v_cndmask_b32_e32 v69, 0, v69, vcc
	s_cselect_b64 vcc, -1, 0
	s_and_b64 s[18:19], vcc, exec
	s_cselect_b32 s18, s5, s4
	s_ashr_i32 s19, s18, 31
	s_lshl_b64 s[20:21], s[18:19], 11
	v_lshl_add_u64 v[6:7], v[8:9], 0, s[20:21]
	s_add_i32 s18, s18, s14
	s_ashr_i32 s19, s18, 31
	s_lshl_b64 s[18:19], s[18:19], 2
	s_add_u32 s18, s26, s18
	s_addc_u32 s19, s27, s19
	s_cmp_lt_u32 s4, s23
	v_lshlrev_b32_e32 v84, 16, v71
	v_and_b32_e32 v85, 0xffff0000, v71
	v_lshlrev_b32_e32 v86, 16, v69
	v_and_b32_e32 v87, 0xffff0000, v69
	s_waitcnt vmcnt(2)
	v_pk_mul_f32 v[82:83], v[62:63], v[86:87] op_sel_hi:[0,1]
	v_pk_mul_f32 v[102:103], v[62:63], v[84:85] op_sel_hi:[0,1]
	v_pk_fma_f32 v[16:17], v[62:63], v[84:85], v[16:17] op_sel_hi:[0,1,1]
	v_pk_fma_f32 v[4:5], v[62:63], v[86:87], v[4:5] op_sel_hi:[0,1,1]
	s_waitcnt vmcnt(1)
	v_cndmask_b32_e32 v75, 0, v75, vcc
	v_cndmask_b32_e32 v73, 0, v73, vcc
	s_cselect_b64 vcc, -1, 0
	s_ashr_i32 s5, s4, 31
	s_lshl_b64 s[18:19], s[4:5], 11
	v_lshl_add_u64 v[6:7], v[8:9], 0, s[18:19]
	s_ashr_i32 s7, s6, 31
	s_lshl_b64 s[18:19], s[6:7], 2
	s_add_u32 s18, s26, s18
	s_addc_u32 s19, s27, s19
	s_or_b32 s91, s4, 1
	s_cmp_lt_u32 s91, s23
	v_lshlrev_b32_e32 v62, 16, v75
	v_and_b32_e32 v63, 0xffff0000, v75
	v_lshlrev_b32_e32 v86, 16, v73
	v_and_b32_e32 v87, 0xffff0000, v73
	s_waitcnt vmcnt(2)
	v_pk_mul_f32 v[100:101], v[66:67], v[62:63] op_sel_hi:[0,1]
	v_pk_fma_f32 v[16:17], v[66:67], v[62:63], v[16:17] op_sel_hi:[0,1,1]
	v_pk_mul_f32 v[84:85], v[66:67], v[86:87] op_sel_hi:[0,1]
	v_pk_fma_f32 v[4:5], v[66:67], v[86:87], v[4:5] op_sel_hi:[0,1,1]
	s_waitcnt vmcnt(1)
	v_cndmask_b32_e32 v79, 0, v79, vcc
	v_cndmask_b32_e32 v77, 0, v77, vcc
	s_cselect_b64 vcc, -1, 0
	s_and_b64 s[18:19], vcc, exec
	s_cselect_b32 s18, s91, s4
	s_ashr_i32 s19, s18, 31
	s_lshl_b64 s[20:21], s[18:19], 11
	v_lshl_add_u64 v[6:7], v[8:9], 0, s[20:21]
	s_add_i32 s18, s18, s14
	s_ashr_i32 s19, s18, 31
	s_lshl_b64 s[18:19], s[18:19], 2
	s_add_u32 s18, s26, s18
	s_addc_u32 s19, s27, s19
	s_or_b32 s90, s4, 2
	s_cmp_lt_u32 s90, s23
	v_lshlrev_b32_e32 v62, 16, v79
	v_and_b32_e32 v63, 0xffff0000, v79
	v_lshlrev_b32_e32 v66, 16, v77
	v_and_b32_e32 v67, 0xffff0000, v77
	s_waitcnt vmcnt(2)
	v_pk_mul_f32 v[98:99], v[68:69], v[62:63] op_sel_hi:[0,1]
	v_pk_fma_f32 v[16:17], v[68:69], v[62:63], v[16:17] op_sel_hi:[0,1,1]
	v_pk_mul_f32 v[86:87], v[68:69], v[66:67] op_sel_hi:[0,1]
	v_pk_fma_f32 v[4:5], v[68:69], v[66:67], v[4:5] op_sel_hi:[0,1,1]
	s_waitcnt vmcnt(1)
	v_cndmask_b32_e32 v89, 0, v89, vcc
	v_cndmask_b32_e32 v88, 0, v88, vcc
	s_cselect_b64 vcc, -1, 0
	s_and_b64 s[18:19], vcc, exec
	s_cselect_b32 s18, s90, s4
	s_ashr_i32 s19, s18, 31
	s_lshl_b64 s[20:21], s[18:19], 11
	v_lshl_add_u64 v[6:7], v[8:9], 0, s[20:21]
	s_add_i32 s18, s18, s14
	s_ashr_i32 s19, s18, 31
	s_lshl_b64 s[18:19], s[18:19], 2
	s_add_u32 s18, s26, s18
	s_addc_u32 s19, s27, s19
	s_or_b32 s89, s4, 3
	s_cmp_lt_u32 s89, s23
	v_lshlrev_b32_e32 v62, 16, v89
	v_and_b32_e32 v63, 0xffff0000, v89
	v_lshlrev_b32_e32 v66, 16, v88
	v_and_b32_e32 v67, 0xffff0000, v88
	s_waitcnt vmcnt(2)
	v_pk_mul_f32 v[94:95], v[72:73], v[62:63] op_sel_hi:[0,1]
	v_pk_fma_f32 v[16:17], v[72:73], v[62:63], v[16:17] op_sel_hi:[0,1,1]
	v_pk_mul_f32 v[88:89], v[72:73], v[66:67] op_sel_hi:[0,1]
	v_pk_fma_f32 v[4:5], v[72:73], v[66:67], v[4:5] op_sel_hi:[0,1,1]
	s_waitcnt vmcnt(1)
	v_cndmask_b32_e32 v91, 0, v91, vcc
	v_cndmask_b32_e32 v90, 0, v90, vcc
	s_cselect_b64 vcc, -1, 0
	s_and_b64 s[18:19], vcc, exec
	s_cselect_b32 s18, s89, s4
	s_ashr_i32 s19, s18, 31
	s_lshl_b64 s[20:21], s[18:19], 11
	v_lshl_add_u64 v[6:7], v[8:9], 0, s[20:21]
	s_add_i32 s18, s18, s14
	s_ashr_i32 s19, s18, 31
	s_lshl_b64 s[18:19], s[18:19], 2
	s_add_u32 s18, s26, s18
	s_addc_u32 s19, s27, s19
	s_or_b32 s88, s4, 4
	s_cmp_lt_u32 s88, s23
	v_lshlrev_b32_e32 v62, 16, v91
	v_and_b32_e32 v63, 0xffff0000, v91
	v_lshlrev_b32_e32 v66, 16, v90
	v_and_b32_e32 v67, 0xffff0000, v90
	s_waitcnt vmcnt(2)
	v_pk_fma_f32 v[16:17], v[76:77], v[62:63], v[16:17] op_sel_hi:[0,1,1]
	v_pk_fma_f32 v[4:5], v[76:77], v[66:67], v[4:5] op_sel_hi:[0,1,1]
	v_pk_mul_f32 v[90:91], v[76:77], v[66:67] op_sel_hi:[0,1]
	v_pk_mul_f32 v[92:93], v[76:77], v[62:63] op_sel_hi:[0,1]
	s_waitcnt vmcnt(1)
	v_cndmask_b32_e32 v143, 0, v143, vcc
	v_cndmask_b32_e32 v142, 0, v142, vcc
	s_cselect_b64 vcc, -1, 0
	s_and_b64 s[18:19], vcc, exec
	s_cselect_b32 s18, s88, s4
	s_ashr_i32 s19, s18, 31
	s_lshl_b64 s[20:21], s[18:19], 11
	v_lshl_add_u64 v[6:7], v[8:9], 0, s[20:21]
	s_add_i32 s18, s18, s14
	s_ashr_i32 s19, s18, 31
	s_lshl_b64 s[18:19], s[18:19], 2
	s_add_u32 s18, s26, s18
	s_addc_u32 s19, s27, s19
	s_or_b32 s86, s4, 5
	s_cmp_lt_u32 s86, s23
	v_lshlrev_b32_e32 v68, 16, v143
	v_and_b32_e32 v69, 0xffff0000, v143
	v_lshlrev_b32_e32 v72, 16, v142
	v_and_b32_e32 v73, 0xffff0000, v142
	s_waitcnt vmcnt(1)
	v_cndmask_b32_e32 v141, 0, v141, vcc
	v_cndmask_b32_e32 v140, 0, v140, vcc
	s_cselect_b64 vcc, -1, 0
	s_and_b64 s[18:19], vcc, exec
	s_cselect_b32 s18, s86, s4
	s_ashr_i32 s19, s18, 31
	s_lshl_b64 s[20:21], s[18:19], 11
	v_lshl_add_u64 v[6:7], v[8:9], 0, s[20:21]
	s_add_i32 s18, s18, s14
	s_ashr_i32 s19, s18, 31
	s_lshl_b64 s[18:19], s[18:19], 2
	s_add_u32 s18, s26, s18
	s_addc_u32 s19, s27, s19
	s_or_b32 s87, s4, 6
	s_cmp_lt_u32 s87, s23
	v_lshlrev_b32_e32 v148, 16, v141
	v_and_b32_e32 v149, 0xffff0000, v141
	v_lshlrev_b32_e32 v150, 16, v140
	v_and_b32_e32 v151, 0xffff0000, v140
	s_waitcnt vmcnt(1)
	v_cndmask_b32_e32 v137, 0, v137, vcc
	v_cndmask_b32_e32 v81, 0, v81, vcc
	s_cselect_b64 vcc, -1, 0
	s_and_b64 s[18:19], vcc, exec
	s_cselect_b32 s18, s87, s4
	s_ashr_i32 s19, s18, 31
	s_lshl_b64 s[20:21], s[18:19], 11
	v_lshl_add_u64 v[6:7], v[8:9], 0, s[20:21]
	s_add_i32 s18, s18, s14
	s_ashr_i32 s19, s18, 31
	s_lshl_b64 s[18:19], s[18:19], 2
	s_add_u32 s18, s26, s18
	s_addc_u32 s19, s27, s19
	s_or_b32 s85, s4, 7
	s_cmp_lt_u32 s85, s23
	v_pk_fma_f32 v[142:143], v[80:81], v[68:69], v[16:17] op_sel_hi:[0,1,1]
	v_pk_fma_f32 v[76:77], v[80:81], v[72:73], v[4:5] op_sel_hi:[0,1,1]
	v_pk_mul_f32 v[66:67], v[80:81], v[68:69] op_sel_hi:[0,1]
	v_pk_mul_f32 v[62:63], v[80:81], v[72:73] op_sel_hi:[0,1]
	s_waitcnt vmcnt(1)
	v_cndmask_b32_e32 v139, 0, v139, vcc
	v_cndmask_b32_e32 v138, 0, v138, vcc
	s_cselect_b64 vcc, -1, 0
	s_and_b64 s[18:19], vcc, exec
	s_cselect_b32 s18, s85, s4
	s_ashr_i32 s19, s18, 31
	s_lshl_b64 s[20:21], s[18:19], 11
	v_lshl_add_u64 v[6:7], v[8:9], 0, s[20:21]
	s_add_i32 s18, s18, s14
	s_ashr_i32 s19, s18, 31
	s_lshl_b64 s[18:19], s[18:19], 2
	s_add_u32 s18, s26, s18
	s_addc_u32 s19, s27, s19
	s_or_b32 s35, s4, 8
	s_cmp_lt_u32 s35, s23
	s_waitcnt vmcnt(1)
	v_cndmask_b32_e32 v136, 0, v136, vcc
	v_cndmask_b32_e32 v135, 0, v135, vcc
	s_cselect_b64 vcc, -1, 0
	s_and_b64 s[18:19], vcc, exec
	s_cselect_b32 s18, s35, s4
	s_ashr_i32 s19, s18, 31
	s_lshl_b64 s[20:21], s[18:19], 11
	v_lshl_add_u64 v[6:7], v[8:9], 0, s[20:21]
	s_add_i32 s18, s18, s14
	s_ashr_i32 s19, s18, 31
	s_lshl_b64 s[18:19], s[18:19], 2
	s_add_u32 s18, s26, s18
	s_addc_u32 s19, s27, s19
	s_or_b32 s84, s4, 9
	s_cmp_lt_u32 s84, s23
	s_waitcnt vmcnt(1)
	v_cndmask_b32_e32 v134, 0, v134, vcc
	v_cndmask_b32_e32 v65, 0, v65, vcc
	s_cselect_b64 vcc, -1, 0
	s_and_b64 s[18:19], vcc, exec
	s_cselect_b32 s18, s84, s4
	s_ashr_i32 s19, s18, 31
	s_lshl_b64 s[20:21], s[18:19], 11
	v_lshl_add_u64 v[6:7], v[8:9], 0, s[20:21]
	s_add_i32 s18, s18, s14
	s_ashr_i32 s19, s18, 31
	s_lshl_b64 s[18:19], s[18:19], 2
	s_add_u32 s18, s26, s18
	s_addc_u32 s19, s27, s19
	s_or_b32 s83, s4, 10
	s_cmp_lt_u32 s83, s23
	s_waitcnt vmcnt(1)
	v_cndmask_b32_e32 v133, 0, v133, vcc
	v_cndmask_b32_e32 v61, 0, v61, vcc
	s_cselect_b64 vcc, -1, 0
	s_and_b64 s[18:19], vcc, exec
	s_cselect_b32 s18, s83, s4
	s_ashr_i32 s19, s18, 31
	s_lshl_b64 s[20:21], s[18:19], 11
	v_lshl_add_u64 v[6:7], v[8:9], 0, s[20:21]
	s_add_i32 s18, s18, s14
	s_ashr_i32 s19, s18, 31
	s_lshl_b64 s[18:19], s[18:19], 2
	s_add_u32 s18, s26, s18
	s_addc_u32 s19, s27, s19
	s_or_b32 s81, s4, 11
	s_cmp_lt_u32 s81, s23
	s_waitcnt vmcnt(1)
	v_cndmask_b32_e32 v132, 0, v132, vcc
	v_cndmask_b32_e32 v59, 0, v59, vcc
	s_cselect_b64 vcc, -1, 0
	s_and_b64 s[18:19], vcc, exec
	s_cselect_b32 s18, s81, s4
	s_ashr_i32 s19, s18, 31
	s_lshl_b64 s[20:21], s[18:19], 11
	v_lshl_add_u64 v[6:7], v[8:9], 0, s[20:21]
	s_add_i32 s18, s18, s14
	s_ashr_i32 s19, s18, 31
	s_lshl_b64 s[18:19], s[18:19], 2
	s_add_u32 s18, s26, s18
	s_addc_u32 s19, s27, s19
	s_or_b32 s79, s4, 12
	s_cmp_lt_u32 s79, s23
	s_waitcnt vmcnt(1)
	v_cndmask_b32_e32 v57, 0, v57, vcc
	v_cndmask_b32_e32 v55, 0, v55, vcc
	s_cselect_b64 vcc, -1, 0
	s_and_b64 s[18:19], vcc, exec
	s_cselect_b32 s18, s79, s4
	s_ashr_i32 s19, s18, 31
	s_lshl_b64 s[20:21], s[18:19], 11
	v_lshl_add_u64 v[6:7], v[8:9], 0, s[20:21]
	s_add_i32 s18, s18, s14
	s_ashr_i32 s19, s18, 31
	s_lshl_b64 s[18:19], s[18:19], 2
	s_add_u32 s18, s26, s18
	s_addc_u32 s19, s27, s19
	s_or_b32 s82, s4, 13
	s_cmp_lt_u32 s82, s23
	s_waitcnt vmcnt(1)
	v_cndmask_b32_e32 v53, 0, v53, vcc
	v_cndmask_b32_e32 v51, 0, v51, vcc
	s_cselect_b64 vcc, -1, 0
	s_and_b64 s[18:19], vcc, exec
	s_cselect_b32 s18, s82, s4
	s_ashr_i32 s19, s18, 31
	s_lshl_b64 s[20:21], s[18:19], 11
	v_lshl_add_u64 v[6:7], v[8:9], 0, s[20:21]
	s_add_i32 s18, s18, s14
	s_ashr_i32 s19, s18, 31
	s_lshl_b64 s[18:19], s[18:19], 2
	s_add_u32 s18, s26, s18
	s_addc_u32 s19, s27, s19
	s_or_b32 s80, s4, 14
	s_cmp_lt_u32 s80, s23
	s_waitcnt vmcnt(1)
	v_cndmask_b32_e32 v131, 0, v131, vcc
	v_cndmask_b32_e32 v130, 0, v130, vcc
	s_cselect_b64 vcc, -1, 0
	s_and_b64 s[18:19], vcc, exec
	s_cselect_b32 s18, s80, s4
	s_ashr_i32 s19, s18, 31
	s_lshl_b64 s[20:21], s[18:19], 11
	v_lshl_add_u64 v[6:7], v[8:9], 0, s[20:21]
	s_add_i32 s18, s18, s14
	s_ashr_i32 s19, s18, 31
	s_lshl_b64 s[18:19], s[18:19], 2
	s_add_u32 s18, s26, s18
	s_addc_u32 s19, s27, s19
	s_or_b32 s78, s4, 15
	s_cmp_lt_u32 s78, s23
	s_waitcnt vmcnt(1)
	v_cndmask_b32_e32 v129, 0, v129, vcc
	v_cndmask_b32_e32 v128, 0, v128, vcc
	s_cselect_b64 vcc, -1, 0
	s_and_b64 s[18:19], vcc, exec
	s_cselect_b32 s18, s78, s4
	s_ashr_i32 s19, s18, 31
	s_lshl_b64 s[20:21], s[18:19], 11
	v_lshl_add_u64 v[6:7], v[8:9], 0, s[20:21]
	s_add_i32 s18, s18, s14
	s_ashr_i32 s19, s18, 31
	s_lshl_b64 s[18:19], s[18:19], 2
	s_add_u32 s18, s26, s18
	s_addc_u32 s19, s27, s19
	s_or_b32 s77, s4, 16
	s_cmp_lt_u32 s77, s23
	s_waitcnt vmcnt(1)
	v_cndmask_b32_e32 v127, 0, v127, vcc
	v_cndmask_b32_e32 v49, 0, v49, vcc
	s_cselect_b64 vcc, -1, 0
	s_and_b64 s[18:19], vcc, exec
	s_cselect_b32 s18, s77, s4
	s_ashr_i32 s19, s18, 31
	s_lshl_b64 s[20:21], s[18:19], 11
	v_lshl_add_u64 v[6:7], v[8:9], 0, s[20:21]
	s_add_i32 s18, s18, s14
	s_ashr_i32 s19, s18, 31
	s_lshl_b64 s[18:19], s[18:19], 2
	s_add_u32 s18, s26, s18
	s_addc_u32 s19, s27, s19
	s_or_b32 s76, s4, 17
	s_cmp_lt_u32 s76, s23
	s_waitcnt vmcnt(1)
	v_cndmask_b32_e32 v126, 0, v126, vcc
	v_cndmask_b32_e32 v47, 0, v47, vcc
	s_cselect_b64 vcc, -1, 0
	s_and_b64 s[18:19], vcc, exec
	s_cselect_b32 s18, s76, s4
	s_ashr_i32 s19, s18, 31
	s_lshl_b64 s[20:21], s[18:19], 11
	v_lshl_add_u64 v[6:7], v[8:9], 0, s[20:21]
	s_add_i32 s18, s18, s14
	s_ashr_i32 s19, s18, 31
	s_lshl_b64 s[18:19], s[18:19], 2
	s_add_u32 s18, s26, s18
	s_addc_u32 s19, s27, s19
	s_or_b32 s75, s4, 18
	s_cmp_lt_u32 s75, s23
	s_waitcnt vmcnt(1)
	v_cndmask_b32_e32 v125, 0, v125, vcc
	v_cndmask_b32_e32 v45, 0, v45, vcc
	s_cselect_b64 vcc, -1, 0
	s_and_b64 s[18:19], vcc, exec
	s_cselect_b32 s18, s75, s4
	s_ashr_i32 s19, s18, 31
	s_lshl_b64 s[20:21], s[18:19], 11
	v_lshl_add_u64 v[6:7], v[8:9], 0, s[20:21]
	s_add_i32 s18, s18, s14
	s_ashr_i32 s19, s18, 31
	s_lshl_b64 s[18:19], s[18:19], 2
	s_add_u32 s18, s26, s18
	s_addc_u32 s19, s27, s19
	s_or_b32 s74, s4, 19
	s_cmp_lt_u32 s74, s23
	s_waitcnt vmcnt(1)
	v_cndmask_b32_e32 v124, 0, v124, vcc
	v_cndmask_b32_e32 v43, 0, v43, vcc
	s_cselect_b64 vcc, -1, 0
	s_and_b64 s[18:19], vcc, exec
	s_cselect_b32 s18, s74, s4
	s_ashr_i32 s19, s18, 31
	s_lshl_b64 s[20:21], s[18:19], 11
	v_lshl_add_u64 v[6:7], v[8:9], 0, s[20:21]
	s_add_i32 s18, s18, s14
	s_ashr_i32 s19, s18, 31
	s_lshl_b64 s[18:19], s[18:19], 2
	s_add_u32 s18, s26, s18
	s_addc_u32 s19, s27, s19
	s_or_b32 s71, s4, 20
	s_cmp_lt_u32 s71, s23
	s_waitcnt vmcnt(1)
	v_cndmask_b32_e32 v123, 0, v123, vcc
	v_cndmask_b32_e32 v41, 0, v41, vcc
	s_cselect_b64 vcc, -1, 0
	s_and_b64 s[18:19], vcc, exec
	s_cselect_b32 s18, s71, s4
	s_ashr_i32 s19, s18, 31
	s_lshl_b64 s[20:21], s[18:19], 11
	v_lshl_add_u64 v[6:7], v[8:9], 0, s[20:21]
	s_add_i32 s18, s18, s14
	s_ashr_i32 s19, s18, 31
	s_lshl_b64 s[18:19], s[18:19], 2
	s_add_u32 s18, s26, s18
	s_addc_u32 s19, s27, s19
	s_or_b32 s73, s4, 21
	s_cmp_lt_u32 s73, s23
	s_waitcnt vmcnt(1)
	v_cndmask_b32_e32 v37, 0, v37, vcc
	v_cndmask_b32_e32 v35, 0, v35, vcc
	s_cselect_b64 vcc, -1, 0
	s_and_b64 s[18:19], vcc, exec
	s_cselect_b32 s18, s73, s4
	s_ashr_i32 s19, s18, 31
	s_lshl_b64 s[20:21], s[18:19], 11
	v_lshl_add_u64 v[6:7], v[8:9], 0, s[20:21]
	s_add_i32 s18, s18, s14
	s_ashr_i32 s19, s18, 31
	s_lshl_b64 s[18:19], s[18:19], 2
	s_add_u32 s18, s26, s18
	s_addc_u32 s19, s27, s19
	s_or_b32 s72, s4, 22
	s_cmp_lt_u32 s72, s23
	s_waitcnt vmcnt(1)
	v_cndmask_b32_e32 v122, 0, v122, vcc
	v_cndmask_b32_e32 v39, 0, v39, vcc
	s_cselect_b64 vcc, -1, 0
	s_and_b64 s[18:19], vcc, exec
	s_cselect_b32 s18, s72, s4
	s_ashr_i32 s19, s18, 31
	s_lshl_b64 s[20:21], s[18:19], 11
	v_lshl_add_u64 v[6:7], v[8:9], 0, s[20:21]
	s_add_i32 s18, s18, s14
	s_ashr_i32 s19, s18, 31
	s_lshl_b64 s[18:19], s[18:19], 2
	s_add_u32 s18, s26, s18
	s_addc_u32 s19, s27, s19
	s_or_b32 s69, s4, 23
	s_cmp_lt_u32 s69, s23
	s_waitcnt vmcnt(1)
	v_cndmask_b32_e32 v121, 0, v121, vcc
	v_cndmask_b32_e32 v120, 0, v120, vcc
	s_cselect_b64 vcc, -1, 0
	s_and_b64 s[18:19], vcc, exec
	s_cselect_b32 s18, s69, s4
	s_ashr_i32 s19, s18, 31
	s_lshl_b64 s[20:21], s[18:19], 11
	v_lshl_add_u64 v[6:7], v[8:9], 0, s[20:21]
	s_add_i32 s18, s18, s14
	s_ashr_i32 s19, s18, 31
	s_lshl_b64 s[18:19], s[18:19], 2
	s_add_u32 s18, s26, s18
	s_addc_u32 s19, s27, s19
	s_or_b32 s68, s4, 24
	s_cmp_lt_u32 s68, s23
	s_waitcnt vmcnt(1)
	v_cndmask_b32_e32 v119, 0, v119, vcc
	v_cndmask_b32_e32 v33, 0, v33, vcc
	s_cselect_b64 vcc, -1, 0
	s_and_b64 s[18:19], vcc, exec
	s_cselect_b32 s18, s68, s4
	s_ashr_i32 s19, s18, 31
	s_lshl_b64 s[20:21], s[18:19], 11
	v_lshl_add_u64 v[6:7], v[8:9], 0, s[20:21]
	s_add_i32 s18, s18, s14
	s_ashr_i32 s19, s18, 31
	s_lshl_b64 s[18:19], s[18:19], 2
	s_add_u32 s18, s26, s18
	s_addc_u32 s19, s27, s19
	s_or_b32 s63, s4, 25
	s_cmp_lt_u32 s63, s23
	s_waitcnt vmcnt(1)
	v_cndmask_b32_e32 v118, 0, v118, vcc
	v_cndmask_b32_e32 v31, 0, v31, vcc
	s_cselect_b64 vcc, -1, 0
	s_and_b64 s[18:19], vcc, exec
	s_cselect_b32 s18, s63, s4
	s_ashr_i32 s19, s18, 31
	s_lshl_b64 s[20:21], s[18:19], 11
	v_lshl_add_u64 v[6:7], v[8:9], 0, s[20:21]
	s_add_i32 s18, s18, s14
	s_ashr_i32 s19, s18, 31
	s_lshl_b64 s[18:19], s[18:19], 2
	s_add_u32 s18, s26, s18
	s_addc_u32 s19, s27, s19
	s_or_b32 s62, s4, 26
	s_cmp_lt_u32 s62, s23
	s_waitcnt vmcnt(1)
	v_cndmask_b32_e32 v117, 0, v117, vcc
	v_cndmask_b32_e32 v29, 0, v29, vcc
	s_cselect_b64 vcc, -1, 0
	s_and_b64 s[18:19], vcc, exec
	s_cselect_b32 s18, s62, s4
	s_ashr_i32 s19, s18, 31
	s_lshl_b64 s[20:21], s[18:19], 11
	v_lshl_add_u64 v[6:7], v[8:9], 0, s[20:21]
	s_add_i32 s18, s18, s14
	s_ashr_i32 s19, s18, 31
	s_lshl_b64 s[18:19], s[18:19], 2
	s_add_u32 s18, s26, s18
	s_addc_u32 s19, s27, s19
	s_or_b32 s34, s4, 27
	s_cmp_lt_u32 s34, s23
	s_waitcnt vmcnt(1)
	v_cndmask_b32_e32 v116, 0, v116, vcc
	v_cndmask_b32_e32 v27, 0, v27, vcc
	s_cselect_b64 vcc, -1, 0
	s_and_b64 s[18:19], vcc, exec
	s_cselect_b32 s18, s34, s4
	s_ashr_i32 s19, s18, 31
	s_lshl_b64 s[20:21], s[18:19], 11
	v_lshl_add_u64 v[6:7], v[8:9], 0, s[20:21]
	s_add_i32 s18, s18, s14
	s_ashr_i32 s19, s18, 31
	s_lshl_b64 s[18:19], s[18:19], 2
	s_add_u32 s18, s26, s18
	s_addc_u32 s19, s27, s19
	s_or_b32 s20, s4, 28
	s_cmp_lt_u32 s20, s23
	s_waitcnt vmcnt(1)
	v_cndmask_b32_e32 v115, 0, v115, vcc
	v_cndmask_b32_e32 v25, 0, v25, vcc
	s_cselect_b64 vcc, -1, 0
	s_and_b64 s[18:19], vcc, exec
	s_cselect_b32 s18, s20, s4
	s_ashr_i32 s19, s18, 31
	s_lshl_b64 s[66:67], s[18:19], 11
	v_lshl_add_u64 v[6:7], v[8:9], 0, s[66:67]
	s_add_i32 s18, s18, s14
	s_ashr_i32 s19, s18, 31
	s_lshl_b64 s[18:19], s[18:19], 2
	s_add_u32 s18, s26, s18
	s_addc_u32 s19, s27, s19
	s_or_b32 s21, s4, 29
	s_cmp_lt_u32 s21, s23
	s_waitcnt vmcnt(1)
	v_cndmask_b32_e32 v23, 0, v23, vcc
	v_cndmask_b32_e32 v21, 0, v21, vcc
	s_cselect_b64 vcc, -1, 0
	s_and_b64 s[18:19], vcc, exec
	s_cselect_b32 s18, s21, s4
	s_ashr_i32 s19, s18, 31
	s_lshl_b64 s[66:67], s[18:19], 11
	v_lshl_add_u64 v[6:7], v[8:9], 0, s[66:67]
	s_add_i32 s18, s18, s14
	s_ashr_i32 s19, s18, 31
	s_lshl_b64 s[18:19], s[18:19], 2
	s_add_u32 s18, s26, s18
	s_addc_u32 s19, s27, s19
	s_or_b32 s15, s4, 30
	s_cmp_lt_u32 s15, s23
	s_waitcnt vmcnt(1)
	v_cndmask_b32_e32 v114, 0, v114, vcc
	v_cndmask_b32_e32 v113, 0, v113, vcc
	s_cselect_b64 vcc, -1, 0
	s_and_b64 s[18:19], vcc, exec
	s_cselect_b32 s18, s15, s4
	s_ashr_i32 s19, s18, 31
	s_lshl_b64 s[66:67], s[18:19], 11
	v_lshl_add_u64 v[6:7], v[8:9], 0, s[66:67]
	s_add_i32 s18, s18, s14
	s_ashr_i32 s19, s18, 31
	s_lshl_b64 s[18:19], s[18:19], 2
	s_add_u32 s18, s26, s18
	s_addc_u32 s19, s27, s19
	s_or_b32 s5, s4, 31
	s_cmp_lt_u32 s5, s23
	s_waitcnt vmcnt(1)
	v_cndmask_b32_e32 v112, 0, v112, vcc
	v_cndmask_b32_e32 v111, 0, v111, vcc
	s_cselect_b64 vcc, -1, 0
	s_and_b64 s[18:19], vcc, exec
	s_cselect_b32 s18, s5, s4
	s_ashr_i32 s19, s18, 31
	s_lshl_b64 s[66:67], s[18:19], 11
	v_lshl_add_u64 v[6:7], v[8:9], 0, s[66:67]
	s_add_i32 s18, s18, s14
	s_ashr_i32 s19, s18, 31
	s_lshl_b64 s[18:19], s[18:19], 2
	s_add_u32 s18, s26, s18
	s_addc_u32 s19, s27, s19
	s_add_i32 s70, s4, 32
	s_cmp_lt_u32 s70, s23
	s_waitcnt vmcnt(1)
	v_cndmask_b32_e32 v19, 0, v19, vcc
	v_cndmask_b32_e32 v15, 0, v15, vcc
	s_cselect_b64 vcc, -1, 0
	s_and_b64 s[18:19], vcc, exec
	s_cselect_b32 s18, s70, s4
	s_ashr_i32 s19, s18, 31
	s_lshl_b64 s[66:67], s[18:19], 11
	v_lshl_add_u64 v[6:7], v[8:9], 0, s[66:67]
	s_add_i32 s18, s18, s14
	s_ashr_i32 s19, s18, 31
	s_lshl_b64 s[18:19], s[18:19], 2
	s_add_u32 s18, s26, s18
	s_addc_u32 s19, s27, s19
	s_add_i32 s67, s4, 33
	s_cmp_lt_u32 s67, s23
	s_waitcnt vmcnt(1)
	v_cndmask_b32_e32 v110, 0, v110, vcc
	v_cndmask_b32_e32 v109, 0, v109, vcc
	s_cselect_b64 vcc, -1, 0
	s_and_b64 s[18:19], vcc, exec
	s_cselect_b32 s18, s67, s4
	s_ashr_i32 s19, s18, 31
	s_lshl_b64 s[96:97], s[18:19], 11
	v_lshl_add_u64 v[6:7], v[8:9], 0, s[96:97]
	s_add_i32 s18, s18, s14
	s_ashr_i32 s19, s18, 31
	s_lshl_b64 s[18:19], s[18:19], 2
	s_add_u32 s18, s26, s18
	s_addc_u32 s19, s27, s19
	s_add_i32 s66, s4, 34
	s_cmp_lt_u32 s66, s23
	s_waitcnt vmcnt(0)
	v_cndmask_b32_e32 v13, 0, v154, vcc
	v_cndmask_b32_e32 v7, 0, v155, vcc
	s_cselect_b64 vcc, -1, 0
	global_load_dword v6, v97, s[18:19]
	s_waitcnt vmcnt(0)
	s_and_b64 s[18:19], vcc, exec
	s_cselect_b32 s18, s66, s4
	s_ashr_i32 s19, s18, 31
	s_lshl_b64 s[96:97], s[18:19], 11
	v_lshl_add_u64 v[8:9], v[8:9], 0, s[96:97]
	s_add_i32 s18, s18, s14
	s_ashr_i32 s19, s18, 31
	s_lshl_b64 s[18:19], s[18:19], 2
	s_add_u32 s18, s26, s18
	s_addc_u32 s19, s27, s19
	s_waitcnt vmcnt(0)
	v_cndmask_b32_e32 v108, 0, v156, vcc
	global_load_dword v8, v97, s[18:19]
	s_waitcnt vmcnt(0)
	s_lshl_b64 s[18:19], s[6:7], 11
	s_add_u32 s18, s24, s18
	s_addc_u32 s19, s25, s19
	v_lshl_add_u64 v[16:17], s[18:19], 0, v[96:97]
	v_lshl_add_u64 v[4:5], v[16:17], 0, s[30:31]
	s_max_i32 s7, s4, 4
	s_min_i32 s30, s88, s23
	s_sub_i32 s7, s30, s7
	s_add_i32 s7, s7, 4
	v_cvt_f32_i32_e32 v68, s7
	v_cndmask_b32_e32 v9, 0, v157, vcc
	s_max_i32 s7, s91, 4
	s_min_i32 s30, s86, s23
	v_div_scale_f32 v69, s[96:97], v68, v68, 1.0
	v_rcp_f32_e32 v71, v69
	s_sub_i32 s7, s30, s7
	s_add_i32 s7, s7, 4
	s_movk_i32 s91, 0x2000
	v_fma_f32 v72, -v69, v71, 1.0
	v_fmac_f32_e32 v71, v72, v71
	v_div_scale_f32 v72, vcc, 1.0, v68, 1.0
	v_mul_f32_e32 v73, v72, v71
	v_fma_f32 v75, -v69, v73, v72
	v_fmac_f32_e32 v73, v75, v71
	v_fma_f32 v69, -v69, v73, v72
	v_div_fmas_f32 v69, v69, v71, v73
	v_div_fixup_f32 v68, v69, v68, 1.0
	v_pk_fma_f32 v[72:73], v[68:69], v[142:143], v[98:99] op_sel_hi:[0,1,1] neg_lo:[0,0,1] neg_hi:[0,0,1]
	v_cvt_f32_i32_e32 v71, s7
	v_pk_fma_f32 v[68:69], v[68:69], v[76:77], v[86:87] op_sel_hi:[0,1,1] neg_lo:[0,0,1] neg_hi:[0,0,1]
	v_pk_mul_f32 v[72:73], v[0:1], v[72:73]
	v_pk_mul_f32 v[68:69], v[2:3], v[68:69]
	v_cvt_pk_bf16_f32 v72, v72, v73
	v_pk_fma_f32 v[140:141], v[74:75], v[148:149], v[146:147] op_sel_hi:[0,1,1] neg_lo:[0,0,1] neg_hi:[0,0,1]
	v_cvt_pk_bf16_f32 v73, v68, v69
	global_store_dwordx2 v96, v[72:73], s[18:19] offset:1024
	v_pk_mul_f32 v[68:69], v[74:75], v[150:151] op_sel_hi:[0,1]
	v_pk_mul_f32 v[72:73], v[74:75], v[148:149] op_sel_hi:[0,1]
	v_pk_fma_f32 v[74:75], v[74:75], v[150:151], v[144:145] op_sel_hi:[0,1,1] neg_lo:[0,0,1] neg_hi:[0,0,1]
	v_pk_add_f32 v[76:77], v[76:77], v[74:75]
	v_div_scale_f32 v74, s[96:97], v71, v71, 1.0
	v_rcp_f32_e32 v75, v74
	v_pk_add_f32 v[140:141], v[142:143], v[140:141]
	s_max_i32 s7, s90, 4
	v_lshlrev_b32_e32 v144, 16, v81
	v_fma_f32 v79, -v74, v75, 1.0
	v_fmac_f32_e32 v75, v79, v75
	v_div_scale_f32 v79, vcc, 1.0, v71, 1.0
	v_mul_f32_e32 v80, v79, v75
	v_fma_f32 v142, -v74, v80, v79
	v_fmac_f32_e32 v80, v142, v75
	v_fma_f32 v74, -v74, v80, v79
	v_div_fmas_f32 v74, v74, v75, v80
	v_div_fixup_f32 v74, v74, v71, 1.0
	v_pk_fma_f32 v[142:143], v[74:75], v[140:141], v[94:95] op_sel_hi:[0,1,1] neg_lo:[0,0,1] neg_hi:[0,0,1]
	v_pk_fma_f32 v[74:75], v[74:75], v[76:77], v[88:89] op_sel_hi:[0,1,1] neg_lo:[0,0,1] neg_hi:[0,0,1]
	v_pk_mul_f32 v[142:143], v[0:1], v[142:143]
	v_pk_mul_f32 v[74:75], v[2:3], v[74:75]
	v_cvt_pk_bf16_f32 v142, v142, v143
	v_and_b32_e32 v145, 0xffff0000, v81
	v_cvt_pk_bf16_f32 v143, v74, v75
	global_store_dwordx2 v96, v[142:143], s[18:19] offset:3072
	s_min_i32 s18, s87, s23
	s_sub_i32 s7, s18, s7
	s_add_i32 s7, s7, 4
	v_cvt_f32_i32_e32 v71, s7
	v_lshlrev_b32_e32 v142, 16, v137
	v_and_b32_e32 v143, 0xffff0000, v137
	v_pk_mul_f32 v[74:75], v[78:79], v[144:145] op_sel_hi:[0,1]
	v_pk_mul_f32 v[80:81], v[78:79], v[142:143] op_sel_hi:[0,1]
	v_pk_fma_f32 v[106:107], v[78:79], v[142:143], v[106:107] op_sel_hi:[0,1,1] neg_lo:[0,0,1] neg_hi:[0,0,1]
	v_pk_fma_f32 v[78:79], v[78:79], v[144:145], v[104:105] op_sel_hi:[0,1,1] neg_lo:[0,0,1] neg_hi:[0,0,1]
	v_pk_add_f32 v[104:105], v[76:77], v[78:79]
	v_div_scale_f32 v76, s[18:19], v71, v71, 1.0
	v_rcp_f32_e32 v77, v76
	v_pk_add_f32 v[106:107], v[140:141], v[106:107]
	s_max_i32 s7, s89, 4
	s_min_i32 s18, s85, s23
	v_fma_f32 v78, -v76, v77, 1.0
	v_fmac_f32_e32 v77, v78, v77
	v_div_scale_f32 v78, vcc, 1.0, v71, 1.0
	v_mul_f32_e32 v79, v78, v77
	v_fma_f32 v96, -v76, v79, v78
	v_fmac_f32_e32 v79, v96, v77
	v_fma_f32 v76, -v76, v79, v78
	v_div_fmas_f32 v76, v76, v77, v79
	v_div_fixup_f32 v76, v76, v71, 1.0
	v_pk_fma_f32 v[78:79], v[76:77], v[106:107], v[92:93] op_sel_hi:[0,1,1] neg_lo:[0,0,1] neg_hi:[0,0,1]
	v_pk_fma_f32 v[76:77], v[76:77], v[104:105], v[90:91] op_sel_hi:[0,1,1] neg_lo:[0,0,1] neg_hi:[0,0,1]
	v_pk_mul_f32 v[78:79], v[0:1], v[78:79]
	v_add_co_u32_e32 v140, vcc, s92, v16
	v_pk_mul_f32 v[76:77], v[2:3], v[76:77]
	v_cvt_pk_bf16_f32 v78, v78, v79
	s_nop 0
	v_addc_co_u32_e32 v141, vcc, 0, v17, vcc
	v_cvt_pk_bf16_f32 v79, v76, v77
	v_lshlrev_b32_e32 v142, 16, v139
	v_and_b32_e32 v143, 0xffff0000, v139
	v_lshlrev_b32_e32 v144, 16, v138
	v_and_b32_e32 v145, 0xffff0000, v138
	s_sub_i32 s7, s18, s7
	global_store_dwordx2 v[140:141], v[78:79], off offset:1024
	v_pk_mul_f32 v[76:77], v[70:71], v[144:145] op_sel_hi:[0,1]
	v_pk_mul_f32 v[78:79], v[70:71], v[142:143] op_sel_hi:[0,1]
	v_pk_fma_f32 v[102:103], v[70:71], v[142:143], v[102:103] op_sel_hi:[0,1,1] neg_lo:[0,0,1] neg_hi:[0,0,1]
	v_pk_fma_f32 v[70:71], v[70:71], v[144:145], v[82:83] op_sel_hi:[0,1,1] neg_lo:[0,0,1] neg_hi:[0,0,1]
	s_add_i32 s7, s7, 4
	v_pk_add_f32 v[104:105], v[104:105], v[70:71]
	v_cvt_f32_i32_e32 v70, s7
	v_pk_add_f32 v[102:103], v[106:107], v[102:103]
	s_max_i32 s7, s88, 4
	v_and_b32_e32 v107, 0xffff0000, v136
	v_div_scale_f32 v71, s[18:19], v70, v70, 1.0
	v_rcp_f32_e32 v82, v71
	s_min_i32 s18, s35, s23
	s_sub_i32 s7, s18, s7
	v_and_b32_e32 v137, 0xffff0000, v135
	v_fma_f32 v83, -v71, v82, 1.0
	v_fmac_f32_e32 v82, v83, v82
	v_div_scale_f32 v83, vcc, 1.0, v70, 1.0
	v_mul_f32_e32 v96, v83, v82
	v_fma_f32 v106, -v71, v96, v83
	v_fmac_f32_e32 v96, v106, v82
	v_fma_f32 v71, -v71, v96, v83
	v_div_fmas_f32 v71, v71, v82, v96
	v_div_fixup_f32 v70, v71, v70, 1.0
	v_pk_fma_f32 v[82:83], v[70:71], v[102:103], v[66:67] op_sel_hi:[0,1,1] neg_lo:[0,0,1] neg_hi:[0,0,1]
	v_pk_fma_f32 v[70:71], v[70:71], v[104:105], v[62:63] op_sel_hi:[0,1,1] neg_lo:[0,0,1] neg_hi:[0,0,1]
	v_pk_mul_f32 v[82:83], v[0:1], v[82:83]
	v_pk_mul_f32 v[70:71], v[2:3], v[70:71]
	v_cvt_pk_bf16_f32 v82, v82, v83
	v_lshlrev_b32_e32 v106, 16, v136
	v_cvt_pk_bf16_f32 v83, v70, v71
	v_lshlrev_b32_e32 v136, 16, v135
	s_add_i32 s7, s7, 4
	global_store_dwordx2 v[140:141], v[82:83], off offset:3072
	v_pk_mul_f32 v[70:71], v[64:65], v[136:137] op_sel_hi:[0,1]
	v_pk_mul_f32 v[82:83], v[64:65], v[106:107] op_sel_hi:[0,1]
	v_pk_fma_f32 v[100:101], v[64:65], v[106:107], v[100:101] op_sel_hi:[0,1,1] neg_lo:[0,0,1] neg_hi:[0,0,1]
	v_pk_fma_f32 v[84:85], v[64:65], v[136:137], v[84:85] op_sel_hi:[0,1,1] neg_lo:[0,0,1] neg_hi:[0,0,1]
	v_cvt_f32_i32_e32 v64, s7
	v_pk_add_f32 v[104:105], v[104:105], v[84:85]
	v_pk_add_f32 v[100:101], v[102:103], v[100:101]
	s_max_i32 s7, s86, 4
	v_div_scale_f32 v84, s[18:19], v64, v64, 1.0
	v_rcp_f32_e32 v85, v84
	s_min_i32 s18, s84, s23
	s_sub_i32 s7, s18, s7
	v_lshlrev_b32_e32 v106, 16, v134
	v_fma_f32 v96, -v84, v85, 1.0
	v_fmac_f32_e32 v85, v96, v85
	v_div_scale_f32 v96, vcc, 1.0, v64, 1.0
	v_mul_f32_e32 v102, v96, v85
	v_fma_f32 v103, -v84, v102, v96
	v_fmac_f32_e32 v102, v103, v85
	v_fma_f32 v84, -v84, v102, v96
	v_div_fmas_f32 v84, v84, v85, v102
	v_div_fixup_f32 v64, v84, v64, 1.0
	v_pk_fma_f32 v[84:85], v[64:65], v[100:101], v[72:73] op_sel_hi:[0,1,1] neg_lo:[0,0,1] neg_hi:[0,0,1]
	v_pk_fma_f32 v[102:103], v[64:65], v[104:105], v[68:69] op_sel_hi:[0,1,1] neg_lo:[0,0,1] neg_hi:[0,0,1]
	v_pk_mul_f32 v[102:103], v[2:3], v[102:103]
	v_pk_mul_f32 v[84:85], v[0:1], v[84:85]
	v_and_b32_e32 v107, 0xffff0000, v134
	v_cvt_pk_bf16_f32 v84, v84, v85
	v_cvt_pk_bf16_f32 v85, v102, v103
	v_add_co_u32_e32 v102, vcc, s91, v16
	v_lshlrev_b32_e32 v134, 16, v65
	s_nop 0
	v_addc_co_u32_e32 v103, vcc, 0, v17, vcc
	v_and_b32_e32 v135, 0xffff0000, v65
	s_add_i32 s7, s7, 4
	global_store_dwordx2 v[102:103], v[84:85], off offset:1024
	v_pk_mul_f32 v[64:65], v[60:61], v[134:135] op_sel_hi:[0,1]
	v_pk_mul_f32 v[84:85], v[60:61], v[106:107] op_sel_hi:[0,1]
	v_pk_fma_f32 v[98:99], v[60:61], v[106:107], v[98:99] op_sel_hi:[0,1,1] neg_lo:[0,0,1] neg_hi:[0,0,1]
	v_pk_fma_f32 v[86:87], v[60:61], v[134:135], v[86:87] op_sel_hi:[0,1,1] neg_lo:[0,0,1] neg_hi:[0,0,1]
	v_cvt_f32_i32_e32 v60, s7
	v_pk_add_f32 v[104:105], v[104:105], v[86:87]
	v_pk_add_f32 v[98:99], v[100:101], v[98:99]
	s_max_i32 s7, s87, 4
	v_div_scale_f32 v86, s[18:19], v60, v60, 1.0
	v_rcp_f32_e32 v87, v86
	s_min_i32 s18, s83, s23
	s_sub_i32 s7, s18, s7
	s_add_i32 s7, s7, 4
	v_fma_f32 v96, -v86, v87, 1.0
	v_fmac_f32_e32 v87, v96, v87
	v_div_scale_f32 v96, vcc, 1.0, v60, 1.0
	v_mul_f32_e32 v100, v96, v87
	v_fma_f32 v101, -v86, v100, v96
	v_fmac_f32_e32 v100, v101, v87
	v_fma_f32 v86, -v86, v100, v96
	v_div_fmas_f32 v86, v86, v87, v100
	v_div_fixup_f32 v60, v86, v60, 1.0
	v_pk_fma_f32 v[86:87], v[60:61], v[98:99], v[80:81] op_sel_hi:[0,1,1] neg_lo:[0,0,1] neg_hi:[0,0,1]
	v_pk_fma_f32 v[100:101], v[60:61], v[104:105], v[74:75] op_sel_hi:[0,1,1] neg_lo:[0,0,1] neg_hi:[0,0,1]
	v_pk_mul_f32 v[100:101], v[2:3], v[100:101]
	v_pk_mul_f32 v[86:87], v[0:1], v[86:87]
	s_movk_i32 s97, 0x800
	v_cvt_pk_bf16_f32 v86, v86, v87
	v_cvt_pk_bf16_f32 v87, v100, v101
	global_store_dwordx2 v[102:103], v[86:87], off offset:3072
	v_lshlrev_b32_e32 v100, 16, v133
	v_and_b32_e32 v101, 0xffff0000, v133
	v_lshlrev_b32_e32 v102, 16, v61
	v_and_b32_e32 v103, 0xffff0000, v61
	v_pk_mul_f32 v[60:61], v[58:59], v[102:103] op_sel_hi:[0,1]
	v_pk_mul_f32 v[86:87], v[58:59], v[100:101] op_sel_hi:[0,1]
	v_pk_fma_f32 v[94:95], v[58:59], v[100:101], v[94:95] op_sel_hi:[0,1,1] neg_lo:[0,0,1] neg_hi:[0,0,1]
	v_pk_fma_f32 v[88:89], v[58:59], v[102:103], v[88:89] op_sel_hi:[0,1,1] neg_lo:[0,0,1] neg_hi:[0,0,1]
	v_cvt_f32_i32_e32 v58, s7
	v_pk_add_f32 v[100:101], v[104:105], v[88:89]
	v_pk_add_f32 v[94:95], v[98:99], v[94:95]
	s_movk_i32 s7, 0x3000
	v_div_scale_f32 v88, s[18:19], v58, v58, 1.0
	v_rcp_f32_e32 v89, v88
	s_min_i32 s18, s81, s23
	v_lshlrev_b32_e32 v102, 16, v132
	v_and_b32_e32 v103, 0xffff0000, v132
	v_fma_f32 v96, -v88, v89, 1.0
	v_fmac_f32_e32 v89, v96, v89
	v_div_scale_f32 v96, vcc, 1.0, v58, 1.0
	v_mul_f32_e32 v98, v96, v89
	v_fma_f32 v99, -v88, v98, v96
	v_fmac_f32_e32 v98, v99, v89
	v_fma_f32 v88, -v88, v98, v96
	v_div_fmas_f32 v88, v88, v89, v98
	v_div_fixup_f32 v58, v88, v58, 1.0
	v_pk_fma_f32 v[88:89], v[58:59], v[94:95], v[78:79] op_sel_hi:[0,1,1] neg_lo:[0,0,1] neg_hi:[0,0,1]
	v_pk_fma_f32 v[98:99], v[58:59], v[100:101], v[76:77] op_sel_hi:[0,1,1] neg_lo:[0,0,1] neg_hi:[0,0,1]
	v_pk_mul_f32 v[98:99], v[2:3], v[98:99]
	v_pk_mul_f32 v[88:89], v[0:1], v[88:89]
	v_lshlrev_b32_e32 v104, 16, v59
	v_cvt_pk_bf16_f32 v88, v88, v89
	v_cvt_pk_bf16_f32 v89, v98, v99
	v_add_co_u32_e32 v98, vcc, s7, v16
	s_max_i32 s7, s85, 4
	s_sub_i32 s7, s18, s7
	v_addc_co_u32_e32 v99, vcc, 0, v17, vcc
	v_and_b32_e32 v105, 0xffff0000, v59
	s_add_i32 s7, s7, 4
	global_store_dwordx2 v[98:99], v[88:89], off offset:1024
	v_pk_mul_f32 v[58:59], v[54:55], v[104:105] op_sel_hi:[0,1]
	v_pk_mul_f32 v[88:89], v[54:55], v[102:103] op_sel_hi:[0,1]
	v_pk_fma_f32 v[92:93], v[54:55], v[102:103], v[92:93] op_sel_hi:[0,1,1] neg_lo:[0,0,1] neg_hi:[0,0,1]
	v_pk_fma_f32 v[90:91], v[54:55], v[104:105], v[90:91] op_sel_hi:[0,1,1] neg_lo:[0,0,1] neg_hi:[0,0,1]
	v_cvt_f32_i32_e32 v54, s7
	v_pk_add_f32 v[100:101], v[100:101], v[90:91]
	v_pk_add_f32 v[92:93], v[94:95], v[92:93]
	s_max_i32 s7, s35, 4
	v_div_scale_f32 v90, s[18:19], v54, v54, 1.0
	v_rcp_f32_e32 v91, v90
	s_min_i32 s18, s79, s23
	s_sub_i32 s7, s18, s7
	s_add_i32 s7, s7, 4
	v_fma_f32 v94, -v90, v91, 1.0
	v_fmac_f32_e32 v91, v94, v91
	v_div_scale_f32 v94, vcc, 1.0, v54, 1.0
	v_mul_f32_e32 v95, v94, v91
	v_fma_f32 v96, -v90, v95, v94
	v_fmac_f32_e32 v95, v96, v91
	v_fma_f32 v90, -v90, v95, v94
	v_div_fmas_f32 v90, v90, v91, v95
	v_div_fixup_f32 v54, v90, v54, 1.0
	v_pk_fma_f32 v[90:91], v[54:55], v[92:93], v[82:83] op_sel_hi:[0,1,1] neg_lo:[0,0,1] neg_hi:[0,0,1]
	v_pk_fma_f32 v[94:95], v[54:55], v[100:101], v[70:71] op_sel_hi:[0,1,1] neg_lo:[0,0,1] neg_hi:[0,0,1]
	v_pk_mul_f32 v[94:95], v[2:3], v[94:95]
	v_pk_mul_f32 v[90:91], v[0:1], v[90:91]
	v_readlane_b32 s96, v255, 13
	v_cvt_pk_bf16_f32 v90, v90, v91
	v_cvt_pk_bf16_f32 v91, v94, v95
	global_store_dwordx2 v[98:99], v[90:91], off offset:3072
	v_lshlrev_b32_e32 v94, 16, v57
	v_and_b32_e32 v95, 0xffff0000, v57
	v_lshlrev_b32_e32 v98, 16, v55
	v_and_b32_e32 v99, 0xffff0000, v55
	v_pk_mul_f32 v[54:55], v[50:51], v[98:99] op_sel_hi:[0,1]
	v_pk_mul_f32 v[90:91], v[50:51], v[94:95] op_sel_hi:[0,1]
	v_pk_fma_f32 v[66:67], v[50:51], v[94:95], v[66:67] op_sel_hi:[0,1,1] neg_lo:[0,0,1] neg_hi:[0,0,1]
	v_pk_fma_f32 v[62:63], v[50:51], v[98:99], v[62:63] op_sel_hi:[0,1,1] neg_lo:[0,0,1] neg_hi:[0,0,1]
	v_cvt_f32_i32_e32 v50, s7
	v_pk_add_f32 v[92:93], v[92:93], v[66:67]
	s_max_i32 s7, s84, 4
	v_pk_add_f32 v[62:63], v[100:101], v[62:63]
	v_div_scale_f32 v57, s[18:19], v50, v50, 1.0
	v_rcp_f32_e32 v66, v57
	s_min_i32 s18, s82, s23
	s_sub_i32 s7, s18, s7
	s_add_i32 s7, s7, 4
	v_fma_f32 v67, -v57, v66, 1.0
	v_fmac_f32_e32 v66, v67, v66
	v_div_scale_f32 v67, vcc, 1.0, v50, 1.0
	v_mul_f32_e32 v94, v67, v66
	v_fma_f32 v95, -v57, v94, v67
	v_fmac_f32_e32 v94, v95, v66
	v_fma_f32 v57, -v57, v94, v67
	v_div_fmas_f32 v57, v57, v66, v94
	v_div_fixup_f32 v50, v57, v50, 1.0
	v_pk_fma_f32 v[66:67], v[50:51], v[92:93], v[84:85] op_sel_hi:[0,1,1] neg_lo:[0,0,1] neg_hi:[0,0,1]
	v_pk_fma_f32 v[94:95], v[50:51], v[62:63], v[64:65] op_sel_hi:[0,1,1] neg_lo:[0,0,1] neg_hi:[0,0,1]
	v_pk_mul_f32 v[94:95], v[2:3], v[94:95]
	v_pk_mul_f32 v[66:67], v[0:1], v[66:67]
	v_lshlrev_b32_e32 v98, 16, v53
	v_and_b32_e32 v99, 0xffff0000, v53
	v_cvt_f32_i32_e32 v53, s7
	v_cvt_pk_bf16_f32 v66, v66, v67
	v_cvt_pk_bf16_f32 v67, v94, v95
	v_add_co_u32_e32 v94, vcc, s9, v16
	v_lshlrev_b32_e32 v100, 16, v51
	s_nop 0
	v_addc_co_u32_e32 v95, vcc, 0, v17, vcc
	v_and_b32_e32 v101, 0xffff0000, v51
	global_store_dwordx2 v[94:95], v[66:67], off offset:1024
	v_pk_mul_f32 v[50:51], v[56:57], v[100:101] op_sel_hi:[0,1]
	v_pk_mul_f32 v[66:67], v[56:57], v[98:99] op_sel_hi:[0,1]
	v_pk_fma_f32 v[72:73], v[56:57], v[98:99], v[72:73] op_sel_hi:[0,1,1] neg_lo:[0,0,1] neg_hi:[0,0,1]
	v_pk_fma_f32 v[56:57], v[56:57], v[100:101], v[68:69] op_sel_hi:[0,1,1] neg_lo:[0,0,1] neg_hi:[0,0,1]
	v_pk_add_f32 v[62:63], v[62:63], v[56:57]
	v_div_scale_f32 v56, s[18:19], v53, v53, 1.0
	v_rcp_f32_e32 v57, v56
	v_pk_add_f32 v[72:73], v[92:93], v[72:73]
	s_max_i32 s7, s83, 4
	s_min_i32 s18, s80, s23
	v_fma_f32 v68, -v56, v57, 1.0
	v_fmac_f32_e32 v57, v68, v57
	v_div_scale_f32 v68, vcc, 1.0, v53, 1.0
	v_mul_f32_e32 v69, v68, v57
	v_fma_f32 v92, -v56, v69, v68
	v_fmac_f32_e32 v69, v92, v57
	v_fma_f32 v56, -v56, v69, v68
	v_div_fmas_f32 v56, v56, v57, v69
	v_div_fixup_f32 v56, v56, v53, 1.0
	v_pk_fma_f32 v[68:69], v[56:57], v[72:73], v[86:87] op_sel_hi:[0,1,1] neg_lo:[0,0,1] neg_hi:[0,0,1]
	v_pk_fma_f32 v[56:57], v[56:57], v[62:63], v[60:61] op_sel_hi:[0,1,1] neg_lo:[0,0,1] neg_hi:[0,0,1]
	v_pk_mul_f32 v[68:69], v[0:1], v[68:69]
	v_pk_mul_f32 v[56:57], v[2:3], v[56:57]
	v_cvt_pk_bf16_f32 v68, v68, v69
	v_lshlrev_b32_e32 v92, 16, v131
	v_cvt_pk_bf16_f32 v69, v56, v57
	global_store_dwordx2 v[94:95], v[68:69], off offset:3072
	v_and_b32_e32 v93, 0xffff0000, v131
	v_lshlrev_b32_e32 v94, 16, v130
	v_and_b32_e32 v95, 0xffff0000, v130
	s_sub_i32 s7, s18, s7
	v_pk_mul_f32 v[56:57], v[52:53], v[94:95] op_sel_hi:[0,1]
	v_pk_mul_f32 v[68:69], v[52:53], v[92:93] op_sel_hi:[0,1]
	v_pk_fma_f32 v[80:81], v[52:53], v[92:93], v[80:81] op_sel_hi:[0,1,1] neg_lo:[0,0,1] neg_hi:[0,0,1]
	v_pk_fma_f32 v[52:53], v[52:53], v[94:95], v[74:75] op_sel_hi:[0,1,1] neg_lo:[0,0,1] neg_hi:[0,0,1]
	s_add_i32 s7, s7, 4
	v_pk_add_f32 v[62:63], v[62:63], v[52:53]
	v_cvt_f32_i32_e32 v52, s7
	v_pk_add_f32 v[74:75], v[72:73], v[80:81]
	s_max_i32 s7, s81, 4
	v_lshlrev_b32_e32 v92, 16, v129
	v_div_scale_f32 v53, s[18:19], v52, v52, 1.0
	v_rcp_f32_e32 v72, v53
	s_min_i32 s18, s78, s23
	s_sub_i32 s7, s18, s7
	v_and_b32_e32 v93, 0xffff0000, v129
	v_fma_f32 v73, -v53, v72, 1.0
	v_fmac_f32_e32 v72, v73, v72
	v_div_scale_f32 v73, vcc, 1.0, v52, 1.0
	v_mul_f32_e32 v80, v73, v72
	v_fma_f32 v81, -v53, v80, v73
	v_fmac_f32_e32 v80, v81, v72
	v_fma_f32 v53, -v53, v80, v73
	v_div_fmas_f32 v53, v53, v72, v80
	v_div_fixup_f32 v52, v53, v52, 1.0
	v_pk_fma_f32 v[72:73], v[52:53], v[74:75], v[88:89] op_sel_hi:[0,1,1] neg_lo:[0,0,1] neg_hi:[0,0,1]
	v_pk_fma_f32 v[52:53], v[52:53], v[62:63], v[58:59] op_sel_hi:[0,1,1] neg_lo:[0,0,1] neg_hi:[0,0,1]
	v_pk_mul_f32 v[72:73], v[0:1], v[72:73]
	v_add_co_u32_e32 v80, vcc, s38, v16
	v_pk_mul_f32 v[52:53], v[2:3], v[52:53]
	v_cvt_pk_bf16_f32 v72, v72, v73
	s_nop 0
	v_addc_co_u32_e32 v81, vcc, 0, v17, vcc
	v_cvt_pk_bf16_f32 v73, v52, v53
	v_lshlrev_b32_e32 v94, 16, v128
	v_and_b32_e32 v95, 0xffff0000, v128
	s_add_i32 s7, s7, 4
	global_store_dwordx2 v[80:81], v[72:73], off offset:1024
	v_pk_mul_f32 v[52:53], v[48:49], v[94:95] op_sel_hi:[0,1]
	v_pk_mul_f32 v[72:73], v[48:49], v[92:93] op_sel_hi:[0,1]
	v_pk_fma_f32 v[78:79], v[48:49], v[92:93], v[78:79] op_sel_hi:[0,1,1] neg_lo:[0,0,1] neg_hi:[0,0,1]
	v_pk_fma_f32 v[76:77], v[48:49], v[94:95], v[76:77] op_sel_hi:[0,1,1] neg_lo:[0,0,1] neg_hi:[0,0,1]
	v_cvt_f32_i32_e32 v48, s7
	v_pk_add_f32 v[62:63], v[62:63], v[76:77]
	v_pk_add_f32 v[76:77], v[74:75], v[78:79]
	s_max_i32 s7, s79, 4
	v_div_scale_f32 v74, s[18:19], v48, v48, 1.0
	v_rcp_f32_e32 v75, v74
	s_min_i32 s18, s77, s23
	s_sub_i32 s7, s18, s7
	s_add_i32 s7, s7, 4
	v_fma_f32 v78, -v74, v75, 1.0
	v_fmac_f32_e32 v75, v78, v75
	v_div_scale_f32 v78, vcc, 1.0, v48, 1.0
	v_mul_f32_e32 v79, v78, v75
	v_fma_f32 v92, -v74, v79, v78
	v_fmac_f32_e32 v79, v92, v75
	v_fma_f32 v74, -v74, v79, v78
	v_div_fmas_f32 v74, v74, v75, v79
	v_div_fixup_f32 v48, v74, v48, 1.0
	v_pk_fma_f32 v[74:75], v[48:49], v[76:77], v[90:91] op_sel_hi:[0,1,1] neg_lo:[0,0,1] neg_hi:[0,0,1]
	v_pk_fma_f32 v[78:79], v[48:49], v[62:63], v[54:55] op_sel_hi:[0,1,1] neg_lo:[0,0,1] neg_hi:[0,0,1]
	v_pk_mul_f32 v[78:79], v[2:3], v[78:79]
	v_pk_mul_f32 v[74:75], v[0:1], v[74:75]
	s_movk_i32 s90, 0xff00
	v_cvt_pk_bf16_f32 v74, v74, v75
	v_cvt_pk_bf16_f32 v75, v78, v79
	global_store_dwordx2 v[80:81], v[74:75], off offset:3072
	v_lshlrev_b32_e32 v78, 16, v127
	v_and_b32_e32 v79, 0xffff0000, v127
	v_lshlrev_b32_e32 v80, 16, v49
	v_and_b32_e32 v81, 0xffff0000, v49
	v_pk_mul_f32 v[48:49], v[46:47], v[80:81] op_sel_hi:[0,1]
	v_pk_mul_f32 v[74:75], v[46:47], v[78:79] op_sel_hi:[0,1]
	v_pk_fma_f32 v[78:79], v[46:47], v[78:79], v[82:83] op_sel_hi:[0,1,1] neg_lo:[0,0,1] neg_hi:[0,0,1]
	v_pk_fma_f32 v[70:71], v[46:47], v[80:81], v[70:71] op_sel_hi:[0,1,1] neg_lo:[0,0,1] neg_hi:[0,0,1]
	v_cvt_f32_i32_e32 v46, s7
	v_pk_add_f32 v[70:71], v[62:63], v[70:71]
	v_pk_add_f32 v[76:77], v[76:77], v[78:79]
	s_max_i32 s7, s82, 4
	v_div_scale_f32 v62, s[18:19], v46, v46, 1.0
	v_rcp_f32_e32 v63, v62
	s_min_i32 s18, s76, s23
	s_sub_i32 s7, s18, s7
	v_and_b32_e32 v81, 0xffff0000, v126
	v_fma_f32 v78, -v62, v63, 1.0
	v_fmac_f32_e32 v63, v78, v63
	v_div_scale_f32 v78, vcc, 1.0, v46, 1.0
	v_mul_f32_e32 v79, v78, v63
	v_fma_f32 v80, -v62, v79, v78
	v_fmac_f32_e32 v79, v80, v63
	v_fma_f32 v62, -v62, v79, v78
	v_div_fmas_f32 v62, v62, v63, v79
	v_div_fixup_f32 v46, v62, v46, 1.0
	v_pk_fma_f32 v[62:63], v[46:47], v[76:77], v[66:67] op_sel_hi:[0,1,1] neg_lo:[0,0,1] neg_hi:[0,0,1]
	v_pk_fma_f32 v[78:79], v[46:47], v[70:71], v[50:51] op_sel_hi:[0,1,1] neg_lo:[0,0,1] neg_hi:[0,0,1]
	v_pk_mul_f32 v[78:79], v[2:3], v[78:79]
	v_pk_mul_f32 v[62:63], v[0:1], v[62:63]
	v_lshlrev_b32_e32 v80, 16, v126
	v_cvt_pk_bf16_f32 v62, v62, v63
	v_cvt_pk_bf16_f32 v63, v78, v79
	v_add_co_u32_e32 v78, vcc, s39, v16
	v_lshlrev_b32_e32 v82, 16, v47
	s_nop 0
	v_addc_co_u32_e32 v79, vcc, 0, v17, vcc
	v_and_b32_e32 v83, 0xffff0000, v47
	s_add_i32 s7, s7, 4
	global_store_dwordx2 v[78:79], v[62:63], off offset:1024
	v_pk_mul_f32 v[46:47], v[44:45], v[82:83] op_sel_hi:[0,1]
	v_pk_mul_f32 v[62:63], v[44:45], v[80:81] op_sel_hi:[0,1]
	v_pk_fma_f32 v[80:81], v[44:45], v[80:81], v[84:85] op_sel_hi:[0,1,1] neg_lo:[0,0,1] neg_hi:[0,0,1]
	v_pk_fma_f32 v[64:65], v[44:45], v[82:83], v[64:65] op_sel_hi:[0,1,1] neg_lo:[0,0,1] neg_hi:[0,0,1]
	v_cvt_f32_i32_e32 v44, s7
	v_pk_add_f32 v[70:71], v[70:71], v[64:65]
	v_pk_add_f32 v[76:77], v[76:77], v[80:81]
	s_max_i32 s7, s80, 4
	v_div_scale_f32 v64, s[18:19], v44, v44, 1.0
	v_rcp_f32_e32 v65, v64
	s_min_i32 s18, s75, s23
	s_sub_i32 s7, s18, s7
	s_add_i32 s7, s7, 4
	v_fma_f32 v80, -v64, v65, 1.0
	v_fmac_f32_e32 v65, v80, v65
	v_div_scale_f32 v80, vcc, 1.0, v44, 1.0
	v_mul_f32_e32 v81, v80, v65
	v_fma_f32 v82, -v64, v81, v80
	v_fmac_f32_e32 v81, v82, v65
	v_fma_f32 v64, -v64, v81, v80
	v_div_fmas_f32 v64, v64, v65, v81
	v_div_fixup_f32 v44, v64, v44, 1.0
	v_pk_fma_f32 v[64:65], v[44:45], v[76:77], v[68:69] op_sel_hi:[0,1,1] neg_lo:[0,0,1] neg_hi:[0,0,1]
	v_pk_fma_f32 v[80:81], v[44:45], v[70:71], v[56:57] op_sel_hi:[0,1,1] neg_lo:[0,0,1] neg_hi:[0,0,1]
	v_pk_mul_f32 v[80:81], v[2:3], v[80:81]
	v_pk_mul_f32 v[64:65], v[0:1], v[64:65]
	v_lshlrev_b32_e32 v82, 16, v43
	v_cvt_pk_bf16_f32 v64, v64, v65
	v_cvt_pk_bf16_f32 v65, v80, v81
	global_store_dwordx2 v[78:79], v[64:65], off offset:3072
	v_lshlrev_b32_e32 v78, 16, v125
	v_and_b32_e32 v79, 0xffff0000, v125
	v_lshlrev_b32_e32 v80, 16, v45
	v_and_b32_e32 v81, 0xffff0000, v45
	v_pk_mul_f32 v[44:45], v[42:43], v[80:81] op_sel_hi:[0,1]
	v_pk_mul_f32 v[64:65], v[42:43], v[78:79] op_sel_hi:[0,1]
	v_pk_fma_f32 v[78:79], v[42:43], v[78:79], v[86:87] op_sel_hi:[0,1,1] neg_lo:[0,0,1] neg_hi:[0,0,1]
	v_pk_fma_f32 v[60:61], v[42:43], v[80:81], v[60:61] op_sel_hi:[0,1,1] neg_lo:[0,0,1] neg_hi:[0,0,1]
	v_cvt_f32_i32_e32 v42, s7
	v_pk_add_f32 v[70:71], v[70:71], v[60:61]
	v_pk_add_f32 v[76:77], v[76:77], v[78:79]
	s_movk_i32 s7, 0x7000
	v_div_scale_f32 v60, s[18:19], v42, v42, 1.0
	v_rcp_f32_e32 v61, v60
	s_min_i32 s18, s74, s23
	v_and_b32_e32 v81, 0xffff0000, v124
	v_and_b32_e32 v83, 0xffff0000, v43
	v_fma_f32 v78, -v60, v61, 1.0
	v_fmac_f32_e32 v61, v78, v61
	v_div_scale_f32 v78, vcc, 1.0, v42, 1.0
	v_mul_f32_e32 v79, v78, v61
	v_fma_f32 v80, -v60, v79, v78
	v_fmac_f32_e32 v79, v80, v61
	v_fma_f32 v60, -v60, v79, v78
	v_div_fmas_f32 v60, v60, v61, v79
	v_div_fixup_f32 v42, v60, v42, 1.0
	v_pk_fma_f32 v[60:61], v[42:43], v[76:77], v[72:73] op_sel_hi:[0,1,1] neg_lo:[0,0,1] neg_hi:[0,0,1]
	v_pk_fma_f32 v[78:79], v[42:43], v[70:71], v[52:53] op_sel_hi:[0,1,1] neg_lo:[0,0,1] neg_hi:[0,0,1]
	v_pk_mul_f32 v[78:79], v[2:3], v[78:79]
	v_pk_mul_f32 v[60:61], v[0:1], v[60:61]
	v_lshlrev_b32_e32 v80, 16, v124
	v_cvt_pk_bf16_f32 v60, v60, v61
	v_cvt_pk_bf16_f32 v61, v78, v79
	v_add_co_u32_e32 v78, vcc, s7, v16
	s_max_i32 s7, s78, 4
	s_sub_i32 s7, s18, s7
	v_addc_co_u32_e32 v79, vcc, 0, v17, vcc
	s_add_i32 s7, s7, 4
	global_store_dwordx2 v[78:79], v[60:61], off offset:1024
	v_pk_mul_f32 v[42:43], v[40:41], v[82:83] op_sel_hi:[0,1]
	v_pk_mul_f32 v[60:61], v[40:41], v[80:81] op_sel_hi:[0,1]
	v_pk_fma_f32 v[80:81], v[40:41], v[80:81], v[88:89] op_sel_hi:[0,1,1] neg_lo:[0,0,1] neg_hi:[0,0,1]
	v_pk_fma_f32 v[58:59], v[40:41], v[82:83], v[58:59] op_sel_hi:[0,1,1] neg_lo:[0,0,1] neg_hi:[0,0,1]
	v_cvt_f32_i32_e32 v40, s7
	v_pk_add_f32 v[70:71], v[70:71], v[58:59]
	v_pk_add_f32 v[76:77], v[76:77], v[80:81]
	s_max_i32 s7, s77, 4
	v_div_scale_f32 v58, s[18:19], v40, v40, 1.0
	v_rcp_f32_e32 v59, v58
	s_min_i32 s18, s71, s23
	s_sub_i32 s7, s18, s7
	s_add_i32 s7, s7, 4
	v_fma_f32 v80, -v58, v59, 1.0
	v_fmac_f32_e32 v59, v80, v59
	v_div_scale_f32 v80, vcc, 1.0, v40, 1.0
	v_mul_f32_e32 v81, v80, v59
	v_fma_f32 v82, -v58, v81, v80
	v_fmac_f32_e32 v81, v82, v59
	v_fma_f32 v58, -v58, v81, v80
	v_div_fmas_f32 v58, v58, v59, v81
	v_div_fixup_f32 v40, v58, v40, 1.0
	v_pk_fma_f32 v[58:59], v[40:41], v[76:77], v[74:75] op_sel_hi:[0,1,1] neg_lo:[0,0,1] neg_hi:[0,0,1]
	v_pk_fma_f32 v[80:81], v[40:41], v[70:71], v[48:49] op_sel_hi:[0,1,1] neg_lo:[0,0,1] neg_hi:[0,0,1]
	v_pk_mul_f32 v[80:81], v[2:3], v[80:81]
	v_pk_mul_f32 v[58:59], v[0:1], v[58:59]
	v_lshlrev_b32_e32 v82, 16, v35
	v_cvt_pk_bf16_f32 v58, v58, v59
	v_cvt_pk_bf16_f32 v59, v80, v81
	global_store_dwordx2 v[78:79], v[58:59], off offset:3072
	v_lshlrev_b32_e32 v78, 16, v123
	v_and_b32_e32 v79, 0xffff0000, v123
	v_lshlrev_b32_e32 v80, 16, v41
	v_and_b32_e32 v81, 0xffff0000, v41
	v_pk_mul_f32 v[40:41], v[34:35], v[80:81] op_sel_hi:[0,1]
	v_pk_mul_f32 v[58:59], v[34:35], v[78:79] op_sel_hi:[0,1]
	v_pk_fma_f32 v[78:79], v[34:35], v[78:79], v[90:91] op_sel_hi:[0,1,1] neg_lo:[0,0,1] neg_hi:[0,0,1]
	v_pk_fma_f32 v[54:55], v[34:35], v[80:81], v[54:55] op_sel_hi:[0,1,1] neg_lo:[0,0,1] neg_hi:[0,0,1]
	v_cvt_f32_i32_e32 v34, s7
	v_pk_add_f32 v[70:71], v[70:71], v[54:55]
	v_pk_add_f32 v[76:77], v[76:77], v[78:79]
	s_max_i32 s7, s76, 4
	v_div_scale_f32 v54, s[18:19], v34, v34, 1.0
	v_rcp_f32_e32 v55, v54
	s_min_i32 s18, s73, s23
	s_sub_i32 s7, s18, s7
	s_add_i32 s7, s7, 4
	v_fma_f32 v78, -v54, v55, 1.0
	v_fmac_f32_e32 v55, v78, v55
	v_div_scale_f32 v78, vcc, 1.0, v34, 1.0
	v_mul_f32_e32 v79, v78, v55
	v_fma_f32 v80, -v54, v79, v78
	v_fmac_f32_e32 v79, v80, v55
	v_fma_f32 v54, -v54, v79, v78
	v_div_fmas_f32 v54, v54, v55, v79
	v_div_fixup_f32 v34, v54, v34, 1.0
	v_pk_fma_f32 v[54:55], v[34:35], v[76:77], v[62:63] op_sel_hi:[0,1,1] neg_lo:[0,0,1] neg_hi:[0,0,1]
	v_pk_fma_f32 v[78:79], v[34:35], v[70:71], v[46:47] op_sel_hi:[0,1,1] neg_lo:[0,0,1] neg_hi:[0,0,1]
	v_lshlrev_b32_e32 v80, 16, v37
	v_and_b32_e32 v81, 0xffff0000, v37
	v_cvt_f32_i32_e32 v37, s7
	v_pk_mul_f32 v[78:79], v[2:3], v[78:79]
	v_pk_mul_f32 v[54:55], v[0:1], v[54:55]
	v_and_b32_e32 v83, 0xffff0000, v35
	v_cvt_pk_bf16_f32 v54, v54, v55
	v_cvt_pk_bf16_f32 v55, v78, v79
	v_add_co_u32_e32 v78, vcc, s61, v16
	v_pk_mul_f32 v[34:35], v[38:39], v[82:83] op_sel_hi:[0,1]
	s_nop 0
	v_addc_co_u32_e32 v79, vcc, 0, v17, vcc
	global_store_dwordx2 v[78:79], v[54:55], off offset:1024
	v_pk_mul_f32 v[54:55], v[38:39], v[80:81] op_sel_hi:[0,1]
	v_pk_fma_f32 v[66:67], v[38:39], v[80:81], v[66:67] op_sel_hi:[0,1,1] neg_lo:[0,0,1] neg_hi:[0,0,1]
	v_pk_fma_f32 v[50:51], v[38:39], v[82:83], v[50:51] op_sel_hi:[0,1,1] neg_lo:[0,0,1] neg_hi:[0,0,1]
	v_div_scale_f32 v38, s[18:19], v37, v37, 1.0
	v_pk_add_f32 v[70:71], v[70:71], v[50:51]
	v_rcp_f32_e32 v50, v38
	v_pk_add_f32 v[66:67], v[76:77], v[66:67]
	s_max_i32 s7, s75, 4
	s_min_i32 s18, s72, s23
	v_fma_f32 v51, -v38, v50, 1.0
	v_fmac_f32_e32 v50, v51, v50
	v_div_scale_f32 v51, vcc, 1.0, v37, 1.0
	v_mul_f32_e32 v76, v51, v50
	v_fma_f32 v77, -v38, v76, v51
	v_fmac_f32_e32 v76, v77, v50
	v_fma_f32 v38, -v38, v76, v51
	v_div_fmas_f32 v38, v38, v50, v76
	v_div_fixup_f32 v38, v38, v37, 1.0
	v_pk_fma_f32 v[50:51], v[38:39], v[66:67], v[64:65] op_sel_hi:[0,1,1] neg_lo:[0,0,1] neg_hi:[0,0,1]
	v_pk_fma_f32 v[76:77], v[38:39], v[70:71], v[44:45] op_sel_hi:[0,1,1] neg_lo:[0,0,1] neg_hi:[0,0,1]
	v_pk_mul_f32 v[76:77], v[2:3], v[76:77]
	v_pk_mul_f32 v[50:51], v[0:1], v[50:51]
	s_sub_i32 s7, s18, s7
	v_cvt_pk_bf16_f32 v50, v50, v51
	v_cvt_pk_bf16_f32 v51, v76, v77
	global_store_dwordx2 v[78:79], v[50:51], off offset:3072
	v_lshlrev_b32_e32 v76, 16, v122
	v_and_b32_e32 v77, 0xffff0000, v122
	v_lshlrev_b32_e32 v78, 16, v39
	v_and_b32_e32 v79, 0xffff0000, v39
	v_pk_mul_f32 v[38:39], v[36:37], v[78:79] op_sel_hi:[0,1]
	v_pk_mul_f32 v[50:51], v[36:37], v[76:77] op_sel_hi:[0,1]
	v_pk_fma_f32 v[68:69], v[36:37], v[76:77], v[68:69] op_sel_hi:[0,1,1] neg_lo:[0,0,1] neg_hi:[0,0,1]
	v_pk_fma_f32 v[36:37], v[36:37], v[78:79], v[56:57] op_sel_hi:[0,1,1] neg_lo:[0,0,1] neg_hi:[0,0,1]
	s_add_i32 s7, s7, 4
	v_pk_add_f32 v[70:71], v[70:71], v[36:37]
	v_cvt_f32_i32_e32 v36, s7
	v_pk_add_f32 v[66:67], v[66:67], v[68:69]
	s_max_i32 s7, s74, 4
	v_lshlrev_b32_e32 v76, 16, v121
	v_div_scale_f32 v37, s[18:19], v36, v36, 1.0
	v_rcp_f32_e32 v56, v37
	s_min_i32 s18, s69, s23
	s_sub_i32 s7, s18, s7
	v_and_b32_e32 v77, 0xffff0000, v121
	v_fma_f32 v57, -v37, v56, 1.0
	v_fmac_f32_e32 v56, v57, v56
	v_div_scale_f32 v57, vcc, 1.0, v36, 1.0
	v_mul_f32_e32 v68, v57, v56
	v_fma_f32 v69, -v37, v68, v57
	v_fmac_f32_e32 v68, v69, v56
	v_fma_f32 v37, -v37, v68, v57
	v_div_fmas_f32 v37, v37, v56, v68
	v_div_fixup_f32 v36, v37, v36, 1.0
	v_pk_fma_f32 v[56:57], v[36:37], v[66:67], v[60:61] op_sel_hi:[0,1,1] neg_lo:[0,0,1] neg_hi:[0,0,1]
	v_pk_fma_f32 v[36:37], v[36:37], v[70:71], v[42:43] op_sel_hi:[0,1,1] neg_lo:[0,0,1] neg_hi:[0,0,1]
	v_pk_mul_f32 v[56:57], v[0:1], v[56:57]
	v_add_co_u32_e32 v68, vcc, s94, v16
	v_pk_mul_f32 v[36:37], v[2:3], v[36:37]
	v_cvt_pk_bf16_f32 v56, v56, v57
	s_nop 0
	v_addc_co_u32_e32 v69, vcc, 0, v17, vcc
	v_cvt_pk_bf16_f32 v57, v36, v37
	v_lshlrev_b32_e32 v78, 16, v120
	v_and_b32_e32 v79, 0xffff0000, v120
	s_add_i32 s7, s7, 4
	global_store_dwordx2 v[68:69], v[56:57], off offset:1024
	v_pk_mul_f32 v[36:37], v[32:33], v[78:79] op_sel_hi:[0,1]
	v_pk_mul_f32 v[56:57], v[32:33], v[76:77] op_sel_hi:[0,1]
	v_pk_fma_f32 v[72:73], v[32:33], v[76:77], v[72:73] op_sel_hi:[0,1,1] neg_lo:[0,0,1] neg_hi:[0,0,1]
	v_pk_fma_f32 v[52:53], v[32:33], v[78:79], v[52:53] op_sel_hi:[0,1,1] neg_lo:[0,0,1] neg_hi:[0,0,1]
	v_cvt_f32_i32_e32 v32, s7
	v_pk_add_f32 v[70:71], v[70:71], v[52:53]
	v_pk_add_f32 v[66:67], v[66:67], v[72:73]
	s_max_i32 s7, s71, 4
	v_div_scale_f32 v52, s[18:19], v32, v32, 1.0
	v_rcp_f32_e32 v53, v52
	s_min_i32 s18, s68, s23
	s_sub_i32 s7, s18, s7
	s_add_i32 s7, s7, 4
	v_fma_f32 v72, -v52, v53, 1.0
	v_fmac_f32_e32 v53, v72, v53
	v_div_scale_f32 v72, vcc, 1.0, v32, 1.0
	v_mul_f32_e32 v73, v72, v53
	v_fma_f32 v76, -v52, v73, v72
	v_fmac_f32_e32 v73, v76, v53
	v_fma_f32 v52, -v52, v73, v72
	v_div_fmas_f32 v52, v52, v53, v73
	v_div_fixup_f32 v32, v52, v32, 1.0
	v_pk_fma_f32 v[52:53], v[32:33], v[66:67], v[58:59] op_sel_hi:[0,1,1] neg_lo:[0,0,1] neg_hi:[0,0,1]
	v_pk_fma_f32 v[72:73], v[32:33], v[70:71], v[40:41] op_sel_hi:[0,1,1] neg_lo:[0,0,1] neg_hi:[0,0,1]
	v_pk_mul_f32 v[72:73], v[2:3], v[72:73]
	v_pk_mul_f32 v[52:53], v[0:1], v[52:53]
	s_nop 0
	v_cvt_pk_bf16_f32 v52, v52, v53
	v_cvt_pk_bf16_f32 v53, v72, v73
	global_store_dwordx2 v[68:69], v[52:53], off offset:3072
	v_lshlrev_b32_e32 v68, 16, v119
	v_and_b32_e32 v69, 0xffff0000, v119
	v_lshlrev_b32_e32 v72, 16, v33
	v_and_b32_e32 v73, 0xffff0000, v33
	v_pk_mul_f32 v[32:33], v[30:31], v[72:73] op_sel_hi:[0,1]
	v_pk_mul_f32 v[52:53], v[30:31], v[68:69] op_sel_hi:[0,1]
	v_pk_fma_f32 v[68:69], v[30:31], v[68:69], v[74:75] op_sel_hi:[0,1,1] neg_lo:[0,0,1] neg_hi:[0,0,1]
	v_pk_fma_f32 v[48:49], v[30:31], v[72:73], v[48:49] op_sel_hi:[0,1,1] neg_lo:[0,0,1] neg_hi:[0,0,1]
	v_cvt_f32_i32_e32 v30, s7
	v_pk_add_f32 v[70:71], v[70:71], v[48:49]
	v_pk_add_f32 v[66:67], v[66:67], v[68:69]
	s_mov_b32 s7, 0xa000
	v_div_scale_f32 v48, s[18:19], v30, v30, 1.0
	v_rcp_f32_e32 v49, v48
	s_min_i32 s18, s63, s23
	v_and_b32_e32 v73, 0xffff0000, v118
	v_lshlrev_b32_e32 v74, 16, v31
	v_fma_f32 v68, -v48, v49, 1.0
	v_fmac_f32_e32 v49, v68, v49
	v_div_scale_f32 v68, vcc, 1.0, v30, 1.0
	v_mul_f32_e32 v69, v68, v49
	v_fma_f32 v72, -v48, v69, v68
	v_fmac_f32_e32 v69, v72, v49
	v_fma_f32 v48, -v48, v69, v68
	v_div_fmas_f32 v48, v48, v49, v69
	v_div_fixup_f32 v30, v48, v30, 1.0
	v_pk_fma_f32 v[48:49], v[30:31], v[66:67], v[54:55] op_sel_hi:[0,1,1] neg_lo:[0,0,1] neg_hi:[0,0,1]
	v_pk_fma_f32 v[68:69], v[30:31], v[70:71], v[34:35] op_sel_hi:[0,1,1] neg_lo:[0,0,1] neg_hi:[0,0,1]
	v_pk_mul_f32 v[68:69], v[2:3], v[68:69]
	v_pk_mul_f32 v[48:49], v[0:1], v[48:49]
	v_lshlrev_b32_e32 v72, 16, v118
	v_cvt_pk_bf16_f32 v48, v48, v49
	v_cvt_pk_bf16_f32 v49, v68, v69
	v_add_co_u32_e32 v68, vcc, s7, v16
	s_max_i32 s7, s73, 4
	s_sub_i32 s7, s18, s7
	v_addc_co_u32_e32 v69, vcc, 0, v17, vcc
	v_and_b32_e32 v75, 0xffff0000, v31
	s_add_i32 s7, s7, 4
	global_store_dwordx2 v[68:69], v[48:49], off offset:1024
	v_pk_mul_f32 v[30:31], v[28:29], v[74:75] op_sel_hi:[0,1]
	v_pk_mul_f32 v[48:49], v[28:29], v[72:73] op_sel_hi:[0,1]
	v_pk_fma_f32 v[62:63], v[28:29], v[72:73], v[62:63] op_sel_hi:[0,1,1] neg_lo:[0,0,1] neg_hi:[0,0,1]
	v_pk_fma_f32 v[46:47], v[28:29], v[74:75], v[46:47] op_sel_hi:[0,1,1] neg_lo:[0,0,1] neg_hi:[0,0,1]
	v_cvt_f32_i32_e32 v28, s7
	v_pk_add_f32 v[70:71], v[70:71], v[46:47]
	v_pk_add_f32 v[62:63], v[66:67], v[62:63]
	s_max_i32 s7, s72, 4
	v_div_scale_f32 v46, s[18:19], v28, v28, 1.0
	v_rcp_f32_e32 v47, v46
	s_min_i32 s18, s62, s23
	s_sub_i32 s7, s18, s7
	s_add_i32 s7, s7, 4
	v_fma_f32 v66, -v46, v47, 1.0
	v_fmac_f32_e32 v47, v66, v47
	v_div_scale_f32 v66, vcc, 1.0, v28, 1.0
	v_mul_f32_e32 v67, v66, v47
	v_fma_f32 v72, -v46, v67, v66
	v_fmac_f32_e32 v67, v72, v47
	v_fma_f32 v46, -v46, v67, v66
	v_div_fmas_f32 v46, v46, v47, v67
	v_div_fixup_f32 v28, v46, v28, 1.0
	v_pk_fma_f32 v[46:47], v[28:29], v[62:63], v[50:51] op_sel_hi:[0,1,1] neg_lo:[0,0,1] neg_hi:[0,0,1]
	v_pk_fma_f32 v[66:67], v[28:29], v[70:71], v[38:39] op_sel_hi:[0,1,1] neg_lo:[0,0,1] neg_hi:[0,0,1]
	v_pk_mul_f32 v[66:67], v[2:3], v[66:67]
	v_pk_mul_f32 v[46:47], v[0:1], v[46:47]
	s_nop 0
	v_cvt_pk_bf16_f32 v46, v46, v47
	v_cvt_pk_bf16_f32 v47, v66, v67
	global_store_dwordx2 v[68:69], v[46:47], off offset:3072
	v_lshlrev_b32_e32 v66, 16, v117
	v_and_b32_e32 v67, 0xffff0000, v117
	v_lshlrev_b32_e32 v68, 16, v29
	v_and_b32_e32 v69, 0xffff0000, v29
	v_pk_mul_f32 v[28:29], v[26:27], v[68:69] op_sel_hi:[0,1]
	v_pk_mul_f32 v[46:47], v[26:27], v[66:67] op_sel_hi:[0,1]
	v_pk_fma_f32 v[64:65], v[26:27], v[66:67], v[64:65] op_sel_hi:[0,1,1] neg_lo:[0,0,1] neg_hi:[0,0,1]
	v_pk_fma_f32 v[44:45], v[26:27], v[68:69], v[44:45] op_sel_hi:[0,1,1] neg_lo:[0,0,1] neg_hi:[0,0,1]
	v_cvt_f32_i32_e32 v26, s7
	v_pk_add_f32 v[66:67], v[70:71], v[44:45]
	v_pk_add_f32 v[62:63], v[62:63], v[64:65]
	s_max_i32 s7, s69, 4
	v_div_scale_f32 v44, s[18:19], v26, v26, 1.0
	v_rcp_f32_e32 v45, v44
	s_min_i32 s18, s34, s23
	s_sub_i32 s7, s18, s7
	v_and_b32_e32 v69, 0xffff0000, v116
	v_fma_f32 v64, -v44, v45, 1.0
	v_fmac_f32_e32 v45, v64, v45
	v_div_scale_f32 v64, vcc, 1.0, v26, 1.0
	v_mul_f32_e32 v65, v64, v45
	v_fma_f32 v68, -v44, v65, v64
	v_fmac_f32_e32 v65, v68, v45
	v_fma_f32 v44, -v44, v65, v64
	v_div_fmas_f32 v44, v44, v45, v65
	v_div_fixup_f32 v26, v44, v26, 1.0
	v_pk_fma_f32 v[44:45], v[26:27], v[62:63], v[56:57] op_sel_hi:[0,1,1] neg_lo:[0,0,1] neg_hi:[0,0,1]
	v_pk_fma_f32 v[64:65], v[26:27], v[66:67], v[36:37] op_sel_hi:[0,1,1] neg_lo:[0,0,1] neg_hi:[0,0,1]
	v_pk_mul_f32 v[64:65], v[2:3], v[64:65]
	v_pk_mul_f32 v[44:45], v[0:1], v[44:45]
	v_lshlrev_b32_e32 v68, 16, v116
	v_cvt_pk_bf16_f32 v44, v44, v45
	v_cvt_pk_bf16_f32 v45, v64, v65
	v_add_co_u32_e32 v64, vcc, s51, v16
	v_lshlrev_b32_e32 v70, 16, v27
	s_nop 0
	v_addc_co_u32_e32 v65, vcc, 0, v17, vcc
	v_and_b32_e32 v71, 0xffff0000, v27
	s_add_i32 s7, s7, 4
	global_store_dwordx2 v[64:65], v[44:45], off offset:1024
	v_pk_mul_f32 v[26:27], v[24:25], v[70:71] op_sel_hi:[0,1]
	v_pk_mul_f32 v[44:45], v[24:25], v[68:69] op_sel_hi:[0,1]
	v_pk_fma_f32 v[60:61], v[24:25], v[68:69], v[60:61] op_sel_hi:[0,1,1] neg_lo:[0,0,1] neg_hi:[0,0,1]
	v_pk_fma_f32 v[42:43], v[24:25], v[70:71], v[42:43] op_sel_hi:[0,1,1] neg_lo:[0,0,1] neg_hi:[0,0,1]
	v_cvt_f32_i32_e32 v24, s7
	v_pk_add_f32 v[66:67], v[66:67], v[42:43]
	v_pk_add_f32 v[60:61], v[62:63], v[60:61]
	s_max_i32 s7, s68, 4
	v_div_scale_f32 v42, s[18:19], v24, v24, 1.0
	v_rcp_f32_e32 v43, v42
	s_min_i32 s18, s20, s23
	s_sub_i32 s7, s18, s7
	s_add_i32 s7, s7, 4
	v_fma_f32 v62, -v42, v43, 1.0
	v_fmac_f32_e32 v43, v62, v43
	v_div_scale_f32 v62, vcc, 1.0, v24, 1.0
	v_mul_f32_e32 v63, v62, v43
	v_fma_f32 v68, -v42, v63, v62
	v_fmac_f32_e32 v63, v68, v43
	v_fma_f32 v42, -v42, v63, v62
	v_div_fmas_f32 v42, v42, v43, v63
	v_div_fixup_f32 v24, v42, v24, 1.0
	v_pk_fma_f32 v[42:43], v[24:25], v[60:61], v[52:53] op_sel_hi:[0,1,1] neg_lo:[0,0,1] neg_hi:[0,0,1]
	v_pk_fma_f32 v[62:63], v[24:25], v[66:67], v[32:33] op_sel_hi:[0,1,1] neg_lo:[0,0,1] neg_hi:[0,0,1]
	v_pk_mul_f32 v[62:63], v[2:3], v[62:63]
	v_pk_mul_f32 v[42:43], v[0:1], v[42:43]
	s_nop 0
	v_cvt_pk_bf16_f32 v42, v42, v43
	v_cvt_pk_bf16_f32 v43, v62, v63
	global_store_dwordx2 v[64:65], v[42:43], off offset:3072
	v_lshlrev_b32_e32 v62, 16, v115
	v_and_b32_e32 v63, 0xffff0000, v115
	v_lshlrev_b32_e32 v64, 16, v25
	v_and_b32_e32 v65, 0xffff0000, v25
	v_pk_mul_f32 v[24:25], v[20:21], v[64:65] op_sel_hi:[0,1]
	v_pk_mul_f32 v[42:43], v[20:21], v[62:63] op_sel_hi:[0,1]
	v_pk_fma_f32 v[58:59], v[20:21], v[62:63], v[58:59] op_sel_hi:[0,1,1] neg_lo:[0,0,1] neg_hi:[0,0,1]
	v_pk_fma_f32 v[40:41], v[20:21], v[64:65], v[40:41] op_sel_hi:[0,1,1] neg_lo:[0,0,1] neg_hi:[0,0,1]
	v_cvt_f32_i32_e32 v20, s7
	v_pk_add_f32 v[62:63], v[66:67], v[40:41]
	v_pk_add_f32 v[60:61], v[60:61], v[58:59]
	s_max_i32 s7, s63, 4
	v_div_scale_f32 v40, s[18:19], v20, v20, 1.0
	v_rcp_f32_e32 v41, v40
	s_min_i32 s18, s21, s23
	s_sub_i32 s7, s18, s7
	s_add_i32 s7, s7, 4
	v_fma_f32 v58, -v40, v41, 1.0
	v_fmac_f32_e32 v41, v58, v41
	v_div_scale_f32 v58, vcc, 1.0, v20, 1.0
	v_mul_f32_e32 v59, v58, v41
	v_fma_f32 v64, -v40, v59, v58
	v_fmac_f32_e32 v59, v64, v41
	v_fma_f32 v40, -v40, v59, v58
	v_div_fmas_f32 v40, v40, v41, v59
	v_div_fixup_f32 v20, v40, v20, 1.0
	v_pk_fma_f32 v[40:41], v[20:21], v[60:61], v[48:49] op_sel_hi:[0,1,1] neg_lo:[0,0,1] neg_hi:[0,0,1]
	v_pk_fma_f32 v[58:59], v[20:21], v[62:63], v[30:31] op_sel_hi:[0,1,1] neg_lo:[0,0,1] neg_hi:[0,0,1]
	v_pk_mul_f32 v[40:41], v[0:1], v[40:41]
	v_add_co_u32_e32 v64, vcc, s58, v16
	v_pk_mul_f32 v[58:59], v[2:3], v[58:59]
	v_cvt_pk_bf16_f32 v40, v40, v41
	s_nop 0
	v_addc_co_u32_e32 v65, vcc, 0, v17, vcc
	v_cvt_pk_bf16_f32 v41, v58, v59
	v_lshlrev_b32_e32 v20, 16, v21
	v_and_b32_e32 v21, 0xffff0000, v21
	global_store_dwordx2 v[64:65], v[40:41], off offset:1024
	v_pk_mul_f32 v[40:41], v[22:23], v[20:21] op_sel_hi:[0,1]
	v_pk_fma_f32 v[20:21], v[22:23], v[20:21], v[34:35] op_sel_hi:[0,1,1] neg_lo:[0,0,1] neg_hi:[0,0,1]
	v_pk_add_f32 v[34:35], v[62:63], v[20:21]
	v_cvt_f32_i32_e32 v20, s7
	v_lshlrev_b32_e32 v66, 16, v23
	v_and_b32_e32 v67, 0xffff0000, v23
	v_pk_mul_f32 v[58:59], v[22:23], v[66:67] op_sel_hi:[0,1]
	v_div_scale_f32 v21, s[18:19], v20, v20, 1.0
	v_pk_fma_f32 v[54:55], v[22:23], v[66:67], v[54:55] op_sel_hi:[0,1,1] neg_lo:[0,0,1] neg_hi:[0,0,1]
	v_rcp_f32_e32 v22, v21
	v_pk_add_f32 v[54:55], v[60:61], v[54:55]
	s_max_i32 s7, s62, 4
	s_min_i32 s18, s15, s23
	v_fma_f32 v23, -v21, v22, 1.0
	v_fmac_f32_e32 v22, v23, v22
	v_div_scale_f32 v23, vcc, 1.0, v20, 1.0
	v_mul_f32_e32 v60, v23, v22
	v_fma_f32 v61, -v21, v60, v23
	v_fmac_f32_e32 v60, v61, v22
	v_fma_f32 v21, -v21, v60, v23
	v_div_fmas_f32 v21, v21, v22, v60
	v_div_fixup_f32 v20, v21, v20, 1.0
	v_pk_fma_f32 v[22:23], v[20:21], v[54:55], v[46:47] op_sel_hi:[0,1,1] neg_lo:[0,0,1] neg_hi:[0,0,1]
	v_pk_fma_f32 v[20:21], v[20:21], v[34:35], v[28:29] op_sel_hi:[0,1,1] neg_lo:[0,0,1] neg_hi:[0,0,1]
	v_pk_mul_f32 v[22:23], v[0:1], v[22:23]
	s_sub_i32 s7, s18, s7
	v_pk_mul_f32 v[20:21], v[2:3], v[20:21]
	v_cvt_pk_bf16_f32 v22, v22, v23
	v_lshlrev_b32_e32 v60, 16, v114
	v_cvt_pk_bf16_f32 v23, v20, v21
	v_and_b32_e32 v61, 0xffff0000, v114
	v_lshlrev_b32_e32 v62, 16, v113
	v_and_b32_e32 v63, 0xffff0000, v113
	s_add_i32 s7, s7, 4
	global_store_dwordx2 v[64:65], v[22:23], off offset:3072
	v_pk_mul_f32 v[20:21], v[18:19], v[62:63] op_sel_hi:[0,1]
	v_pk_mul_f32 v[22:23], v[18:19], v[60:61] op_sel_hi:[0,1]
	v_pk_fma_f32 v[50:51], v[18:19], v[60:61], v[50:51] op_sel_hi:[0,1,1] neg_lo:[0,0,1] neg_hi:[0,0,1]
	v_pk_fma_f32 v[38:39], v[18:19], v[62:63], v[38:39] op_sel_hi:[0,1,1] neg_lo:[0,0,1] neg_hi:[0,0,1]
	v_cvt_f32_i32_e32 v18, s7
	v_pk_add_f32 v[60:61], v[34:35], v[38:39]
	v_pk_add_f32 v[50:51], v[54:55], v[50:51]
	s_max_i32 s7, s34, 4
	v_div_scale_f32 v34, s[18:19], v18, v18, 1.0
	v_rcp_f32_e32 v35, v34
	s_min_i32 s18, s5, s23
	s_sub_i32 s7, s18, s7
	v_lshlrev_b32_e32 v62, 16, v112
	v_fma_f32 v38, -v34, v35, 1.0
	v_fmac_f32_e32 v35, v38, v35
	v_div_scale_f32 v38, vcc, 1.0, v18, 1.0
	v_mul_f32_e32 v39, v38, v35
	v_fma_f32 v54, -v34, v39, v38
	v_fmac_f32_e32 v39, v54, v35
	v_fma_f32 v34, -v34, v39, v38
	v_div_fmas_f32 v34, v34, v35, v39
	v_div_fixup_f32 v18, v34, v18, 1.0
	v_pk_fma_f32 v[34:35], v[18:19], v[50:51], v[44:45] op_sel_hi:[0,1,1] neg_lo:[0,0,1] neg_hi:[0,0,1]
	v_pk_fma_f32 v[38:39], v[18:19], v[60:61], v[26:27] op_sel_hi:[0,1,1] neg_lo:[0,0,1] neg_hi:[0,0,1]
	v_pk_mul_f32 v[34:35], v[0:1], v[34:35]
	v_add_co_u32_e32 v54, vcc, s59, v16
	v_pk_mul_f32 v[38:39], v[2:3], v[38:39]
	v_cvt_pk_bf16_f32 v34, v34, v35
	s_nop 0
	v_addc_co_u32_e32 v55, vcc, 0, v17, vcc
	v_cvt_pk_bf16_f32 v35, v38, v39
	v_and_b32_e32 v63, 0xffff0000, v112
	v_lshlrev_b32_e32 v64, 16, v111
	v_and_b32_e32 v65, 0xffff0000, v111
	s_add_i32 s7, s7, 4
	global_store_dwordx2 v[54:55], v[34:35], off offset:1024
	v_pk_mul_f32 v[34:35], v[14:15], v[64:65] op_sel_hi:[0,1]
	v_pk_mul_f32 v[38:39], v[14:15], v[62:63] op_sel_hi:[0,1]
	v_pk_fma_f32 v[56:57], v[14:15], v[62:63], v[56:57] op_sel_hi:[0,1,1] neg_lo:[0,0,1] neg_hi:[0,0,1]
	v_pk_fma_f32 v[36:37], v[14:15], v[64:65], v[36:37] op_sel_hi:[0,1,1] neg_lo:[0,0,1] neg_hi:[0,0,1]
	v_cvt_f32_i32_e32 v14, s7
	v_pk_add_f32 v[50:51], v[50:51], v[56:57]
	v_pk_add_f32 v[36:37], v[60:61], v[36:37]
	s_max_i32 s7, s20, 4
	v_div_scale_f32 v18, s[18:19], v14, v14, 1.0
	v_rcp_f32_e32 v56, v18
	s_min_i32 s18, s70, s23
	s_sub_i32 s7, s18, s7
	s_add_i32 s7, s7, 4
	v_fma_f32 v57, -v18, v56, 1.0
	v_fmac_f32_e32 v56, v57, v56
	v_div_scale_f32 v57, vcc, 1.0, v14, 1.0
	v_mul_f32_e32 v60, v57, v56
	v_fma_f32 v61, -v18, v60, v57
	v_fmac_f32_e32 v60, v61, v56
	v_fma_f32 v18, -v18, v60, v57
	v_div_fmas_f32 v18, v18, v56, v60
	v_div_fixup_f32 v14, v18, v14, 1.0
	v_pk_fma_f32 v[42:43], v[14:15], v[50:51], v[42:43] op_sel_hi:[0,1,1] neg_lo:[0,0,1] neg_hi:[0,0,1]
	v_pk_fma_f32 v[24:25], v[14:15], v[36:37], v[24:25] op_sel_hi:[0,1,1] neg_lo:[0,0,1] neg_hi:[0,0,1]
	v_pk_mul_f32 v[42:43], v[0:1], v[42:43]
	v_pk_mul_f32 v[24:25], v[2:3], v[24:25]
	v_cvt_pk_bf16_f32 v42, v42, v43
	s_max_i32 s5, s5, 4
	v_cvt_pk_bf16_f32 v43, v24, v25
	global_store_dwordx2 v[54:55], v[42:43], off offset:3072
	v_lshlrev_b32_e32 v24, 16, v19
	v_and_b32_e32 v25, 0xffff0000, v19
	v_lshlrev_b32_e32 v42, 16, v15
	v_and_b32_e32 v43, 0xffff0000, v15
	v_pk_mul_f32 v[14:15], v[12:13], v[42:43] op_sel_hi:[0,1]
	v_pk_mul_f32 v[18:19], v[12:13], v[24:25] op_sel_hi:[0,1]
	v_pk_fma_f32 v[24:25], v[12:13], v[24:25], v[52:53] op_sel_hi:[0,1,1] neg_lo:[0,0,1] neg_hi:[0,0,1]
	v_pk_fma_f32 v[32:33], v[12:13], v[42:43], v[32:33] op_sel_hi:[0,1,1] neg_lo:[0,0,1] neg_hi:[0,0,1]
	v_cvt_f32_i32_e32 v12, s7
	v_pk_add_f32 v[32:33], v[36:37], v[32:33]
	v_pk_add_f32 v[24:25], v[50:51], v[24:25]
	s_max_i32 s7, s21, 4
	v_div_scale_f32 v36, s[18:19], v12, v12, 1.0
	v_rcp_f32_e32 v37, v36
	s_min_i32 s18, s67, s23
	s_sub_i32 s7, s18, s7
	s_add_i32 s7, s7, 4
	v_fma_f32 v42, -v36, v37, 1.0
	v_fmac_f32_e32 v37, v42, v37
	v_div_scale_f32 v42, vcc, 1.0, v12, 1.0
	v_mul_f32_e32 v43, v42, v37
	v_fma_f32 v50, -v36, v43, v42
	v_fmac_f32_e32 v43, v50, v37
	v_fma_f32 v36, -v36, v43, v42
	v_div_fmas_f32 v36, v36, v37, v43
	v_div_fixup_f32 v12, v36, v12, 1.0
	v_pk_fma_f32 v[36:37], v[12:13], v[24:25], v[58:59] op_sel_hi:[0,1,1] neg_lo:[0,0,1] neg_hi:[0,0,1]
	v_pk_fma_f32 v[40:41], v[12:13], v[32:33], v[40:41] op_sel_hi:[0,1,1] neg_lo:[0,0,1] neg_hi:[0,0,1]
	v_pk_mul_f32 v[40:41], v[2:3], v[40:41]
	v_pk_mul_f32 v[36:37], v[0:1], v[36:37]
	v_lshlrev_b32_e32 v42, 16, v109
	v_cvt_pk_bf16_f32 v36, v36, v37
	v_cvt_pk_bf16_f32 v37, v40, v41
	v_add_co_u32_e32 v40, vcc, s60, v16
	v_and_b32_e32 v43, 0xffff0000, v109
	s_nop 0
	v_addc_co_u32_e32 v41, vcc, 0, v17, vcc
	global_store_dwordx2 v[40:41], v[36:37], off offset:1024
	v_lshlrev_b32_e32 v36, 16, v110
	v_and_b32_e32 v37, 0xffff0000, v110
	v_pk_fma_f32 v[36:37], v[10:11], v[36:37], v[48:49] op_sel_hi:[0,1,1] neg_lo:[0,0,1] neg_hi:[0,0,1]
	v_pk_fma_f32 v[30:31], v[10:11], v[42:43], v[30:31] op_sel_hi:[0,1,1] neg_lo:[0,0,1] neg_hi:[0,0,1]
	v_cvt_f32_i32_e32 v10, s7
	v_pk_add_f32 v[30:31], v[32:33], v[30:31]
	v_pk_add_f32 v[24:25], v[24:25], v[36:37]
	s_max_i32 s7, s15, 4
	v_div_scale_f32 v12, s[18:19], v10, v10, 1.0
	v_rcp_f32_e32 v32, v12
	s_min_i32 s15, s66, s23
	s_sub_i32 s7, s15, s7
	s_add_i32 s7, s7, 4
	v_fma_f32 v33, -v12, v32, 1.0
	v_fmac_f32_e32 v32, v33, v32
	v_div_scale_f32 v33, vcc, 1.0, v10, 1.0
	v_mul_f32_e32 v36, v33, v32
	v_fma_f32 v37, -v12, v36, v33
	v_fmac_f32_e32 v36, v37, v32
	v_fma_f32 v12, -v12, v36, v33
	v_div_fmas_f32 v12, v12, v32, v36
	v_div_fixup_f32 v10, v12, v10, 1.0
	v_pk_fma_f32 v[22:23], v[10:11], v[24:25], v[22:23] op_sel_hi:[0,1,1] neg_lo:[0,0,1] neg_hi:[0,0,1]
	v_pk_fma_f32 v[20:21], v[10:11], v[30:31], v[20:21] op_sel_hi:[0,1,1] neg_lo:[0,0,1] neg_hi:[0,0,1]
	v_cvt_f32_i32_e32 v10, s7
	v_pk_mul_f32 v[20:21], v[2:3], v[20:21]
	v_pk_mul_f32 v[22:23], v[0:1], v[22:23]
	v_lshlrev_b32_e32 v12, 16, v13
	v_cvt_pk_bf16_f32 v22, v22, v23
	v_cvt_pk_bf16_f32 v23, v20, v21
	v_and_b32_e32 v13, 0xffff0000, v13
	v_lshlrev_b32_e32 v20, 16, v7
	v_and_b32_e32 v21, 0xffff0000, v7
	v_pk_fma_f32 v[12:13], v[6:7], v[12:13], v[46:47] op_sel_hi:[0,1,1] neg_lo:[0,0,1] neg_hi:[0,0,1]
	v_pk_fma_f32 v[6:7], v[6:7], v[20:21], v[28:29] op_sel_hi:[0,1,1] neg_lo:[0,0,1] neg_hi:[0,0,1]
	v_div_scale_f32 v20, s[18:19], v10, v10, 1.0
	v_rcp_f32_e32 v21, v20
	global_store_dwordx2 v[40:41], v[22:23], off offset:3072
	v_pk_add_f32 v[12:13], v[24:25], v[12:13]
	s_add_i32 s7, s4, 35
	v_fma_f32 v22, -v20, v21, 1.0
	v_fmac_f32_e32 v21, v22, v21
	v_div_scale_f32 v22, vcc, 1.0, v10, 1.0
	v_mul_f32_e32 v23, v22, v21
	v_fma_f32 v24, -v20, v23, v22
	v_fmac_f32_e32 v23, v24, v21
	v_fma_f32 v20, -v20, v23, v22
	v_div_fmas_f32 v20, v20, v21, v23
	s_min_i32 s7, s7, s23
	v_div_fixup_f32 v10, v20, v10, 1.0
	s_sub_i32 s5, s7, s5
	v_pk_add_f32 v[6:7], v[30:31], v[6:7]
	v_pk_fma_f32 v[20:21], v[10:11], v[12:13], v[38:39] op_sel_hi:[0,1,1] neg_lo:[0,0,1] neg_hi:[0,0,1]
	s_add_i32 s5, s5, 4
	v_pk_fma_f32 v[22:23], v[10:11], v[6:7], v[34:35] op_sel_hi:[0,1,1] neg_lo:[0,0,1] neg_hi:[0,0,1]
	v_pk_mul_f32 v[20:21], v[0:1], v[20:21]
	v_add_co_u32_e32 v16, vcc, s50, v16
	v_cvt_f32_i32_e32 v10, s5
	v_pk_mul_f32 v[22:23], v[2:3], v[22:23]
	v_cvt_pk_bf16_f32 v20, v20, v21
	v_addc_co_u32_e32 v17, vcc, 0, v17, vcc
	v_cvt_pk_bf16_f32 v21, v22, v23
	global_store_dwordx2 v[16:17], v[20:21], off offset:1024
	v_lshlrev_b32_e32 v16, 16, v108
	v_and_b32_e32 v17, 0xffff0000, v108
	v_lshlrev_b32_e32 v20, 16, v9
	v_and_b32_e32 v21, 0xffff0000, v9
	s_waitcnt vmcnt(31)
	v_pk_fma_f32 v[16:17], v[8:9], v[16:17], v[44:45] op_sel_hi:[0,1,1] neg_lo:[0,0,1] neg_hi:[0,0,1]
	v_pk_fma_f32 v[8:9], v[8:9], v[20:21], v[26:27] op_sel_hi:[0,1,1] neg_lo:[0,0,1] neg_hi:[0,0,1]
	v_pk_add_f32 v[6:7], v[6:7], v[8:9]
	v_pk_add_f32 v[8:9], v[12:13], v[16:17]
	v_div_scale_f32 v12, s[18:19], v10, v10, 1.0
	v_rcp_f32_e32 v13, v12
	s_mov_b64 s[18:19], 0
	v_fma_f32 v16, -v12, v13, 1.0
	v_fmac_f32_e32 v13, v16, v13
	v_div_scale_f32 v16, vcc, 1.0, v10, 1.0
	v_mul_f32_e32 v17, v16, v13
	v_fma_f32 v20, -v12, v17, v16
	v_fmac_f32_e32 v17, v20, v13
	v_fma_f32 v12, -v12, v17, v16
	v_div_fmas_f32 v12, v12, v13, v17
	v_div_fixup_f32 v10, v12, v10, 1.0
	v_pk_fma_f32 v[8:9], v[10:11], v[8:9], v[18:19] op_sel_hi:[0,1,1] neg_lo:[0,0,1] neg_hi:[0,0,1]
	v_pk_fma_f32 v[6:7], v[10:11], v[6:7], v[14:15] op_sel_hi:[0,1,1] neg_lo:[0,0,1] neg_hi:[0,0,1]
	v_pk_mul_f32 v[12:13], v[2:3], v[6:7]
	v_pk_mul_f32 v[6:7], v[0:1], v[8:9]
	s_nop 0
	v_cvt_pk_bf16_f32 v6, v6, v7
	v_cvt_pk_bf16_f32 v7, v12, v13

.LBB0_400:
	s_and_b64 vcc, exec, s[20:21]
	s_cbranch_vccz .LBB0_402
	v_writelane_b32 v244, s5, 0
	v_writelane_b32 v244, vcc_lo, 1
	v_writelane_b32 v244, vcc_hi, 2
	v_writelane_b32 v244, s20, 3
	v_writelane_b32 v244, s21, 4
	v_writelane_b32 v244, s34, 5
	v_writelane_b32 v244, s35, 6
	v_writelane_b32 v244, s30, 7
	v_writelane_b32 v244, s31, 8
	v_writelane_b32 v244, s7, 9
	v_writelane_b32 v244, s91, 10
	v_writelane_b32 v244, s90, 11
	v_writelane_b32 v244, s89, 12
	v_writelane_b32 v244, s88, 13
	v_writelane_b32 v244, s87, 14
	v_writelane_b32 v244, s86, 15
	v_writelane_b32 v244, s85, 16
	v_writelane_b32 v244, s84, 17
	v_writelane_b32 v244, s83, 18
	v_writelane_b32 v244, s82, 19
	v_writelane_b32 v244, s81, 20
	v_writelane_b32 v244, s80, 21
	v_writelane_b32 v244, s79, 22
	v_writelane_b32 v244, s62, 23
	v_writelane_b32 v244, s63, 24
	v_writelane_b32 v244, s78, 25
	v_writelane_b32 v244, s77, 26
	v_writelane_b32 v244, s76, 27
	v_writelane_b32 v244, s75, 28
	v_writelane_b32 v244, s74, 29
	v_writelane_b32 v244, s72, 30
	v_writelane_b32 v244, s73, 31
	v_writelane_b32 v244, s71, 32
	v_writelane_b32 v244, s70, 33
	v_writelane_b32 v244, s69, 34
	v_writelane_b32 v244, s68, 35
	v_writelane_b32 v244, s66, 36
	v_writelane_b32 v244, s67, 37
	v_writelane_b32 v244, s96, 38
	v_writelane_b32 v244, s97, 39
	v_writelane_b32 v244, s15, 40
	s_add_i32 s5, s4, -2
	s_cmp_lt_u32 s5, s23
	s_cselect_b64 vcc, -1, 0
	s_and_b64 s[20:21], vcc, exec
	s_cselect_b32 s20, s5, s4
	v_lshlrev_b32_e32 v96, 1, v11
	s_ashr_i32 s21, s20, 31
	v_lshl_add_u64 v[248:249], s[2:3], 0, v[96:97]
	s_lshl_b64 s[34:35], s[20:21], 11
	v_lshl_add_u64 v[246:247], v[248:249], 0, s[34:35]
	global_load_dwordx2 v[132:133], v[246:247], off offset:512
	s_add_i32 s20, s20, s14
	s_ashr_i32 s21, s20, 31
	s_lshl_b64 s[20:21], s[20:21], 2
	s_add_u32 s20, s26, s20
	s_addc_u32 s21, s27, s21
	s_add_i32 s5, s4, -1
	s_cmp_lt_u32 s5, s23
	s_mov_b64 s[30:31], 0x200
	s_cselect_b64 vcc, -1, 0
	s_and_b64 s[20:21], vcc, exec
	s_cselect_b32 s20, s5, s4
	s_ashr_i32 s21, s20, 31
	s_lshl_b64 s[34:35], s[20:21], 11
	v_lshl_add_u64 v[246:247], v[248:249], 0, s[34:35]
	global_load_dword v74, v[246:247], off offset:512
	global_load_dword v71, v[246:247], off offset:516
	s_add_i32 s20, s20, s14
	s_ashr_i32 s21, s20, 31
	s_lshl_b64 s[20:21], s[20:21], 2
	s_add_u32 s20, s26, s20
	s_addc_u32 s21, s27, s21
	s_cmp_lt_u32 s4, s23
	global_load_dword v14, v97, s[20:21]
	s_cselect_b64 vcc, -1, 0
	s_ashr_i32 s5, s4, 31
	s_lshl_b64 s[20:21], s[4:5], 11
	v_lshl_add_u64 v[246:247], v[248:249], 0, s[20:21]
	global_load_dword v77, v[246:247], off offset:512
	global_load_dword v75, v[246:247], off offset:516
	s_ashr_i32 s7, s6, 31
	s_lshl_b64 s[20:21], s[6:7], 2
	s_add_u32 s20, s26, s20
	s_addc_u32 s21, s27, s21
	s_or_b32 s91, s4, 1
	s_cmp_lt_u32 s91, s23
	global_load_dword v70, v97, s[20:21]
	s_cselect_b64 vcc, -1, 0
	s_and_b64 s[20:21], vcc, exec
	s_cselect_b32 s20, s91, s4
	s_ashr_i32 s21, s20, 31
	s_lshl_b64 s[34:35], s[20:21], 11
	v_lshl_add_u64 v[246:247], v[248:249], 0, s[34:35]
	global_load_dword v81, v[246:247], off offset:512
	global_load_dword v79, v[246:247], off offset:516
	s_add_i32 s20, s20, s14
	s_ashr_i32 s21, s20, 31
	s_lshl_b64 s[20:21], s[20:21], 2
	s_add_u32 s20, s26, s20
	s_addc_u32 s21, s27, s21
	s_or_b32 s90, s4, 2
	s_cmp_lt_u32 s90, s23
	global_load_dword v72, v97, s[20:21]
	s_cselect_b64 vcc, -1, 0
	s_and_b64 s[20:21], vcc, exec
	s_cselect_b32 s20, s90, s4
	s_ashr_i32 s21, s20, 31
	s_lshl_b64 s[34:35], s[20:21], 11
	v_lshl_add_u64 v[246:247], v[248:249], 0, s[34:35]
	global_load_dword v76, v[246:247], off offset:512
	global_load_dword v73, v[246:247], off offset:516
	s_add_i32 s20, s20, s14
	s_ashr_i32 s21, s20, 31
	s_lshl_b64 s[20:21], s[20:21], 2
	s_add_u32 s20, s26, s20
	s_addc_u32 s21, s27, s21
	s_or_b32 s89, s4, 3
	s_cmp_lt_u32 s89, s23
	global_load_dword v68, v97, s[20:21]
	s_cselect_b64 vcc, -1, 0
	s_and_b64 s[20:21], vcc, exec
	s_cselect_b32 s20, s89, s4
	s_ashr_i32 s21, s20, 31
	s_lshl_b64 s[34:35], s[20:21], 11
	v_lshl_add_u64 v[246:247], v[248:249], 0, s[34:35]
	global_load_dword v78, v[246:247], off offset:512
	global_load_dword v69, v[246:247], off offset:516
	s_add_i32 s20, s20, s14
	s_ashr_i32 s21, s20, 31
	s_lshl_b64 s[20:21], s[20:21], 2
	s_add_u32 s20, s26, s20
	s_addc_u32 s21, s27, s21
	s_or_b32 s88, s4, 4
	s_cmp_lt_u32 s88, s23
	global_load_dword v66, v97, s[20:21]
	s_cselect_b64 vcc, -1, 0
	s_and_b64 s[20:21], vcc, exec
	s_cselect_b32 s20, s88, s4
	s_ashr_i32 s21, s20, 31
	s_lshl_b64 s[34:35], s[20:21], 11
	v_lshl_add_u64 v[246:247], v[248:249], 0, s[34:35]
	global_load_dword v80, v[246:247], off offset:512
	global_load_dword v67, v[246:247], off offset:516
	s_add_i32 s20, s20, s14
	s_ashr_i32 s21, s20, 31
	s_lshl_b64 s[20:21], s[20:21], 2
	s_add_u32 s20, s26, s20
	s_addc_u32 s21, s27, s21
	s_or_b32 s87, s4, 5
	s_cmp_lt_u32 s87, s23
	global_load_dword v64, v97, s[20:21]
	s_cselect_b64 vcc, -1, 0
	s_and_b64 s[20:21], vcc, exec
	s_cselect_b32 s20, s87, s4
	s_ashr_i32 s21, s20, 31
	s_lshl_b64 s[34:35], s[20:21], 11
	v_lshl_add_u64 v[246:247], v[248:249], 0, s[34:35]
	global_load_dword v115, v[246:247], off offset:512
	global_load_dword v65, v[246:247], off offset:516
	s_add_i32 s20, s20, s14
	s_ashr_i32 s21, s20, 31
	s_lshl_b64 s[20:21], s[20:21], 2
	s_add_u32 s20, s26, s20
	s_addc_u32 s21, s27, s21
	s_or_b32 s86, s4, 6
	s_cmp_lt_u32 s86, s23
	global_load_dword v62, v97, s[20:21]
	s_cselect_b64 vcc, -1, 0
	s_and_b64 s[20:21], vcc, exec
	s_cselect_b32 s20, s86, s4
	s_ashr_i32 s21, s20, 31
	s_lshl_b64 s[34:35], s[20:21], 11
	v_lshl_add_u64 v[246:247], v[248:249], 0, s[34:35]
	global_load_dword v114, v[246:247], off offset:512
	global_load_dword v63, v[246:247], off offset:516
	s_add_i32 s20, s20, s14
	s_ashr_i32 s21, s20, 31
	s_lshl_b64 s[20:21], s[20:21], 2
	s_add_u32 s20, s26, s20
	s_addc_u32 s21, s27, s21
	s_or_b32 s85, s4, 7
	s_cmp_lt_u32 s85, s23
	global_load_dword v60, v97, s[20:21]
	s_cselect_b64 vcc, -1, 0
	s_and_b64 s[20:21], vcc, exec
	s_cselect_b32 s20, s85, s4
	s_ashr_i32 s21, s20, 31
	s_lshl_b64 s[34:35], s[20:21], 11
	v_lshl_add_u64 v[246:247], v[248:249], 0, s[34:35]
	global_load_dword v113, v[246:247], off offset:512
	global_load_dword v61, v[246:247], off offset:516
	s_add_i32 s20, s20, s14
	s_ashr_i32 s21, s20, 31
	s_lshl_b64 s[20:21], s[20:21], 2
	s_add_u32 s20, s26, s20
	s_addc_u32 s21, s27, s21
	s_or_b32 s84, s4, 8
	s_cmp_lt_u32 s84, s23
	global_load_dword v58, v97, s[20:21]
	s_cselect_b64 vcc, -1, 0
	s_and_b64 s[20:21], vcc, exec
	s_cselect_b32 s20, s84, s4
	s_ashr_i32 s21, s20, 31
	s_lshl_b64 s[34:35], s[20:21], 11
	v_lshl_add_u64 v[246:247], v[248:249], 0, s[34:35]
	global_load_dword v112, v[246:247], off offset:512
	global_load_dword v59, v[246:247], off offset:516
	s_add_i32 s20, s20, s14
	s_ashr_i32 s21, s20, 31
	s_lshl_b64 s[20:21], s[20:21], 2
	s_add_u32 s20, s26, s20
	s_addc_u32 s21, s27, s21
	s_or_b32 s83, s4, 9
	s_cmp_lt_u32 s83, s23
	global_load_dword v56, v97, s[20:21]
	s_cselect_b64 vcc, -1, 0
	s_and_b64 s[20:21], vcc, exec
	s_cselect_b32 s20, s83, s4
	s_ashr_i32 s21, s20, 31
	s_lshl_b64 s[34:35], s[20:21], 11
	v_lshl_add_u64 v[246:247], v[248:249], 0, s[34:35]
	global_load_dword v111, v[246:247], off offset:512
	global_load_dword v57, v[246:247], off offset:516
	s_add_i32 s20, s20, s14
	s_ashr_i32 s21, s20, 31
	s_lshl_b64 s[20:21], s[20:21], 2
	s_add_u32 s20, s26, s20
	s_addc_u32 s21, s27, s21
	s_or_b32 s82, s4, 10
	s_cmp_lt_u32 s82, s23
	global_load_dword v54, v97, s[20:21]
	s_cselect_b64 vcc, -1, 0
	s_and_b64 s[20:21], vcc, exec
	s_cselect_b32 s20, s82, s4
	s_ashr_i32 s21, s20, 31
	s_lshl_b64 s[34:35], s[20:21], 11
	v_lshl_add_u64 v[246:247], v[248:249], 0, s[34:35]
	global_load_dword v110, v[246:247], off offset:512
	global_load_dword v55, v[246:247], off offset:516
	s_add_i32 s20, s20, s14
	s_ashr_i32 s21, s20, 31
	s_lshl_b64 s[20:21], s[20:21], 2
	s_add_u32 s20, s26, s20
	s_addc_u32 s21, s27, s21
	s_or_b32 s81, s4, 11
	s_cmp_lt_u32 s81, s23
	global_load_dword v52, v97, s[20:21]
	s_cselect_b64 vcc, -1, 0
	s_and_b64 s[20:21], vcc, exec
	s_cselect_b32 s20, s81, s4
	s_ashr_i32 s21, s20, 31
	s_lshl_b64 s[34:35], s[20:21], 11
	v_lshl_add_u64 v[246:247], v[248:249], 0, s[34:35]
	global_load_dword v109, v[246:247], off offset:512
	global_load_dword v53, v[246:247], off offset:516
	s_add_i32 s20, s20, s14
	s_ashr_i32 s21, s20, 31
	s_lshl_b64 s[20:21], s[20:21], 2
	s_add_u32 s20, s26, s20
	s_addc_u32 s21, s27, s21
	s_or_b32 s80, s4, 12
	s_cmp_lt_u32 s80, s23
	global_load_dword v50, v97, s[20:21]
	s_cselect_b64 vcc, -1, 0
	s_and_b64 s[20:21], vcc, exec
	s_cselect_b32 s20, s80, s4
	s_ashr_i32 s21, s20, 31
	s_lshl_b64 s[34:35], s[20:21], 11
	v_lshl_add_u64 v[246:247], v[248:249], 0, s[34:35]
	global_load_dword v51, v[246:247], off offset:512
	global_load_dword v47, v[246:247], off offset:516
	s_add_i32 s20, s20, s14
	s_ashr_i32 s21, s20, 31
	s_lshl_b64 s[20:21], s[20:21], 2
	s_add_u32 s20, s26, s20
	s_addc_u32 s21, s27, s21
	s_or_b32 s79, s4, 13
	s_cmp_lt_u32 s79, s23
	global_load_dword v46, v97, s[20:21]
	s_cselect_b64 vcc, -1, 0
	s_and_b64 s[20:21], vcc, exec
	s_cselect_b32 s20, s79, s4
	s_ashr_i32 s21, s20, 31
	s_lshl_b64 s[34:35], s[20:21], 11
	v_lshl_add_u64 v[246:247], v[248:249], 0, s[34:35]
	global_load_dword v108, v[246:247], off offset:512
	global_load_dword v107, v[246:247], off offset:516
	s_add_i32 s20, s20, s14
	s_ashr_i32 s21, s20, 31
	s_lshl_b64 s[20:21], s[20:21], 2
	s_add_u32 s20, s26, s20
	s_addc_u32 s21, s27, s21
	s_or_b32 s35, s4, 14
	s_cmp_lt_u32 s35, s23
	global_load_dword v48, v97, s[20:21]
	s_cselect_b64 vcc, -1, 0
	s_and_b64 s[20:21], vcc, exec
	s_cselect_b32 s20, s35, s4
	s_ashr_i32 s21, s20, 31
	s_lshl_b64 s[62:63], s[20:21], 11
	v_lshl_add_u64 v[246:247], v[248:249], 0, s[62:63]
	global_load_dword v106, v[246:247], off offset:512
	global_load_dword v49, v[246:247], off offset:516
	s_add_i32 s20, s20, s14
	s_ashr_i32 s21, s20, 31
	s_lshl_b64 s[20:21], s[20:21], 2
	s_add_u32 s20, s26, s20
	s_addc_u32 s21, s27, s21
	s_or_b32 s78, s4, 15
	s_cmp_lt_u32 s78, s23
	global_load_dword v44, v97, s[20:21]
	s_cselect_b64 vcc, -1, 0
	s_and_b64 s[20:21], vcc, exec
	s_cselect_b32 s20, s78, s4
	s_ashr_i32 s21, s20, 31
	s_lshl_b64 s[62:63], s[20:21], 11
	v_lshl_add_u64 v[246:247], v[248:249], 0, s[62:63]
	global_load_dword v105, v[246:247], off offset:512
	global_load_dword v45, v[246:247], off offset:516
	s_add_i32 s20, s20, s14
	s_ashr_i32 s21, s20, 31
	s_lshl_b64 s[20:21], s[20:21], 2
	s_add_u32 s20, s26, s20
	s_addc_u32 s21, s27, s21
	s_or_b32 s77, s4, 16
	s_cmp_lt_u32 s77, s23
	global_load_dword v42, v97, s[20:21]
	s_cselect_b64 vcc, -1, 0
	s_and_b64 s[20:21], vcc, exec
	s_cselect_b32 s20, s77, s4
	s_ashr_i32 s21, s20, 31
	s_lshl_b64 s[62:63], s[20:21], 11
	v_lshl_add_u64 v[246:247], v[248:249], 0, s[62:63]
	global_load_dword v104, v[246:247], off offset:512
	global_load_dword v43, v[246:247], off offset:516
	s_add_i32 s20, s20, s14
	s_ashr_i32 s21, s20, 31
	s_lshl_b64 s[20:21], s[20:21], 2
	s_add_u32 s20, s26, s20
	s_addc_u32 s21, s27, s21
	s_or_b32 s76, s4, 17
	s_cmp_lt_u32 s76, s23
	global_load_dword v40, v97, s[20:21]
	s_cselect_b64 vcc, -1, 0
	s_and_b64 s[20:21], vcc, exec
	s_cselect_b32 s20, s76, s4
	s_ashr_i32 s21, s20, 31
	s_lshl_b64 s[62:63], s[20:21], 11
	v_lshl_add_u64 v[246:247], v[248:249], 0, s[62:63]
	global_load_dword v103, v[246:247], off offset:512
	global_load_dword v41, v[246:247], off offset:516
	s_add_i32 s20, s20, s14
	s_ashr_i32 s21, s20, 31
	s_lshl_b64 s[20:21], s[20:21], 2
	s_add_u32 s20, s26, s20
	s_addc_u32 s21, s27, s21
	s_or_b32 s75, s4, 18
	s_cmp_lt_u32 s75, s23
	global_load_dword v38, v97, s[20:21]
	s_cselect_b64 vcc, -1, 0
	s_and_b64 s[20:21], vcc, exec
	s_cselect_b32 s20, s75, s4
	s_ashr_i32 s21, s20, 31
	s_lshl_b64 s[62:63], s[20:21], 11
	v_lshl_add_u64 v[246:247], v[248:249], 0, s[62:63]
	global_load_dword v102, v[246:247], off offset:512
	global_load_dword v39, v[246:247], off offset:516
	s_add_i32 s20, s20, s14
	s_ashr_i32 s21, s20, 31
	s_lshl_b64 s[20:21], s[20:21], 2
	s_add_u32 s20, s26, s20
	s_addc_u32 s21, s27, s21
	s_or_b32 s74, s4, 19
	s_cmp_lt_u32 s74, s23
	global_load_dword v36, v97, s[20:21]
	s_cselect_b64 vcc, -1, 0
	s_and_b64 s[20:21], vcc, exec
	s_cselect_b32 s20, s74, s4
	s_ashr_i32 s21, s20, 31
	s_lshl_b64 s[62:63], s[20:21], 11
	v_lshl_add_u64 v[246:247], v[248:249], 0, s[62:63]
	global_load_dword v101, v[246:247], off offset:512
	global_load_dword v37, v[246:247], off offset:516
	s_add_i32 s20, s20, s14
	s_ashr_i32 s21, s20, 31
	s_lshl_b64 s[20:21], s[20:21], 2
	s_add_u32 s20, s26, s20
	s_addc_u32 s21, s27, s21
	s_or_b32 s72, s4, 20
	s_cmp_lt_u32 s72, s23
	global_load_dword v32, v97, s[20:21]
	s_cselect_b64 vcc, -1, 0
	s_and_b64 s[20:21], vcc, exec
	s_cselect_b32 s20, s72, s4
	s_ashr_i32 s21, s20, 31
	s_lshl_b64 s[62:63], s[20:21], 11
	v_lshl_add_u64 v[246:247], v[248:249], 0, s[62:63]
	global_load_dword v35, v[246:247], off offset:512
	global_load_dword v33, v[246:247], off offset:516
	s_add_i32 s20, s20, s14
	s_ashr_i32 s21, s20, 31
	s_lshl_b64 s[20:21], s[20:21], 2
	s_add_u32 s20, s26, s20
	s_addc_u32 s21, s27, s21
	s_or_b32 s73, s4, 21
	s_cmp_lt_u32 s73, s23
	global_load_dword v34, v97, s[20:21]
	s_cselect_b64 vcc, -1, 0
	s_and_b64 s[20:21], vcc, exec
	s_cselect_b32 s20, s73, s4
	s_ashr_i32 s21, s20, 31
	s_lshl_b64 s[62:63], s[20:21], 11
	v_lshl_add_u64 v[246:247], v[248:249], 0, s[62:63]
	global_load_dword v100, v[246:247], off offset:512
	global_load_dword v99, v[246:247], off offset:516
	s_add_i32 s20, s20, s14
	s_ashr_i32 s21, s20, 31
	s_lshl_b64 s[20:21], s[20:21], 2
	s_add_u32 s20, s26, s20
	s_addc_u32 s21, s27, s21
	s_or_b32 s71, s4, 22
	s_cmp_lt_u32 s71, s23
	global_load_dword v30, v97, s[20:21]
	s_cselect_b64 vcc, -1, 0
	s_and_b64 s[20:21], vcc, exec
	s_cselect_b32 s20, s71, s4
	s_ashr_i32 s21, s20, 31
	s_lshl_b64 s[62:63], s[20:21], 11
	v_lshl_add_u64 v[246:247], v[248:249], 0, s[62:63]
	global_load_dword v98, v[246:247], off offset:512
	global_load_dword v31, v[246:247], off offset:516
	s_add_i32 s20, s20, s14
	s_ashr_i32 s21, s20, 31
	s_lshl_b64 s[20:21], s[20:21], 2
	s_add_u32 s20, s26, s20
	s_addc_u32 s21, s27, s21
	s_or_b32 s70, s4, 23
	s_cmp_lt_u32 s70, s23
	global_load_dword v28, v97, s[20:21]
	s_cselect_b64 vcc, -1, 0
	s_and_b64 s[20:21], vcc, exec
	s_cselect_b32 s20, s70, s4
	s_ashr_i32 s21, s20, 31
	s_lshl_b64 s[62:63], s[20:21], 11
	v_lshl_add_u64 v[246:247], v[248:249], 0, s[62:63]
	global_load_dword v95, v[246:247], off offset:512
	global_load_dword v29, v[246:247], off offset:516
	s_add_i32 s20, s20, s14
	s_ashr_i32 s21, s20, 31
	s_lshl_b64 s[20:21], s[20:21], 2
	s_add_u32 s20, s26, s20
	s_addc_u32 s21, s27, s21
	s_or_b32 s69, s4, 24
	s_cmp_lt_u32 s69, s23
	global_load_dword v26, v97, s[20:21]
	s_cselect_b64 vcc, -1, 0
	s_and_b64 s[20:21], vcc, exec
	s_cselect_b32 s20, s69, s4
	s_ashr_i32 s21, s20, 31
	s_lshl_b64 s[62:63], s[20:21], 11
	v_lshl_add_u64 v[246:247], v[248:249], 0, s[62:63]
	global_load_dword v94, v[246:247], off offset:512
	global_load_dword v27, v[246:247], off offset:516
	s_add_i32 s20, s20, s14
	s_ashr_i32 s21, s20, 31
	s_lshl_b64 s[20:21], s[20:21], 2
	s_add_u32 s20, s26, s20
	s_addc_u32 s21, s27, s21
	s_or_b32 s68, s4, 25
	s_cmp_lt_u32 s68, s23
	global_load_dword v24, v97, s[20:21]
	s_cselect_b64 vcc, -1, 0
	s_and_b64 s[20:21], vcc, exec
	s_cselect_b32 s20, s68, s4
	s_ashr_i32 s21, s20, 31
	s_lshl_b64 s[62:63], s[20:21], 11
	v_lshl_add_u64 v[246:247], v[248:249], 0, s[62:63]
	global_load_dword v93, v[246:247], off offset:512
	global_load_dword v25, v[246:247], off offset:516
	s_add_i32 s20, s20, s14
	s_ashr_i32 s21, s20, 31
	s_lshl_b64 s[20:21], s[20:21], 2
	s_add_u32 s20, s26, s20
	s_addc_u32 s21, s27, s21
	s_or_b32 s66, s4, 26
	s_cmp_lt_u32 s66, s23
	global_load_dword v20, v97, s[20:21]
	s_cselect_b64 vcc, -1, 0
	s_and_b64 s[20:21], vcc, exec
	s_cselect_b32 s20, s66, s4
	s_ashr_i32 s21, s20, 31
	s_lshl_b64 s[62:63], s[20:21], 11
	v_lshl_add_u64 v[246:247], v[248:249], 0, s[62:63]
	global_load_dword v23, v[246:247], off offset:512
	global_load_dword v21, v[246:247], off offset:516
	s_add_i32 s20, s20, s14
	s_ashr_i32 s21, s20, 31
	s_lshl_b64 s[20:21], s[20:21], 2
	s_add_u32 s20, s26, s20
	s_addc_u32 s21, s27, s21
	s_or_b32 s67, s4, 27
	s_cmp_lt_u32 s67, s23
	global_load_dword v22, v97, s[20:21]
	s_cselect_b64 vcc, -1, 0
	s_and_b64 s[20:21], vcc, exec
	s_cselect_b32 s20, s67, s4
	s_ashr_i32 s21, s20, 31
	s_lshl_b64 s[62:63], s[20:21], 11
	v_lshl_add_u64 v[246:247], v[248:249], 0, s[62:63]
	global_load_dword v92, v[246:247], off offset:512
	global_load_dword v91, v[246:247], off offset:516
	s_add_i32 s20, s20, s14
	s_ashr_i32 s21, s20, 31
	s_lshl_b64 s[20:21], s[20:21], 2
	s_add_u32 s20, s26, s20
	s_addc_u32 s21, s27, s21
	s_or_b32 s63, s4, 28
	s_cmp_lt_u32 s63, s23
	global_load_dword v18, v97, s[20:21]
	s_cselect_b64 vcc, -1, 0
	s_and_b64 s[20:21], vcc, exec
	s_cselect_b32 s20, s63, s4
	s_ashr_i32 s21, s20, 31
	s_lshl_b64 s[96:97], s[20:21], 11
	v_lshl_add_u64 v[246:247], v[248:249], 0, s[96:97]
	global_load_dword v90, v[246:247], off offset:512
	global_load_dword v19, v[246:247], off offset:516
	s_add_i32 s20, s20, s14
	s_ashr_i32 s21, s20, 31
	s_lshl_b64 s[20:21], s[20:21], 2
	s_add_u32 s20, s26, s20
	s_addc_u32 s21, s27, s21
	s_or_b32 s34, s4, 29
	s_cmp_lt_u32 s34, s23
	global_load_dword v16, v97, s[20:21]
	s_cselect_b64 vcc, -1, 0
	s_and_b64 s[20:21], vcc, exec
	s_cselect_b32 s20, s34, s4
	s_ashr_i32 s21, s20, 31
	s_lshl_b64 s[96:97], s[20:21], 11
	v_lshl_add_u64 v[246:247], v[248:249], 0, s[96:97]
	global_load_dword v89, v[246:247], off offset:512
	global_load_dword v88, v[246:247], off offset:516
	s_add_i32 s20, s20, s14
	s_ashr_i32 s21, s20, 31
	s_lshl_b64 s[20:21], s[20:21], 2
	s_add_u32 s20, s26, s20
	s_addc_u32 s21, s27, s21
	s_or_b32 s15, s4, 30
	s_cmp_lt_u32 s15, s23
	global_load_dword v12, v97, s[20:21]
	s_cselect_b64 vcc, -1, 0
	s_and_b64 s[20:21], vcc, exec
	s_cselect_b32 s20, s15, s4
	s_ashr_i32 s21, s20, 31
	s_lshl_b64 s[96:97], s[20:21], 11
	v_lshl_add_u64 v[246:247], v[248:249], 0, s[96:97]
	global_load_dword v87, v[246:247], off offset:512
	global_load_dword v86, v[246:247], off offset:516
	s_add_i32 s20, s20, s14
	s_ashr_i32 s21, s20, 31
	s_lshl_b64 s[20:21], s[20:21], 2
	s_add_u32 s20, s26, s20
	s_addc_u32 s21, s27, s21
	s_or_b32 s5, s4, 31
	s_cmp_lt_u32 s5, s23
	global_load_dword v10, v97, s[20:21]
	s_cselect_b64 vcc, -1, 0
	s_and_b64 s[20:21], vcc, exec
	s_cselect_b32 s20, s5, s4
	s_ashr_i32 s21, s20, 31
	s_lshl_b64 s[96:97], s[20:21], 11
	v_lshl_add_u64 v[246:247], v[248:249], 0, s[96:97]
	global_load_dwordx2 v[134:135], v[246:247], off offset:512
	s_add_i32 s20, s20, s14
	s_ashr_i32 s21, s20, 31
	s_lshl_b64 s[20:21], s[20:21], 2
	s_add_u32 s20, s26, s20
	s_addc_u32 s21, s27, s21
	s_add_i32 s62, s4, 32
	s_cmp_lt_u32 s62, s23
	s_cselect_b64 vcc, -1, 0
	s_and_b64 s[20:21], vcc, exec
	s_cselect_b32 s20, s62, s4
	s_ashr_i32 s21, s20, 31
	s_lshl_b64 s[96:97], s[20:21], 11
	v_lshl_add_u64 v[246:247], v[248:249], 0, s[96:97]
	global_load_dwordx2 v[136:137], v[246:247], off offset:512
	s_add_i32 s20, s20, s14
	s_ashr_i32 s21, s20, 31
	s_lshl_b64 s[20:21], s[20:21], 2
	s_add_u32 s20, s26, s20
	s_addc_u32 s21, s27, s21
	v_readlane_b32 s5, v244, 0
	v_readlane_b32 vcc_lo, v244, 1
	v_readlane_b32 vcc_hi, v244, 2
	v_readlane_b32 s20, v244, 3
	v_readlane_b32 s21, v244, 4
	v_readlane_b32 s34, v244, 5
	v_readlane_b32 s35, v244, 6
	v_readlane_b32 s30, v244, 7
	v_readlane_b32 s31, v244, 8
	v_readlane_b32 s7, v244, 9
	v_readlane_b32 s91, v244, 10
	v_readlane_b32 s90, v244, 11
	v_readlane_b32 s89, v244, 12
	v_readlane_b32 s88, v244, 13
	v_readlane_b32 s87, v244, 14
	v_readlane_b32 s86, v244, 15
	v_readlane_b32 s85, v244, 16
	v_readlane_b32 s84, v244, 17
	v_readlane_b32 s83, v244, 18
	v_readlane_b32 s82, v244, 19
	v_readlane_b32 s81, v244, 20
	v_readlane_b32 s80, v244, 21
	v_readlane_b32 s79, v244, 22
	v_readlane_b32 s62, v244, 23
	v_readlane_b32 s63, v244, 24
	v_readlane_b32 s78, v244, 25
	v_readlane_b32 s77, v244, 26
	v_readlane_b32 s76, v244, 27
	v_readlane_b32 s75, v244, 28
	v_readlane_b32 s74, v244, 29
	v_readlane_b32 s72, v244, 30
	v_readlane_b32 s73, v244, 31
	v_readlane_b32 s71, v244, 32
	v_readlane_b32 s70, v244, 33
	v_readlane_b32 s69, v244, 34
	v_readlane_b32 s68, v244, 35
	v_readlane_b32 s66, v244, 36
	v_readlane_b32 s67, v244, 37
	v_readlane_b32 s96, v244, 38
	v_readlane_b32 s97, v244, 39
	v_readlane_b32 s15, v244, 40
	s_nop 4
	s_waitcnt vmcnt(0)
	s_add_i32 s5, s4, -2
	s_cmp_lt_u32 s5, s23
	s_cselect_b64 vcc, -1, 0
	s_and_b64 s[20:21], vcc, exec
	s_cselect_b32 s20, s5, s4
	v_lshlrev_b32_e32 v96, 1, v11
	s_ashr_i32 s21, s20, 31
	v_lshl_add_u64 v[8:9], s[2:3], 0, v[96:97]
	s_lshl_b64 s[34:35], s[20:21], 11
	v_lshl_add_u64 v[4:5], v[8:9], 0, s[34:35]
	s_add_i32 s20, s20, s14
	s_ashr_i32 s21, s20, 31
	s_lshl_b64 s[20:21], s[20:21], 2
	s_add_u32 s20, s26, s20
	s_addc_u32 s21, s27, s21
	s_add_i32 s5, s4, -1
	s_cmp_lt_u32 s5, s23
	s_mov_b64 s[30:31], 0x200
	s_waitcnt vmcnt(0)
	v_cndmask_b32_e32 v15, 0, v132, vcc
	v_cndmask_b32_e32 v5, 0, v133, vcc
	s_cselect_b64 vcc, -1, 0
	global_load_dword v4, v97, s[20:21]
	s_waitcnt vmcnt(0)
	s_and_b64 s[20:21], vcc, exec
	s_cselect_b32 s20, s5, s4
	s_ashr_i32 s21, s20, 31
	s_lshl_b64 s[34:35], s[20:21], 11
	v_lshl_add_u64 v[6:7], v[8:9], 0, s[34:35]
	s_add_i32 s20, s20, s14
	s_ashr_i32 s21, s20, 31
	s_lshl_b64 s[20:21], s[20:21], 2
	s_add_u32 s20, s26, s20
	s_addc_u32 s21, s27, s21
	s_cmp_lt_u32 s4, s23
	v_lshlrev_b32_e32 v82, 16, v15
	v_and_b32_e32 v83, 0xffff0000, v15
	v_lshlrev_b32_e32 v84, 16, v5
	v_and_b32_e32 v85, 0xffff0000, v5
	s_waitcnt vmcnt(2)
	v_pk_mul_f32 v[116:117], v[4:5], v[84:85] op_sel_hi:[0,1]
	v_pk_mul_f32 v[118:119], v[4:5], v[82:83] op_sel_hi:[0,1]
	v_pk_fma_f32 v[82:83], v[4:5], v[82:83], 0 op_sel_hi:[0,1,0]
	v_pk_fma_f32 v[4:5], v[4:5], v[84:85], 0 op_sel_hi:[0,1,0]
	s_waitcnt vmcnt(1)
	v_cndmask_b32_e32 v74, 0, v74, vcc
	v_cndmask_b32_e32 v71, 0, v71, vcc
	s_cselect_b64 vcc, -1, 0
	s_ashr_i32 s5, s4, 31
	s_lshl_b64 s[20:21], s[4:5], 11
	v_lshl_add_u64 v[6:7], v[8:9], 0, s[20:21]
	s_ashr_i32 s7, s6, 31
	s_lshl_b64 s[20:21], s[6:7], 2
	s_add_u32 s20, s26, s20
	s_addc_u32 s21, s27, s21
	s_or_b32 s91, s4, 1
	s_cmp_lt_u32 s91, s23
	v_lshlrev_b32_e32 v84, 16, v74
	v_and_b32_e32 v85, 0xffff0000, v74
	v_lshlrev_b32_e32 v120, 16, v71
	v_and_b32_e32 v121, 0xffff0000, v71
	s_waitcnt vmcnt(2)
	v_pk_mul_f32 v[122:123], v[14:15], v[120:121] op_sel_hi:[0,1]
	v_pk_mul_f32 v[124:125], v[14:15], v[84:85] op_sel_hi:[0,1]
	v_pk_fma_f32 v[4:5], v[14:15], v[120:121], v[4:5] op_sel_hi:[0,1,1]
	v_pk_fma_f32 v[14:15], v[14:15], v[84:85], v[82:83] op_sel_hi:[0,1,1]
	s_waitcnt vmcnt(1)
	v_cndmask_b32_e32 v77, 0, v77, vcc
	v_cndmask_b32_e32 v75, 0, v75, vcc
	s_cselect_b64 vcc, -1, 0
	s_and_b64 s[20:21], vcc, exec
	s_cselect_b32 s20, s91, s4
	s_ashr_i32 s21, s20, 31
	s_lshl_b64 s[34:35], s[20:21], 11
	v_lshl_add_u64 v[6:7], v[8:9], 0, s[34:35]
	s_add_i32 s20, s20, s14
	s_ashr_i32 s21, s20, 31
	s_lshl_b64 s[20:21], s[20:21], 2
	s_add_u32 s20, s26, s20
	s_addc_u32 s21, s27, s21
	s_or_b32 s90, s4, 2
	s_cmp_lt_u32 s90, s23
	v_lshlrev_b32_e32 v120, 16, v77
	v_and_b32_e32 v121, 0xffff0000, v77
	v_lshlrev_b32_e32 v74, 16, v75
	v_and_b32_e32 v75, 0xffff0000, v75
	s_waitcnt vmcnt(2)
	v_pk_mul_f32 v[84:85], v[70:71], v[120:121] op_sel_hi:[0,1]
	v_pk_fma_f32 v[14:15], v[70:71], v[120:121], v[14:15] op_sel_hi:[0,1,1]
	v_pk_mul_f32 v[82:83], v[70:71], v[74:75] op_sel_hi:[0,1]
	v_pk_fma_f32 v[4:5], v[70:71], v[74:75], v[4:5] op_sel_hi:[0,1,1]
	s_waitcnt vmcnt(1)
	v_cndmask_b32_e32 v81, 0, v81, vcc
	v_cndmask_b32_e32 v79, 0, v79, vcc
	s_cselect_b64 vcc, -1, 0
	s_and_b64 s[20:21], vcc, exec
	s_cselect_b32 s20, s90, s4
	s_ashr_i32 s21, s20, 31
	s_lshl_b64 s[34:35], s[20:21], 11
	v_lshl_add_u64 v[6:7], v[8:9], 0, s[34:35]
	s_add_i32 s20, s20, s14
	s_ashr_i32 s21, s20, 31
	s_lshl_b64 s[20:21], s[20:21], 2
	s_add_u32 s20, s26, s20
	s_addc_u32 s21, s27, s21
	s_or_b32 s89, s4, 3
	s_cmp_lt_u32 s89, s23
	v_lshlrev_b32_e32 v120, 16, v81
	v_and_b32_e32 v121, 0xffff0000, v81
	v_lshlrev_b32_e32 v126, 16, v79
	v_and_b32_e32 v127, 0xffff0000, v79
	s_waitcnt vmcnt(1)
	v_cndmask_b32_e32 v76, 0, v76, vcc
	v_cndmask_b32_e32 v73, 0, v73, vcc
	s_cselect_b64 vcc, -1, 0
	s_and_b64 s[20:21], vcc, exec
	s_cselect_b32 s20, s89, s4
	s_ashr_i32 s21, s20, 31
	s_lshl_b64 s[34:35], s[20:21], 11
	v_lshl_add_u64 v[6:7], v[8:9], 0, s[34:35]
	s_add_i32 s20, s20, s14
	s_ashr_i32 s21, s20, 31
	s_lshl_b64 s[20:21], s[20:21], 2
	s_add_u32 s20, s26, s20
	s_addc_u32 s21, s27, s21
	s_or_b32 s88, s4, 4
	s_cmp_lt_u32 s88, s23
	v_pk_mul_f32 v[74:75], v[72:73], v[120:121] op_sel_hi:[0,1]
	v_pk_fma_f32 v[120:121], v[72:73], v[120:121], v[14:15] op_sel_hi:[0,1,1]
	v_pk_mul_f32 v[70:71], v[72:73], v[126:127] op_sel_hi:[0,1]
	v_pk_fma_f32 v[126:127], v[72:73], v[126:127], v[4:5] op_sel_hi:[0,1,1]
	s_waitcnt vmcnt(1)
	v_cndmask_b32_e32 v78, 0, v78, vcc
	v_cndmask_b32_e32 v69, 0, v69, vcc
	s_cselect_b64 vcc, -1, 0
	s_and_b64 s[20:21], vcc, exec
	s_cselect_b32 s20, s88, s4
	s_ashr_i32 s21, s20, 31
	s_lshl_b64 s[34:35], s[20:21], 11
	v_lshl_add_u64 v[6:7], v[8:9], 0, s[34:35]
	s_add_i32 s20, s20, s14
	s_ashr_i32 s21, s20, 31
	s_lshl_b64 s[20:21], s[20:21], 2
	s_add_u32 s20, s26, s20
	s_addc_u32 s21, s27, s21
	s_or_b32 s87, s4, 5
	s_cmp_lt_u32 s87, s23
	s_waitcnt vmcnt(1)
	v_cndmask_b32_e32 v80, 0, v80, vcc
	v_cndmask_b32_e32 v67, 0, v67, vcc
	s_cselect_b64 vcc, -1, 0
	s_and_b64 s[20:21], vcc, exec
	s_cselect_b32 s20, s87, s4
	s_ashr_i32 s21, s20, 31
	s_lshl_b64 s[34:35], s[20:21], 11
	v_lshl_add_u64 v[6:7], v[8:9], 0, s[34:35]
	s_add_i32 s20, s20, s14
	s_ashr_i32 s21, s20, 31
	s_lshl_b64 s[20:21], s[20:21], 2
	s_add_u32 s20, s26, s20
	s_addc_u32 s21, s27, s21
	s_or_b32 s86, s4, 6
	s_cmp_lt_u32 s86, s23
	s_waitcnt vmcnt(1)
	v_cndmask_b32_e32 v115, 0, v115, vcc
	v_cndmask_b32_e32 v65, 0, v65, vcc
	s_cselect_b64 vcc, -1, 0
	s_and_b64 s[20:21], vcc, exec
	s_cselect_b32 s20, s86, s4
	s_ashr_i32 s21, s20, 31
	s_lshl_b64 s[34:35], s[20:21], 11
	v_lshl_add_u64 v[6:7], v[8:9], 0, s[34:35]
	s_add_i32 s20, s20, s14
	s_ashr_i32 s21, s20, 31
	s_lshl_b64 s[20:21], s[20:21], 2
	s_add_u32 s20, s26, s20
	s_addc_u32 s21, s27, s21
	s_or_b32 s85, s4, 7
	s_cmp_lt_u32 s85, s23
	s_waitcnt vmcnt(1)
	v_cndmask_b32_e32 v114, 0, v114, vcc
	v_cndmask_b32_e32 v63, 0, v63, vcc
	s_cselect_b64 vcc, -1, 0
	s_and_b64 s[20:21], vcc, exec
	s_cselect_b32 s20, s85, s4
	s_ashr_i32 s21, s20, 31
	s_lshl_b64 s[34:35], s[20:21], 11
	v_lshl_add_u64 v[6:7], v[8:9], 0, s[34:35]
	s_add_i32 s20, s20, s14
	s_ashr_i32 s21, s20, 31
	s_lshl_b64 s[20:21], s[20:21], 2
	s_add_u32 s20, s26, s20
	s_addc_u32 s21, s27, s21
	s_or_b32 s84, s4, 8
	s_cmp_lt_u32 s84, s23
	s_waitcnt vmcnt(1)
	v_cndmask_b32_e32 v113, 0, v113, vcc
	v_cndmask_b32_e32 v61, 0, v61, vcc
	s_cselect_b64 vcc, -1, 0
	s_and_b64 s[20:21], vcc, exec
	s_cselect_b32 s20, s84, s4
	s_ashr_i32 s21, s20, 31
	s_lshl_b64 s[34:35], s[20:21], 11
	v_lshl_add_u64 v[6:7], v[8:9], 0, s[34:35]
	s_add_i32 s20, s20, s14
	s_ashr_i32 s21, s20, 31
	s_lshl_b64 s[20:21], s[20:21], 2
	s_add_u32 s20, s26, s20
	s_addc_u32 s21, s27, s21
	s_or_b32 s83, s4, 9
	s_cmp_lt_u32 s83, s23
	s_waitcnt vmcnt(1)
	v_cndmask_b32_e32 v112, 0, v112, vcc
	v_cndmask_b32_e32 v59, 0, v59, vcc
	s_cselect_b64 vcc, -1, 0
	s_and_b64 s[20:21], vcc, exec
	s_cselect_b32 s20, s83, s4
	s_ashr_i32 s21, s20, 31
	s_lshl_b64 s[34:35], s[20:21], 11
	v_lshl_add_u64 v[6:7], v[8:9], 0, s[34:35]
	s_add_i32 s20, s20, s14
	s_ashr_i32 s21, s20, 31
	s_lshl_b64 s[20:21], s[20:21], 2
	s_add_u32 s20, s26, s20
	s_addc_u32 s21, s27, s21
	s_or_b32 s82, s4, 10
	s_cmp_lt_u32 s82, s23
	s_waitcnt vmcnt(1)
	v_cndmask_b32_e32 v111, 0, v111, vcc
	v_cndmask_b32_e32 v57, 0, v57, vcc
	s_cselect_b64 vcc, -1, 0
	s_and_b64 s[20:21], vcc, exec
	s_cselect_b32 s20, s82, s4
	s_ashr_i32 s21, s20, 31
	s_lshl_b64 s[34:35], s[20:21], 11
	v_lshl_add_u64 v[6:7], v[8:9], 0, s[34:35]
	s_add_i32 s20, s20, s14
	s_ashr_i32 s21, s20, 31
	s_lshl_b64 s[20:21], s[20:21], 2
	s_add_u32 s20, s26, s20
	s_addc_u32 s21, s27, s21
	s_or_b32 s81, s4, 11
	s_cmp_lt_u32 s81, s23
	s_waitcnt vmcnt(1)
	v_cndmask_b32_e32 v110, 0, v110, vcc
	v_cndmask_b32_e32 v55, 0, v55, vcc
	s_cselect_b64 vcc, -1, 0
	s_and_b64 s[20:21], vcc, exec
	s_cselect_b32 s20, s81, s4
	s_ashr_i32 s21, s20, 31
	s_lshl_b64 s[34:35], s[20:21], 11
	v_lshl_add_u64 v[6:7], v[8:9], 0, s[34:35]
	s_add_i32 s20, s20, s14
	s_ashr_i32 s21, s20, 31
	s_lshl_b64 s[20:21], s[20:21], 2
	s_add_u32 s20, s26, s20
	s_addc_u32 s21, s27, s21
	s_or_b32 s80, s4, 12
	s_cmp_lt_u32 s80, s23
	s_waitcnt vmcnt(1)
	v_cndmask_b32_e32 v109, 0, v109, vcc
	v_cndmask_b32_e32 v53, 0, v53, vcc
	s_cselect_b64 vcc, -1, 0
	s_and_b64 s[20:21], vcc, exec
	s_cselect_b32 s20, s80, s4
	s_ashr_i32 s21, s20, 31
	s_lshl_b64 s[34:35], s[20:21], 11
	v_lshl_add_u64 v[6:7], v[8:9], 0, s[34:35]
	s_add_i32 s20, s20, s14
	s_ashr_i32 s21, s20, 31
	s_lshl_b64 s[20:21], s[20:21], 2
	s_add_u32 s20, s26, s20
	s_addc_u32 s21, s27, s21
	s_or_b32 s79, s4, 13
	s_cmp_lt_u32 s79, s23
	s_waitcnt vmcnt(1)
	v_cndmask_b32_e32 v51, 0, v51, vcc
	v_cndmask_b32_e32 v47, 0, v47, vcc
	s_cselect_b64 vcc, -1, 0
	s_and_b64 s[20:21], vcc, exec
	s_cselect_b32 s20, s79, s4
	s_ashr_i32 s21, s20, 31
	s_lshl_b64 s[34:35], s[20:21], 11
	v_lshl_add_u64 v[6:7], v[8:9], 0, s[34:35]
	s_add_i32 s20, s20, s14
	s_ashr_i32 s21, s20, 31
	s_lshl_b64 s[20:21], s[20:21], 2
	s_add_u32 s20, s26, s20
	s_addc_u32 s21, s27, s21
	s_or_b32 s35, s4, 14
	s_cmp_lt_u32 s35, s23
	s_waitcnt vmcnt(1)
	v_cndmask_b32_e32 v108, 0, v108, vcc
	v_cndmask_b32_e32 v107, 0, v107, vcc
	s_cselect_b64 vcc, -1, 0
	s_and_b64 s[20:21], vcc, exec
	s_cselect_b32 s20, s35, s4
	s_ashr_i32 s21, s20, 31
	s_lshl_b64 s[62:63], s[20:21], 11
	v_lshl_add_u64 v[6:7], v[8:9], 0, s[62:63]
	s_add_i32 s20, s20, s14
	s_ashr_i32 s21, s20, 31
	s_lshl_b64 s[20:21], s[20:21], 2
	s_add_u32 s20, s26, s20
	s_addc_u32 s21, s27, s21
	s_or_b32 s78, s4, 15
	s_cmp_lt_u32 s78, s23
	s_waitcnt vmcnt(1)
	v_cndmask_b32_e32 v106, 0, v106, vcc
	v_cndmask_b32_e32 v49, 0, v49, vcc
	s_cselect_b64 vcc, -1, 0
	s_and_b64 s[20:21], vcc, exec
	s_cselect_b32 s20, s78, s4
	s_ashr_i32 s21, s20, 31
	s_lshl_b64 s[62:63], s[20:21], 11
	v_lshl_add_u64 v[6:7], v[8:9], 0, s[62:63]
	s_add_i32 s20, s20, s14
	s_ashr_i32 s21, s20, 31
	s_lshl_b64 s[20:21], s[20:21], 2
	s_add_u32 s20, s26, s20
	s_addc_u32 s21, s27, s21
	s_or_b32 s77, s4, 16
	s_cmp_lt_u32 s77, s23
	s_waitcnt vmcnt(1)
	v_cndmask_b32_e32 v105, 0, v105, vcc
	v_cndmask_b32_e32 v45, 0, v45, vcc
	s_cselect_b64 vcc, -1, 0
	s_and_b64 s[20:21], vcc, exec
	s_cselect_b32 s20, s77, s4
	s_ashr_i32 s21, s20, 31
	s_lshl_b64 s[62:63], s[20:21], 11
	v_lshl_add_u64 v[6:7], v[8:9], 0, s[62:63]
	s_add_i32 s20, s20, s14
	s_ashr_i32 s21, s20, 31
	s_lshl_b64 s[20:21], s[20:21], 2
	s_add_u32 s20, s26, s20
	s_addc_u32 s21, s27, s21
	s_or_b32 s76, s4, 17
	s_cmp_lt_u32 s76, s23
	s_waitcnt vmcnt(1)
	v_cndmask_b32_e32 v104, 0, v104, vcc
	v_cndmask_b32_e32 v43, 0, v43, vcc
	s_cselect_b64 vcc, -1, 0
	s_and_b64 s[20:21], vcc, exec
	s_cselect_b32 s20, s76, s4
	s_ashr_i32 s21, s20, 31
	s_lshl_b64 s[62:63], s[20:21], 11
	v_lshl_add_u64 v[6:7], v[8:9], 0, s[62:63]
	s_add_i32 s20, s20, s14
	s_ashr_i32 s21, s20, 31
	s_lshl_b64 s[20:21], s[20:21], 2
	s_add_u32 s20, s26, s20
	s_addc_u32 s21, s27, s21
	s_or_b32 s75, s4, 18
	s_cmp_lt_u32 s75, s23
	s_waitcnt vmcnt(1)
	v_cndmask_b32_e32 v103, 0, v103, vcc
	v_cndmask_b32_e32 v41, 0, v41, vcc
	s_cselect_b64 vcc, -1, 0
	s_and_b64 s[20:21], vcc, exec
	s_cselect_b32 s20, s75, s4
	s_ashr_i32 s21, s20, 31
	s_lshl_b64 s[62:63], s[20:21], 11
	v_lshl_add_u64 v[6:7], v[8:9], 0, s[62:63]
	s_add_i32 s20, s20, s14
	s_ashr_i32 s21, s20, 31
	s_lshl_b64 s[20:21], s[20:21], 2
	s_add_u32 s20, s26, s20
	s_addc_u32 s21, s27, s21
	s_or_b32 s74, s4, 19
	s_cmp_lt_u32 s74, s23
	s_waitcnt vmcnt(1)
	v_cndmask_b32_e32 v102, 0, v102, vcc
	v_cndmask_b32_e32 v39, 0, v39, vcc
	s_cselect_b64 vcc, -1, 0
	s_and_b64 s[20:21], vcc, exec
	s_cselect_b32 s20, s74, s4
	s_ashr_i32 s21, s20, 31
	s_lshl_b64 s[62:63], s[20:21], 11
	v_lshl_add_u64 v[6:7], v[8:9], 0, s[62:63]
	s_add_i32 s20, s20, s14
	s_ashr_i32 s21, s20, 31
	s_lshl_b64 s[20:21], s[20:21], 2
	s_add_u32 s20, s26, s20
	s_addc_u32 s21, s27, s21
	s_or_b32 s72, s4, 20
	s_cmp_lt_u32 s72, s23
	s_waitcnt vmcnt(1)
	v_cndmask_b32_e32 v101, 0, v101, vcc
	v_cndmask_b32_e32 v37, 0, v37, vcc
	s_cselect_b64 vcc, -1, 0
	s_and_b64 s[20:21], vcc, exec
	s_cselect_b32 s20, s72, s4
	s_ashr_i32 s21, s20, 31
	s_lshl_b64 s[62:63], s[20:21], 11
	v_lshl_add_u64 v[6:7], v[8:9], 0, s[62:63]
	s_add_i32 s20, s20, s14
	s_ashr_i32 s21, s20, 31
	s_lshl_b64 s[20:21], s[20:21], 2
	s_add_u32 s20, s26, s20
	s_addc_u32 s21, s27, s21
	s_or_b32 s73, s4, 21
	s_cmp_lt_u32 s73, s23
	s_waitcnt vmcnt(1)
	v_cndmask_b32_e32 v35, 0, v35, vcc
	v_cndmask_b32_e32 v33, 0, v33, vcc
	s_cselect_b64 vcc, -1, 0
	s_and_b64 s[20:21], vcc, exec
	s_cselect_b32 s20, s73, s4
	s_ashr_i32 s21, s20, 31
	s_lshl_b64 s[62:63], s[20:21], 11
	v_lshl_add_u64 v[6:7], v[8:9], 0, s[62:63]
	s_add_i32 s20, s20, s14
	s_ashr_i32 s21, s20, 31
	s_lshl_b64 s[20:21], s[20:21], 2
	s_add_u32 s20, s26, s20
	s_addc_u32 s21, s27, s21
	s_or_b32 s71, s4, 22
	s_cmp_lt_u32 s71, s23
	s_waitcnt vmcnt(1)
	v_cndmask_b32_e32 v100, 0, v100, vcc
	v_cndmask_b32_e32 v99, 0, v99, vcc
	s_cselect_b64 vcc, -1, 0
	s_and_b64 s[20:21], vcc, exec
	s_cselect_b32 s20, s71, s4
	s_ashr_i32 s21, s20, 31
	s_lshl_b64 s[62:63], s[20:21], 11
	v_lshl_add_u64 v[6:7], v[8:9], 0, s[62:63]
	s_add_i32 s20, s20, s14
	s_ashr_i32 s21, s20, 31
	s_lshl_b64 s[20:21], s[20:21], 2
	s_add_u32 s20, s26, s20
	s_addc_u32 s21, s27, s21
	s_or_b32 s70, s4, 23
	s_cmp_lt_u32 s70, s23
	s_waitcnt vmcnt(1)
	v_cndmask_b32_e32 v98, 0, v98, vcc
	v_cndmask_b32_e32 v31, 0, v31, vcc
	s_cselect_b64 vcc, -1, 0
	s_and_b64 s[20:21], vcc, exec
	s_cselect_b32 s20, s70, s4
	s_ashr_i32 s21, s20, 31
	s_lshl_b64 s[62:63], s[20:21], 11
	v_lshl_add_u64 v[6:7], v[8:9], 0, s[62:63]
	s_add_i32 s20, s20, s14
	s_ashr_i32 s21, s20, 31
	s_lshl_b64 s[20:21], s[20:21], 2
	s_add_u32 s20, s26, s20
	s_addc_u32 s21, s27, s21
	s_or_b32 s69, s4, 24
	s_cmp_lt_u32 s69, s23
	s_waitcnt vmcnt(1)
	v_cndmask_b32_e32 v95, 0, v95, vcc
	v_cndmask_b32_e32 v29, 0, v29, vcc
	s_cselect_b64 vcc, -1, 0
	s_and_b64 s[20:21], vcc, exec
	s_cselect_b32 s20, s69, s4
	s_ashr_i32 s21, s20, 31
	s_lshl_b64 s[62:63], s[20:21], 11
	v_lshl_add_u64 v[6:7], v[8:9], 0, s[62:63]
	s_add_i32 s20, s20, s14
	s_ashr_i32 s21, s20, 31
	s_lshl_b64 s[20:21], s[20:21], 2
	s_add_u32 s20, s26, s20
	s_addc_u32 s21, s27, s21
	s_or_b32 s68, s4, 25
	s_cmp_lt_u32 s68, s23
	s_waitcnt vmcnt(1)
	v_cndmask_b32_e32 v94, 0, v94, vcc
	v_cndmask_b32_e32 v27, 0, v27, vcc
	s_cselect_b64 vcc, -1, 0
	s_and_b64 s[20:21], vcc, exec
	s_cselect_b32 s20, s68, s4
	s_ashr_i32 s21, s20, 31
	s_lshl_b64 s[62:63], s[20:21], 11
	v_lshl_add_u64 v[6:7], v[8:9], 0, s[62:63]
	s_add_i32 s20, s20, s14
	s_ashr_i32 s21, s20, 31
	s_lshl_b64 s[20:21], s[20:21], 2
	s_add_u32 s20, s26, s20
	s_addc_u32 s21, s27, s21
	s_or_b32 s66, s4, 26
	s_cmp_lt_u32 s66, s23
	s_waitcnt vmcnt(1)
	v_cndmask_b32_e32 v93, 0, v93, vcc
	v_cndmask_b32_e32 v25, 0, v25, vcc
	s_cselect_b64 vcc, -1, 0
	s_and_b64 s[20:21], vcc, exec
	s_cselect_b32 s20, s66, s4
	s_ashr_i32 s21, s20, 31
	s_lshl_b64 s[62:63], s[20:21], 11
	v_lshl_add_u64 v[6:7], v[8:9], 0, s[62:63]
	s_add_i32 s20, s20, s14
	s_ashr_i32 s21, s20, 31
	s_lshl_b64 s[20:21], s[20:21], 2
	s_add_u32 s20, s26, s20
	s_addc_u32 s21, s27, s21
	s_or_b32 s67, s4, 27
	s_cmp_lt_u32 s67, s23
	s_waitcnt vmcnt(1)
	v_cndmask_b32_e32 v23, 0, v23, vcc
	v_cndmask_b32_e32 v21, 0, v21, vcc
	s_cselect_b64 vcc, -1, 0
	s_and_b64 s[20:21], vcc, exec
	s_cselect_b32 s20, s67, s4
	s_ashr_i32 s21, s20, 31
	s_lshl_b64 s[62:63], s[20:21], 11
	v_lshl_add_u64 v[6:7], v[8:9], 0, s[62:63]
	s_add_i32 s20, s20, s14
	s_ashr_i32 s21, s20, 31
	s_lshl_b64 s[20:21], s[20:21], 2
	s_add_u32 s20, s26, s20
	s_addc_u32 s21, s27, s21
	s_or_b32 s63, s4, 28
	s_cmp_lt_u32 s63, s23
	s_waitcnt vmcnt(1)
	v_cndmask_b32_e32 v92, 0, v92, vcc
	v_cndmask_b32_e32 v91, 0, v91, vcc
	s_cselect_b64 vcc, -1, 0
	s_and_b64 s[20:21], vcc, exec
	s_cselect_b32 s20, s63, s4
	s_ashr_i32 s21, s20, 31
	s_lshl_b64 s[96:97], s[20:21], 11
	v_lshl_add_u64 v[6:7], v[8:9], 0, s[96:97]
	s_add_i32 s20, s20, s14
	s_ashr_i32 s21, s20, 31
	s_lshl_b64 s[20:21], s[20:21], 2
	s_add_u32 s20, s26, s20
	s_addc_u32 s21, s27, s21
	s_or_b32 s34, s4, 29
	s_cmp_lt_u32 s34, s23
	s_waitcnt vmcnt(1)
	v_cndmask_b32_e32 v90, 0, v90, vcc
	v_cndmask_b32_e32 v19, 0, v19, vcc
	s_cselect_b64 vcc, -1, 0
	s_and_b64 s[20:21], vcc, exec
	s_cselect_b32 s20, s34, s4
	s_ashr_i32 s21, s20, 31
	s_lshl_b64 s[96:97], s[20:21], 11
	v_lshl_add_u64 v[6:7], v[8:9], 0, s[96:97]
	s_add_i32 s20, s20, s14
	s_ashr_i32 s21, s20, 31
	s_lshl_b64 s[20:21], s[20:21], 2
	s_add_u32 s20, s26, s20
	s_addc_u32 s21, s27, s21
	s_or_b32 s15, s4, 30
	s_cmp_lt_u32 s15, s23
	s_waitcnt vmcnt(1)
	v_cndmask_b32_e32 v89, 0, v89, vcc
	v_cndmask_b32_e32 v88, 0, v88, vcc
	s_cselect_b64 vcc, -1, 0
	s_and_b64 s[20:21], vcc, exec
	s_cselect_b32 s20, s15, s4
	s_ashr_i32 s21, s20, 31
	s_lshl_b64 s[96:97], s[20:21], 11
	v_lshl_add_u64 v[6:7], v[8:9], 0, s[96:97]
	s_add_i32 s20, s20, s14
	s_ashr_i32 s21, s20, 31
	s_lshl_b64 s[20:21], s[20:21], 2
	s_add_u32 s20, s26, s20
	s_addc_u32 s21, s27, s21
	s_or_b32 s5, s4, 31
	s_cmp_lt_u32 s5, s23
	s_waitcnt vmcnt(1)
	v_cndmask_b32_e32 v87, 0, v87, vcc
	v_cndmask_b32_e32 v86, 0, v86, vcc
	s_cselect_b64 vcc, -1, 0
	s_and_b64 s[20:21], vcc, exec
	s_cselect_b32 s20, s5, s4
	s_ashr_i32 s21, s20, 31
	s_lshl_b64 s[96:97], s[20:21], 11
	v_lshl_add_u64 v[6:7], v[8:9], 0, s[96:97]
	s_add_i32 s20, s20, s14
	s_ashr_i32 s21, s20, 31
	s_lshl_b64 s[20:21], s[20:21], 2
	s_add_u32 s20, s26, s20
	s_addc_u32 s21, s27, s21
	s_add_i32 s62, s4, 32
	s_cmp_lt_u32 s62, s23
	s_waitcnt vmcnt(0)
	v_cndmask_b32_e32 v13, 0, v134, vcc
	v_cndmask_b32_e32 v7, 0, v135, vcc
	s_cselect_b64 vcc, -1, 0
	global_load_dword v6, v97, s[20:21]
	s_waitcnt vmcnt(0)
	s_and_b64 s[20:21], vcc, exec
	s_cselect_b32 s20, s62, s4
	s_ashr_i32 s21, s20, 31
	s_lshl_b64 s[96:97], s[20:21], 11
	v_lshl_add_u64 v[8:9], v[8:9], 0, s[96:97]
	s_add_i32 s20, s20, s14
	s_ashr_i32 s21, s20, 31
	s_lshl_b64 s[20:21], s[20:21], 2
	s_add_u32 s20, s26, s20
	s_addc_u32 s21, s27, s21
	s_waitcnt vmcnt(0)
	v_cndmask_b32_e32 v17, 0, v136, vcc
	global_load_dword v8, v97, s[20:21]
	s_waitcnt vmcnt(0)
	s_lshl_b64 s[20:21], s[6:7], 11
	s_add_u32 s20, s24, s20
	s_addc_u32 s21, s25, s21
	v_lshl_add_u64 v[14:15], s[20:21], 0, v[96:97]
	v_lshl_add_u64 v[4:5], v[14:15], 0, s[30:31]
	s_max_i32 s7, s4, 2
	s_min_i32 s30, s90, s23
	s_sub_i32 s7, s30, s7
	s_add_i32 s7, s7, 2
	v_cvt_f32_i32_e32 v72, s7
	v_cndmask_b32_e32 v9, 0, v137, vcc
	s_max_i32 s7, s91, 2
	s_min_i32 s30, s89, s23
	v_div_scale_f32 v77, s[96:97], v72, v72, 1.0
	v_rcp_f32_e32 v79, v77
	s_sub_i32 s7, s30, s7
	s_add_i32 s7, s7, 2
	s_movk_i32 s91, 0x2000
	v_fma_f32 v81, -v77, v79, 1.0
	v_fmac_f32_e32 v79, v81, v79
	v_div_scale_f32 v81, vcc, 1.0, v72, 1.0
	v_mul_f32_e32 v128, v81, v79
	v_fma_f32 v129, -v77, v128, v81
	v_fmac_f32_e32 v128, v129, v79
	v_fma_f32 v77, -v77, v128, v81
	v_div_fmas_f32 v77, v77, v79, v128
	v_div_fixup_f32 v72, v77, v72, 1.0
	v_pk_fma_f32 v[128:129], v[72:73], v[120:121], v[84:85] op_sel_hi:[0,1,1] neg_lo:[0,0,1] neg_hi:[0,0,1]
	v_pk_fma_f32 v[130:131], v[72:73], v[126:127], v[82:83] op_sel_hi:[0,1,1] neg_lo:[0,0,1] neg_hi:[0,0,1]
	v_pk_mul_f32 v[128:129], v[0:1], v[128:129]
	v_pk_mul_f32 v[130:131], v[2:3], v[130:131]
	v_cvt_pk_bf16_f32 v128, v128, v129
	s_nop 0
	v_cvt_pk_bf16_f32 v129, v130, v131
	global_store_dwordx2 v96, v[128:129], s[20:21] offset:512
	v_lshlrev_b32_e32 v128, 16, v76
	v_and_b32_e32 v129, 0xffff0000, v76
	v_lshlrev_b32_e32 v130, 16, v73
	v_and_b32_e32 v131, 0xffff0000, v73
	v_pk_mul_f32 v[72:73], v[68:69], v[130:131] op_sel_hi:[0,1]
	v_pk_mul_f32 v[76:77], v[68:69], v[128:129] op_sel_hi:[0,1]
	v_pk_fma_f32 v[118:119], v[68:69], v[128:129], v[118:119] op_sel_hi:[0,1,1] neg_lo:[0,0,1] neg_hi:[0,0,1]
	v_pk_fma_f32 v[116:117], v[68:69], v[130:131], v[116:117] op_sel_hi:[0,1,1] neg_lo:[0,0,1] neg_hi:[0,0,1]
	v_cvt_f32_i32_e32 v68, s7
	v_pk_add_f32 v[118:119], v[120:121], v[118:119]
	v_pk_add_f32 v[116:117], v[126:127], v[116:117]
	s_max_i32 s7, s90, 2
	v_div_scale_f32 v79, s[96:97], v68, v68, 1.0
	v_rcp_f32_e32 v81, v79
	s_movk_i32 s97, 0x800
	v_readlane_b32 s96, v255, 13
	s_movk_i32 s90, 0xff00
	v_fma_f32 v120, -v79, v81, 1.0
	v_fmac_f32_e32 v81, v120, v81
	v_div_scale_f32 v120, vcc, 1.0, v68, 1.0
	v_mul_f32_e32 v121, v120, v81
	v_fma_f32 v126, -v79, v121, v120
	v_fmac_f32_e32 v121, v126, v81
	v_fma_f32 v79, -v79, v121, v120
	v_div_fmas_f32 v79, v79, v81, v121
	v_div_fixup_f32 v68, v79, v68, 1.0
	v_pk_fma_f32 v[120:121], v[68:69], v[118:119], v[74:75] op_sel_hi:[0,1,1] neg_lo:[0,0,1] neg_hi:[0,0,1]
	v_pk_fma_f32 v[126:127], v[68:69], v[116:117], v[70:71] op_sel_hi:[0,1,1] neg_lo:[0,0,1] neg_hi:[0,0,1]
	v_pk_mul_f32 v[120:121], v[0:1], v[120:121]
	v_pk_mul_f32 v[126:127], v[2:3], v[126:127]
	v_cvt_pk_bf16_f32 v120, v120, v121
	s_nop 0
	v_cvt_pk_bf16_f32 v121, v126, v127
	global_store_dwordx2 v96, v[120:121], s[20:21] offset:2560
	s_min_i32 s20, s88, s23
	s_sub_i32 s7, s20, s7
	v_lshlrev_b32_e32 v120, 16, v78
	v_and_b32_e32 v121, 0xffff0000, v78
	v_lshlrev_b32_e32 v126, 16, v69
	v_and_b32_e32 v127, 0xffff0000, v69
	s_add_i32 s7, s7, 2
	v_pk_mul_f32 v[68:69], v[66:67], v[126:127] op_sel_hi:[0,1]
	v_pk_mul_f32 v[78:79], v[66:67], v[120:121] op_sel_hi:[0,1]
	v_pk_fma_f32 v[120:121], v[66:67], v[120:121], v[124:125] op_sel_hi:[0,1,1] neg_lo:[0,0,1] neg_hi:[0,0,1]
	v_pk_fma_f32 v[122:123], v[66:67], v[126:127], v[122:123] op_sel_hi:[0,1,1] neg_lo:[0,0,1] neg_hi:[0,0,1]
	v_cvt_f32_i32_e32 v66, s7
	v_pk_add_f32 v[118:119], v[118:119], v[120:121]
	v_pk_add_f32 v[116:117], v[116:117], v[122:123]
	s_max_i32 s7, s89, 2
	v_div_scale_f32 v81, s[20:21], v66, v66, 1.0
	v_rcp_f32_e32 v96, v81
	s_min_i32 s20, s87, s23
	s_sub_i32 s7, s20, s7
	v_lshlrev_b32_e32 v124, 16, v67
	v_fma_f32 v120, -v81, v96, 1.0
	v_fmac_f32_e32 v96, v120, v96
	v_div_scale_f32 v120, vcc, 1.0, v66, 1.0
	v_mul_f32_e32 v121, v120, v96
	v_fma_f32 v122, -v81, v121, v120
	v_fmac_f32_e32 v121, v122, v96
	v_fma_f32 v81, -v81, v121, v120
	v_div_fmas_f32 v81, v81, v96, v121
	v_div_fixup_f32 v66, v81, v66, 1.0
	v_pk_fma_f32 v[120:121], v[66:67], v[118:119], v[76:77] op_sel_hi:[0,1,1] neg_lo:[0,0,1] neg_hi:[0,0,1]
	v_pk_fma_f32 v[122:123], v[66:67], v[116:117], v[72:73] op_sel_hi:[0,1,1] neg_lo:[0,0,1] neg_hi:[0,0,1]
	v_pk_mul_f32 v[122:123], v[2:3], v[122:123]
	v_pk_mul_f32 v[120:121], v[0:1], v[120:121]
	v_and_b32_e32 v125, 0xffff0000, v67
	v_cvt_pk_bf16_f32 v120, v120, v121
	v_cvt_pk_bf16_f32 v121, v122, v123
	v_add_co_u32_e32 v122, vcc, s92, v14
	s_add_i32 s7, s7, 2
	s_nop 0
	v_addc_co_u32_e32 v123, vcc, 0, v15, vcc
	global_store_dwordx2 v[122:123], v[120:121], off offset:512
	v_lshlrev_b32_e32 v120, 16, v80
	v_and_b32_e32 v121, 0xffff0000, v80
	v_pk_mul_f32 v[66:67], v[64:65], v[124:125] op_sel_hi:[0,1]
	v_pk_mul_f32 v[80:81], v[64:65], v[120:121] op_sel_hi:[0,1]
	v_pk_fma_f32 v[84:85], v[64:65], v[120:121], v[84:85] op_sel_hi:[0,1,1] neg_lo:[0,0,1] neg_hi:[0,0,1]
	v_pk_fma_f32 v[82:83], v[64:65], v[124:125], v[82:83] op_sel_hi:[0,1,1] neg_lo:[0,0,1] neg_hi:[0,0,1]
	v_cvt_f32_i32_e32 v64, s7
	v_pk_add_f32 v[116:117], v[116:117], v[82:83]
	v_pk_add_f32 v[84:85], v[118:119], v[84:85]
	s_max_i32 s7, s88, 2
	v_div_scale_f32 v82, s[20:21], v64, v64, 1.0
	v_rcp_f32_e32 v83, v82
	s_min_i32 s20, s86, s23
	s_sub_i32 s7, s20, s7
	v_lshlrev_b32_e32 v120, 16, v65
	v_fma_f32 v96, -v82, v83, 1.0
	v_fmac_f32_e32 v83, v96, v83
	v_div_scale_f32 v96, vcc, 1.0, v64, 1.0
	v_mul_f32_e32 v118, v96, v83
	v_fma_f32 v119, -v82, v118, v96
	v_fmac_f32_e32 v118, v119, v83
	v_fma_f32 v82, -v82, v118, v96
	v_div_fmas_f32 v82, v82, v83, v118
	v_div_fixup_f32 v64, v82, v64, 1.0
	v_pk_fma_f32 v[82:83], v[64:65], v[84:85], v[78:79] op_sel_hi:[0,1,1] neg_lo:[0,0,1] neg_hi:[0,0,1]
	v_pk_fma_f32 v[118:119], v[64:65], v[116:117], v[68:69] op_sel_hi:[0,1,1] neg_lo:[0,0,1] neg_hi:[0,0,1]
	v_pk_mul_f32 v[118:119], v[2:3], v[118:119]
	v_pk_mul_f32 v[82:83], v[0:1], v[82:83]
	v_and_b32_e32 v121, 0xffff0000, v65
	v_cvt_pk_bf16_f32 v82, v82, v83
	v_cvt_pk_bf16_f32 v83, v118, v119
	v_lshlrev_b32_e32 v118, 16, v115
	v_and_b32_e32 v119, 0xffff0000, v115
	s_add_i32 s7, s7, 2
	global_store_dwordx2 v[122:123], v[82:83], off offset:2560
	v_pk_mul_f32 v[64:65], v[62:63], v[120:121] op_sel_hi:[0,1]
	v_pk_mul_f32 v[82:83], v[62:63], v[118:119] op_sel_hi:[0,1]
	v_pk_fma_f32 v[74:75], v[62:63], v[118:119], v[74:75] op_sel_hi:[0,1,1] neg_lo:[0,0,1] neg_hi:[0,0,1]
	v_pk_fma_f32 v[70:71], v[62:63], v[120:121], v[70:71] op_sel_hi:[0,1,1] neg_lo:[0,0,1] neg_hi:[0,0,1]
	v_cvt_f32_i32_e32 v62, s7
	v_pk_add_f32 v[116:117], v[116:117], v[70:71]
	v_pk_add_f32 v[74:75], v[84:85], v[74:75]
	s_max_i32 s7, s87, 2
	v_div_scale_f32 v70, s[20:21], v62, v62, 1.0
	v_rcp_f32_e32 v71, v70
	s_min_i32 s20, s85, s23
	s_sub_i32 s7, s20, s7
	v_lshlrev_b32_e32 v118, 16, v114
	v_fma_f32 v84, -v70, v71, 1.0
	v_fmac_f32_e32 v71, v84, v71
	v_div_scale_f32 v84, vcc, 1.0, v62, 1.0
	v_mul_f32_e32 v85, v84, v71
	v_fma_f32 v96, -v70, v85, v84
	v_fmac_f32_e32 v85, v96, v71
	v_fma_f32 v70, -v70, v85, v84
	v_div_fmas_f32 v70, v70, v71, v85
	v_div_fixup_f32 v62, v70, v62, 1.0
	v_pk_fma_f32 v[70:71], v[62:63], v[74:75], v[80:81] op_sel_hi:[0,1,1] neg_lo:[0,0,1] neg_hi:[0,0,1]
	v_pk_fma_f32 v[84:85], v[62:63], v[116:117], v[66:67] op_sel_hi:[0,1,1] neg_lo:[0,0,1] neg_hi:[0,0,1]
	v_pk_mul_f32 v[84:85], v[2:3], v[84:85]
	v_pk_mul_f32 v[70:71], v[0:1], v[70:71]
	v_and_b32_e32 v119, 0xffff0000, v114
	v_cvt_pk_bf16_f32 v70, v70, v71
	v_cvt_pk_bf16_f32 v71, v84, v85
	v_add_co_u32_e32 v84, vcc, s91, v14
	v_lshlrev_b32_e32 v114, 16, v63
	s_nop 0
	v_addc_co_u32_e32 v85, vcc, 0, v15, vcc
	v_and_b32_e32 v115, 0xffff0000, v63
	s_add_i32 s7, s7, 2
	global_store_dwordx2 v[84:85], v[70:71], off offset:512
	v_pk_mul_f32 v[62:63], v[60:61], v[114:115] op_sel_hi:[0,1]
	v_pk_mul_f32 v[70:71], v[60:61], v[118:119] op_sel_hi:[0,1]
	v_pk_fma_f32 v[76:77], v[60:61], v[118:119], v[76:77] op_sel_hi:[0,1,1] neg_lo:[0,0,1] neg_hi:[0,0,1]
	v_pk_fma_f32 v[72:73], v[60:61], v[114:115], v[72:73] op_sel_hi:[0,1,1] neg_lo:[0,0,1] neg_hi:[0,0,1]
	v_cvt_f32_i32_e32 v60, s7
	v_pk_add_f32 v[114:115], v[116:117], v[72:73]
	v_pk_add_f32 v[74:75], v[74:75], v[76:77]
	s_max_i32 s7, s86, 2
	v_div_scale_f32 v72, s[20:21], v60, v60, 1.0
	v_rcp_f32_e32 v73, v72
	s_min_i32 s20, s84, s23
	s_sub_i32 s7, s20, s7
	s_add_i32 s7, s7, 2
	v_fma_f32 v76, -v72, v73, 1.0
	v_fmac_f32_e32 v73, v76, v73
	v_div_scale_f32 v76, vcc, 1.0, v60, 1.0
	v_mul_f32_e32 v77, v76, v73
	v_fma_f32 v96, -v72, v77, v76
	v_fmac_f32_e32 v77, v96, v73
	v_fma_f32 v72, -v72, v77, v76
	v_div_fmas_f32 v72, v72, v73, v77
	v_div_fixup_f32 v60, v72, v60, 1.0
	v_pk_fma_f32 v[72:73], v[60:61], v[74:75], v[82:83] op_sel_hi:[0,1,1] neg_lo:[0,0,1] neg_hi:[0,0,1]
	v_pk_fma_f32 v[76:77], v[60:61], v[114:115], v[64:65] op_sel_hi:[0,1,1] neg_lo:[0,0,1] neg_hi:[0,0,1]
	v_pk_mul_f32 v[76:77], v[2:3], v[76:77]
	v_pk_mul_f32 v[72:73], v[0:1], v[72:73]
	s_nop 0
	v_cvt_pk_bf16_f32 v72, v72, v73
	v_cvt_pk_bf16_f32 v73, v76, v77
	global_store_dwordx2 v[84:85], v[72:73], off offset:2560
	v_lshlrev_b32_e32 v76, 16, v113
	v_and_b32_e32 v77, 0xffff0000, v113
	v_lshlrev_b32_e32 v84, 16, v61
	v_and_b32_e32 v85, 0xffff0000, v61
	v_pk_mul_f32 v[60:61], v[58:59], v[84:85] op_sel_hi:[0,1]
	v_pk_mul_f32 v[72:73], v[58:59], v[76:77] op_sel_hi:[0,1]
	v_pk_fma_f32 v[76:77], v[58:59], v[76:77], v[78:79] op_sel_hi:[0,1,1] neg_lo:[0,0,1] neg_hi:[0,0,1]
	v_pk_fma_f32 v[68:69], v[58:59], v[84:85], v[68:69] op_sel_hi:[0,1,1] neg_lo:[0,0,1] neg_hi:[0,0,1]
	v_cvt_f32_i32_e32 v58, s7
	v_pk_add_f32 v[78:79], v[114:115], v[68:69]
	v_pk_add_f32 v[74:75], v[74:75], v[76:77]
	s_movk_i32 s7, 0x3000
	v_div_scale_f32 v68, s[20:21], v58, v58, 1.0
	v_rcp_f32_e32 v69, v68
	s_min_i32 s20, s83, s23
	v_and_b32_e32 v85, 0xffff0000, v112
	v_and_b32_e32 v113, 0xffff0000, v59
	v_fma_f32 v76, -v68, v69, 1.0
	v_fmac_f32_e32 v69, v76, v69
	v_div_scale_f32 v76, vcc, 1.0, v58, 1.0
	v_mul_f32_e32 v77, v76, v69
	v_fma_f32 v84, -v68, v77, v76
	v_fmac_f32_e32 v77, v84, v69
	v_fma_f32 v68, -v68, v77, v76
	v_div_fmas_f32 v68, v68, v69, v77
	v_div_fixup_f32 v58, v68, v58, 1.0
	v_pk_fma_f32 v[68:69], v[58:59], v[74:75], v[70:71] op_sel_hi:[0,1,1] neg_lo:[0,0,1] neg_hi:[0,0,1]
	v_pk_fma_f32 v[76:77], v[58:59], v[78:79], v[62:63] op_sel_hi:[0,1,1] neg_lo:[0,0,1] neg_hi:[0,0,1]
	v_pk_mul_f32 v[76:77], v[2:3], v[76:77]
	v_pk_mul_f32 v[68:69], v[0:1], v[68:69]
	v_lshlrev_b32_e32 v84, 16, v112
	v_cvt_pk_bf16_f32 v68, v68, v69
	v_cvt_pk_bf16_f32 v69, v76, v77
	v_add_co_u32_e32 v76, vcc, s7, v14
	s_max_i32 s7, s85, 2
	s_sub_i32 s7, s20, s7
	v_addc_co_u32_e32 v77, vcc, 0, v15, vcc
	v_lshlrev_b32_e32 v112, 16, v59
	s_add_i32 s7, s7, 2
	global_store_dwordx2 v[76:77], v[68:69], off offset:512
	v_pk_mul_f32 v[58:59], v[56:57], v[112:113] op_sel_hi:[0,1]
	v_pk_mul_f32 v[68:69], v[56:57], v[84:85] op_sel_hi:[0,1]
	v_pk_fma_f32 v[80:81], v[56:57], v[84:85], v[80:81] op_sel_hi:[0,1,1] neg_lo:[0,0,1] neg_hi:[0,0,1]
	v_pk_fma_f32 v[66:67], v[56:57], v[112:113], v[66:67] op_sel_hi:[0,1,1] neg_lo:[0,0,1] neg_hi:[0,0,1]
	v_cvt_f32_i32_e32 v56, s7
	v_pk_add_f32 v[78:79], v[78:79], v[66:67]
	v_pk_add_f32 v[74:75], v[74:75], v[80:81]
	s_max_i32 s7, s84, 2
	v_div_scale_f32 v66, s[20:21], v56, v56, 1.0
	v_rcp_f32_e32 v67, v66
	s_min_i32 s20, s82, s23
	s_sub_i32 s7, s20, s7
	s_add_i32 s7, s7, 2
	v_fma_f32 v80, -v66, v67, 1.0
	v_fmac_f32_e32 v67, v80, v67
	v_div_scale_f32 v80, vcc, 1.0, v56, 1.0
	v_mul_f32_e32 v81, v80, v67
	v_fma_f32 v84, -v66, v81, v80
	v_fmac_f32_e32 v81, v84, v67
	v_fma_f32 v66, -v66, v81, v80
	v_div_fmas_f32 v66, v66, v67, v81
	v_div_fixup_f32 v56, v66, v56, 1.0
	v_pk_fma_f32 v[66:67], v[56:57], v[74:75], v[72:73] op_sel_hi:[0,1,1] neg_lo:[0,0,1] neg_hi:[0,0,1]
	v_pk_fma_f32 v[80:81], v[56:57], v[78:79], v[60:61] op_sel_hi:[0,1,1] neg_lo:[0,0,1] neg_hi:[0,0,1]
	v_pk_mul_f32 v[80:81], v[2:3], v[80:81]
	v_pk_mul_f32 v[66:67], v[0:1], v[66:67]
	s_nop 0
	v_cvt_pk_bf16_f32 v66, v66, v67
	v_cvt_pk_bf16_f32 v67, v80, v81
	global_store_dwordx2 v[76:77], v[66:67], off offset:2560
	v_lshlrev_b32_e32 v76, 16, v111
	v_and_b32_e32 v77, 0xffff0000, v111
	v_lshlrev_b32_e32 v80, 16, v57
	v_and_b32_e32 v81, 0xffff0000, v57
	v_pk_mul_f32 v[56:57], v[54:55], v[80:81] op_sel_hi:[0,1]
	v_pk_mul_f32 v[66:67], v[54:55], v[76:77] op_sel_hi:[0,1]
	v_pk_fma_f32 v[76:77], v[54:55], v[76:77], v[82:83] op_sel_hi:[0,1,1] neg_lo:[0,0,1] neg_hi:[0,0,1]
	v_pk_fma_f32 v[64:65], v[54:55], v[80:81], v[64:65] op_sel_hi:[0,1,1] neg_lo:[0,0,1] neg_hi:[0,0,1]
	v_cvt_f32_i32_e32 v54, s7
	v_pk_add_f32 v[78:79], v[78:79], v[64:65]
	v_pk_add_f32 v[74:75], v[74:75], v[76:77]
	s_max_i32 s7, s83, 2
	v_div_scale_f32 v64, s[20:21], v54, v54, 1.0
	v_rcp_f32_e32 v65, v64
	s_min_i32 s20, s81, s23
	s_sub_i32 s7, s20, s7
	v_and_b32_e32 v81, 0xffff0000, v110
	v_fma_f32 v76, -v64, v65, 1.0
	v_fmac_f32_e32 v65, v76, v65
	v_div_scale_f32 v76, vcc, 1.0, v54, 1.0
	v_mul_f32_e32 v77, v76, v65
	v_fma_f32 v80, -v64, v77, v76
	v_fmac_f32_e32 v77, v80, v65
	v_fma_f32 v64, -v64, v77, v76
	v_div_fmas_f32 v64, v64, v65, v77
	v_div_fixup_f32 v54, v64, v54, 1.0
	v_pk_fma_f32 v[64:65], v[54:55], v[74:75], v[68:69] op_sel_hi:[0,1,1] neg_lo:[0,0,1] neg_hi:[0,0,1]
	v_pk_fma_f32 v[76:77], v[54:55], v[78:79], v[58:59] op_sel_hi:[0,1,1] neg_lo:[0,0,1] neg_hi:[0,0,1]
	v_pk_mul_f32 v[76:77], v[2:3], v[76:77]
	v_pk_mul_f32 v[64:65], v[0:1], v[64:65]
	v_lshlrev_b32_e32 v80, 16, v110
	v_cvt_pk_bf16_f32 v64, v64, v65
	v_cvt_pk_bf16_f32 v65, v76, v77
	v_add_co_u32_e32 v76, vcc, s9, v14
	v_lshlrev_b32_e32 v82, 16, v55
	s_nop 0
	v_addc_co_u32_e32 v77, vcc, 0, v15, vcc
	v_and_b32_e32 v83, 0xffff0000, v55
	s_add_i32 s7, s7, 2
	global_store_dwordx2 v[76:77], v[64:65], off offset:512
	v_pk_mul_f32 v[54:55], v[52:53], v[82:83] op_sel_hi:[0,1]
	v_pk_mul_f32 v[64:65], v[52:53], v[80:81] op_sel_hi:[0,1]
	v_pk_fma_f32 v[70:71], v[52:53], v[80:81], v[70:71] op_sel_hi:[0,1,1] neg_lo:[0,0,1] neg_hi:[0,0,1]
	v_pk_fma_f32 v[62:63], v[52:53], v[82:83], v[62:63] op_sel_hi:[0,1,1] neg_lo:[0,0,1] neg_hi:[0,0,1]
	v_cvt_f32_i32_e32 v52, s7
	v_pk_add_f32 v[78:79], v[78:79], v[62:63]
	v_pk_add_f32 v[70:71], v[74:75], v[70:71]
	s_max_i32 s7, s82, 2
	v_div_scale_f32 v62, s[20:21], v52, v52, 1.0
	v_rcp_f32_e32 v63, v62
	s_min_i32 s20, s80, s23
	s_sub_i32 s7, s20, s7
	s_add_i32 s7, s7, 2
	v_fma_f32 v74, -v62, v63, 1.0
	v_fmac_f32_e32 v63, v74, v63
	v_div_scale_f32 v74, vcc, 1.0, v52, 1.0
	v_mul_f32_e32 v75, v74, v63
	v_fma_f32 v80, -v62, v75, v74
	v_fmac_f32_e32 v75, v80, v63
	v_fma_f32 v62, -v62, v75, v74
	v_div_fmas_f32 v62, v62, v63, v75
	v_div_fixup_f32 v52, v62, v52, 1.0
	v_pk_fma_f32 v[62:63], v[52:53], v[70:71], v[66:67] op_sel_hi:[0,1,1] neg_lo:[0,0,1] neg_hi:[0,0,1]
	v_pk_fma_f32 v[74:75], v[52:53], v[78:79], v[56:57] op_sel_hi:[0,1,1] neg_lo:[0,0,1] neg_hi:[0,0,1]
	v_pk_mul_f32 v[74:75], v[2:3], v[74:75]
	v_pk_mul_f32 v[62:63], v[0:1], v[62:63]
	s_nop 0
	v_cvt_pk_bf16_f32 v62, v62, v63
	v_cvt_pk_bf16_f32 v63, v74, v75
	global_store_dwordx2 v[76:77], v[62:63], off offset:2560
	v_lshlrev_b32_e32 v74, 16, v109
	v_and_b32_e32 v75, 0xffff0000, v109
	v_lshlrev_b32_e32 v76, 16, v53
	v_and_b32_e32 v77, 0xffff0000, v53
	v_pk_mul_f32 v[52:53], v[50:51], v[76:77] op_sel_hi:[0,1]
	v_pk_mul_f32 v[62:63], v[50:51], v[74:75] op_sel_hi:[0,1]
	v_pk_fma_f32 v[72:73], v[50:51], v[74:75], v[72:73] op_sel_hi:[0,1,1] neg_lo:[0,0,1] neg_hi:[0,0,1]
	v_pk_fma_f32 v[60:61], v[50:51], v[76:77], v[60:61] op_sel_hi:[0,1,1] neg_lo:[0,0,1] neg_hi:[0,0,1]
	v_cvt_f32_i32_e32 v50, s7
	v_pk_add_f32 v[74:75], v[78:79], v[60:61]
	v_pk_add_f32 v[70:71], v[70:71], v[72:73]
	s_max_i32 s7, s81, 2
	v_div_scale_f32 v60, s[20:21], v50, v50, 1.0
	v_rcp_f32_e32 v61, v60
	s_min_i32 s20, s79, s23
	v_and_b32_e32 v77, 0xffff0000, v51
	v_lshlrev_b32_e32 v78, 16, v47
	v_fma_f32 v72, -v60, v61, 1.0
	v_fmac_f32_e32 v61, v72, v61
	v_div_scale_f32 v72, vcc, 1.0, v50, 1.0
	v_mul_f32_e32 v73, v72, v61
	v_fma_f32 v76, -v60, v73, v72
	v_fmac_f32_e32 v73, v76, v61
	v_fma_f32 v60, -v60, v73, v72
	v_div_fmas_f32 v60, v60, v61, v73
	v_div_fixup_f32 v50, v60, v50, 1.0
	v_pk_fma_f32 v[60:61], v[50:51], v[70:71], v[64:65] op_sel_hi:[0,1,1] neg_lo:[0,0,1] neg_hi:[0,0,1]
	v_pk_fma_f32 v[72:73], v[50:51], v[74:75], v[54:55] op_sel_hi:[0,1,1] neg_lo:[0,0,1] neg_hi:[0,0,1]
	v_pk_mul_f32 v[72:73], v[2:3], v[72:73]
	v_pk_mul_f32 v[60:61], v[0:1], v[60:61]
	v_lshlrev_b32_e32 v76, 16, v51
	v_cvt_pk_bf16_f32 v60, v60, v61
	v_cvt_pk_bf16_f32 v61, v72, v73
	v_add_co_u32_e32 v72, vcc, s38, v14
	v_and_b32_e32 v79, 0xffff0000, v47
	s_nop 0
	v_addc_co_u32_e32 v73, vcc, 0, v15, vcc
	s_sub_i32 s7, s20, s7
	global_store_dwordx2 v[72:73], v[60:61], off offset:512
	v_pk_mul_f32 v[50:51], v[46:47], v[78:79] op_sel_hi:[0,1]
	v_pk_mul_f32 v[60:61], v[46:47], v[76:77] op_sel_hi:[0,1]
	v_pk_fma_f32 v[68:69], v[46:47], v[76:77], v[68:69] op_sel_hi:[0,1,1] neg_lo:[0,0,1] neg_hi:[0,0,1]
	v_pk_fma_f32 v[46:47], v[46:47], v[78:79], v[58:59] op_sel_hi:[0,1,1] neg_lo:[0,0,1] neg_hi:[0,0,1]
	s_add_i32 s7, s7, 2
	v_pk_add_f32 v[74:75], v[74:75], v[46:47]
	v_cvt_f32_i32_e32 v46, s7
	v_pk_add_f32 v[68:69], v[70:71], v[68:69]
	s_max_i32 s7, s80, 2
	v_div_scale_f32 v47, s[20:21], v46, v46, 1.0
	v_rcp_f32_e32 v58, v47
	s_min_i32 s20, s35, s23
	s_sub_i32 s7, s20, s7
	s_add_i32 s7, s7, 2
	v_fma_f32 v59, -v47, v58, 1.0
	v_fmac_f32_e32 v58, v59, v58
	v_div_scale_f32 v59, vcc, 1.0, v46, 1.0
	v_mul_f32_e32 v70, v59, v58
	v_fma_f32 v71, -v47, v70, v59
	v_fmac_f32_e32 v70, v71, v58
	v_fma_f32 v47, -v47, v70, v59
	v_div_fmas_f32 v47, v47, v58, v70
	v_div_fixup_f32 v46, v47, v46, 1.0
	v_pk_fma_f32 v[58:59], v[46:47], v[68:69], v[62:63] op_sel_hi:[0,1,1] neg_lo:[0,0,1] neg_hi:[0,0,1]
	v_pk_fma_f32 v[46:47], v[46:47], v[74:75], v[52:53] op_sel_hi:[0,1,1] neg_lo:[0,0,1] neg_hi:[0,0,1]
	v_pk_mul_f32 v[58:59], v[0:1], v[58:59]
	v_pk_mul_f32 v[46:47], v[2:3], v[46:47]
	v_cvt_pk_bf16_f32 v58, v58, v59
	v_lshlrev_b32_e32 v70, 16, v108
	v_cvt_pk_bf16_f32 v59, v46, v47
	global_store_dwordx2 v[72:73], v[58:59], off offset:2560
	v_and_b32_e32 v71, 0xffff0000, v108
	v_lshlrev_b32_e32 v72, 16, v107
	v_and_b32_e32 v73, 0xffff0000, v107
	v_pk_mul_f32 v[46:47], v[48:49], v[72:73] op_sel_hi:[0,1]
	v_pk_mul_f32 v[58:59], v[48:49], v[70:71] op_sel_hi:[0,1]
	v_pk_fma_f32 v[66:67], v[48:49], v[70:71], v[66:67] op_sel_hi:[0,1,1] neg_lo:[0,0,1] neg_hi:[0,0,1]
	v_pk_fma_f32 v[56:57], v[48:49], v[72:73], v[56:57] op_sel_hi:[0,1,1] neg_lo:[0,0,1] neg_hi:[0,0,1]
	v_cvt_f32_i32_e32 v48, s7
	v_pk_add_f32 v[70:71], v[74:75], v[56:57]
	v_pk_add_f32 v[66:67], v[68:69], v[66:67]
	s_max_i32 s7, s79, 2
	v_div_scale_f32 v56, s[20:21], v48, v48, 1.0
	v_rcp_f32_e32 v57, v56
	s_min_i32 s20, s78, s23
	s_sub_i32 s7, s20, s7
	v_and_b32_e32 v73, 0xffff0000, v106
	v_fma_f32 v68, -v56, v57, 1.0
	v_fmac_f32_e32 v57, v68, v57
	v_div_scale_f32 v68, vcc, 1.0, v48, 1.0
	v_mul_f32_e32 v69, v68, v57
	v_fma_f32 v72, -v56, v69, v68
	v_fmac_f32_e32 v69, v72, v57
	v_fma_f32 v56, -v56, v69, v68
	v_div_fmas_f32 v56, v56, v57, v69
	v_div_fixup_f32 v48, v56, v48, 1.0
	v_pk_fma_f32 v[56:57], v[48:49], v[66:67], v[60:61] op_sel_hi:[0,1,1] neg_lo:[0,0,1] neg_hi:[0,0,1]
	v_pk_fma_f32 v[68:69], v[48:49], v[70:71], v[50:51] op_sel_hi:[0,1,1] neg_lo:[0,0,1] neg_hi:[0,0,1]
	v_pk_mul_f32 v[68:69], v[2:3], v[68:69]
	v_pk_mul_f32 v[56:57], v[0:1], v[56:57]
	v_lshlrev_b32_e32 v72, 16, v106
	v_cvt_pk_bf16_f32 v56, v56, v57
	v_cvt_pk_bf16_f32 v57, v68, v69
	v_add_co_u32_e32 v68, vcc, s39, v14
	v_lshlrev_b32_e32 v74, 16, v49
	s_nop 0
	v_addc_co_u32_e32 v69, vcc, 0, v15, vcc
	v_and_b32_e32 v75, 0xffff0000, v49
	s_add_i32 s7, s7, 2
	global_store_dwordx2 v[68:69], v[56:57], off offset:512
	v_pk_mul_f32 v[48:49], v[44:45], v[74:75] op_sel_hi:[0,1]
	v_pk_mul_f32 v[56:57], v[44:45], v[72:73] op_sel_hi:[0,1]
	v_pk_fma_f32 v[64:65], v[44:45], v[72:73], v[64:65] op_sel_hi:[0,1,1] neg_lo:[0,0,1] neg_hi:[0,0,1]
	v_pk_fma_f32 v[54:55], v[44:45], v[74:75], v[54:55] op_sel_hi:[0,1,1] neg_lo:[0,0,1] neg_hi:[0,0,1]
	v_cvt_f32_i32_e32 v44, s7
	v_pk_add_f32 v[70:71], v[70:71], v[54:55]
	v_pk_add_f32 v[64:65], v[66:67], v[64:65]
	s_max_i32 s7, s35, 2
	v_div_scale_f32 v54, s[20:21], v44, v44, 1.0
	v_rcp_f32_e32 v55, v54
	s_min_i32 s20, s77, s23
	s_sub_i32 s7, s20, s7
	s_add_i32 s7, s7, 2
	v_fma_f32 v66, -v54, v55, 1.0
	v_fmac_f32_e32 v55, v66, v55
	v_div_scale_f32 v66, vcc, 1.0, v44, 1.0
	v_mul_f32_e32 v67, v66, v55
	v_fma_f32 v72, -v54, v67, v66
	v_fmac_f32_e32 v67, v72, v55
	v_fma_f32 v54, -v54, v67, v66
	v_div_fmas_f32 v54, v54, v55, v67
	v_div_fixup_f32 v44, v54, v44, 1.0
	v_pk_fma_f32 v[54:55], v[44:45], v[64:65], v[58:59] op_sel_hi:[0,1,1] neg_lo:[0,0,1] neg_hi:[0,0,1]
	v_pk_fma_f32 v[66:67], v[44:45], v[70:71], v[46:47] op_sel_hi:[0,1,1] neg_lo:[0,0,1] neg_hi:[0,0,1]
	v_pk_mul_f32 v[66:67], v[2:3], v[66:67]
	v_pk_mul_f32 v[54:55], v[0:1], v[54:55]
	s_nop 0
	v_cvt_pk_bf16_f32 v54, v54, v55
	v_cvt_pk_bf16_f32 v55, v66, v67
	global_store_dwordx2 v[68:69], v[54:55], off offset:2560
	v_lshlrev_b32_e32 v66, 16, v105
	v_and_b32_e32 v67, 0xffff0000, v105
	v_lshlrev_b32_e32 v68, 16, v45
	v_and_b32_e32 v69, 0xffff0000, v45
	v_pk_mul_f32 v[44:45], v[42:43], v[68:69] op_sel_hi:[0,1]
	v_pk_mul_f32 v[54:55], v[42:43], v[66:67] op_sel_hi:[0,1]
	v_pk_fma_f32 v[62:63], v[42:43], v[66:67], v[62:63] op_sel_hi:[0,1,1] neg_lo:[0,0,1] neg_hi:[0,0,1]
	v_pk_fma_f32 v[52:53], v[42:43], v[68:69], v[52:53] op_sel_hi:[0,1,1] neg_lo:[0,0,1] neg_hi:[0,0,1]
	v_cvt_f32_i32_e32 v42, s7
	v_pk_add_f32 v[66:67], v[70:71], v[52:53]
	v_pk_add_f32 v[62:63], v[64:65], v[62:63]
	s_movk_i32 s7, 0x7000
	v_div_scale_f32 v52, s[20:21], v42, v42, 1.0
	v_rcp_f32_e32 v53, v52
	s_min_i32 s20, s76, s23
	v_and_b32_e32 v69, 0xffff0000, v104
	v_lshlrev_b32_e32 v70, 16, v43
	v_fma_f32 v64, -v52, v53, 1.0
	v_fmac_f32_e32 v53, v64, v53
	v_div_scale_f32 v64, vcc, 1.0, v42, 1.0
	v_mul_f32_e32 v65, v64, v53
	v_fma_f32 v68, -v52, v65, v64
	v_fmac_f32_e32 v65, v68, v53
	v_fma_f32 v52, -v52, v65, v64
	v_div_fmas_f32 v52, v52, v53, v65
	v_div_fixup_f32 v42, v52, v42, 1.0
	v_pk_fma_f32 v[52:53], v[42:43], v[62:63], v[56:57] op_sel_hi:[0,1,1] neg_lo:[0,0,1] neg_hi:[0,0,1]
	v_pk_fma_f32 v[64:65], v[42:43], v[66:67], v[48:49] op_sel_hi:[0,1,1] neg_lo:[0,0,1] neg_hi:[0,0,1]
	v_pk_mul_f32 v[64:65], v[2:3], v[64:65]
	v_pk_mul_f32 v[52:53], v[0:1], v[52:53]
	v_lshlrev_b32_e32 v68, 16, v104
	v_cvt_pk_bf16_f32 v52, v52, v53
	v_cvt_pk_bf16_f32 v53, v64, v65
	v_add_co_u32_e32 v64, vcc, s7, v14
	s_max_i32 s7, s78, 2
	s_sub_i32 s7, s20, s7
	v_addc_co_u32_e32 v65, vcc, 0, v15, vcc
	v_and_b32_e32 v71, 0xffff0000, v43
	s_add_i32 s7, s7, 2
	global_store_dwordx2 v[64:65], v[52:53], off offset:512
	v_pk_mul_f32 v[42:43], v[40:41], v[70:71] op_sel_hi:[0,1]
	v_pk_mul_f32 v[52:53], v[40:41], v[68:69] op_sel_hi:[0,1]
	v_pk_fma_f32 v[60:61], v[40:41], v[68:69], v[60:61] op_sel_hi:[0,1,1] neg_lo:[0,0,1] neg_hi:[0,0,1]
	v_pk_fma_f32 v[50:51], v[40:41], v[70:71], v[50:51] op_sel_hi:[0,1,1] neg_lo:[0,0,1] neg_hi:[0,0,1]
	v_cvt_f32_i32_e32 v40, s7
	v_pk_add_f32 v[66:67], v[66:67], v[50:51]
	v_pk_add_f32 v[60:61], v[62:63], v[60:61]
	s_max_i32 s7, s77, 2
	v_div_scale_f32 v50, s[20:21], v40, v40, 1.0
	v_rcp_f32_e32 v51, v50
	s_min_i32 s20, s75, s23
	s_sub_i32 s7, s20, s7
	s_add_i32 s7, s7, 2
	v_fma_f32 v62, -v50, v51, 1.0
	v_fmac_f32_e32 v51, v62, v51
	v_div_scale_f32 v62, vcc, 1.0, v40, 1.0
	v_mul_f32_e32 v63, v62, v51
	v_fma_f32 v68, -v50, v63, v62
	v_fmac_f32_e32 v63, v68, v51
	v_fma_f32 v50, -v50, v63, v62
	v_div_fmas_f32 v50, v50, v51, v63
	v_div_fixup_f32 v40, v50, v40, 1.0
	v_pk_fma_f32 v[50:51], v[40:41], v[60:61], v[54:55] op_sel_hi:[0,1,1] neg_lo:[0,0,1] neg_hi:[0,0,1]
	v_pk_fma_f32 v[62:63], v[40:41], v[66:67], v[44:45] op_sel_hi:[0,1,1] neg_lo:[0,0,1] neg_hi:[0,0,1]
	v_pk_mul_f32 v[62:63], v[2:3], v[62:63]
	v_pk_mul_f32 v[50:51], v[0:1], v[50:51]
	s_nop 0
	v_cvt_pk_bf16_f32 v50, v50, v51
	v_cvt_pk_bf16_f32 v51, v62, v63
	global_store_dwordx2 v[64:65], v[50:51], off offset:2560
	v_lshlrev_b32_e32 v62, 16, v103
	v_and_b32_e32 v63, 0xffff0000, v103
	v_lshlrev_b32_e32 v64, 16, v41
	v_and_b32_e32 v65, 0xffff0000, v41
	v_pk_mul_f32 v[40:41], v[38:39], v[64:65] op_sel_hi:[0,1]
	v_pk_mul_f32 v[50:51], v[38:39], v[62:63] op_sel_hi:[0,1]
	v_pk_fma_f32 v[58:59], v[38:39], v[62:63], v[58:59] op_sel_hi:[0,1,1] neg_lo:[0,0,1] neg_hi:[0,0,1]
	v_pk_fma_f32 v[46:47], v[38:39], v[64:65], v[46:47] op_sel_hi:[0,1,1] neg_lo:[0,0,1] neg_hi:[0,0,1]
	v_cvt_f32_i32_e32 v38, s7
	v_pk_add_f32 v[62:63], v[66:67], v[46:47]
	v_pk_add_f32 v[58:59], v[60:61], v[58:59]
	s_max_i32 s7, s76, 2
	v_div_scale_f32 v46, s[20:21], v38, v38, 1.0
	v_rcp_f32_e32 v47, v46
	s_min_i32 s20, s74, s23
	s_sub_i32 s7, s20, s7
	v_and_b32_e32 v65, 0xffff0000, v102
	v_fma_f32 v60, -v46, v47, 1.0
	v_fmac_f32_e32 v47, v60, v47
	v_div_scale_f32 v60, vcc, 1.0, v38, 1.0
	v_mul_f32_e32 v61, v60, v47
	v_fma_f32 v64, -v46, v61, v60
	v_fmac_f32_e32 v61, v64, v47
	v_fma_f32 v46, -v46, v61, v60
	v_div_fmas_f32 v46, v46, v47, v61
	v_div_fixup_f32 v38, v46, v38, 1.0
	v_pk_fma_f32 v[46:47], v[38:39], v[58:59], v[52:53] op_sel_hi:[0,1,1] neg_lo:[0,0,1] neg_hi:[0,0,1]
	v_pk_fma_f32 v[60:61], v[38:39], v[62:63], v[42:43] op_sel_hi:[0,1,1] neg_lo:[0,0,1] neg_hi:[0,0,1]
	v_pk_mul_f32 v[60:61], v[2:3], v[60:61]
	v_pk_mul_f32 v[46:47], v[0:1], v[46:47]
	v_lshlrev_b32_e32 v64, 16, v102
	v_cvt_pk_bf16_f32 v46, v46, v47
	v_cvt_pk_bf16_f32 v47, v60, v61
	v_add_co_u32_e32 v60, vcc, s61, v14
	v_lshlrev_b32_e32 v66, 16, v39
	s_nop 0
	v_addc_co_u32_e32 v61, vcc, 0, v15, vcc
	v_and_b32_e32 v67, 0xffff0000, v39
	s_add_i32 s7, s7, 2
	global_store_dwordx2 v[60:61], v[46:47], off offset:512
	v_pk_mul_f32 v[38:39], v[36:37], v[66:67] op_sel_hi:[0,1]
	v_pk_mul_f32 v[46:47], v[36:37], v[64:65] op_sel_hi:[0,1]
	v_pk_fma_f32 v[56:57], v[36:37], v[64:65], v[56:57] op_sel_hi:[0,1,1] neg_lo:[0,0,1] neg_hi:[0,0,1]
	v_pk_fma_f32 v[48:49], v[36:37], v[66:67], v[48:49] op_sel_hi:[0,1,1] neg_lo:[0,0,1] neg_hi:[0,0,1]
	v_cvt_f32_i32_e32 v36, s7
	v_pk_add_f32 v[62:63], v[62:63], v[48:49]
	v_pk_add_f32 v[56:57], v[58:59], v[56:57]
	s_max_i32 s7, s75, 2
	v_div_scale_f32 v48, s[20:21], v36, v36, 1.0
	v_rcp_f32_e32 v49, v48
	s_min_i32 s20, s72, s23
	s_sub_i32 s7, s20, s7
	s_add_i32 s7, s7, 2
	v_fma_f32 v58, -v48, v49, 1.0
	v_fmac_f32_e32 v49, v58, v49
	v_div_scale_f32 v58, vcc, 1.0, v36, 1.0
	v_mul_f32_e32 v59, v58, v49
	v_fma_f32 v64, -v48, v59, v58
	v_fmac_f32_e32 v59, v64, v49
	v_fma_f32 v48, -v48, v59, v58
	v_div_fmas_f32 v48, v48, v49, v59
	v_div_fixup_f32 v36, v48, v36, 1.0
	v_pk_fma_f32 v[48:49], v[36:37], v[56:57], v[50:51] op_sel_hi:[0,1,1] neg_lo:[0,0,1] neg_hi:[0,0,1]
	v_pk_fma_f32 v[58:59], v[36:37], v[62:63], v[40:41] op_sel_hi:[0,1,1] neg_lo:[0,0,1] neg_hi:[0,0,1]
	v_pk_mul_f32 v[58:59], v[2:3], v[58:59]
	v_pk_mul_f32 v[48:49], v[0:1], v[48:49]
	s_nop 0
	v_cvt_pk_bf16_f32 v48, v48, v49
	v_cvt_pk_bf16_f32 v49, v58, v59
	global_store_dwordx2 v[60:61], v[48:49], off offset:2560
	v_lshlrev_b32_e32 v58, 16, v101
	v_and_b32_e32 v59, 0xffff0000, v101
	v_lshlrev_b32_e32 v60, 16, v37
	v_and_b32_e32 v61, 0xffff0000, v37
	v_pk_mul_f32 v[36:37], v[32:33], v[60:61] op_sel_hi:[0,1]
	v_pk_mul_f32 v[48:49], v[32:33], v[58:59] op_sel_hi:[0,1]
	v_pk_fma_f32 v[54:55], v[32:33], v[58:59], v[54:55] op_sel_hi:[0,1,1] neg_lo:[0,0,1] neg_hi:[0,0,1]
	v_pk_fma_f32 v[44:45], v[32:33], v[60:61], v[44:45] op_sel_hi:[0,1,1] neg_lo:[0,0,1] neg_hi:[0,0,1]
	v_cvt_f32_i32_e32 v32, s7
	v_pk_add_f32 v[58:59], v[62:63], v[44:45]
	v_pk_add_f32 v[54:55], v[56:57], v[54:55]
	s_max_i32 s7, s74, 2
	v_div_scale_f32 v44, s[20:21], v32, v32, 1.0
	v_rcp_f32_e32 v45, v44
	s_min_i32 s20, s73, s23
	v_and_b32_e32 v61, 0xffff0000, v35
	v_lshlrev_b32_e32 v62, 16, v33
	v_fma_f32 v56, -v44, v45, 1.0
	v_fmac_f32_e32 v45, v56, v45
	v_div_scale_f32 v56, vcc, 1.0, v32, 1.0
	v_mul_f32_e32 v57, v56, v45
	v_fma_f32 v60, -v44, v57, v56
	v_fmac_f32_e32 v57, v60, v45
	v_fma_f32 v44, -v44, v57, v56
	v_div_fmas_f32 v44, v44, v45, v57
	v_div_fixup_f32 v32, v44, v32, 1.0
	v_pk_fma_f32 v[44:45], v[32:33], v[54:55], v[46:47] op_sel_hi:[0,1,1] neg_lo:[0,0,1] neg_hi:[0,0,1]
	v_pk_fma_f32 v[56:57], v[32:33], v[58:59], v[38:39] op_sel_hi:[0,1,1] neg_lo:[0,0,1] neg_hi:[0,0,1]
	v_pk_mul_f32 v[56:57], v[2:3], v[56:57]
	v_pk_mul_f32 v[44:45], v[0:1], v[44:45]
	v_lshlrev_b32_e32 v60, 16, v35
	v_cvt_pk_bf16_f32 v44, v44, v45
	v_cvt_pk_bf16_f32 v45, v56, v57
	v_add_co_u32_e32 v56, vcc, s94, v14
	v_and_b32_e32 v63, 0xffff0000, v33
	s_nop 0
	v_addc_co_u32_e32 v57, vcc, 0, v15, vcc
	s_sub_i32 s7, s20, s7
	global_store_dwordx2 v[56:57], v[44:45], off offset:512
	v_pk_mul_f32 v[32:33], v[34:35], v[62:63] op_sel_hi:[0,1]
	v_pk_mul_f32 v[44:45], v[34:35], v[60:61] op_sel_hi:[0,1]
	v_pk_fma_f32 v[52:53], v[34:35], v[60:61], v[52:53] op_sel_hi:[0,1,1] neg_lo:[0,0,1] neg_hi:[0,0,1]
	v_pk_fma_f32 v[34:35], v[34:35], v[62:63], v[42:43] op_sel_hi:[0,1,1] neg_lo:[0,0,1] neg_hi:[0,0,1]
	s_add_i32 s7, s7, 2
	v_pk_add_f32 v[58:59], v[58:59], v[34:35]
	v_cvt_f32_i32_e32 v34, s7
	v_pk_add_f32 v[52:53], v[54:55], v[52:53]
	s_max_i32 s7, s72, 2
	v_div_scale_f32 v35, s[20:21], v34, v34, 1.0
	v_rcp_f32_e32 v42, v35
	s_min_i32 s20, s71, s23
	s_sub_i32 s7, s20, s7
	s_add_i32 s7, s7, 2
	v_fma_f32 v43, -v35, v42, 1.0
	v_fmac_f32_e32 v42, v43, v42
	v_div_scale_f32 v43, vcc, 1.0, v34, 1.0
	v_mul_f32_e32 v54, v43, v42
	v_fma_f32 v55, -v35, v54, v43
	v_fmac_f32_e32 v54, v55, v42
	v_fma_f32 v35, -v35, v54, v43
	v_div_fmas_f32 v35, v35, v42, v54
	v_div_fixup_f32 v34, v35, v34, 1.0
	v_pk_fma_f32 v[42:43], v[34:35], v[52:53], v[48:49] op_sel_hi:[0,1,1] neg_lo:[0,0,1] neg_hi:[0,0,1]
	v_pk_fma_f32 v[34:35], v[34:35], v[58:59], v[36:37] op_sel_hi:[0,1,1] neg_lo:[0,0,1] neg_hi:[0,0,1]
	v_pk_mul_f32 v[42:43], v[0:1], v[42:43]
	v_pk_mul_f32 v[34:35], v[2:3], v[34:35]
	v_cvt_pk_bf16_f32 v42, v42, v43
	v_lshlrev_b32_e32 v54, 16, v100
	v_cvt_pk_bf16_f32 v43, v34, v35
	global_store_dwordx2 v[56:57], v[42:43], off offset:2560
	v_and_b32_e32 v55, 0xffff0000, v100
	v_lshlrev_b32_e32 v56, 16, v99
	v_and_b32_e32 v57, 0xffff0000, v99
	v_pk_mul_f32 v[34:35], v[30:31], v[56:57] op_sel_hi:[0,1]
	v_pk_mul_f32 v[42:43], v[30:31], v[54:55] op_sel_hi:[0,1]
	v_pk_fma_f32 v[50:51], v[30:31], v[54:55], v[50:51] op_sel_hi:[0,1,1] neg_lo:[0,0,1] neg_hi:[0,0,1]
	v_pk_fma_f32 v[40:41], v[30:31], v[56:57], v[40:41] op_sel_hi:[0,1,1] neg_lo:[0,0,1] neg_hi:[0,0,1]
	v_cvt_f32_i32_e32 v30, s7
	v_pk_add_f32 v[54:55], v[58:59], v[40:41]
	v_pk_add_f32 v[50:51], v[52:53], v[50:51]
	s_mov_b32 s7, 0xa000
	v_div_scale_f32 v40, s[20:21], v30, v30, 1.0
	v_rcp_f32_e32 v41, v40
	s_min_i32 s20, s70, s23
	v_and_b32_e32 v57, 0xffff0000, v98
	v_lshlrev_b32_e32 v58, 16, v31
	v_fma_f32 v52, -v40, v41, 1.0
	v_fmac_f32_e32 v41, v52, v41
	v_div_scale_f32 v52, vcc, 1.0, v30, 1.0
	v_mul_f32_e32 v53, v52, v41
	v_fma_f32 v56, -v40, v53, v52
	v_fmac_f32_e32 v53, v56, v41
	v_fma_f32 v40, -v40, v53, v52
	v_div_fmas_f32 v40, v40, v41, v53
	v_div_fixup_f32 v30, v40, v30, 1.0
	v_pk_fma_f32 v[40:41], v[30:31], v[50:51], v[44:45] op_sel_hi:[0,1,1] neg_lo:[0,0,1] neg_hi:[0,0,1]
	v_pk_fma_f32 v[52:53], v[30:31], v[54:55], v[32:33] op_sel_hi:[0,1,1] neg_lo:[0,0,1] neg_hi:[0,0,1]
	v_pk_mul_f32 v[52:53], v[2:3], v[52:53]
	v_pk_mul_f32 v[40:41], v[0:1], v[40:41]
	v_lshlrev_b32_e32 v56, 16, v98
	v_cvt_pk_bf16_f32 v40, v40, v41
	v_cvt_pk_bf16_f32 v41, v52, v53
	v_add_co_u32_e32 v52, vcc, s7, v14
	s_max_i32 s7, s73, 2
	s_sub_i32 s7, s20, s7
	v_addc_co_u32_e32 v53, vcc, 0, v15, vcc
	v_and_b32_e32 v59, 0xffff0000, v31
	s_add_i32 s7, s7, 2
	global_store_dwordx2 v[52:53], v[40:41], off offset:512
	v_pk_mul_f32 v[30:31], v[28:29], v[58:59] op_sel_hi:[0,1]
	v_pk_mul_f32 v[40:41], v[28:29], v[56:57] op_sel_hi:[0,1]
	v_pk_fma_f32 v[46:47], v[28:29], v[56:57], v[46:47] op_sel_hi:[0,1,1] neg_lo:[0,0,1] neg_hi:[0,0,1]
	v_pk_fma_f32 v[38:39], v[28:29], v[58:59], v[38:39] op_sel_hi:[0,1,1] neg_lo:[0,0,1] neg_hi:[0,0,1]
	v_cvt_f32_i32_e32 v28, s7
	v_pk_add_f32 v[54:55], v[54:55], v[38:39]
	v_pk_add_f32 v[46:47], v[50:51], v[46:47]
	s_max_i32 s7, s71, 2
	v_div_scale_f32 v38, s[20:21], v28, v28, 1.0
	v_rcp_f32_e32 v39, v38
	s_min_i32 s20, s69, s23
	s_sub_i32 s7, s20, s7
	s_add_i32 s7, s7, 2
	v_fma_f32 v50, -v38, v39, 1.0
	v_fmac_f32_e32 v39, v50, v39
	v_div_scale_f32 v50, vcc, 1.0, v28, 1.0
	v_mul_f32_e32 v51, v50, v39
	v_fma_f32 v56, -v38, v51, v50
	v_fmac_f32_e32 v51, v56, v39
	v_fma_f32 v38, -v38, v51, v50
	v_div_fmas_f32 v38, v38, v39, v51
	v_div_fixup_f32 v28, v38, v28, 1.0
	v_pk_fma_f32 v[38:39], v[28:29], v[46:47], v[42:43] op_sel_hi:[0,1,1] neg_lo:[0,0,1] neg_hi:[0,0,1]
	v_pk_fma_f32 v[50:51], v[28:29], v[54:55], v[34:35] op_sel_hi:[0,1,1] neg_lo:[0,0,1] neg_hi:[0,0,1]
	v_pk_mul_f32 v[50:51], v[2:3], v[50:51]
	v_pk_mul_f32 v[38:39], v[0:1], v[38:39]
	s_nop 0
	v_cvt_pk_bf16_f32 v38, v38, v39
	v_cvt_pk_bf16_f32 v39, v50, v51
	global_store_dwordx2 v[52:53], v[38:39], off offset:2560
	v_lshlrev_b32_e32 v50, 16, v95
	v_and_b32_e32 v51, 0xffff0000, v95
	v_lshlrev_b32_e32 v52, 16, v29
	v_and_b32_e32 v53, 0xffff0000, v29
	v_pk_mul_f32 v[28:29], v[26:27], v[52:53] op_sel_hi:[0,1]
	v_pk_mul_f32 v[38:39], v[26:27], v[50:51] op_sel_hi:[0,1]
	v_pk_fma_f32 v[48:49], v[26:27], v[50:51], v[48:49] op_sel_hi:[0,1,1] neg_lo:[0,0,1] neg_hi:[0,0,1]
	v_pk_fma_f32 v[36:37], v[26:27], v[52:53], v[36:37] op_sel_hi:[0,1,1] neg_lo:[0,0,1] neg_hi:[0,0,1]
	v_cvt_f32_i32_e32 v26, s7
	v_pk_add_f32 v[50:51], v[54:55], v[36:37]
	v_pk_add_f32 v[46:47], v[46:47], v[48:49]
	s_max_i32 s7, s70, 2
	v_div_scale_f32 v36, s[20:21], v26, v26, 1.0
	v_rcp_f32_e32 v37, v36
	s_min_i32 s20, s68, s23
	s_sub_i32 s7, s20, s7
	v_and_b32_e32 v53, 0xffff0000, v94
	v_fma_f32 v48, -v36, v37, 1.0
	v_fmac_f32_e32 v37, v48, v37
	v_div_scale_f32 v48, vcc, 1.0, v26, 1.0
	v_mul_f32_e32 v49, v48, v37
	v_fma_f32 v52, -v36, v49, v48
	v_fmac_f32_e32 v49, v52, v37
	v_fma_f32 v36, -v36, v49, v48
	v_div_fmas_f32 v36, v36, v37, v49
	v_div_fixup_f32 v26, v36, v26, 1.0
	v_pk_fma_f32 v[36:37], v[26:27], v[46:47], v[40:41] op_sel_hi:[0,1,1] neg_lo:[0,0,1] neg_hi:[0,0,1]
	v_pk_fma_f32 v[48:49], v[26:27], v[50:51], v[30:31] op_sel_hi:[0,1,1] neg_lo:[0,0,1] neg_hi:[0,0,1]
	v_pk_mul_f32 v[48:49], v[2:3], v[48:49]
	v_pk_mul_f32 v[36:37], v[0:1], v[36:37]
	v_lshlrev_b32_e32 v52, 16, v94
	v_cvt_pk_bf16_f32 v36, v36, v37
	v_cvt_pk_bf16_f32 v37, v48, v49
	v_add_co_u32_e32 v48, vcc, s51, v14
	v_lshlrev_b32_e32 v54, 16, v27
	s_nop 0
	v_addc_co_u32_e32 v49, vcc, 0, v15, vcc
	v_and_b32_e32 v55, 0xffff0000, v27
	s_add_i32 s7, s7, 2
	global_store_dwordx2 v[48:49], v[36:37], off offset:512
	v_pk_mul_f32 v[26:27], v[24:25], v[54:55] op_sel_hi:[0,1]
	v_pk_mul_f32 v[36:37], v[24:25], v[52:53] op_sel_hi:[0,1]
	v_pk_fma_f32 v[44:45], v[24:25], v[52:53], v[44:45] op_sel_hi:[0,1,1] neg_lo:[0,0,1] neg_hi:[0,0,1]
	v_pk_fma_f32 v[32:33], v[24:25], v[54:55], v[32:33] op_sel_hi:[0,1,1] neg_lo:[0,0,1] neg_hi:[0,0,1]
	v_cvt_f32_i32_e32 v24, s7
	v_pk_add_f32 v[50:51], v[50:51], v[32:33]
	v_pk_add_f32 v[44:45], v[46:47], v[44:45]
	s_max_i32 s7, s69, 2
	v_div_scale_f32 v32, s[20:21], v24, v24, 1.0
	v_rcp_f32_e32 v33, v32
	s_min_i32 s20, s66, s23
	s_sub_i32 s7, s20, s7
	s_add_i32 s7, s7, 2
	v_fma_f32 v46, -v32, v33, 1.0
	v_fmac_f32_e32 v33, v46, v33
	v_div_scale_f32 v46, vcc, 1.0, v24, 1.0
	v_mul_f32_e32 v47, v46, v33
	v_fma_f32 v52, -v32, v47, v46
	v_fmac_f32_e32 v47, v52, v33
	v_fma_f32 v32, -v32, v47, v46
	v_div_fmas_f32 v32, v32, v33, v47
	v_div_fixup_f32 v24, v32, v24, 1.0
	v_pk_fma_f32 v[32:33], v[24:25], v[44:45], v[38:39] op_sel_hi:[0,1,1] neg_lo:[0,0,1] neg_hi:[0,0,1]
	v_pk_fma_f32 v[46:47], v[24:25], v[50:51], v[28:29] op_sel_hi:[0,1,1] neg_lo:[0,0,1] neg_hi:[0,0,1]
	v_pk_mul_f32 v[46:47], v[2:3], v[46:47]
	v_pk_mul_f32 v[32:33], v[0:1], v[32:33]
	s_nop 0
	v_cvt_pk_bf16_f32 v32, v32, v33
	v_cvt_pk_bf16_f32 v33, v46, v47
	global_store_dwordx2 v[48:49], v[32:33], off offset:2560
	v_lshlrev_b32_e32 v46, 16, v93
	v_and_b32_e32 v47, 0xffff0000, v93
	v_lshlrev_b32_e32 v48, 16, v25
	v_and_b32_e32 v49, 0xffff0000, v25
	v_pk_mul_f32 v[24:25], v[20:21], v[48:49] op_sel_hi:[0,1]
	v_pk_mul_f32 v[32:33], v[20:21], v[46:47] op_sel_hi:[0,1]
	v_pk_fma_f32 v[42:43], v[20:21], v[46:47], v[42:43] op_sel_hi:[0,1,1] neg_lo:[0,0,1] neg_hi:[0,0,1]
	v_pk_fma_f32 v[34:35], v[20:21], v[48:49], v[34:35] op_sel_hi:[0,1,1] neg_lo:[0,0,1] neg_hi:[0,0,1]
	v_cvt_f32_i32_e32 v20, s7
	v_pk_add_f32 v[46:47], v[50:51], v[34:35]
	v_pk_add_f32 v[42:43], v[44:45], v[42:43]
	s_max_i32 s7, s68, 2
	v_div_scale_f32 v34, s[20:21], v20, v20, 1.0
	v_rcp_f32_e32 v35, v34
	s_min_i32 s20, s67, s23
	v_and_b32_e32 v49, 0xffff0000, v23
	v_lshlrev_b32_e32 v50, 16, v21
	v_fma_f32 v44, -v34, v35, 1.0
	v_fmac_f32_e32 v35, v44, v35
	v_div_scale_f32 v44, vcc, 1.0, v20, 1.0
	v_mul_f32_e32 v45, v44, v35
	v_fma_f32 v48, -v34, v45, v44
	v_fmac_f32_e32 v45, v48, v35
	v_fma_f32 v34, -v34, v45, v44
	v_div_fmas_f32 v34, v34, v35, v45
	v_div_fixup_f32 v20, v34, v20, 1.0
	v_pk_fma_f32 v[34:35], v[20:21], v[42:43], v[36:37] op_sel_hi:[0,1,1] neg_lo:[0,0,1] neg_hi:[0,0,1]
	v_pk_fma_f32 v[44:45], v[20:21], v[46:47], v[26:27] op_sel_hi:[0,1,1] neg_lo:[0,0,1] neg_hi:[0,0,1]
	v_pk_mul_f32 v[44:45], v[2:3], v[44:45]
	v_pk_mul_f32 v[34:35], v[0:1], v[34:35]
	v_lshlrev_b32_e32 v48, 16, v23
	v_cvt_pk_bf16_f32 v34, v34, v35
	v_cvt_pk_bf16_f32 v35, v44, v45
	v_add_co_u32_e32 v44, vcc, s58, v14
	v_and_b32_e32 v51, 0xffff0000, v21
	s_nop 0
	v_addc_co_u32_e32 v45, vcc, 0, v15, vcc
	s_sub_i32 s7, s20, s7
	global_store_dwordx2 v[44:45], v[34:35], off offset:512
	v_pk_mul_f32 v[20:21], v[22:23], v[50:51] op_sel_hi:[0,1]
	v_pk_mul_f32 v[34:35], v[22:23], v[48:49] op_sel_hi:[0,1]
	v_pk_fma_f32 v[40:41], v[22:23], v[48:49], v[40:41] op_sel_hi:[0,1,1] neg_lo:[0,0,1] neg_hi:[0,0,1]
	v_pk_fma_f32 v[22:23], v[22:23], v[50:51], v[30:31] op_sel_hi:[0,1,1] neg_lo:[0,0,1] neg_hi:[0,0,1]
	s_add_i32 s7, s7, 2
	v_pk_add_f32 v[46:47], v[46:47], v[22:23]
	v_cvt_f32_i32_e32 v22, s7
	v_pk_add_f32 v[40:41], v[42:43], v[40:41]
	s_max_i32 s7, s66, 2
	v_div_scale_f32 v23, s[20:21], v22, v22, 1.0
	v_rcp_f32_e32 v30, v23
	s_min_i32 s20, s63, s23
	s_sub_i32 s7, s20, s7
	s_add_i32 s7, s7, 2
	v_fma_f32 v31, -v23, v30, 1.0
	v_fmac_f32_e32 v30, v31, v30
	v_div_scale_f32 v31, vcc, 1.0, v22, 1.0
	v_mul_f32_e32 v42, v31, v30
	v_fma_f32 v43, -v23, v42, v31
	v_fmac_f32_e32 v42, v43, v30
	v_fma_f32 v23, -v23, v42, v31
	v_div_fmas_f32 v23, v23, v30, v42
	v_div_fixup_f32 v22, v23, v22, 1.0
	v_pk_fma_f32 v[30:31], v[22:23], v[40:41], v[32:33] op_sel_hi:[0,1,1] neg_lo:[0,0,1] neg_hi:[0,0,1]
	v_pk_fma_f32 v[22:23], v[22:23], v[46:47], v[24:25] op_sel_hi:[0,1,1] neg_lo:[0,0,1] neg_hi:[0,0,1]
	v_pk_mul_f32 v[30:31], v[0:1], v[30:31]
	v_pk_mul_f32 v[22:23], v[2:3], v[22:23]
	v_cvt_pk_bf16_f32 v30, v30, v31
	v_lshlrev_b32_e32 v42, 16, v92
	v_cvt_pk_bf16_f32 v31, v22, v23
	global_store_dwordx2 v[44:45], v[30:31], off offset:2560
	v_and_b32_e32 v43, 0xffff0000, v92
	v_lshlrev_b32_e32 v44, 16, v91
	v_and_b32_e32 v45, 0xffff0000, v91
	v_pk_mul_f32 v[22:23], v[18:19], v[44:45] op_sel_hi:[0,1]
	v_pk_mul_f32 v[30:31], v[18:19], v[42:43] op_sel_hi:[0,1]
	v_pk_fma_f32 v[38:39], v[18:19], v[42:43], v[38:39] op_sel_hi:[0,1,1] neg_lo:[0,0,1] neg_hi:[0,0,1]
	v_pk_fma_f32 v[28:29], v[18:19], v[44:45], v[28:29] op_sel_hi:[0,1,1] neg_lo:[0,0,1] neg_hi:[0,0,1]
	v_cvt_f32_i32_e32 v18, s7
	v_pk_add_f32 v[42:43], v[46:47], v[28:29]
	v_pk_add_f32 v[38:39], v[40:41], v[38:39]
	s_max_i32 s7, s67, 2
	v_div_scale_f32 v28, s[20:21], v18, v18, 1.0
	v_rcp_f32_e32 v29, v28
	s_min_i32 s20, s34, s23
	s_sub_i32 s7, s20, s7
	v_and_b32_e32 v45, 0xffff0000, v90
	v_fma_f32 v40, -v28, v29, 1.0
	v_fmac_f32_e32 v29, v40, v29
	v_div_scale_f32 v40, vcc, 1.0, v18, 1.0
	v_mul_f32_e32 v41, v40, v29
	v_fma_f32 v44, -v28, v41, v40
	v_fmac_f32_e32 v41, v44, v29
	v_fma_f32 v28, -v28, v41, v40
	v_div_fmas_f32 v28, v28, v29, v41
	v_div_fixup_f32 v18, v28, v18, 1.0
	v_pk_fma_f32 v[28:29], v[18:19], v[38:39], v[34:35] op_sel_hi:[0,1,1] neg_lo:[0,0,1] neg_hi:[0,0,1]
	v_pk_fma_f32 v[40:41], v[18:19], v[42:43], v[20:21] op_sel_hi:[0,1,1] neg_lo:[0,0,1] neg_hi:[0,0,1]
	v_pk_mul_f32 v[40:41], v[2:3], v[40:41]
	v_pk_mul_f32 v[28:29], v[0:1], v[28:29]
	v_lshlrev_b32_e32 v44, 16, v90
	v_cvt_pk_bf16_f32 v28, v28, v29
	v_cvt_pk_bf16_f32 v29, v40, v41
	v_add_co_u32_e32 v40, vcc, s59, v14
	v_lshlrev_b32_e32 v46, 16, v19
	s_nop 0
	v_addc_co_u32_e32 v41, vcc, 0, v15, vcc
	v_and_b32_e32 v47, 0xffff0000, v19
	s_add_i32 s7, s7, 2
	global_store_dwordx2 v[40:41], v[28:29], off offset:512
	v_pk_mul_f32 v[18:19], v[16:17], v[46:47] op_sel_hi:[0,1]
	v_pk_mul_f32 v[28:29], v[16:17], v[44:45] op_sel_hi:[0,1]
	v_pk_fma_f32 v[36:37], v[16:17], v[44:45], v[36:37] op_sel_hi:[0,1,1] neg_lo:[0,0,1] neg_hi:[0,0,1]
	v_pk_fma_f32 v[26:27], v[16:17], v[46:47], v[26:27] op_sel_hi:[0,1,1] neg_lo:[0,0,1] neg_hi:[0,0,1]
	v_cvt_f32_i32_e32 v16, s7
	v_pk_add_f32 v[36:37], v[38:39], v[36:37]
	v_pk_add_f32 v[26:27], v[42:43], v[26:27]
	s_max_i32 s7, s63, 2
	v_div_scale_f32 v38, s[20:21], v16, v16, 1.0
	v_rcp_f32_e32 v39, v38
	s_min_i32 s20, s15, s23
	s_sub_i32 s7, s20, s7
	s_add_i32 s7, s7, 2
	v_fma_f32 v42, -v38, v39, 1.0
	v_fmac_f32_e32 v39, v42, v39
	v_div_scale_f32 v42, vcc, 1.0, v16, 1.0
	v_mul_f32_e32 v43, v42, v39
	v_fma_f32 v44, -v38, v43, v42
	v_fmac_f32_e32 v43, v44, v39
	v_fma_f32 v38, -v38, v43, v42
	v_div_fmas_f32 v38, v38, v39, v43
	v_div_fixup_f32 v16, v38, v16, 1.0
	v_pk_fma_f32 v[38:39], v[16:17], v[36:37], v[30:31] op_sel_hi:[0,1,1] neg_lo:[0,0,1] neg_hi:[0,0,1]
	v_pk_fma_f32 v[42:43], v[16:17], v[26:27], v[22:23] op_sel_hi:[0,1,1] neg_lo:[0,0,1] neg_hi:[0,0,1]
	v_pk_mul_f32 v[38:39], v[0:1], v[38:39]
	v_pk_mul_f32 v[42:43], v[2:3], v[42:43]
	v_cvt_pk_bf16_f32 v38, v38, v39
	s_nop 0
	v_cvt_pk_bf16_f32 v39, v42, v43
	global_store_dwordx2 v[40:41], v[38:39], off offset:2560
	v_lshlrev_b32_e32 v38, 16, v89
	v_and_b32_e32 v39, 0xffff0000, v89
	v_lshlrev_b32_e32 v40, 16, v88
	v_and_b32_e32 v41, 0xffff0000, v88
	v_pk_mul_f32 v[42:43], v[12:13], v[40:41] op_sel_hi:[0,1]
	v_pk_mul_f32 v[44:45], v[12:13], v[38:39] op_sel_hi:[0,1]
	v_pk_fma_f32 v[32:33], v[12:13], v[38:39], v[32:33] op_sel_hi:[0,1,1] neg_lo:[0,0,1] neg_hi:[0,0,1]
	v_pk_fma_f32 v[24:25], v[12:13], v[40:41], v[24:25] op_sel_hi:[0,1,1] neg_lo:[0,0,1] neg_hi:[0,0,1]
	v_cvt_f32_i32_e32 v12, s7
	v_pk_add_f32 v[24:25], v[26:27], v[24:25]
	v_pk_add_f32 v[26:27], v[36:37], v[32:33]
	s_max_i32 s7, s34, 2
	v_div_scale_f32 v16, s[20:21], v12, v12, 1.0
	v_rcp_f32_e32 v32, v16
	s_min_i32 s20, s5, s23
	s_sub_i32 s7, s20, s7
	v_lshlrev_b32_e32 v38, 16, v86
	v_fma_f32 v33, -v16, v32, 1.0
	v_fmac_f32_e32 v32, v33, v32
	v_div_scale_f32 v33, vcc, 1.0, v12, 1.0
	v_mul_f32_e32 v36, v33, v32
	v_fma_f32 v37, -v16, v36, v33
	v_fmac_f32_e32 v36, v37, v32
	v_fma_f32 v16, -v16, v36, v33
	v_div_fmas_f32 v16, v16, v32, v36
	v_div_fixup_f32 v12, v16, v12, 1.0
	v_pk_fma_f32 v[32:33], v[12:13], v[26:27], v[28:29] op_sel_hi:[0,1,1] neg_lo:[0,0,1] neg_hi:[0,0,1]
	v_pk_fma_f32 v[36:37], v[12:13], v[24:25], v[18:19] op_sel_hi:[0,1,1] neg_lo:[0,0,1] neg_hi:[0,0,1]
	v_pk_mul_f32 v[36:37], v[2:3], v[36:37]
	v_pk_mul_f32 v[32:33], v[0:1], v[32:33]
	v_and_b32_e32 v39, 0xffff0000, v86
	v_cvt_pk_bf16_f32 v32, v32, v33
	v_cvt_pk_bf16_f32 v33, v36, v37
	v_add_co_u32_e32 v36, vcc, s60, v14
	s_add_i32 s7, s7, 2
	s_nop 0
	v_addc_co_u32_e32 v37, vcc, 0, v15, vcc
	global_store_dwordx2 v[36:37], v[32:33], off offset:512
	v_lshlrev_b32_e32 v32, 16, v87
	v_and_b32_e32 v33, 0xffff0000, v87
	v_pk_mul_f32 v[40:41], v[10:11], v[38:39] op_sel_hi:[0,1]
	v_pk_mul_f32 v[46:47], v[10:11], v[32:33] op_sel_hi:[0,1]
	v_pk_fma_f32 v[32:33], v[10:11], v[32:33], v[34:35] op_sel_hi:[0,1,1] neg_lo:[0,0,1] neg_hi:[0,0,1]
	v_pk_fma_f32 v[20:21], v[10:11], v[38:39], v[20:21] op_sel_hi:[0,1,1] neg_lo:[0,0,1] neg_hi:[0,0,1]
	v_cvt_f32_i32_e32 v10, s7
	v_pk_add_f32 v[20:21], v[24:25], v[20:21]
	v_pk_add_f32 v[24:25], v[26:27], v[32:33]
	s_max_i32 s7, s15, 2
	v_div_scale_f32 v12, s[20:21], v10, v10, 1.0
	v_rcp_f32_e32 v16, v12
	s_min_i32 s15, s62, s23
	s_sub_i32 s7, s15, s7
	s_add_i32 s7, s7, 2
	v_fma_f32 v26, -v12, v16, 1.0
	v_fmac_f32_e32 v16, v26, v16
	v_div_scale_f32 v26, vcc, 1.0, v10, 1.0
	v_mul_f32_e32 v27, v26, v16
	v_fma_f32 v32, -v12, v27, v26
	v_fmac_f32_e32 v27, v32, v16
	v_fma_f32 v12, -v12, v27, v26
	v_div_fmas_f32 v12, v12, v16, v27
	v_div_fixup_f32 v10, v12, v10, 1.0
	v_pk_fma_f32 v[26:27], v[10:11], v[24:25], v[44:45] op_sel_hi:[0,1,1] neg_lo:[0,0,1] neg_hi:[0,0,1]
	v_pk_fma_f32 v[32:33], v[10:11], v[20:21], v[42:43] op_sel_hi:[0,1,1] neg_lo:[0,0,1] neg_hi:[0,0,1]
	v_cvt_f32_i32_e32 v10, s7
	v_pk_mul_f32 v[26:27], v[0:1], v[26:27]
	v_pk_mul_f32 v[32:33], v[2:3], v[32:33]
	v_cvt_pk_bf16_f32 v26, v26, v27
	v_lshlrev_b32_e32 v12, 16, v13
	v_cvt_pk_bf16_f32 v27, v32, v33
	global_store_dwordx2 v[36:37], v[26:27], off offset:2560
	v_and_b32_e32 v13, 0xffff0000, v13
	v_lshlrev_b32_e32 v26, 16, v7
	v_and_b32_e32 v27, 0xffff0000, v7
	v_pk_mul_f32 v[32:33], v[6:7], v[26:27] op_sel_hi:[0,1]
	v_pk_mul_f32 v[34:35], v[6:7], v[12:13] op_sel_hi:[0,1]
	v_pk_fma_f32 v[12:13], v[6:7], v[12:13], v[30:31] op_sel_hi:[0,1,1] neg_lo:[0,0,1] neg_hi:[0,0,1]
	v_pk_fma_f32 v[6:7], v[6:7], v[26:27], v[22:23] op_sel_hi:[0,1,1] neg_lo:[0,0,1] neg_hi:[0,0,1]
	v_div_scale_f32 v16, s[20:21], v10, v10, 1.0
	v_pk_add_f32 v[6:7], v[20:21], v[6:7]
	v_rcp_f32_e32 v20, v16
	s_add_i32 s7, s4, 33
	s_max_i32 s5, s5, 2
	s_min_i32 s7, s7, s23
	v_fma_f32 v21, -v16, v20, 1.0
	v_fmac_f32_e32 v20, v21, v20
	v_div_scale_f32 v21, vcc, 1.0, v10, 1.0
	v_mul_f32_e32 v22, v21, v20
	v_fma_f32 v23, -v16, v22, v21
	v_fmac_f32_e32 v22, v23, v20
	v_fma_f32 v16, -v16, v22, v21
	v_div_fmas_f32 v16, v16, v20, v22
	s_sub_i32 s5, s7, s5
	v_pk_add_f32 v[12:13], v[24:25], v[12:13]
	v_div_fixup_f32 v10, v16, v10, 1.0
	s_add_i32 s5, s5, 2
	v_pk_fma_f32 v[20:21], v[10:11], v[12:13], v[46:47] op_sel_hi:[0,1,1] neg_lo:[0,0,1] neg_hi:[0,0,1]
	v_pk_fma_f32 v[22:23], v[10:11], v[6:7], v[40:41] op_sel_hi:[0,1,1] neg_lo:[0,0,1] neg_hi:[0,0,1]
	v_add_co_u32_e32 v14, vcc, s50, v14
	v_cvt_f32_i32_e32 v10, s5
	v_pk_mul_f32 v[20:21], v[0:1], v[20:21]
	v_addc_co_u32_e32 v15, vcc, 0, v15, vcc
	v_pk_mul_f32 v[22:23], v[2:3], v[22:23]
	v_cvt_pk_bf16_f32 v20, v20, v21
	v_lshlrev_b32_e32 v16, 16, v9
	v_cvt_pk_bf16_f32 v21, v22, v23
	global_store_dwordx2 v[14:15], v[20:21], off offset:512
	v_lshlrev_b32_e32 v14, 16, v17
	v_and_b32_e32 v15, 0xffff0000, v17
	v_and_b32_e32 v17, 0xffff0000, v9
	s_waitcnt vmcnt(31)
	v_pk_fma_f32 v[14:15], v[8:9], v[14:15], v[28:29] op_sel_hi:[0,1,1] neg_lo:[0,0,1] neg_hi:[0,0,1]
	v_pk_fma_f32 v[8:9], v[8:9], v[16:17], v[18:19] op_sel_hi:[0,1,1] neg_lo:[0,0,1] neg_hi:[0,0,1]
	v_pk_add_f32 v[6:7], v[6:7], v[8:9]
	v_pk_add_f32 v[8:9], v[12:13], v[14:15]
	v_div_scale_f32 v12, s[20:21], v10, v10, 1.0
	v_rcp_f32_e32 v13, v12
	s_nop 0
	v_fma_f32 v14, -v12, v13, 1.0
	v_fmac_f32_e32 v13, v14, v13
	v_div_scale_f32 v14, vcc, 1.0, v10, 1.0
	v_mul_f32_e32 v15, v14, v13
	v_fma_f32 v16, -v12, v15, v14
	v_fmac_f32_e32 v15, v16, v13
	v_fma_f32 v12, -v12, v15, v14
	v_div_fmas_f32 v12, v12, v13, v15
	v_div_fixup_f32 v10, v12, v10, 1.0
	v_pk_fma_f32 v[8:9], v[10:11], v[8:9], v[34:35] op_sel_hi:[0,1,1] neg_lo:[0,0,1] neg_hi:[0,0,1]
	v_pk_fma_f32 v[6:7], v[10:11], v[6:7], v[32:33] op_sel_hi:[0,1,1] neg_lo:[0,0,1] neg_hi:[0,0,1]
	v_pk_mul_f32 v[12:13], v[2:3], v[6:7]
	v_pk_mul_f32 v[6:7], v[0:1], v[8:9]
	s_nop 0
	v_cvt_pk_bf16_f32 v6, v6, v7
	v_cvt_pk_bf16_f32 v7, v12, v13

.LBB0_404:
	v_writelane_b32 v244, s5, 0
	v_writelane_b32 v244, vcc_lo, 1
	v_writelane_b32 v244, vcc_hi, 2
	v_writelane_b32 v244, s16, 3
	v_writelane_b32 v244, s17, 4
	v_writelane_b32 v244, s18, 5
	v_writelane_b32 v244, s19, 6
	v_writelane_b32 v244, s7, 7
	v_writelane_b32 v244, s35, 8
	v_writelane_b32 v244, s97, 9
	v_writelane_b32 v244, s96, 10
	v_writelane_b32 v244, s91, 11
	v_writelane_b32 v244, s90, 12
	v_writelane_b32 v244, s89, 13
	v_writelane_b32 v244, s87, 14
	v_writelane_b32 v244, s85, 15
	v_writelane_b32 v244, s88, 16
	v_writelane_b32 v244, s86, 17
	v_writelane_b32 v244, s84, 18
	v_writelane_b32 v244, s83, 19
	v_writelane_b32 v244, s81, 20
	v_writelane_b32 v244, s78, 21
	v_writelane_b32 v244, s76, 22
	v_writelane_b32 v244, s73, 23
	v_writelane_b32 v244, s74, 24
	v_writelane_b32 v244, s71, 25
	v_writelane_b32 v244, s69, 26
	v_writelane_b32 v244, s68, 27
	v_writelane_b32 v244, s67, 28
	v_writelane_b32 v244, s66, 29
	v_writelane_b32 v244, s63, 30
	v_writelane_b32 v244, s62, 31
	v_writelane_b32 v244, s21, 32
	v_writelane_b32 v244, s34, 33
	v_writelane_b32 v244, s30, 34
	v_writelane_b32 v244, s31, 35
	v_writelane_b32 v244, s20, 36
	v_writelane_b32 v244, s15, 37
	v_writelane_b32 v244, s80, 38
	v_writelane_b32 v244, s82, 39
	v_writelane_b32 v244, s79, 40
	v_writelane_b32 v244, s77, 41
	v_writelane_b32 v244, s75, 42
	v_writelane_b32 v244, s72, 43
	v_writelane_b32 v244, s70, 44
	s_add_i32 s5, s4, -8
	s_cmp_lt_u32 s5, s23
	s_cselect_b64 vcc, -1, 0
	s_and_b64 s[16:17], vcc, exec
	s_cselect_b32 s16, s5, s4
	s_ashr_i32 s17, s16, 31
	v_lshl_add_u64 v[248:249], s[2:3], 0, v[96:97]
	s_lshl_b64 s[18:19], s[16:17], 11
	v_lshl_add_u64 v[246:247], v[248:249], 0, s[18:19]
	global_load_dwordx2 v[200:201], v[246:247], off offset:1536
	s_add_i32 s16, s16, s14
	s_ashr_i32 s17, s16, 31
	s_lshl_b64 s[16:17], s[16:17], 2
	s_add_u32 s16, s26, s16
	s_addc_u32 s17, s27, s17
	s_add_i32 s5, s4, -7
	s_cmp_lt_u32 s5, s23
	s_cselect_b64 vcc, -1, 0
	s_and_b64 s[16:17], vcc, exec
	s_cselect_b32 s16, s5, s4
	s_ashr_i32 s17, s16, 31
	s_lshl_b64 s[18:19], s[16:17], 11
	v_lshl_add_u64 v[246:247], v[248:249], 0, s[18:19]
	global_load_dword v47, v[246:247], off offset:1536
	global_load_dword v43, v[246:247], off offset:1540
	s_add_i32 s16, s16, s14
	s_ashr_i32 s17, s16, 31
	s_lshl_b64 s[16:17], s[16:17], 2
	s_add_u32 s16, s26, s16
	s_addc_u32 s17, s27, s17
	s_add_i32 s5, s4, -6
	s_cmp_lt_u32 s5, s23
	global_load_dword v22, v97, s[16:17]
	s_cselect_b64 vcc, -1, 0
	s_and_b64 s[16:17], vcc, exec
	s_cselect_b32 s16, s5, s4
	s_ashr_i32 s17, s16, 31
	s_lshl_b64 s[18:19], s[16:17], 11
	v_lshl_add_u64 v[246:247], v[248:249], 0, s[18:19]
	global_load_dword v51, v[246:247], off offset:1536
	global_load_dword v49, v[246:247], off offset:1540
	s_add_i32 s16, s16, s14
	s_ashr_i32 s17, s16, 31
	s_lshl_b64 s[16:17], s[16:17], 2
	s_add_u32 s16, s26, s16
	s_addc_u32 s17, s27, s17
	s_add_i32 s5, s4, -5
	s_cmp_lt_u32 s5, s23
	global_load_dword v42, v97, s[16:17]
	s_cselect_b64 vcc, -1, 0
	s_and_b64 s[16:17], vcc, exec
	s_cselect_b32 s16, s5, s4
	s_ashr_i32 s17, s16, 31
	s_lshl_b64 s[18:19], s[16:17], 11
	v_lshl_add_u64 v[246:247], v[248:249], 0, s[18:19]
	global_load_dword v57, v[246:247], off offset:1536
	global_load_dword v53, v[246:247], off offset:1540
	s_add_i32 s16, s16, s14
	s_ashr_i32 s17, s16, 31
	s_lshl_b64 s[16:17], s[16:17], 2
	s_add_u32 s16, s26, s16
	s_addc_u32 s17, s27, s17
	s_add_i32 s5, s4, -4
	s_cmp_lt_u32 s5, s23
	global_load_dword v46, v97, s[16:17]
	s_cselect_b64 vcc, -1, 0
	s_and_b64 s[16:17], vcc, exec
	s_cselect_b32 s16, s5, s4
	s_ashr_i32 s17, s16, 31
	s_lshl_b64 s[18:19], s[16:17], 11
	v_lshl_add_u64 v[246:247], v[248:249], 0, s[18:19]
	global_load_dword v61, v[246:247], off offset:1536
	global_load_dword v59, v[246:247], off offset:1540
	s_add_i32 s16, s16, s14
	s_ashr_i32 s17, s16, 31
	s_lshl_b64 s[16:17], s[16:17], 2
	s_add_u32 s16, s26, s16
	s_addc_u32 s17, s27, s17
	s_add_i32 s5, s4, -3
	s_cmp_lt_u32 s5, s23
	global_load_dword v48, v97, s[16:17]
	s_cselect_b64 vcc, -1, 0
	s_and_b64 s[16:17], vcc, exec
	s_cselect_b32 s16, s5, s4
	s_ashr_i32 s17, s16, 31
	s_lshl_b64 s[18:19], s[16:17], 11
	v_lshl_add_u64 v[246:247], v[248:249], 0, s[18:19]
	global_load_dword v65, v[246:247], off offset:1536
	global_load_dword v63, v[246:247], off offset:1540
	s_add_i32 s16, s16, s14
	s_ashr_i32 s17, s16, 31
	s_lshl_b64 s[16:17], s[16:17], 2
	s_add_u32 s16, s26, s16
	s_addc_u32 s17, s27, s17
	s_add_i32 s5, s4, -2
	s_cmp_lt_u32 s5, s23
	global_load_dword v52, v97, s[16:17]
	s_cselect_b64 vcc, -1, 0
	s_and_b64 s[16:17], vcc, exec
	s_cselect_b32 s16, s5, s4
	s_ashr_i32 s17, s16, 31
	s_lshl_b64 s[18:19], s[16:17], 11
	v_lshl_add_u64 v[246:247], v[248:249], 0, s[18:19]
	global_load_dword v69, v[246:247], off offset:1536
	global_load_dword v67, v[246:247], off offset:1540
	s_add_i32 s16, s16, s14
	s_ashr_i32 s17, s16, 31
	s_lshl_b64 s[16:17], s[16:17], 2
	s_add_u32 s16, s26, s16
	s_addc_u32 s17, s27, s17
	s_add_i32 s5, s4, -1
	s_cmp_lt_u32 s5, s23
	global_load_dword v56, v97, s[16:17]
	s_cselect_b64 vcc, -1, 0
	s_and_b64 s[16:17], vcc, exec
	s_cselect_b32 s16, s5, s4
	s_ashr_i32 s17, s16, 31
	s_lshl_b64 s[18:19], s[16:17], 11
	v_lshl_add_u64 v[246:247], v[248:249], 0, s[18:19]
	global_load_dword v73, v[246:247], off offset:1536
	global_load_dword v71, v[246:247], off offset:1540
	s_add_i32 s16, s16, s14
	s_ashr_i32 s17, s16, 31
	s_lshl_b64 s[16:17], s[16:17], 2
	s_add_u32 s16, s26, s16
	s_addc_u32 s17, s27, s17
	s_cmp_lt_u32 s4, s23
	global_load_dword v60, v97, s[16:17]
	s_cselect_b64 vcc, -1, 0
	s_ashr_i32 s5, s4, 31
	s_lshl_b64 s[16:17], s[4:5], 11
	v_lshl_add_u64 v[246:247], v[248:249], 0, s[16:17]
	global_load_dword v77, v[246:247], off offset:1536
	global_load_dword v75, v[246:247], off offset:1540
	s_ashr_i32 s7, s6, 31
	s_lshl_b64 s[16:17], s[6:7], 2
	s_add_u32 s16, s26, s16
	s_addc_u32 s17, s27, s17
	s_or_b32 s35, s4, 1
	s_cmp_lt_u32 s35, s23
	global_load_dword v66, v97, s[16:17]
	s_cselect_b64 vcc, -1, 0
	s_and_b64 s[16:17], vcc, exec
	s_cselect_b32 s16, s35, s4
	s_ashr_i32 s17, s16, 31
	s_lshl_b64 s[18:19], s[16:17], 11
	v_lshl_add_u64 v[246:247], v[248:249], 0, s[18:19]
	global_load_dword v81, v[246:247], off offset:1536
	global_load_dword v79, v[246:247], off offset:1540
	s_add_i32 s16, s16, s14
	s_ashr_i32 s17, s16, 31
	s_lshl_b64 s[16:17], s[16:17], 2
	s_add_u32 s16, s26, s16
	s_addc_u32 s17, s27, s17
	s_or_b32 s97, s4, 2
	s_cmp_lt_u32 s97, s23
	global_load_dword v72, v97, s[16:17]
	s_cselect_b64 vcc, -1, 0
	s_and_b64 s[16:17], vcc, exec
	s_cselect_b32 s16, s97, s4
	s_ashr_i32 s17, s16, 31
	s_lshl_b64 s[18:19], s[16:17], 11
	v_lshl_add_u64 v[246:247], v[248:249], 0, s[18:19]
	global_load_dword v85, v[246:247], off offset:1536
	global_load_dword v83, v[246:247], off offset:1540
	s_add_i32 s16, s16, s14
	s_ashr_i32 s17, s16, 31
	s_lshl_b64 s[16:17], s[16:17], 2
	s_add_u32 s16, s26, s16
	s_addc_u32 s17, s27, s17
	s_or_b32 s96, s4, 3
	s_cmp_lt_u32 s96, s23
	global_load_dword v76, v97, s[16:17]
	s_cselect_b64 vcc, -1, 0
	s_and_b64 s[16:17], vcc, exec
	s_cselect_b32 s16, s96, s4
	s_ashr_i32 s17, s16, 31
	s_lshl_b64 s[18:19], s[16:17], 11
	v_lshl_add_u64 v[246:247], v[248:249], 0, s[18:19]
	global_load_dword v103, v[246:247], off offset:1536
	global_load_dword v102, v[246:247], off offset:1540
	s_add_i32 s16, s16, s14
	s_ashr_i32 s17, s16, 31
	s_lshl_b64 s[16:17], s[16:17], 2
	s_add_u32 s16, s26, s16
	s_addc_u32 s17, s27, s17
	s_or_b32 s91, s4, 4
	s_cmp_lt_u32 s91, s23
	global_load_dword v80, v97, s[16:17]
	s_cselect_b64 vcc, -1, 0
	s_and_b64 s[16:17], vcc, exec
	s_cselect_b32 s16, s91, s4
	s_ashr_i32 s17, s16, 31
	s_lshl_b64 s[18:19], s[16:17], 11
	v_lshl_add_u64 v[246:247], v[248:249], 0, s[18:19]
	global_load_dword v105, v[246:247], off offset:1536
	global_load_dword v104, v[246:247], off offset:1540
	s_add_i32 s16, s16, s14
	s_ashr_i32 s17, s16, 31
	s_lshl_b64 s[16:17], s[16:17], 2
	s_add_u32 s16, s26, s16
	s_addc_u32 s17, s27, s17
	s_or_b32 s90, s4, 5
	s_cmp_lt_u32 s90, s23
	global_load_dword v82, v97, s[16:17]
	s_cselect_b64 vcc, -1, 0
	s_and_b64 s[16:17], vcc, exec
	s_cselect_b32 s16, s90, s4
	s_ashr_i32 s17, s16, 31
	s_lshl_b64 s[18:19], s[16:17], 11
	v_lshl_add_u64 v[246:247], v[248:249], 0, s[18:19]
	global_load_dword v107, v[246:247], off offset:1536
	global_load_dword v106, v[246:247], off offset:1540
	s_add_i32 s16, s16, s14
	s_ashr_i32 s17, s16, 31
	s_lshl_b64 s[16:17], s[16:17], 2
	s_add_u32 s16, s26, s16
	s_addc_u32 s17, s27, s17
	s_or_b32 s89, s4, 6
	s_cmp_lt_u32 s89, s23
	global_load_dword v86, v97, s[16:17]
	s_cselect_b64 vcc, -1, 0
	s_and_b64 s[16:17], vcc, exec
	s_cselect_b32 s16, s89, s4
	s_ashr_i32 s17, s16, 31
	s_lshl_b64 s[18:19], s[16:17], 11
	v_lshl_add_u64 v[246:247], v[248:249], 0, s[18:19]
	global_load_dword v109, v[246:247], off offset:1536
	global_load_dword v108, v[246:247], off offset:1540
	s_add_i32 s16, s16, s14
	s_ashr_i32 s17, s16, 31
	s_lshl_b64 s[16:17], s[16:17], 2
	s_add_u32 s16, s26, s16
	s_addc_u32 s17, s27, s17
	s_or_b32 s87, s4, 7
	s_cmp_lt_u32 s87, s23
	global_load_dword v90, v97, s[16:17]
	s_cselect_b64 vcc, -1, 0
	s_and_b64 s[16:17], vcc, exec
	s_cselect_b32 s16, s87, s4
	s_ashr_i32 s17, s16, 31
	s_lshl_b64 s[18:19], s[16:17], 11
	v_lshl_add_u64 v[246:247], v[248:249], 0, s[18:19]
	global_load_dword v196, v[246:247], off offset:1536
	global_load_dword v195, v[246:247], off offset:1540
	s_add_i32 s16, s16, s14
	s_ashr_i32 s17, s16, 31
	s_lshl_b64 s[16:17], s[16:17], 2
	s_add_u32 s16, s26, s16
	s_addc_u32 s17, s27, s17
	s_or_b32 s85, s4, 8
	s_cmp_lt_u32 s85, s23
	global_load_dword v92, v97, s[16:17]
	s_cselect_b64 vcc, -1, 0
	s_and_b64 s[16:17], vcc, exec
	s_cselect_b32 s16, s85, s4
	s_ashr_i32 s17, s16, 31
	s_lshl_b64 s[18:19], s[16:17], 11
	v_lshl_add_u64 v[246:247], v[248:249], 0, s[18:19]
	global_load_dword v194, v[246:247], off offset:1536
	global_load_dword v193, v[246:247], off offset:1540
	s_add_i32 s16, s16, s14
	s_ashr_i32 s17, s16, 31
	s_lshl_b64 s[16:17], s[16:17], 2
	s_add_u32 s16, s26, s16
	s_addc_u32 s17, s27, s17
	s_or_b32 s88, s4, 9
	s_cmp_lt_u32 s88, s23
	global_load_dword v98, v97, s[16:17]
	s_cselect_b64 vcc, -1, 0
	s_and_b64 s[16:17], vcc, exec
	s_cselect_b32 s16, s88, s4
	s_ashr_i32 s17, s16, 31
	s_lshl_b64 s[18:19], s[16:17], 11
	v_lshl_add_u64 v[246:247], v[248:249], 0, s[18:19]
	global_load_dword v198, v[246:247], off offset:1536
	global_load_dword v197, v[246:247], off offset:1540
	s_add_i32 s16, s16, s14
	s_ashr_i32 s17, s16, 31
	s_lshl_b64 s[16:17], s[16:17], 2
	s_add_u32 s16, s26, s16
	s_addc_u32 s17, s27, s17
	s_or_b32 s86, s4, 10
	s_cmp_lt_u32 s86, s23
	global_load_dword v94, v97, s[16:17]
	s_cselect_b64 vcc, -1, 0
	s_and_b64 s[16:17], vcc, exec
	s_cselect_b32 s16, s86, s4
	s_ashr_i32 s17, s16, 31
	s_lshl_b64 s[18:19], s[16:17], 11
	v_lshl_add_u64 v[246:247], v[248:249], 0, s[18:19]
	global_load_dword v192, v[246:247], off offset:1536
	global_load_dword v191, v[246:247], off offset:1540
	s_add_i32 s16, s16, s14
	s_ashr_i32 s17, s16, 31
	s_lshl_b64 s[16:17], s[16:17], 2
	s_add_u32 s16, s26, s16
	s_addc_u32 s17, s27, s17
	s_or_b32 s84, s4, 11
	s_cmp_lt_u32 s84, s23
	global_load_dword v88, v97, s[16:17]
	s_cselect_b64 vcc, -1, 0
	s_and_b64 s[16:17], vcc, exec
	s_cselect_b32 s16, s84, s4
	s_ashr_i32 s17, s16, 31
	s_lshl_b64 s[18:19], s[16:17], 11
	v_lshl_add_u64 v[246:247], v[248:249], 0, s[18:19]
	global_load_dword v190, v[246:247], off offset:1536
	global_load_dword v189, v[246:247], off offset:1540
	s_add_i32 s16, s16, s14
	s_ashr_i32 s17, s16, 31
	s_lshl_b64 s[16:17], s[16:17], 2
	s_add_u32 s16, s26, s16
	s_addc_u32 s17, s27, s17
	s_or_b32 s83, s4, 12
	s_cmp_lt_u32 s83, s23
	global_load_dword v84, v97, s[16:17]
	s_cselect_b64 vcc, -1, 0
	s_and_b64 s[16:17], vcc, exec
	s_cselect_b32 s16, s83, s4
	s_ashr_i32 s17, s16, 31
	s_lshl_b64 s[18:19], s[16:17], 11
	v_lshl_add_u64 v[246:247], v[248:249], 0, s[18:19]
	global_load_dword v188, v[246:247], off offset:1536
	global_load_dword v187, v[246:247], off offset:1540
	s_add_i32 s16, s16, s14
	s_ashr_i32 s17, s16, 31
	s_lshl_b64 s[16:17], s[16:17], 2
	s_add_u32 s16, s26, s16
	s_addc_u32 s17, s27, s17
	s_or_b32 s81, s4, 13
	s_cmp_lt_u32 s81, s23
	global_load_dword v78, v97, s[16:17]
	s_cselect_b64 vcc, -1, 0
	s_and_b64 s[16:17], vcc, exec
	s_cselect_b32 s16, s81, s4
	s_ashr_i32 s17, s16, 31
	s_lshl_b64 s[18:19], s[16:17], 11
	v_lshl_add_u64 v[246:247], v[248:249], 0, s[18:19]
	global_load_dword v186, v[246:247], off offset:1536
	global_load_dword v87, v[246:247], off offset:1540
	s_add_i32 s16, s16, s14
	s_ashr_i32 s17, s16, 31
	s_lshl_b64 s[16:17], s[16:17], 2
	s_add_u32 s16, s26, s16
	s_addc_u32 s17, s27, s17
	s_or_b32 s78, s4, 14
	s_cmp_lt_u32 s78, s23
	global_load_dword v74, v97, s[16:17]
	s_cselect_b64 vcc, -1, 0
	s_and_b64 s[16:17], vcc, exec
	s_cselect_b32 s16, s78, s4
	s_ashr_i32 s17, s16, 31
	s_lshl_b64 s[18:19], s[16:17], 11
	v_lshl_add_u64 v[246:247], v[248:249], 0, s[18:19]
	global_load_dword v185, v[246:247], off offset:1536
	global_load_dword v89, v[246:247], off offset:1540
	s_add_i32 s16, s16, s14
	s_ashr_i32 s17, s16, 31
	s_lshl_b64 s[16:17], s[16:17], 2
	s_add_u32 s16, s26, s16
	s_addc_u32 s17, s27, s17
	s_or_b32 s76, s4, 15
	s_cmp_lt_u32 s76, s23
	global_load_dword v70, v97, s[16:17]
	s_cselect_b64 vcc, -1, 0
	s_and_b64 s[16:17], vcc, exec
	s_cselect_b32 s16, s76, s4
	s_ashr_i32 s17, s16, 31
	s_lshl_b64 s[18:19], s[16:17], 11
	v_lshl_add_u64 v[246:247], v[248:249], 0, s[18:19]
	global_load_dword v184, v[246:247], off offset:1536
	global_load_dword v91, v[246:247], off offset:1540
	s_add_i32 s16, s16, s14
	s_ashr_i32 s17, s16, 31
	s_lshl_b64 s[16:17], s[16:17], 2
	s_add_u32 s16, s26, s16
	s_addc_u32 s17, s27, s17
	s_or_b32 s73, s4, 16
	s_cmp_lt_u32 s73, s23
	global_load_dword v64, v97, s[16:17]
	s_cselect_b64 vcc, -1, 0
	s_and_b64 s[16:17], vcc, exec
	s_cselect_b32 s16, s73, s4
	s_ashr_i32 s17, s16, 31
	s_lshl_b64 s[18:19], s[16:17], 11
	v_lshl_add_u64 v[246:247], v[248:249], 0, s[18:19]
	global_load_dword v95, v[246:247], off offset:1536
	global_load_dword v93, v[246:247], off offset:1540
	s_add_i32 s16, s16, s14
	s_ashr_i32 s17, s16, 31
	s_lshl_b64 s[16:17], s[16:17], 2
	s_add_u32 s16, s26, s16
	s_addc_u32 s17, s27, s17
	s_or_b32 s74, s4, 17
	s_cmp_lt_u32 s74, s23
	global_load_dword v68, v97, s[16:17]
	s_cselect_b64 vcc, -1, 0
	s_and_b64 s[16:17], vcc, exec
	s_cselect_b32 s16, s74, s4
	s_ashr_i32 s17, s16, 31
	s_lshl_b64 s[18:19], s[16:17], 11
	v_lshl_add_u64 v[246:247], v[248:249], 0, s[18:19]
	global_load_dword v183, v[246:247], off offset:1536
	global_load_dword v182, v[246:247], off offset:1540
	s_add_i32 s16, s16, s14
	s_ashr_i32 s17, s16, 31
	s_lshl_b64 s[16:17], s[16:17], 2
	s_add_u32 s16, s26, s16
	s_addc_u32 s17, s27, s17
	s_or_b32 s71, s4, 18
	s_cmp_lt_u32 s71, s23
	global_load_dword v62, v97, s[16:17]
	s_cselect_b64 vcc, -1, 0
	s_and_b64 s[16:17], vcc, exec
	s_cselect_b32 s16, s71, s4
	s_ashr_i32 s17, s16, 31
	s_lshl_b64 s[18:19], s[16:17], 11
	v_lshl_add_u64 v[246:247], v[248:249], 0, s[18:19]
	global_load_dword v181, v[246:247], off offset:1536
	global_load_dword v99, v[246:247], off offset:1540
	s_add_i32 s16, s16, s14
	s_ashr_i32 s17, s16, 31
	s_lshl_b64 s[16:17], s[16:17], 2
	s_add_u32 s16, s26, s16
	s_addc_u32 s17, s27, s17
	s_or_b32 s69, s4, 19
	s_cmp_lt_u32 s69, s23
	global_load_dword v58, v97, s[16:17]
	s_cselect_b64 vcc, -1, 0
	s_and_b64 s[16:17], vcc, exec
	s_cselect_b32 s16, s69, s4
	s_ashr_i32 s17, s16, 31
	s_lshl_b64 s[18:19], s[16:17], 11
	v_lshl_add_u64 v[246:247], v[248:249], 0, s[18:19]
	global_load_dword v180, v[246:247], off offset:1536
	global_load_dword v179, v[246:247], off offset:1540
	s_add_i32 s16, s16, s14
	s_ashr_i32 s17, s16, 31
	s_lshl_b64 s[16:17], s[16:17], 2
	s_add_u32 s16, s26, s16
	s_addc_u32 s17, s27, s17
	s_or_b32 s68, s4, 20
	s_cmp_lt_u32 s68, s23
	global_load_dword v54, v97, s[16:17]
	s_cselect_b64 vcc, -1, 0
	s_and_b64 s[16:17], vcc, exec
	s_cselect_b32 s16, s68, s4
	s_ashr_i32 s17, s16, 31
	s_lshl_b64 s[18:19], s[16:17], 11
	v_lshl_add_u64 v[246:247], v[248:249], 0, s[18:19]
	global_load_dword v178, v[246:247], off offset:1536
	global_load_dword v55, v[246:247], off offset:1540
	s_add_i32 s16, s16, s14
	s_ashr_i32 s17, s16, 31
	s_lshl_b64 s[16:17], s[16:17], 2
	s_add_u32 s16, s26, s16
	s_addc_u32 s17, s27, s17
	s_or_b32 s67, s4, 21
	s_cmp_lt_u32 s67, s23
	global_load_dword v50, v97, s[16:17]
	s_cselect_b64 vcc, -1, 0
	s_and_b64 s[16:17], vcc, exec
	s_cselect_b32 s16, s67, s4
	s_ashr_i32 s17, s16, 31
	s_lshl_b64 s[18:19], s[16:17], 11
	v_lshl_add_u64 v[246:247], v[248:249], 0, s[18:19]
	global_load_dword v177, v[246:247], off offset:1536
	global_load_dword v176, v[246:247], off offset:1540
	s_add_i32 s16, s16, s14
	s_ashr_i32 s17, s16, 31
	s_lshl_b64 s[16:17], s[16:17], 2
	s_add_u32 s16, s26, s16
	s_addc_u32 s17, s27, s17
	s_or_b32 s66, s4, 22
	s_cmp_lt_u32 s66, s23
	global_load_dword v44, v97, s[16:17]
	s_cselect_b64 vcc, -1, 0
	s_and_b64 s[16:17], vcc, exec
	s_cselect_b32 s16, s66, s4
	s_ashr_i32 s17, s16, 31
	s_lshl_b64 s[18:19], s[16:17], 11
	v_lshl_add_u64 v[246:247], v[248:249], 0, s[18:19]
	global_load_dword v175, v[246:247], off offset:1536
	global_load_dword v45, v[246:247], off offset:1540
	s_add_i32 s16, s16, s14
	s_ashr_i32 s17, s16, 31
	s_lshl_b64 s[16:17], s[16:17], 2
	s_add_u32 s16, s26, s16
	s_addc_u32 s17, s27, s17
	s_or_b32 s63, s4, 23
	s_cmp_lt_u32 s63, s23
	global_load_dword v40, v97, s[16:17]
	s_cselect_b64 vcc, -1, 0
	s_and_b64 s[16:17], vcc, exec
	s_cselect_b32 s16, s63, s4
	s_ashr_i32 s17, s16, 31
	s_lshl_b64 s[18:19], s[16:17], 11
	v_lshl_add_u64 v[246:247], v[248:249], 0, s[18:19]
	global_load_dword v174, v[246:247], off offset:1536
	global_load_dword v41, v[246:247], off offset:1540
	s_add_i32 s16, s16, s14
	s_ashr_i32 s17, s16, 31
	s_lshl_b64 s[16:17], s[16:17], 2
	s_add_u32 s16, s26, s16
	s_addc_u32 s17, s27, s17
	s_or_b32 s62, s4, 24
	s_cmp_lt_u32 s62, s23
	global_load_dword v38, v97, s[16:17]
	s_cselect_b64 vcc, -1, 0
	s_and_b64 s[16:17], vcc, exec
	s_cselect_b32 s16, s62, s4
	s_ashr_i32 s17, s16, 31
	s_lshl_b64 s[18:19], s[16:17], 11
	v_lshl_add_u64 v[246:247], v[248:249], 0, s[18:19]
	global_load_dword v173, v[246:247], off offset:1536
	global_load_dword v39, v[246:247], off offset:1540
	s_add_i32 s16, s16, s14
	s_ashr_i32 s17, s16, 31
	s_lshl_b64 s[16:17], s[16:17], 2
	s_add_u32 s16, s26, s16
	s_addc_u32 s17, s27, s17
	s_or_b32 s21, s4, 25
	s_cmp_lt_u32 s21, s23
	global_load_dword v34, v97, s[16:17]
	s_cselect_b64 vcc, -1, 0
	s_and_b64 s[16:17], vcc, exec
	s_cselect_b32 s16, s21, s4
	s_ashr_i32 s17, s16, 31
	s_lshl_b64 s[18:19], s[16:17], 11
	v_lshl_add_u64 v[246:247], v[248:249], 0, s[18:19]
	global_load_dword v172, v[246:247], off offset:1536
	global_load_dword v35, v[246:247], off offset:1540
	s_add_i32 s16, s16, s14
	s_ashr_i32 s17, s16, 31
	s_lshl_b64 s[16:17], s[16:17], 2
	s_add_u32 s16, s26, s16
	s_addc_u32 s17, s27, s17
	s_or_b32 s34, s4, 26
	s_cmp_lt_u32 s34, s23
	global_load_dword v36, v97, s[16:17]
	s_cselect_b64 vcc, -1, 0
	s_and_b64 s[16:17], vcc, exec
	s_cselect_b32 s16, s34, s4
	s_ashr_i32 s17, s16, 31
	s_lshl_b64 s[18:19], s[16:17], 11
	v_lshl_add_u64 v[246:247], v[248:249], 0, s[18:19]
	global_load_dword v171, v[246:247], off offset:1536
	global_load_dword v37, v[246:247], off offset:1540
	s_add_i32 s16, s16, s14
	s_ashr_i32 s17, s16, 31
	s_lshl_b64 s[16:17], s[16:17], 2
	s_add_u32 s16, s26, s16
	s_addc_u32 s17, s27, s17
	s_or_b32 s19, s4, 27
	s_cmp_lt_u32 s19, s23
	global_load_dword v30, v97, s[16:17]
	s_cselect_b64 vcc, -1, 0
	s_and_b64 s[16:17], vcc, exec
	s_cselect_b32 s16, s19, s4
	s_ashr_i32 s17, s16, 31
	s_lshl_b64 s[30:31], s[16:17], 11
	v_lshl_add_u64 v[246:247], v[248:249], 0, s[30:31]
	global_load_dword v170, v[246:247], off offset:1536
	global_load_dword v31, v[246:247], off offset:1540
	s_add_i32 s16, s16, s14
	s_ashr_i32 s17, s16, 31
	s_lshl_b64 s[16:17], s[16:17], 2
	s_add_u32 s16, s26, s16
	s_addc_u32 s17, s27, s17
	s_or_b32 s20, s4, 28
	s_cmp_lt_u32 s20, s23
	global_load_dword v32, v97, s[16:17]
	s_cselect_b64 vcc, -1, 0
	s_and_b64 s[16:17], vcc, exec
	s_cselect_b32 s16, s20, s4
	s_ashr_i32 s17, s16, 31
	s_lshl_b64 s[30:31], s[16:17], 11
	v_lshl_add_u64 v[246:247], v[248:249], 0, s[30:31]
	global_load_dword v169, v[246:247], off offset:1536
	global_load_dword v33, v[246:247], off offset:1540
	s_add_i32 s16, s16, s14
	s_ashr_i32 s17, s16, 31
	s_lshl_b64 s[16:17], s[16:17], 2
	s_add_u32 s16, s26, s16
	s_addc_u32 s17, s27, s17
	s_or_b32 s18, s4, 29
	s_cmp_lt_u32 s18, s23
	global_load_dword v28, v97, s[16:17]
	s_cselect_b64 vcc, -1, 0
	s_and_b64 s[16:17], vcc, exec
	s_cselect_b32 s16, s18, s4
	s_ashr_i32 s17, s16, 31
	s_lshl_b64 s[30:31], s[16:17], 11
	v_lshl_add_u64 v[246:247], v[248:249], 0, s[30:31]
	global_load_dword v168, v[246:247], off offset:1536
	global_load_dword v29, v[246:247], off offset:1540
	s_add_i32 s16, s16, s14
	s_ashr_i32 s17, s16, 31
	s_lshl_b64 s[16:17], s[16:17], 2
	s_add_u32 s16, s26, s16
	s_addc_u32 s17, s27, s17
	s_or_b32 s15, s4, 30
	s_cmp_lt_u32 s15, s23
	global_load_dword v26, v97, s[16:17]
	s_cselect_b64 vcc, -1, 0
	s_and_b64 s[16:17], vcc, exec
	s_cselect_b32 s16, s15, s4
	s_ashr_i32 s17, s16, 31
	s_lshl_b64 s[30:31], s[16:17], 11
	v_lshl_add_u64 v[246:247], v[248:249], 0, s[30:31]
	global_load_dword v167, v[246:247], off offset:1536
	global_load_dword v166, v[246:247], off offset:1540
	s_add_i32 s16, s16, s14
	s_ashr_i32 s17, s16, 31
	s_lshl_b64 s[16:17], s[16:17], 2
	s_add_u32 s16, s26, s16
	s_addc_u32 s17, s27, s17
	s_or_b32 s5, s4, 31
	s_cmp_lt_u32 s5, s23
	global_load_dword v24, v97, s[16:17]
	s_cselect_b64 vcc, -1, 0
	s_and_b64 s[16:17], vcc, exec
	s_cselect_b32 s16, s5, s4
	s_ashr_i32 s17, s16, 31
	s_lshl_b64 s[30:31], s[16:17], 11
	v_lshl_add_u64 v[246:247], v[248:249], 0, s[30:31]
	global_load_dword v27, v[246:247], off offset:1536
	global_load_dword v25, v[246:247], off offset:1540
	s_add_i32 s16, s16, s14
	s_ashr_i32 s17, s16, 31
	s_lshl_b64 s[16:17], s[16:17], 2
	s_add_u32 s16, s26, s16
	s_addc_u32 s17, s27, s17
	s_add_i32 s80, s4, 32
	s_cmp_lt_u32 s80, s23
	global_load_dword v18, v97, s[16:17]
	s_cselect_b64 vcc, -1, 0
	s_and_b64 s[16:17], vcc, exec
	s_cselect_b32 s16, s80, s4
	s_ashr_i32 s17, s16, 31
	s_lshl_b64 s[30:31], s[16:17], 11
	v_lshl_add_u64 v[246:247], v[248:249], 0, s[30:31]
	global_load_dword v163, v[246:247], off offset:1536
	global_load_dword v162, v[246:247], off offset:1540
	s_add_i32 s16, s16, s14
	s_ashr_i32 s17, s16, 31
	s_lshl_b64 s[16:17], s[16:17], 2
	s_add_u32 s16, s26, s16
	s_addc_u32 s17, s27, s17
	s_add_i32 s82, s4, 33
	s_cmp_lt_u32 s82, s23
	global_load_dword v20, v97, s[16:17]
	s_cselect_b64 vcc, -1, 0
	s_and_b64 s[16:17], vcc, exec
	s_cselect_b32 s16, s82, s4
	s_ashr_i32 s17, s16, 31
	s_lshl_b64 s[30:31], s[16:17], 11
	v_lshl_add_u64 v[246:247], v[248:249], 0, s[30:31]
	global_load_dword v165, v[246:247], off offset:1536
	global_load_dword v164, v[246:247], off offset:1540
	s_add_i32 s16, s16, s14
	s_ashr_i32 s17, s16, 31
	s_lshl_b64 s[16:17], s[16:17], 2
	s_add_u32 s16, s26, s16
	s_addc_u32 s17, s27, s17
	s_add_i32 s79, s4, 34
	s_cmp_lt_u32 s79, s23
	global_load_dword v16, v97, s[16:17]
	s_cselect_b64 vcc, -1, 0
	s_and_b64 s[16:17], vcc, exec
	s_cselect_b32 s16, s79, s4
	s_ashr_i32 s17, s16, 31
	s_lshl_b64 s[30:31], s[16:17], 11
	v_lshl_add_u64 v[246:247], v[248:249], 0, s[30:31]
	global_load_dword v161, v[246:247], off offset:1536
	global_load_dword v160, v[246:247], off offset:1540
	s_add_i32 s16, s16, s14
	s_ashr_i32 s17, s16, 31
	s_lshl_b64 s[16:17], s[16:17], 2
	s_add_u32 s16, s26, s16
	s_addc_u32 s17, s27, s17
	s_add_i32 s77, s4, 35
	s_cmp_lt_u32 s77, s23
	global_load_dword v14, v97, s[16:17]
	s_cselect_b64 vcc, -1, 0
	s_and_b64 s[16:17], vcc, exec
	s_cselect_b32 s16, s77, s4
	s_ashr_i32 s17, s16, 31
	s_lshl_b64 s[30:31], s[16:17], 11
	v_lshl_add_u64 v[246:247], v[248:249], 0, s[30:31]
	global_load_dword v21, v[246:247], off offset:1536
	global_load_dword v19, v[246:247], off offset:1540
	s_add_i32 s16, s16, s14
	s_ashr_i32 s17, s16, 31
	s_lshl_b64 s[16:17], s[16:17], 2
	s_add_u32 s16, s26, s16
	s_addc_u32 s17, s27, s17
	s_add_i32 s75, s4, 36
	s_cmp_lt_u32 s75, s23
	global_load_dword v12, v97, s[16:17]
	s_cselect_b64 vcc, -1, 0
	s_and_b64 s[16:17], vcc, exec
	s_cselect_b32 s16, s75, s4
	s_ashr_i32 s17, s16, 31
	s_lshl_b64 s[30:31], s[16:17], 11
	v_lshl_add_u64 v[246:247], v[248:249], 0, s[30:31]
	global_load_dword v17, v[246:247], off offset:1536
	global_load_dword v15, v[246:247], off offset:1540
	s_add_i32 s16, s16, s14
	s_ashr_i32 s17, s16, 31
	s_lshl_b64 s[16:17], s[16:17], 2
	s_add_u32 s16, s26, s16
	s_addc_u32 s17, s27, s17
	s_add_i32 s72, s4, 37
	s_cmp_lt_u32 s72, s23
	global_load_dword v10, v97, s[16:17]
	s_cselect_b64 vcc, -1, 0
	s_and_b64 s[16:17], vcc, exec
	s_cselect_b32 s16, s72, s4
	s_ashr_i32 s17, s16, 31
	s_lshl_b64 s[30:31], s[16:17], 11
	v_lshl_add_u64 v[246:247], v[248:249], 0, s[30:31]
	global_load_dwordx2 v[202:203], v[246:247], off offset:1536
	s_add_i32 s16, s16, s14
	s_ashr_i32 s17, s16, 31
	s_lshl_b64 s[16:17], s[16:17], 2
	s_add_u32 s16, s26, s16
	s_addc_u32 s17, s27, s17
	s_add_i32 s70, s4, 38
	s_cmp_lt_u32 s70, s23
	s_cselect_b64 vcc, -1, 0
	s_and_b64 s[16:17], vcc, exec
	s_cselect_b32 s16, s70, s4
	s_ashr_i32 s17, s16, 31
	s_lshl_b64 s[30:31], s[16:17], 11
	v_lshl_add_u64 v[246:247], v[248:249], 0, s[30:31]
	global_load_dwordx2 v[204:205], v[246:247], off offset:1536
	s_add_i32 s16, s16, s14
	s_ashr_i32 s17, s16, 31
	s_lshl_b64 s[16:17], s[16:17], 2
	s_add_u32 s16, s26, s16
	s_addc_u32 s17, s27, s17
	s_mov_b64 s[30:31], 0x600
	v_readlane_b32 s5, v244, 0
	v_readlane_b32 vcc_lo, v244, 1
	v_readlane_b32 vcc_hi, v244, 2
	v_readlane_b32 s16, v244, 3
	v_readlane_b32 s17, v244, 4
	v_readlane_b32 s18, v244, 5
	v_readlane_b32 s19, v244, 6
	v_readlane_b32 s7, v244, 7
	v_readlane_b32 s35, v244, 8
	v_readlane_b32 s97, v244, 9
	v_readlane_b32 s96, v244, 10
	v_readlane_b32 s91, v244, 11
	v_readlane_b32 s90, v244, 12
	v_readlane_b32 s89, v244, 13
	v_readlane_b32 s87, v244, 14
	v_readlane_b32 s85, v244, 15
	v_readlane_b32 s88, v244, 16
	v_readlane_b32 s86, v244, 17
	v_readlane_b32 s84, v244, 18
	v_readlane_b32 s83, v244, 19
	v_readlane_b32 s81, v244, 20
	v_readlane_b32 s78, v244, 21
	v_readlane_b32 s76, v244, 22
	v_readlane_b32 s73, v244, 23
	v_readlane_b32 s74, v244, 24
	v_readlane_b32 s71, v244, 25
	v_readlane_b32 s69, v244, 26
	v_readlane_b32 s68, v244, 27
	v_readlane_b32 s67, v244, 28
	v_readlane_b32 s66, v244, 29
	v_readlane_b32 s63, v244, 30
	v_readlane_b32 s62, v244, 31
	v_readlane_b32 s21, v244, 32
	v_readlane_b32 s34, v244, 33
	v_readlane_b32 s30, v244, 34
	v_readlane_b32 s31, v244, 35
	v_readlane_b32 s20, v244, 36
	v_readlane_b32 s15, v244, 37
	v_readlane_b32 s80, v244, 38
	v_readlane_b32 s82, v244, 39
	v_readlane_b32 s79, v244, 40
	v_readlane_b32 s77, v244, 41
	v_readlane_b32 s75, v244, 42
	v_readlane_b32 s72, v244, 43
	v_readlane_b32 s70, v244, 44
	s_nop 4
	s_waitcnt vmcnt(0)
	s_add_i32 s5, s4, -8
	s_cmp_lt_u32 s5, s23
	s_cselect_b64 vcc, -1, 0
	s_and_b64 s[16:17], vcc, exec
	s_cselect_b32 s16, s5, s4
	s_ashr_i32 s17, s16, 31
	v_lshl_add_u64 v[8:9], s[2:3], 0, v[96:97]
	s_lshl_b64 s[18:19], s[16:17], 11
	v_lshl_add_u64 v[4:5], v[8:9], 0, s[18:19]
	s_add_i32 s16, s16, s14
	s_ashr_i32 s17, s16, 31
	s_lshl_b64 s[16:17], s[16:17], 2
	s_add_u32 s16, s26, s16
	s_addc_u32 s17, s27, s17
	s_add_i32 s5, s4, -7
	s_cmp_lt_u32 s5, s23
	s_waitcnt vmcnt(0)
	v_cndmask_b32_e32 v23, 0, v200, vcc
	v_cndmask_b32_e32 v5, 0, v201, vcc
	s_cselect_b64 vcc, -1, 0
	global_load_dword v4, v97, s[16:17]
	s_waitcnt vmcnt(0)
	s_and_b64 s[16:17], vcc, exec
	s_cselect_b32 s16, s5, s4
	s_ashr_i32 s17, s16, 31
	s_lshl_b64 s[18:19], s[16:17], 11
	v_lshl_add_u64 v[6:7], v[8:9], 0, s[18:19]
	s_add_i32 s16, s16, s14
	s_ashr_i32 s17, s16, 31
	s_lshl_b64 s[16:17], s[16:17], 2
	s_add_u32 s16, s26, s16
	s_addc_u32 s17, s27, s17
	s_add_i32 s5, s4, -6
	s_cmp_lt_u32 s5, s23
	v_lshlrev_b32_e32 v100, 16, v23
	v_and_b32_e32 v101, 0xffff0000, v23
	v_lshlrev_b32_e32 v110, 16, v5
	v_and_b32_e32 v111, 0xffff0000, v5
	s_waitcnt vmcnt(2)
	v_pk_mul_f32 v[156:157], v[4:5], v[110:111] op_sel_hi:[0,1]
	v_pk_mul_f32 v[158:159], v[4:5], v[100:101] op_sel_hi:[0,1]
	v_pk_fma_f32 v[100:101], v[4:5], v[100:101], 0 op_sel_hi:[0,1,0]
	v_pk_fma_f32 v[4:5], v[4:5], v[110:111], 0 op_sel_hi:[0,1,0]
	s_waitcnt vmcnt(1)
	v_cndmask_b32_e32 v47, 0, v47, vcc
	v_cndmask_b32_e32 v43, 0, v43, vcc
	s_cselect_b64 vcc, -1, 0
	s_and_b64 s[16:17], vcc, exec
	s_cselect_b32 s16, s5, s4
	s_ashr_i32 s17, s16, 31
	s_lshl_b64 s[18:19], s[16:17], 11
	v_lshl_add_u64 v[6:7], v[8:9], 0, s[18:19]
	s_add_i32 s16, s16, s14
	s_ashr_i32 s17, s16, 31
	s_lshl_b64 s[16:17], s[16:17], 2
	s_add_u32 s16, s26, s16
	s_addc_u32 s17, s27, s17
	s_add_i32 s5, s4, -5
	s_cmp_lt_u32 s5, s23
	v_lshlrev_b32_e32 v110, 16, v47
	v_and_b32_e32 v111, 0xffff0000, v47
	v_lshlrev_b32_e32 v112, 16, v43
	v_and_b32_e32 v113, 0xffff0000, v43
	s_waitcnt vmcnt(2)
	v_pk_mul_f32 v[152:153], v[22:23], v[112:113] op_sel_hi:[0,1]
	v_pk_mul_f32 v[154:155], v[22:23], v[110:111] op_sel_hi:[0,1]
	v_pk_fma_f32 v[4:5], v[22:23], v[112:113], v[4:5] op_sel_hi:[0,1,1]
	v_pk_fma_f32 v[22:23], v[22:23], v[110:111], v[100:101] op_sel_hi:[0,1,1]
	s_waitcnt vmcnt(1)
	v_cndmask_b32_e32 v51, 0, v51, vcc
	v_cndmask_b32_e32 v49, 0, v49, vcc
	s_cselect_b64 vcc, -1, 0
	s_and_b64 s[16:17], vcc, exec
	s_cselect_b32 s16, s5, s4
	s_ashr_i32 s17, s16, 31
	s_lshl_b64 s[18:19], s[16:17], 11
	v_lshl_add_u64 v[6:7], v[8:9], 0, s[18:19]
	s_add_i32 s16, s16, s14
	s_ashr_i32 s17, s16, 31
	s_lshl_b64 s[16:17], s[16:17], 2
	s_add_u32 s16, s26, s16
	s_addc_u32 s17, s27, s17
	s_add_i32 s5, s4, -4
	s_cmp_lt_u32 s5, s23
	v_lshlrev_b32_e32 v100, 16, v51
	v_and_b32_e32 v101, 0xffff0000, v51
	v_lshlrev_b32_e32 v110, 16, v49
	v_and_b32_e32 v111, 0xffff0000, v49
	s_waitcnt vmcnt(2)
	v_pk_mul_f32 v[148:149], v[42:43], v[110:111] op_sel_hi:[0,1]
	v_pk_mul_f32 v[150:151], v[42:43], v[100:101] op_sel_hi:[0,1]
	v_pk_fma_f32 v[22:23], v[42:43], v[100:101], v[22:23] op_sel_hi:[0,1,1]
	v_pk_fma_f32 v[4:5], v[42:43], v[110:111], v[4:5] op_sel_hi:[0,1,1]
	s_waitcnt vmcnt(1)
	v_cndmask_b32_e32 v57, 0, v57, vcc
	v_cndmask_b32_e32 v53, 0, v53, vcc
	s_cselect_b64 vcc, -1, 0
	s_and_b64 s[16:17], vcc, exec
	s_cselect_b32 s16, s5, s4
	s_ashr_i32 s17, s16, 31
	s_lshl_b64 s[18:19], s[16:17], 11
	v_lshl_add_u64 v[6:7], v[8:9], 0, s[18:19]
	s_add_i32 s16, s16, s14
	s_ashr_i32 s17, s16, 31
	s_lshl_b64 s[16:17], s[16:17], 2
	s_add_u32 s16, s26, s16
	s_addc_u32 s17, s27, s17
	s_add_i32 s5, s4, -3
	s_cmp_lt_u32 s5, s23
	v_lshlrev_b32_e32 v42, 16, v57
	v_and_b32_e32 v43, 0xffff0000, v57
	v_lshlrev_b32_e32 v100, 16, v53
	v_and_b32_e32 v101, 0xffff0000, v53
	s_waitcnt vmcnt(2)
	v_pk_mul_f32 v[146:147], v[46:47], v[42:43] op_sel_hi:[0,1]
	v_pk_fma_f32 v[22:23], v[46:47], v[42:43], v[22:23] op_sel_hi:[0,1,1]
	v_pk_mul_f32 v[144:145], v[46:47], v[100:101] op_sel_hi:[0,1]
	v_pk_fma_f32 v[4:5], v[46:47], v[100:101], v[4:5] op_sel_hi:[0,1,1]
	s_waitcnt vmcnt(1)
	v_cndmask_b32_e32 v61, 0, v61, vcc
	v_cndmask_b32_e32 v59, 0, v59, vcc
	s_cselect_b64 vcc, -1, 0
	s_and_b64 s[16:17], vcc, exec
	s_cselect_b32 s16, s5, s4
	s_ashr_i32 s17, s16, 31
	s_lshl_b64 s[18:19], s[16:17], 11
	v_lshl_add_u64 v[6:7], v[8:9], 0, s[18:19]
	s_add_i32 s16, s16, s14
	s_ashr_i32 s17, s16, 31
	s_lshl_b64 s[16:17], s[16:17], 2
	s_add_u32 s16, s26, s16
	s_addc_u32 s17, s27, s17
	s_add_i32 s5, s4, -2
	s_cmp_lt_u32 s5, s23
	v_lshlrev_b32_e32 v42, 16, v61
	v_and_b32_e32 v43, 0xffff0000, v61
	v_lshlrev_b32_e32 v46, 16, v59
	v_and_b32_e32 v47, 0xffff0000, v59
	s_waitcnt vmcnt(2)
	v_pk_mul_f32 v[142:143], v[48:49], v[42:43] op_sel_hi:[0,1]
	v_pk_fma_f32 v[22:23], v[48:49], v[42:43], v[22:23] op_sel_hi:[0,1,1]
	v_pk_mul_f32 v[140:141], v[48:49], v[46:47] op_sel_hi:[0,1]
	v_pk_fma_f32 v[4:5], v[48:49], v[46:47], v[4:5] op_sel_hi:[0,1,1]
	s_waitcnt vmcnt(1)
	v_cndmask_b32_e32 v65, 0, v65, vcc
	v_cndmask_b32_e32 v63, 0, v63, vcc
	s_cselect_b64 vcc, -1, 0
	s_and_b64 s[16:17], vcc, exec
	s_cselect_b32 s16, s5, s4
	s_ashr_i32 s17, s16, 31
	s_lshl_b64 s[18:19], s[16:17], 11
	v_lshl_add_u64 v[6:7], v[8:9], 0, s[18:19]
	s_add_i32 s16, s16, s14
	s_ashr_i32 s17, s16, 31
	s_lshl_b64 s[16:17], s[16:17], 2
	s_add_u32 s16, s26, s16
	s_addc_u32 s17, s27, s17
	s_add_i32 s5, s4, -1
	s_cmp_lt_u32 s5, s23
	v_lshlrev_b32_e32 v42, 16, v65
	v_and_b32_e32 v43, 0xffff0000, v65
	v_lshlrev_b32_e32 v46, 16, v63
	v_and_b32_e32 v47, 0xffff0000, v63
	s_waitcnt vmcnt(2)
	v_pk_mul_f32 v[138:139], v[52:53], v[42:43] op_sel_hi:[0,1]
	v_pk_fma_f32 v[22:23], v[52:53], v[42:43], v[22:23] op_sel_hi:[0,1,1]
	v_pk_mul_f32 v[136:137], v[52:53], v[46:47] op_sel_hi:[0,1]
	v_pk_fma_f32 v[4:5], v[52:53], v[46:47], v[4:5] op_sel_hi:[0,1,1]
	s_waitcnt vmcnt(1)
	v_cndmask_b32_e32 v69, 0, v69, vcc
	v_cndmask_b32_e32 v67, 0, v67, vcc
	s_cselect_b64 vcc, -1, 0
	s_and_b64 s[16:17], vcc, exec
	s_cselect_b32 s16, s5, s4
	s_ashr_i32 s17, s16, 31
	s_lshl_b64 s[18:19], s[16:17], 11
	v_lshl_add_u64 v[6:7], v[8:9], 0, s[18:19]
	s_add_i32 s16, s16, s14
	s_ashr_i32 s17, s16, 31
	s_lshl_b64 s[16:17], s[16:17], 2
	s_add_u32 s16, s26, s16
	s_addc_u32 s17, s27, s17
	s_cmp_lt_u32 s4, s23
	v_lshlrev_b32_e32 v42, 16, v69
	v_and_b32_e32 v43, 0xffff0000, v69
	v_lshlrev_b32_e32 v46, 16, v67
	v_and_b32_e32 v47, 0xffff0000, v67
	s_waitcnt vmcnt(2)
	v_pk_mul_f32 v[134:135], v[56:57], v[42:43] op_sel_hi:[0,1]
	v_pk_fma_f32 v[22:23], v[56:57], v[42:43], v[22:23] op_sel_hi:[0,1,1]
	v_pk_mul_f32 v[132:133], v[56:57], v[46:47] op_sel_hi:[0,1]
	v_pk_fma_f32 v[4:5], v[56:57], v[46:47], v[4:5] op_sel_hi:[0,1,1]
	s_waitcnt vmcnt(1)
	v_cndmask_b32_e32 v73, 0, v73, vcc
	v_cndmask_b32_e32 v71, 0, v71, vcc
	s_cselect_b64 vcc, -1, 0
	s_ashr_i32 s5, s4, 31
	s_lshl_b64 s[16:17], s[4:5], 11
	v_lshl_add_u64 v[6:7], v[8:9], 0, s[16:17]
	s_ashr_i32 s7, s6, 31
	s_lshl_b64 s[16:17], s[6:7], 2
	s_add_u32 s16, s26, s16
	s_addc_u32 s17, s27, s17
	s_or_b32 s35, s4, 1
	s_cmp_lt_u32 s35, s23
	v_lshlrev_b32_e32 v42, 16, v73
	v_and_b32_e32 v43, 0xffff0000, v73
	v_lshlrev_b32_e32 v46, 16, v71
	v_and_b32_e32 v47, 0xffff0000, v71
	s_waitcnt vmcnt(2)
	v_pk_mul_f32 v[130:131], v[60:61], v[42:43] op_sel_hi:[0,1]
	v_pk_fma_f32 v[22:23], v[60:61], v[42:43], v[22:23] op_sel_hi:[0,1,1]
	v_pk_mul_f32 v[128:129], v[60:61], v[46:47] op_sel_hi:[0,1]
	v_pk_fma_f32 v[4:5], v[60:61], v[46:47], v[4:5] op_sel_hi:[0,1,1]
	s_waitcnt vmcnt(1)
	v_cndmask_b32_e32 v77, 0, v77, vcc
	v_cndmask_b32_e32 v75, 0, v75, vcc
	s_cselect_b64 vcc, -1, 0
	s_and_b64 s[16:17], vcc, exec
	s_cselect_b32 s16, s35, s4
	s_ashr_i32 s17, s16, 31
	s_lshl_b64 s[18:19], s[16:17], 11
	v_lshl_add_u64 v[6:7], v[8:9], 0, s[18:19]
	s_add_i32 s16, s16, s14
	s_ashr_i32 s17, s16, 31
	s_lshl_b64 s[16:17], s[16:17], 2
	s_add_u32 s16, s26, s16
	s_addc_u32 s17, s27, s17
	s_or_b32 s97, s4, 2
	s_cmp_lt_u32 s97, s23
	v_lshlrev_b32_e32 v42, 16, v77
	v_and_b32_e32 v43, 0xffff0000, v77
	v_lshlrev_b32_e32 v46, 16, v75
	v_and_b32_e32 v47, 0xffff0000, v75
	s_waitcnt vmcnt(2)
	v_pk_mul_f32 v[126:127], v[66:67], v[42:43] op_sel_hi:[0,1]
	v_pk_fma_f32 v[22:23], v[66:67], v[42:43], v[22:23] op_sel_hi:[0,1,1]
	v_pk_mul_f32 v[124:125], v[66:67], v[46:47] op_sel_hi:[0,1]
	v_pk_fma_f32 v[4:5], v[66:67], v[46:47], v[4:5] op_sel_hi:[0,1,1]
	s_waitcnt vmcnt(1)
	v_cndmask_b32_e32 v81, 0, v81, vcc
	v_cndmask_b32_e32 v79, 0, v79, vcc
	s_cselect_b64 vcc, -1, 0
	s_and_b64 s[16:17], vcc, exec
	s_cselect_b32 s16, s97, s4
	s_ashr_i32 s17, s16, 31
	s_lshl_b64 s[18:19], s[16:17], 11
	v_lshl_add_u64 v[6:7], v[8:9], 0, s[18:19]
	s_add_i32 s16, s16, s14
	s_ashr_i32 s17, s16, 31
	s_lshl_b64 s[16:17], s[16:17], 2
	s_add_u32 s16, s26, s16
	s_addc_u32 s17, s27, s17
	s_or_b32 s96, s4, 3
	s_cmp_lt_u32 s96, s23
	v_lshlrev_b32_e32 v42, 16, v81
	v_and_b32_e32 v43, 0xffff0000, v81
	v_lshlrev_b32_e32 v46, 16, v79
	v_and_b32_e32 v47, 0xffff0000, v79
	s_waitcnt vmcnt(2)
	v_pk_mul_f32 v[122:123], v[72:73], v[42:43] op_sel_hi:[0,1]
	v_pk_fma_f32 v[22:23], v[72:73], v[42:43], v[22:23] op_sel_hi:[0,1,1]
	v_pk_mul_f32 v[120:121], v[72:73], v[46:47] op_sel_hi:[0,1]
	v_pk_fma_f32 v[4:5], v[72:73], v[46:47], v[4:5] op_sel_hi:[0,1,1]
	s_waitcnt vmcnt(1)
	v_cndmask_b32_e32 v85, 0, v85, vcc
	v_cndmask_b32_e32 v83, 0, v83, vcc
	s_cselect_b64 vcc, -1, 0
	s_and_b64 s[16:17], vcc, exec
	s_cselect_b32 s16, s96, s4
	s_ashr_i32 s17, s16, 31
	s_lshl_b64 s[18:19], s[16:17], 11
	v_lshl_add_u64 v[6:7], v[8:9], 0, s[18:19]
	s_add_i32 s16, s16, s14
	s_ashr_i32 s17, s16, 31
	s_lshl_b64 s[16:17], s[16:17], 2
	s_add_u32 s16, s26, s16
	s_addc_u32 s17, s27, s17
	s_or_b32 s91, s4, 4
	s_cmp_lt_u32 s91, s23
	v_lshlrev_b32_e32 v42, 16, v85
	v_and_b32_e32 v43, 0xffff0000, v85
	v_lshlrev_b32_e32 v46, 16, v83
	v_and_b32_e32 v47, 0xffff0000, v83
	s_waitcnt vmcnt(2)
	v_pk_mul_f32 v[118:119], v[76:77], v[42:43] op_sel_hi:[0,1]
	v_pk_fma_f32 v[22:23], v[76:77], v[42:43], v[22:23] op_sel_hi:[0,1,1]
	v_pk_mul_f32 v[100:101], v[76:77], v[46:47] op_sel_hi:[0,1]
	v_pk_fma_f32 v[4:5], v[76:77], v[46:47], v[4:5] op_sel_hi:[0,1,1]
	s_waitcnt vmcnt(1)
	v_cndmask_b32_e32 v103, 0, v103, vcc
	v_cndmask_b32_e32 v102, 0, v102, vcc
	s_cselect_b64 vcc, -1, 0
	s_and_b64 s[16:17], vcc, exec
	s_cselect_b32 s16, s91, s4
	s_ashr_i32 s17, s16, 31
	s_lshl_b64 s[18:19], s[16:17], 11
	v_lshl_add_u64 v[6:7], v[8:9], 0, s[18:19]
	s_add_i32 s16, s16, s14
	s_ashr_i32 s17, s16, 31
	s_lshl_b64 s[16:17], s[16:17], 2
	s_add_u32 s16, s26, s16
	s_addc_u32 s17, s27, s17
	s_or_b32 s90, s4, 5
	s_cmp_lt_u32 s90, s23
	v_lshlrev_b32_e32 v42, 16, v103
	v_and_b32_e32 v43, 0xffff0000, v103
	v_lshlrev_b32_e32 v46, 16, v102
	v_and_b32_e32 v47, 0xffff0000, v102
	s_waitcnt vmcnt(2)
	v_pk_mul_f32 v[116:117], v[80:81], v[42:43] op_sel_hi:[0,1]
	v_pk_fma_f32 v[22:23], v[80:81], v[42:43], v[22:23] op_sel_hi:[0,1,1]
	v_pk_mul_f32 v[102:103], v[80:81], v[46:47] op_sel_hi:[0,1]
	v_pk_fma_f32 v[4:5], v[80:81], v[46:47], v[4:5] op_sel_hi:[0,1,1]
	s_waitcnt vmcnt(1)
	v_cndmask_b32_e32 v105, 0, v105, vcc
	v_cndmask_b32_e32 v104, 0, v104, vcc
	s_cselect_b64 vcc, -1, 0
	s_and_b64 s[16:17], vcc, exec
	s_cselect_b32 s16, s90, s4
	s_ashr_i32 s17, s16, 31
	s_lshl_b64 s[18:19], s[16:17], 11
	v_lshl_add_u64 v[6:7], v[8:9], 0, s[18:19]
	s_add_i32 s16, s16, s14
	s_ashr_i32 s17, s16, 31
	s_lshl_b64 s[16:17], s[16:17], 2
	s_add_u32 s16, s26, s16
	s_addc_u32 s17, s27, s17
	s_or_b32 s89, s4, 6
	s_cmp_lt_u32 s89, s23
	v_lshlrev_b32_e32 v42, 16, v105
	v_and_b32_e32 v43, 0xffff0000, v105
	v_lshlrev_b32_e32 v46, 16, v104
	v_and_b32_e32 v47, 0xffff0000, v104
	s_waitcnt vmcnt(2)
	v_pk_mul_f32 v[114:115], v[82:83], v[42:43] op_sel_hi:[0,1]
	v_pk_fma_f32 v[22:23], v[82:83], v[42:43], v[22:23] op_sel_hi:[0,1,1]
	v_pk_mul_f32 v[104:105], v[82:83], v[46:47] op_sel_hi:[0,1]
	v_pk_fma_f32 v[4:5], v[82:83], v[46:47], v[4:5] op_sel_hi:[0,1,1]
	s_waitcnt vmcnt(1)
	v_cndmask_b32_e32 v107, 0, v107, vcc
	v_cndmask_b32_e32 v106, 0, v106, vcc
	s_cselect_b64 vcc, -1, 0
	s_and_b64 s[16:17], vcc, exec
	s_cselect_b32 s16, s89, s4
	s_ashr_i32 s17, s16, 31
	s_lshl_b64 s[18:19], s[16:17], 11
	v_lshl_add_u64 v[6:7], v[8:9], 0, s[18:19]
	s_add_i32 s16, s16, s14
	s_ashr_i32 s17, s16, 31
	s_lshl_b64 s[16:17], s[16:17], 2
	s_add_u32 s16, s26, s16
	s_addc_u32 s17, s27, s17
	s_or_b32 s87, s4, 7
	s_cmp_lt_u32 s87, s23
	v_lshlrev_b32_e32 v42, 16, v107
	v_and_b32_e32 v43, 0xffff0000, v107
	v_lshlrev_b32_e32 v46, 16, v106
	v_and_b32_e32 v47, 0xffff0000, v106
	s_waitcnt vmcnt(1)
	v_cndmask_b32_e32 v109, 0, v109, vcc
	v_cndmask_b32_e32 v108, 0, v108, vcc
	s_cselect_b64 vcc, -1, 0
	s_and_b64 s[16:17], vcc, exec
	s_cselect_b32 s16, s87, s4
	s_ashr_i32 s17, s16, 31
	s_lshl_b64 s[18:19], s[16:17], 11
	v_lshl_add_u64 v[6:7], v[8:9], 0, s[18:19]
	s_add_i32 s16, s16, s14
	s_ashr_i32 s17, s16, 31
	s_lshl_b64 s[16:17], s[16:17], 2
	s_add_u32 s16, s26, s16
	s_addc_u32 s17, s27, s17
	s_or_b32 s85, s4, 8
	s_cmp_lt_u32 s85, s23
	s_waitcnt vmcnt(1)
	v_cndmask_b32_e32 v196, 0, v196, vcc
	v_cndmask_b32_e32 v195, 0, v195, vcc
	s_cselect_b64 vcc, -1, 0
	s_and_b64 s[16:17], vcc, exec
	s_cselect_b32 s16, s85, s4
	s_ashr_i32 s17, s16, 31
	s_lshl_b64 s[18:19], s[16:17], 11
	v_lshl_add_u64 v[6:7], v[8:9], 0, s[18:19]
	s_add_i32 s16, s16, s14
	s_ashr_i32 s17, s16, 31
	s_lshl_b64 s[16:17], s[16:17], 2
	s_add_u32 s16, s26, s16
	s_addc_u32 s17, s27, s17
	s_or_b32 s88, s4, 9
	s_cmp_lt_u32 s88, s23
	v_lshlrev_b32_e32 v48, 16, v196
	v_and_b32_e32 v49, 0xffff0000, v196
	v_lshlrev_b32_e32 v52, 16, v195
	v_and_b32_e32 v53, 0xffff0000, v195
	s_waitcnt vmcnt(1)
	v_cndmask_b32_e32 v194, 0, v194, vcc
	v_cndmask_b32_e32 v193, 0, v193, vcc
	s_cselect_b64 vcc, -1, 0
	s_and_b64 s[16:17], vcc, exec
	s_cselect_b32 s16, s88, s4
	s_ashr_i32 s17, s16, 31
	s_lshl_b64 s[18:19], s[16:17], 11
	v_lshl_add_u64 v[6:7], v[8:9], 0, s[18:19]
	s_add_i32 s16, s16, s14
	s_ashr_i32 s17, s16, 31
	s_lshl_b64 s[16:17], s[16:17], 2
	s_add_u32 s16, s26, s16
	s_addc_u32 s17, s27, s17
	s_or_b32 s86, s4, 10
	s_cmp_lt_u32 s86, s23
	v_lshlrev_b32_e32 v72, 16, v193
	v_and_b32_e32 v73, 0xffff0000, v193
	v_lshlrev_b32_e32 v66, 16, v194
	v_and_b32_e32 v67, 0xffff0000, v194
	s_waitcnt vmcnt(1)
	v_cndmask_b32_e32 v198, 0, v198, vcc
	v_cndmask_b32_e32 v197, 0, v197, vcc
	s_cselect_b64 vcc, -1, 0
	s_and_b64 s[16:17], vcc, exec
	s_cselect_b32 s16, s86, s4
	s_ashr_i32 s17, s16, 31
	s_lshl_b64 s[18:19], s[16:17], 11
	v_lshl_add_u64 v[6:7], v[8:9], 0, s[18:19]
	s_add_i32 s16, s16, s14
	s_ashr_i32 s17, s16, 31
	s_lshl_b64 s[16:17], s[16:17], 2
	s_add_u32 s16, s26, s16
	s_addc_u32 s17, s27, s17
	s_or_b32 s84, s4, 11
	s_cmp_lt_u32 s84, s23
	v_lshlrev_b32_e32 v76, 16, v198
	v_and_b32_e32 v77, 0xffff0000, v198
	v_lshlrev_b32_e32 v80, 16, v197
	v_and_b32_e32 v81, 0xffff0000, v197
	s_waitcnt vmcnt(1)
	v_cndmask_b32_e32 v192, 0, v192, vcc
	v_cndmask_b32_e32 v191, 0, v191, vcc
	s_cselect_b64 vcc, -1, 0
	s_and_b64 s[16:17], vcc, exec
	s_cselect_b32 s16, s84, s4
	s_ashr_i32 s17, s16, 31
	s_lshl_b64 s[18:19], s[16:17], 11
	v_lshl_add_u64 v[6:7], v[8:9], 0, s[18:19]
	s_add_i32 s16, s16, s14
	s_ashr_i32 s17, s16, 31
	s_lshl_b64 s[16:17], s[16:17], 2
	s_add_u32 s16, s26, s16
	s_addc_u32 s17, s27, s17
	s_or_b32 s83, s4, 12
	s_cmp_lt_u32 s83, s23
	s_waitcnt vmcnt(1)
	v_cndmask_b32_e32 v190, 0, v190, vcc
	v_cndmask_b32_e32 v189, 0, v189, vcc
	s_cselect_b64 vcc, -1, 0
	s_and_b64 s[16:17], vcc, exec
	s_cselect_b32 s16, s83, s4
	s_ashr_i32 s17, s16, 31
	s_lshl_b64 s[18:19], s[16:17], 11
	v_lshl_add_u64 v[6:7], v[8:9], 0, s[18:19]
	s_add_i32 s16, s16, s14
	s_ashr_i32 s17, s16, 31
	s_lshl_b64 s[16:17], s[16:17], 2
	s_add_u32 s16, s26, s16
	s_addc_u32 s17, s27, s17
	s_or_b32 s81, s4, 13
	s_cmp_lt_u32 s81, s23
	s_waitcnt vmcnt(1)
	v_cndmask_b32_e32 v188, 0, v188, vcc
	v_cndmask_b32_e32 v187, 0, v187, vcc
	s_cselect_b64 vcc, -1, 0
	s_and_b64 s[16:17], vcc, exec
	s_cselect_b32 s16, s81, s4
	s_ashr_i32 s17, s16, 31
	s_lshl_b64 s[18:19], s[16:17], 11
	v_lshl_add_u64 v[6:7], v[8:9], 0, s[18:19]
	s_add_i32 s16, s16, s14
	s_ashr_i32 s17, s16, 31
	s_lshl_b64 s[16:17], s[16:17], 2
	s_add_u32 s16, s26, s16
	s_addc_u32 s17, s27, s17
	s_or_b32 s78, s4, 14
	s_cmp_lt_u32 s78, s23
	s_waitcnt vmcnt(1)
	v_cndmask_b32_e32 v186, 0, v186, vcc
	v_cndmask_b32_e32 v87, 0, v87, vcc
	s_cselect_b64 vcc, -1, 0
	s_and_b64 s[16:17], vcc, exec
	s_cselect_b32 s16, s78, s4
	s_ashr_i32 s17, s16, 31
	s_lshl_b64 s[18:19], s[16:17], 11
	v_lshl_add_u64 v[6:7], v[8:9], 0, s[18:19]
	s_add_i32 s16, s16, s14
	s_ashr_i32 s17, s16, 31
	s_lshl_b64 s[16:17], s[16:17], 2
	s_add_u32 s16, s26, s16
	s_addc_u32 s17, s27, s17
	s_or_b32 s76, s4, 15
	s_cmp_lt_u32 s76, s23
	v_pk_mul_f32 v[112:113], v[86:87], v[42:43] op_sel_hi:[0,1]
	v_pk_fma_f32 v[22:23], v[86:87], v[42:43], v[22:23] op_sel_hi:[0,1,1]
	v_lshlrev_b32_e32 v42, 16, v109
	v_and_b32_e32 v43, 0xffff0000, v109
	v_pk_mul_f32 v[106:107], v[86:87], v[46:47] op_sel_hi:[0,1]
	v_pk_fma_f32 v[4:5], v[86:87], v[46:47], v[4:5] op_sel_hi:[0,1,1]
	v_lshlrev_b32_e32 v46, 16, v108
	v_and_b32_e32 v47, 0xffff0000, v108
	s_waitcnt vmcnt(1)
	v_cndmask_b32_e32 v185, 0, v185, vcc
	v_cndmask_b32_e32 v89, 0, v89, vcc
	s_cselect_b64 vcc, -1, 0
	s_and_b64 s[16:17], vcc, exec
	s_cselect_b32 s16, s76, s4
	s_ashr_i32 s17, s16, 31
	s_lshl_b64 s[18:19], s[16:17], 11
	v_lshl_add_u64 v[6:7], v[8:9], 0, s[18:19]
	s_add_i32 s16, s16, s14
	s_ashr_i32 s17, s16, 31
	s_lshl_b64 s[16:17], s[16:17], 2
	s_add_u32 s16, s26, s16
	s_addc_u32 s17, s27, s17
	s_or_b32 s73, s4, 16
	s_cmp_lt_u32 s73, s23
	s_waitcnt vmcnt(1)
	v_cndmask_b32_e32 v184, 0, v184, vcc
	v_cndmask_b32_e32 v91, 0, v91, vcc
	s_cselect_b64 vcc, -1, 0
	s_and_b64 s[16:17], vcc, exec
	s_cselect_b32 s16, s73, s4
	s_ashr_i32 s17, s16, 31
	s_lshl_b64 s[18:19], s[16:17], 11
	v_lshl_add_u64 v[6:7], v[8:9], 0, s[18:19]
	s_add_i32 s16, s16, s14
	s_ashr_i32 s17, s16, 31
	s_lshl_b64 s[16:17], s[16:17], 2
	s_add_u32 s16, s26, s16
	s_addc_u32 s17, s27, s17
	s_or_b32 s74, s4, 17
	s_cmp_lt_u32 s74, s23
	v_pk_fma_f32 v[22:23], v[90:91], v[42:43], v[22:23] op_sel_hi:[0,1,1]
	v_pk_fma_f32 v[4:5], v[90:91], v[46:47], v[4:5] op_sel_hi:[0,1,1]
	v_pk_mul_f32 v[110:111], v[90:91], v[42:43] op_sel_hi:[0,1]
	v_pk_mul_f32 v[108:109], v[90:91], v[46:47] op_sel_hi:[0,1]
	s_waitcnt vmcnt(1)
	v_cndmask_b32_e32 v95, 0, v95, vcc
	v_cndmask_b32_e32 v93, 0, v93, vcc
	s_cselect_b64 vcc, -1, 0
	s_and_b64 s[16:17], vcc, exec
	s_cselect_b32 s16, s74, s4
	s_ashr_i32 s17, s16, 31
	s_lshl_b64 s[18:19], s[16:17], 11
	v_lshl_add_u64 v[6:7], v[8:9], 0, s[18:19]
	s_add_i32 s16, s16, s14
	s_ashr_i32 s17, s16, 31
	s_lshl_b64 s[16:17], s[16:17], 2
	s_add_u32 s16, s26, s16
	s_addc_u32 s17, s27, s17
	s_or_b32 s71, s4, 18
	s_cmp_lt_u32 s71, s23
	v_pk_fma_f32 v[56:57], v[92:93], v[48:49], v[22:23] op_sel_hi:[0,1,1]
	v_pk_mul_f32 v[42:43], v[92:93], v[52:53] op_sel_hi:[0,1]
	v_pk_fma_f32 v[52:53], v[92:93], v[52:53], v[4:5] op_sel_hi:[0,1,1]
	v_pk_mul_f32 v[46:47], v[92:93], v[48:49] op_sel_hi:[0,1]
	s_waitcnt vmcnt(1)
	v_cndmask_b32_e32 v183, 0, v183, vcc
	v_cndmask_b32_e32 v182, 0, v182, vcc
	s_cselect_b64 vcc, -1, 0
	s_and_b64 s[16:17], vcc, exec
	s_cselect_b32 s16, s71, s4
	s_ashr_i32 s17, s16, 31
	s_lshl_b64 s[18:19], s[16:17], 11
	v_lshl_add_u64 v[6:7], v[8:9], 0, s[18:19]
	s_add_i32 s16, s16, s14
	s_ashr_i32 s17, s16, 31
	s_lshl_b64 s[16:17], s[16:17], 2
	s_add_u32 s16, s26, s16
	s_addc_u32 s17, s27, s17
	s_or_b32 s69, s4, 19
	s_cmp_lt_u32 s69, s23
	s_waitcnt vmcnt(1)
	v_cndmask_b32_e32 v181, 0, v181, vcc
	v_cndmask_b32_e32 v99, 0, v99, vcc
	s_cselect_b64 vcc, -1, 0
	s_and_b64 s[16:17], vcc, exec
	s_cselect_b32 s16, s69, s4
	s_ashr_i32 s17, s16, 31
	s_lshl_b64 s[18:19], s[16:17], 11
	v_lshl_add_u64 v[6:7], v[8:9], 0, s[18:19]
	s_add_i32 s16, s16, s14
	s_ashr_i32 s17, s16, 31
	s_lshl_b64 s[16:17], s[16:17], 2
	s_add_u32 s16, s26, s16
	s_addc_u32 s17, s27, s17
	s_or_b32 s68, s4, 20
	s_cmp_lt_u32 s68, s23
	s_waitcnt vmcnt(1)
	v_cndmask_b32_e32 v180, 0, v180, vcc
	v_cndmask_b32_e32 v179, 0, v179, vcc
	s_cselect_b64 vcc, -1, 0
	s_and_b64 s[16:17], vcc, exec
	s_cselect_b32 s16, s68, s4
	s_ashr_i32 s17, s16, 31
	s_lshl_b64 s[18:19], s[16:17], 11
	v_lshl_add_u64 v[6:7], v[8:9], 0, s[18:19]
	s_add_i32 s16, s16, s14
	s_ashr_i32 s17, s16, 31
	s_lshl_b64 s[16:17], s[16:17], 2
	s_add_u32 s16, s26, s16
	s_addc_u32 s17, s27, s17
	s_or_b32 s67, s4, 21
	s_cmp_lt_u32 s67, s23
	s_waitcnt vmcnt(1)
	v_cndmask_b32_e32 v178, 0, v178, vcc
	v_cndmask_b32_e32 v55, 0, v55, vcc
	s_cselect_b64 vcc, -1, 0
	s_and_b64 s[16:17], vcc, exec
	s_cselect_b32 s16, s67, s4
	s_ashr_i32 s17, s16, 31
	s_lshl_b64 s[18:19], s[16:17], 11
	v_lshl_add_u64 v[6:7], v[8:9], 0, s[18:19]
	s_add_i32 s16, s16, s14
	s_ashr_i32 s17, s16, 31
	s_lshl_b64 s[16:17], s[16:17], 2
	s_add_u32 s16, s26, s16
	s_addc_u32 s17, s27, s17
	s_or_b32 s66, s4, 22
	s_cmp_lt_u32 s66, s23
	s_waitcnt vmcnt(1)
	v_cndmask_b32_e32 v177, 0, v177, vcc
	v_cndmask_b32_e32 v176, 0, v176, vcc
	s_cselect_b64 vcc, -1, 0
	s_and_b64 s[16:17], vcc, exec
	s_cselect_b32 s16, s66, s4
	s_ashr_i32 s17, s16, 31
	s_lshl_b64 s[18:19], s[16:17], 11
	v_lshl_add_u64 v[6:7], v[8:9], 0, s[18:19]
	s_add_i32 s16, s16, s14
	s_ashr_i32 s17, s16, 31
	s_lshl_b64 s[16:17], s[16:17], 2
	s_add_u32 s16, s26, s16
	s_addc_u32 s17, s27, s17
	s_or_b32 s63, s4, 23
	s_cmp_lt_u32 s63, s23
	s_waitcnt vmcnt(1)
	v_cndmask_b32_e32 v175, 0, v175, vcc
	v_cndmask_b32_e32 v45, 0, v45, vcc
	s_cselect_b64 vcc, -1, 0
	s_and_b64 s[16:17], vcc, exec
	s_cselect_b32 s16, s63, s4
	s_ashr_i32 s17, s16, 31
	s_lshl_b64 s[18:19], s[16:17], 11
	v_lshl_add_u64 v[6:7], v[8:9], 0, s[18:19]
	s_add_i32 s16, s16, s14
	s_ashr_i32 s17, s16, 31
	s_lshl_b64 s[16:17], s[16:17], 2
	s_add_u32 s16, s26, s16
	s_addc_u32 s17, s27, s17
	s_or_b32 s62, s4, 24
	s_cmp_lt_u32 s62, s23
	s_waitcnt vmcnt(1)
	v_cndmask_b32_e32 v174, 0, v174, vcc
	v_cndmask_b32_e32 v41, 0, v41, vcc
	s_cselect_b64 vcc, -1, 0
	s_and_b64 s[16:17], vcc, exec
	s_cselect_b32 s16, s62, s4
	s_ashr_i32 s17, s16, 31
	s_lshl_b64 s[18:19], s[16:17], 11
	v_lshl_add_u64 v[6:7], v[8:9], 0, s[18:19]
	s_add_i32 s16, s16, s14
	s_ashr_i32 s17, s16, 31
	s_lshl_b64 s[16:17], s[16:17], 2
	s_add_u32 s16, s26, s16
	s_addc_u32 s17, s27, s17
	s_or_b32 s21, s4, 25
	s_cmp_lt_u32 s21, s23
	s_waitcnt vmcnt(1)
	v_cndmask_b32_e32 v173, 0, v173, vcc
	v_cndmask_b32_e32 v39, 0, v39, vcc
	s_cselect_b64 vcc, -1, 0
	s_and_b64 s[16:17], vcc, exec
	s_cselect_b32 s16, s21, s4
	s_ashr_i32 s17, s16, 31
	s_lshl_b64 s[18:19], s[16:17], 11
	v_lshl_add_u64 v[6:7], v[8:9], 0, s[18:19]
	s_add_i32 s16, s16, s14
	s_ashr_i32 s17, s16, 31
	s_lshl_b64 s[16:17], s[16:17], 2
	s_add_u32 s16, s26, s16
	s_addc_u32 s17, s27, s17
	s_or_b32 s34, s4, 26
	s_cmp_lt_u32 s34, s23
	s_waitcnt vmcnt(1)
	v_cndmask_b32_e32 v172, 0, v172, vcc
	v_cndmask_b32_e32 v35, 0, v35, vcc
	s_cselect_b64 vcc, -1, 0
	s_and_b64 s[16:17], vcc, exec
	s_cselect_b32 s16, s34, s4
	s_ashr_i32 s17, s16, 31
	s_lshl_b64 s[18:19], s[16:17], 11
	v_lshl_add_u64 v[6:7], v[8:9], 0, s[18:19]
	s_add_i32 s16, s16, s14
	s_ashr_i32 s17, s16, 31
	s_lshl_b64 s[16:17], s[16:17], 2
	s_add_u32 s16, s26, s16
	s_addc_u32 s17, s27, s17
	s_or_b32 s19, s4, 27
	s_cmp_lt_u32 s19, s23
	s_waitcnt vmcnt(1)
	v_cndmask_b32_e32 v171, 0, v171, vcc
	v_cndmask_b32_e32 v37, 0, v37, vcc
	s_cselect_b64 vcc, -1, 0
	s_and_b64 s[16:17], vcc, exec
	s_cselect_b32 s16, s19, s4
	s_ashr_i32 s17, s16, 31
	s_lshl_b64 s[30:31], s[16:17], 11
	v_lshl_add_u64 v[6:7], v[8:9], 0, s[30:31]
	s_add_i32 s16, s16, s14
	s_ashr_i32 s17, s16, 31
	s_lshl_b64 s[16:17], s[16:17], 2
	s_add_u32 s16, s26, s16
	s_addc_u32 s17, s27, s17
	s_or_b32 s20, s4, 28
	s_cmp_lt_u32 s20, s23
	s_waitcnt vmcnt(1)
	v_cndmask_b32_e32 v170, 0, v170, vcc
	v_cndmask_b32_e32 v31, 0, v31, vcc
	s_cselect_b64 vcc, -1, 0
	s_and_b64 s[16:17], vcc, exec
	s_cselect_b32 s16, s20, s4
	s_ashr_i32 s17, s16, 31
	s_lshl_b64 s[30:31], s[16:17], 11
	v_lshl_add_u64 v[6:7], v[8:9], 0, s[30:31]
	s_add_i32 s16, s16, s14
	s_ashr_i32 s17, s16, 31
	s_lshl_b64 s[16:17], s[16:17], 2
	s_add_u32 s16, s26, s16
	s_addc_u32 s17, s27, s17
	s_or_b32 s18, s4, 29
	s_cmp_lt_u32 s18, s23
	s_waitcnt vmcnt(1)
	v_cndmask_b32_e32 v169, 0, v169, vcc
	v_cndmask_b32_e32 v33, 0, v33, vcc
	s_cselect_b64 vcc, -1, 0
	s_and_b64 s[16:17], vcc, exec
	s_cselect_b32 s16, s18, s4
	s_ashr_i32 s17, s16, 31
	s_lshl_b64 s[30:31], s[16:17], 11
	v_lshl_add_u64 v[6:7], v[8:9], 0, s[30:31]
	s_add_i32 s16, s16, s14
	s_ashr_i32 s17, s16, 31
	s_lshl_b64 s[16:17], s[16:17], 2
	s_add_u32 s16, s26, s16
	s_addc_u32 s17, s27, s17
	s_or_b32 s15, s4, 30
	s_cmp_lt_u32 s15, s23
	s_waitcnt vmcnt(1)
	v_cndmask_b32_e32 v168, 0, v168, vcc
	v_cndmask_b32_e32 v29, 0, v29, vcc
	s_cselect_b64 vcc, -1, 0
	s_and_b64 s[16:17], vcc, exec
	s_cselect_b32 s16, s15, s4
	s_ashr_i32 s17, s16, 31
	s_lshl_b64 s[30:31], s[16:17], 11
	v_lshl_add_u64 v[6:7], v[8:9], 0, s[30:31]
	s_add_i32 s16, s16, s14
	s_ashr_i32 s17, s16, 31
	s_lshl_b64 s[16:17], s[16:17], 2
	s_add_u32 s16, s26, s16
	s_addc_u32 s17, s27, s17
	s_or_b32 s5, s4, 31
	s_cmp_lt_u32 s5, s23
	s_waitcnt vmcnt(1)
	v_cndmask_b32_e32 v167, 0, v167, vcc
	v_cndmask_b32_e32 v166, 0, v166, vcc
	s_cselect_b64 vcc, -1, 0
	s_and_b64 s[16:17], vcc, exec
	s_cselect_b32 s16, s5, s4
	s_ashr_i32 s17, s16, 31
	s_lshl_b64 s[30:31], s[16:17], 11
	v_lshl_add_u64 v[6:7], v[8:9], 0, s[30:31]
	s_add_i32 s16, s16, s14
	s_ashr_i32 s17, s16, 31
	s_lshl_b64 s[16:17], s[16:17], 2
	s_add_u32 s16, s26, s16
	s_addc_u32 s17, s27, s17
	s_add_i32 s80, s4, 32
	s_cmp_lt_u32 s80, s23
	s_waitcnt vmcnt(1)
	v_cndmask_b32_e32 v27, 0, v27, vcc
	v_cndmask_b32_e32 v25, 0, v25, vcc
	s_cselect_b64 vcc, -1, 0
	s_and_b64 s[16:17], vcc, exec
	s_cselect_b32 s16, s80, s4
	s_ashr_i32 s17, s16, 31
	s_lshl_b64 s[30:31], s[16:17], 11
	v_lshl_add_u64 v[6:7], v[8:9], 0, s[30:31]
	s_add_i32 s16, s16, s14
	s_ashr_i32 s17, s16, 31
	s_lshl_b64 s[16:17], s[16:17], 2
	s_add_u32 s16, s26, s16
	s_addc_u32 s17, s27, s17
	s_add_i32 s82, s4, 33
	s_cmp_lt_u32 s82, s23
	s_waitcnt vmcnt(1)
	v_cndmask_b32_e32 v163, 0, v163, vcc
	v_cndmask_b32_e32 v162, 0, v162, vcc
	s_cselect_b64 vcc, -1, 0
	s_and_b64 s[16:17], vcc, exec
	s_cselect_b32 s16, s82, s4
	s_ashr_i32 s17, s16, 31
	s_lshl_b64 s[30:31], s[16:17], 11
	v_lshl_add_u64 v[6:7], v[8:9], 0, s[30:31]
	s_add_i32 s16, s16, s14
	s_ashr_i32 s17, s16, 31
	s_lshl_b64 s[16:17], s[16:17], 2
	s_add_u32 s16, s26, s16
	s_addc_u32 s17, s27, s17
	s_add_i32 s79, s4, 34
	s_cmp_lt_u32 s79, s23
	s_waitcnt vmcnt(1)
	v_cndmask_b32_e32 v165, 0, v165, vcc
	v_cndmask_b32_e32 v164, 0, v164, vcc
	s_cselect_b64 vcc, -1, 0
	s_and_b64 s[16:17], vcc, exec
	s_cselect_b32 s16, s79, s4
	s_ashr_i32 s17, s16, 31
	s_lshl_b64 s[30:31], s[16:17], 11
	v_lshl_add_u64 v[6:7], v[8:9], 0, s[30:31]
	s_add_i32 s16, s16, s14
	s_ashr_i32 s17, s16, 31
	s_lshl_b64 s[16:17], s[16:17], 2
	s_add_u32 s16, s26, s16
	s_addc_u32 s17, s27, s17
	s_add_i32 s77, s4, 35
	s_cmp_lt_u32 s77, s23
	s_waitcnt vmcnt(1)
	v_cndmask_b32_e32 v161, 0, v161, vcc
	v_cndmask_b32_e32 v160, 0, v160, vcc
	s_cselect_b64 vcc, -1, 0
	s_and_b64 s[16:17], vcc, exec
	s_cselect_b32 s16, s77, s4
	s_ashr_i32 s17, s16, 31
	s_lshl_b64 s[30:31], s[16:17], 11
	v_lshl_add_u64 v[6:7], v[8:9], 0, s[30:31]
	s_add_i32 s16, s16, s14
	s_ashr_i32 s17, s16, 31
	s_lshl_b64 s[16:17], s[16:17], 2
	s_add_u32 s16, s26, s16
	s_addc_u32 s17, s27, s17
	s_add_i32 s75, s4, 36
	s_cmp_lt_u32 s75, s23
	s_waitcnt vmcnt(1)
	v_cndmask_b32_e32 v21, 0, v21, vcc
	v_cndmask_b32_e32 v19, 0, v19, vcc
	s_cselect_b64 vcc, -1, 0
	s_and_b64 s[16:17], vcc, exec
	s_cselect_b32 s16, s75, s4
	s_ashr_i32 s17, s16, 31
	s_lshl_b64 s[30:31], s[16:17], 11
	v_lshl_add_u64 v[6:7], v[8:9], 0, s[30:31]
	s_add_i32 s16, s16, s14
	s_ashr_i32 s17, s16, 31
	s_lshl_b64 s[16:17], s[16:17], 2
	s_add_u32 s16, s26, s16
	s_addc_u32 s17, s27, s17
	s_add_i32 s72, s4, 37
	s_cmp_lt_u32 s72, s23
	s_waitcnt vmcnt(1)
	v_cndmask_b32_e32 v17, 0, v17, vcc
	v_cndmask_b32_e32 v15, 0, v15, vcc
	s_cselect_b64 vcc, -1, 0
	s_and_b64 s[16:17], vcc, exec
	s_cselect_b32 s16, s72, s4
	s_ashr_i32 s17, s16, 31
	s_lshl_b64 s[30:31], s[16:17], 11
	v_lshl_add_u64 v[6:7], v[8:9], 0, s[30:31]
	s_add_i32 s16, s16, s14
	s_ashr_i32 s17, s16, 31
	s_lshl_b64 s[16:17], s[16:17], 2
	s_add_u32 s16, s26, s16
	s_addc_u32 s17, s27, s17
	s_add_i32 s70, s4, 38
	s_cmp_lt_u32 s70, s23
	s_waitcnt vmcnt(0)
	v_cndmask_b32_e32 v11, 0, v202, vcc
	v_cndmask_b32_e32 v7, 0, v203, vcc
	s_cselect_b64 vcc, -1, 0
	global_load_dword v6, v97, s[16:17]
	s_waitcnt vmcnt(0)
	s_and_b64 s[16:17], vcc, exec
	s_cselect_b32 s16, s70, s4
	s_ashr_i32 s17, s16, 31
	s_lshl_b64 s[30:31], s[16:17], 11
	v_lshl_add_u64 v[8:9], v[8:9], 0, s[30:31]
	s_add_i32 s16, s16, s14
	s_ashr_i32 s17, s16, 31
	s_lshl_b64 s[16:17], s[16:17], 2
	s_add_u32 s16, s26, s16
	s_addc_u32 s17, s27, s17
	s_mov_b64 s[30:31], 0x600
	s_waitcnt vmcnt(0)
	v_cndmask_b32_e32 v13, 0, v204, vcc
	global_load_dword v8, v97, s[16:17]
	s_waitcnt vmcnt(0)
	s_lshl_b64 s[16:17], s[6:7], 11
	s_add_u32 s16, s24, s16
	s_addc_u32 s17, s25, s17
	v_lshl_add_u64 v[22:23], s[16:17], 0, v[96:97]
	v_lshl_add_u64 v[4:5], v[22:23], 0, s[30:31]
	s_max_i32 s7, s4, 8
	s_min_i32 s30, s85, s23
	s_sub_i32 s7, s30, s7
	s_add_i32 s7, s7, 8
	v_cvt_f32_i32_e32 v48, s7
	v_cndmask_b32_e32 v9, 0, v205, vcc
	s_max_i32 s7, s35, 8
	v_div_scale_f32 v49, s[30:31], v48, v48, 1.0
	v_rcp_f32_e32 v51, v49
	s_min_i32 s30, s88, s23
	s_sub_i32 s7, s30, s7
	s_add_i32 s7, s7, 8
	v_fma_f32 v59, -v49, v51, 1.0
	v_fmac_f32_e32 v51, v59, v51
	v_div_scale_f32 v59, vcc, 1.0, v48, 1.0
	v_mul_f32_e32 v60, v59, v51
	v_fma_f32 v61, -v49, v60, v59
	v_fmac_f32_e32 v60, v61, v51
	v_fma_f32 v49, -v49, v60, v59
	v_div_fmas_f32 v49, v49, v51, v60
	v_div_fixup_f32 v48, v49, v48, 1.0
	v_cvt_f32_i32_e32 v51, s7
	v_pk_fma_f32 v[60:61], v[48:49], v[56:57], v[126:127] op_sel_hi:[0,1,1] neg_lo:[0,0,1] neg_hi:[0,0,1]
	v_pk_fma_f32 v[48:49], v[48:49], v[52:53], v[124:125] op_sel_hi:[0,1,1] neg_lo:[0,0,1] neg_hi:[0,0,1]
	v_pk_mul_f32 v[48:49], v[2:3], v[48:49]
	v_pk_mul_f32 v[60:61], v[0:1], v[60:61]
	s_max_i32 s7, s97, 8
	v_cvt_pk_bf16_f32 v60, v60, v61
	v_cvt_pk_bf16_f32 v61, v48, v49
	v_pk_mul_f32 v[48:49], v[98:99], v[72:73] op_sel_hi:[0,1]
	v_pk_fma_f32 v[72:73], v[98:99], v[72:73], v[156:157] op_sel_hi:[0,1,1] neg_lo:[0,0,1] neg_hi:[0,0,1]
	v_pk_add_f32 v[72:73], v[52:53], v[72:73]
	v_div_scale_f32 v52, s[30:31], v51, v51, 1.0
	v_rcp_f32_e32 v53, v52
	global_store_dwordx2 v96, v[60:61], s[16:17] offset:1536
	v_pk_mul_f32 v[60:61], v[98:99], v[66:67] op_sel_hi:[0,1]
	v_pk_fma_f32 v[66:67], v[98:99], v[66:67], v[158:159] op_sel_hi:[0,1,1] neg_lo:[0,0,1] neg_hi:[0,0,1]
	v_fma_f32 v59, -v52, v53, 1.0
	v_fmac_f32_e32 v53, v59, v53
	v_div_scale_f32 v59, vcc, 1.0, v51, 1.0
	v_mul_f32_e32 v63, v59, v53
	v_fma_f32 v65, -v52, v63, v59
	v_fmac_f32_e32 v63, v65, v53
	v_fma_f32 v52, -v52, v63, v59
	v_div_fmas_f32 v52, v52, v53, v63
	v_pk_add_f32 v[56:57], v[56:57], v[66:67]
	v_div_fixup_f32 v52, v52, v51, 1.0
	v_pk_fma_f32 v[66:67], v[52:53], v[56:57], v[122:123] op_sel_hi:[0,1,1] neg_lo:[0,0,1] neg_hi:[0,0,1]
	v_pk_fma_f32 v[52:53], v[52:53], v[72:73], v[120:121] op_sel_hi:[0,1,1] neg_lo:[0,0,1] neg_hi:[0,0,1]
	v_pk_mul_f32 v[66:67], v[0:1], v[66:67]
	v_pk_mul_f32 v[52:53], v[2:3], v[52:53]
	v_cvt_pk_bf16_f32 v66, v66, v67
	s_movk_i32 s97, 0x800
	v_cvt_pk_bf16_f32 v67, v52, v53
	global_store_dwordx2 v96, v[66:67], s[16:17] offset:3584
	s_min_i32 s16, s86, s23
	s_sub_i32 s7, s16, s7
	s_add_i32 s7, s7, 8
	v_cvt_f32_i32_e32 v51, s7
	v_pk_mul_f32 v[66:67], v[94:95], v[76:77] op_sel_hi:[0,1]
	v_pk_fma_f32 v[76:77], v[94:95], v[76:77], v[154:155] op_sel_hi:[0,1,1] neg_lo:[0,0,1] neg_hi:[0,0,1]
	v_pk_add_f32 v[76:77], v[56:57], v[76:77]
	v_div_scale_f32 v56, s[16:17], v51, v51, 1.0
	v_rcp_f32_e32 v57, v56
	s_max_i32 s7, s96, 8
	s_min_i32 s16, s84, s23
	s_sub_i32 s7, s16, s7
	v_fma_f32 v59, -v56, v57, 1.0
	v_fmac_f32_e32 v57, v59, v57
	v_div_scale_f32 v59, vcc, 1.0, v51, 1.0
	v_mul_f32_e32 v63, v59, v57
	v_fma_f32 v65, -v56, v63, v59
	v_fmac_f32_e32 v63, v65, v57
	v_fma_f32 v56, -v56, v63, v59
	v_div_fmas_f32 v56, v56, v57, v63
	s_add_i32 s7, s7, 8
	v_div_fixup_f32 v56, v56, v51, 1.0
	v_cvt_f32_i32_e32 v51, s7
	v_add_co_u32_e32 v82, vcc, s92, v22
	s_max_i32 s7, s91, 8
	v_div_scale_f32 v59, s[16:17], v51, v51, 1.0
	v_rcp_f32_e32 v63, v59
	v_addc_co_u32_e32 v83, vcc, 0, v23, vcc
	s_min_i32 s16, s83, s23
	v_fma_f32 v65, -v59, v63, 1.0
	v_fmac_f32_e32 v63, v65, v63
	v_div_scale_f32 v65, vcc, 1.0, v51, 1.0
	v_mul_f32_e32 v69, v65, v63
	v_fma_f32 v71, -v59, v69, v65
	v_fmac_f32_e32 v69, v71, v63
	v_pk_mul_f32 v[52:53], v[94:95], v[80:81] op_sel_hi:[0,1]
	v_pk_fma_f32 v[80:81], v[94:95], v[80:81], v[152:153] op_sel_hi:[0,1,1] neg_lo:[0,0,1] neg_hi:[0,0,1]
	v_lshlrev_b32_e32 v154, 16, v191
	v_and_b32_e32 v155, 0xffff0000, v191
	v_fma_f32 v59, -v59, v69, v65
	s_sub_i32 s7, s16, s7
	v_pk_add_f32 v[72:73], v[72:73], v[80:81]
	v_pk_fma_f32 v[148:149], v[88:89], v[154:155], v[148:149] op_sel_hi:[0,1,1] neg_lo:[0,0,1] neg_hi:[0,0,1]
	v_div_fmas_f32 v59, v59, v63, v69
	s_add_i32 s7, s7, 8
	v_pk_fma_f32 v[80:81], v[56:57], v[76:77], v[118:119] op_sel_hi:[0,1,1] neg_lo:[0,0,1] neg_hi:[0,0,1]
	v_pk_fma_f32 v[56:57], v[56:57], v[72:73], v[100:101] op_sel_hi:[0,1,1] neg_lo:[0,0,1] neg_hi:[0,0,1]
	v_pk_add_f32 v[148:149], v[72:73], v[148:149]
	v_div_fixup_f32 v72, v59, v51, 1.0
	v_cvt_f32_i32_e32 v51, s7
	v_lshlrev_b32_e32 v152, 16, v192
	v_and_b32_e32 v153, 0xffff0000, v192
	v_pk_fma_f32 v[150:151], v[88:89], v[152:153], v[150:151] op_sel_hi:[0,1,1] neg_lo:[0,0,1] neg_hi:[0,0,1]
	v_div_scale_f32 v59, s[16:17], v51, v51, 1.0
	v_rcp_f32_e32 v63, v59
	v_pk_add_f32 v[76:77], v[76:77], v[150:151]
	v_pk_mul_f32 v[80:81], v[0:1], v[80:81]
	v_pk_fma_f32 v[150:151], v[72:73], v[76:77], v[116:117] op_sel_hi:[0,1,1] neg_lo:[0,0,1] neg_hi:[0,0,1]
	v_fma_f32 v65, -v59, v63, 1.0
	v_fmac_f32_e32 v63, v65, v63
	v_div_scale_f32 v65, vcc, 1.0, v51, 1.0
	v_mul_f32_e32 v69, v65, v63
	v_pk_fma_f32 v[72:73], v[72:73], v[148:149], v[102:103] op_sel_hi:[0,1,1] neg_lo:[0,0,1] neg_hi:[0,0,1]
	v_pk_mul_f32 v[150:151], v[0:1], v[150:151]
	v_fma_f32 v71, -v59, v69, v65
	v_pk_mul_f32 v[56:57], v[2:3], v[56:57]
	v_cvt_pk_bf16_f32 v80, v80, v81
	v_pk_mul_f32 v[72:73], v[2:3], v[72:73]
	v_cvt_pk_bf16_f32 v81, v56, v57
	global_store_dwordx2 v[82:83], v[80:81], off offset:1536
	v_cvt_pk_bf16_f32 v150, v150, v151
	v_cvt_pk_bf16_f32 v151, v72, v73
	v_fmac_f32_e32 v69, v71, v63
	s_max_i32 s7, s90, 8
	s_min_i32 s16, s81, s23
	global_store_dwordx2 v[82:83], v[150:151], off offset:3584
	v_lshlrev_b32_e32 v150, 16, v190
	v_and_b32_e32 v151, 0xffff0000, v190
	v_fma_f32 v59, -v59, v69, v65
	s_sub_i32 s7, s16, s7
	v_pk_fma_f32 v[146:147], v[84:85], v[150:151], v[146:147] op_sel_hi:[0,1,1] neg_lo:[0,0,1] neg_hi:[0,0,1]
	v_div_fmas_f32 v59, v59, v63, v69
	s_add_i32 s7, s7, 8
	v_pk_add_f32 v[146:147], v[76:77], v[146:147]
	v_div_fixup_f32 v76, v59, v51, 1.0
	v_cvt_f32_i32_e32 v51, s7
	v_pk_mul_f32 v[80:81], v[88:89], v[152:153] op_sel_hi:[0,1]
	v_lshlrev_b32_e32 v152, 16, v189
	v_and_b32_e32 v153, 0xffff0000, v189
	v_div_scale_f32 v59, s[16:17], v51, v51, 1.0
	v_rcp_f32_e32 v63, v59
	v_pk_mul_f32 v[72:73], v[84:85], v[152:153] op_sel_hi:[0,1]
	v_pk_mul_f32 v[82:83], v[84:85], v[150:151] op_sel_hi:[0,1]
	v_pk_fma_f32 v[84:85], v[84:85], v[152:153], v[144:145] op_sel_hi:[0,1,1] neg_lo:[0,0,1] neg_hi:[0,0,1]
	s_movk_i32 s91, 0x2000
	v_pk_add_f32 v[144:145], v[148:149], v[84:85]
	v_add_co_u32_e32 v148, vcc, s91, v22
	v_fma_f32 v65, -v59, v63, 1.0
	s_nop 0
	v_addc_co_u32_e32 v149, vcc, 0, v23, vcc
	v_fmac_f32_e32 v63, v65, v63
	v_div_scale_f32 v65, vcc, 1.0, v51, 1.0
	v_mul_f32_e32 v69, v65, v63
	v_pk_fma_f32 v[84:85], v[76:77], v[146:147], v[114:115] op_sel_hi:[0,1,1] neg_lo:[0,0,1] neg_hi:[0,0,1]
	v_fma_f32 v71, -v59, v69, v65
	v_pk_fma_f32 v[76:77], v[76:77], v[144:145], v[104:105] op_sel_hi:[0,1,1] neg_lo:[0,0,1] neg_hi:[0,0,1]
	v_pk_mul_f32 v[84:85], v[0:1], v[84:85]
	v_fmac_f32_e32 v69, v71, v63
	s_max_i32 s7, s89, 8
	s_min_i32 s16, s78, s23
	v_pk_mul_f32 v[76:77], v[2:3], v[76:77]
	v_cvt_pk_bf16_f32 v84, v84, v85
	v_lshlrev_b32_e32 v150, 16, v188
	v_cvt_pk_bf16_f32 v85, v76, v77
	v_and_b32_e32 v151, 0xffff0000, v188
	v_lshlrev_b32_e32 v152, 16, v187
	v_and_b32_e32 v153, 0xffff0000, v187
	v_fma_f32 v59, -v59, v69, v65
	s_sub_i32 s7, s16, s7
	global_store_dwordx2 v[148:149], v[84:85], off offset:1536
	v_pk_mul_f32 v[76:77], v[78:79], v[152:153] op_sel_hi:[0,1]
	v_pk_mul_f32 v[84:85], v[78:79], v[150:151] op_sel_hi:[0,1]
	v_pk_fma_f32 v[142:143], v[78:79], v[150:151], v[142:143] op_sel_hi:[0,1,1] neg_lo:[0,0,1] neg_hi:[0,0,1]
	v_pk_fma_f32 v[78:79], v[78:79], v[152:153], v[140:141] op_sel_hi:[0,1,1] neg_lo:[0,0,1] neg_hi:[0,0,1]
	v_div_fmas_f32 v59, v59, v63, v69
	s_add_i32 s7, s7, 8
	v_pk_add_f32 v[140:141], v[144:145], v[78:79]
	v_div_fixup_f32 v78, v59, v51, 1.0
	v_cvt_f32_i32_e32 v51, s7
	v_pk_add_f32 v[142:143], v[146:147], v[142:143]
	s_movk_i32 s7, 0x3000
	v_pk_fma_f32 v[144:145], v[78:79], v[142:143], v[112:113] op_sel_hi:[0,1,1] neg_lo:[0,0,1] neg_hi:[0,0,1]
	v_div_scale_f32 v59, s[16:17], v51, v51, 1.0
	v_rcp_f32_e32 v63, v59
	v_pk_fma_f32 v[78:79], v[78:79], v[140:141], v[106:107] op_sel_hi:[0,1,1] neg_lo:[0,0,1] neg_hi:[0,0,1]
	v_pk_mul_f32 v[144:145], v[0:1], v[144:145]
	v_pk_mul_f32 v[78:79], v[2:3], v[78:79]
	v_fma_f32 v65, -v59, v63, 1.0
	v_fmac_f32_e32 v63, v65, v63
	v_div_scale_f32 v65, vcc, 1.0, v51, 1.0
	v_mul_f32_e32 v69, v65, v63
	v_cvt_pk_bf16_f32 v144, v144, v145
	v_cvt_pk_bf16_f32 v145, v78, v79
	v_fma_f32 v71, -v59, v69, v65
	global_store_dwordx2 v[148:149], v[144:145], off offset:3584
	v_lshlrev_b32_e32 v144, 16, v186
	v_and_b32_e32 v145, 0xffff0000, v186
	v_fmac_f32_e32 v69, v71, v63
	v_pk_fma_f32 v[138:139], v[74:75], v[144:145], v[138:139] op_sel_hi:[0,1,1] neg_lo:[0,0,1] neg_hi:[0,0,1]
	v_fma_f32 v59, -v59, v69, v65
	v_pk_add_f32 v[138:139], v[142:143], v[138:139]
	v_div_fmas_f32 v59, v59, v63, v69
	v_add_co_u32_e32 v142, vcc, s7, v22
	s_max_i32 s7, s87, 8
	s_min_i32 s16, s76, s23
	v_lshlrev_b32_e32 v146, 16, v87
	v_and_b32_e32 v147, 0xffff0000, v87
	s_sub_i32 s7, s16, s7
	v_pk_mul_f32 v[78:79], v[74:75], v[146:147] op_sel_hi:[0,1]
	v_pk_mul_f32 v[86:87], v[74:75], v[144:145] op_sel_hi:[0,1]
	v_pk_fma_f32 v[74:75], v[74:75], v[146:147], v[136:137] op_sel_hi:[0,1,1] neg_lo:[0,0,1] neg_hi:[0,0,1]
	s_add_i32 s7, s7, 8
	v_pk_add_f32 v[136:137], v[140:141], v[74:75]
	v_div_fixup_f32 v74, v59, v51, 1.0
	v_cvt_f32_i32_e32 v51, s7
	v_pk_fma_f32 v[140:141], v[74:75], v[138:139], v[110:111] op_sel_hi:[0,1,1] neg_lo:[0,0,1] neg_hi:[0,0,1]
	v_pk_fma_f32 v[74:75], v[74:75], v[136:137], v[108:109] op_sel_hi:[0,1,1] neg_lo:[0,0,1] neg_hi:[0,0,1]
	v_pk_mul_f32 v[140:141], v[0:1], v[140:141]
	v_div_scale_f32 v59, s[16:17], v51, v51, 1.0
	v_rcp_f32_e32 v63, v59
	v_pk_mul_f32 v[74:75], v[2:3], v[74:75]
	v_cvt_pk_bf16_f32 v140, v140, v141
	v_addc_co_u32_e32 v143, vcc, 0, v23, vcc
	v_cvt_pk_bf16_f32 v141, v74, v75
	v_fma_f32 v65, -v59, v63, 1.0
	global_store_dwordx2 v[142:143], v[140:141], off offset:1536
	v_lshlrev_b32_e32 v140, 16, v185
	v_and_b32_e32 v141, 0xffff0000, v185
	v_lshlrev_b32_e32 v144, 16, v89
	v_and_b32_e32 v145, 0xffff0000, v89
	v_fmac_f32_e32 v63, v65, v63
	v_div_scale_f32 v65, vcc, 1.0, v51, 1.0
	v_pk_mul_f32 v[56:57], v[88:89], v[154:155] op_sel_hi:[0,1]
	v_pk_mul_f32 v[74:75], v[70:71], v[144:145] op_sel_hi:[0,1]
	v_pk_mul_f32 v[88:89], v[70:71], v[140:141] op_sel_hi:[0,1]
	v_pk_fma_f32 v[134:135], v[70:71], v[140:141], v[134:135] op_sel_hi:[0,1,1] neg_lo:[0,0,1] neg_hi:[0,0,1]
	v_pk_fma_f32 v[70:71], v[70:71], v[144:145], v[132:133] op_sel_hi:[0,1,1] neg_lo:[0,0,1] neg_hi:[0,0,1]
	v_mul_f32_e32 v69, v65, v63
	v_pk_add_f32 v[132:133], v[136:137], v[70:71]
	v_fma_f32 v70, -v59, v69, v65
	v_fmac_f32_e32 v69, v70, v63
	s_max_i32 s7, s85, 8
	s_min_i32 s16, s73, s23
	v_fma_f32 v59, -v59, v69, v65
	s_sub_i32 s7, s16, s7
	v_div_fmas_f32 v59, v59, v63, v69
	s_add_i32 s7, s7, 8
	v_div_fixup_f32 v70, v59, v51, 1.0
	v_cvt_f32_i32_e32 v51, s7
	v_pk_add_f32 v[134:135], v[138:139], v[134:135]
	v_lshlrev_b32_e32 v138, 16, v91
	v_pk_fma_f32 v[136:137], v[70:71], v[134:135], v[46:47] op_sel_hi:[0,1,1] neg_lo:[0,0,1] neg_hi:[0,0,1]
	v_div_scale_f32 v59, s[16:17], v51, v51, 1.0
	v_pk_fma_f32 v[70:71], v[70:71], v[132:133], v[42:43] op_sel_hi:[0,1,1] neg_lo:[0,0,1] neg_hi:[0,0,1]
	v_pk_mul_f32 v[136:137], v[0:1], v[136:137]
	v_rcp_f32_e32 v63, v59
	v_pk_mul_f32 v[70:71], v[2:3], v[70:71]
	v_cvt_pk_bf16_f32 v136, v136, v137
	v_and_b32_e32 v139, 0xffff0000, v91
	v_cvt_pk_bf16_f32 v137, v70, v71
	global_store_dwordx2 v[142:143], v[136:137], off offset:3584
	v_lshlrev_b32_e32 v136, 16, v184
	v_and_b32_e32 v137, 0xffff0000, v184
	v_pk_mul_f32 v[70:71], v[64:65], v[138:139] op_sel_hi:[0,1]
	v_pk_mul_f32 v[90:91], v[64:65], v[136:137] op_sel_hi:[0,1]
	v_pk_fma_f32 v[130:131], v[64:65], v[136:137], v[130:131] op_sel_hi:[0,1,1] neg_lo:[0,0,1] neg_hi:[0,0,1]
	v_pk_fma_f32 v[64:65], v[64:65], v[138:139], v[128:129] op_sel_hi:[0,1,1] neg_lo:[0,0,1] neg_hi:[0,0,1]
	v_pk_add_f32 v[128:129], v[132:133], v[64:65]
	v_fma_f32 v64, -v59, v63, 1.0
	v_fmac_f32_e32 v63, v64, v63
	v_div_scale_f32 v64, vcc, 1.0, v51, 1.0
	v_mul_f32_e32 v65, v64, v63
	v_fma_f32 v69, -v59, v65, v64
	v_fmac_f32_e32 v65, v69, v63
	s_max_i32 s7, s88, 8
	s_min_i32 s16, s74, s23
	v_fma_f32 v59, -v59, v65, v64
	s_sub_i32 s7, s16, s7
	v_div_fmas_f32 v59, v59, v63, v65
	s_add_i32 s7, s7, 8
	v_div_fixup_f32 v64, v59, v51, 1.0
	v_cvt_f32_i32_e32 v51, s7
	v_pk_add_f32 v[130:131], v[134:135], v[130:131]
	v_add_co_u32_e32 v134, vcc, s9, v22
	v_pk_fma_f32 v[132:133], v[64:65], v[130:131], v[60:61] op_sel_hi:[0,1,1] neg_lo:[0,0,1] neg_hi:[0,0,1]
	v_div_scale_f32 v59, s[16:17], v51, v51, 1.0
	v_pk_fma_f32 v[64:65], v[64:65], v[128:129], v[48:49] op_sel_hi:[0,1,1] neg_lo:[0,0,1] neg_hi:[0,0,1]
	v_pk_mul_f32 v[132:133], v[0:1], v[132:133]
	v_rcp_f32_e32 v63, v59
	v_pk_mul_f32 v[64:65], v[2:3], v[64:65]
	v_cvt_pk_bf16_f32 v132, v132, v133
	v_addc_co_u32_e32 v135, vcc, 0, v23, vcc
	v_cvt_pk_bf16_f32 v133, v64, v65
	global_store_dwordx2 v[134:135], v[132:133], off offset:1536
	v_lshlrev_b32_e32 v94, 16, v95
	v_and_b32_e32 v95, 0xffff0000, v95
	v_lshlrev_b32_e32 v132, 16, v93
	v_and_b32_e32 v133, 0xffff0000, v93
	v_pk_mul_f32 v[64:65], v[68:69], v[132:133] op_sel_hi:[0,1]
	v_pk_mul_f32 v[92:93], v[68:69], v[94:95] op_sel_hi:[0,1]
	v_pk_fma_f32 v[94:95], v[68:69], v[94:95], v[126:127] op_sel_hi:[0,1,1] neg_lo:[0,0,1] neg_hi:[0,0,1]
	v_pk_fma_f32 v[68:69], v[68:69], v[132:133], v[124:125] op_sel_hi:[0,1,1] neg_lo:[0,0,1] neg_hi:[0,0,1]
	v_pk_add_f32 v[124:125], v[128:129], v[68:69]
	v_fma_f32 v68, -v59, v63, 1.0
	v_fmac_f32_e32 v63, v68, v63
	v_div_scale_f32 v68, vcc, 1.0, v51, 1.0
	v_mul_f32_e32 v69, v68, v63
	v_pk_add_f32 v[126:127], v[130:131], v[94:95]
	v_fma_f32 v94, -v59, v69, v68
	v_fmac_f32_e32 v69, v94, v63
	s_max_i32 s7, s86, 8
	s_min_i32 s16, s71, s23
	v_fma_f32 v59, -v59, v69, v68
	s_sub_i32 s7, s16, s7
	v_div_fmas_f32 v59, v59, v63, v69
	s_add_i32 s7, s7, 8
	v_div_fixup_f32 v68, v59, v51, 1.0
	v_cvt_f32_i32_e32 v51, s7
	v_pk_fma_f32 v[94:95], v[68:69], v[126:127], v[66:67] op_sel_hi:[0,1,1] neg_lo:[0,0,1] neg_hi:[0,0,1]
	v_pk_fma_f32 v[68:69], v[68:69], v[124:125], v[52:53] op_sel_hi:[0,1,1] neg_lo:[0,0,1] neg_hi:[0,0,1]
	v_pk_mul_f32 v[94:95], v[0:1], v[94:95]
	v_pk_mul_f32 v[68:69], v[2:3], v[68:69]
	v_cvt_pk_bf16_f32 v94, v94, v95
	v_lshlrev_b32_e32 v128, 16, v183
	v_cvt_pk_bf16_f32 v95, v68, v69
	v_and_b32_e32 v129, 0xffff0000, v183
	v_lshlrev_b32_e32 v130, 16, v182
	v_and_b32_e32 v131, 0xffff0000, v182
	global_store_dwordx2 v[134:135], v[94:95], off offset:3584
	v_pk_mul_f32 v[68:69], v[62:63], v[130:131] op_sel_hi:[0,1]
	v_pk_mul_f32 v[94:95], v[62:63], v[128:129] op_sel_hi:[0,1]
	v_pk_fma_f32 v[122:123], v[62:63], v[128:129], v[122:123] op_sel_hi:[0,1,1] neg_lo:[0,0,1] neg_hi:[0,0,1]
	v_pk_fma_f32 v[62:63], v[62:63], v[130:131], v[120:121] op_sel_hi:[0,1,1] neg_lo:[0,0,1] neg_hi:[0,0,1]
	v_div_scale_f32 v59, s[16:17], v51, v51, 1.0
	v_pk_add_f32 v[120:121], v[124:125], v[62:63]
	v_rcp_f32_e32 v62, v59
	s_max_i32 s7, s84, 8
	s_min_i32 s16, s69, s23
	v_pk_add_f32 v[122:123], v[126:127], v[122:123]
	v_fma_f32 v63, -v59, v62, 1.0
	v_fmac_f32_e32 v62, v63, v62
	v_div_scale_f32 v63, vcc, 1.0, v51, 1.0
	v_mul_f32_e32 v98, v63, v62
	v_fma_f32 v124, -v59, v98, v63
	v_fmac_f32_e32 v98, v124, v62
	v_fma_f32 v59, -v59, v98, v63
	v_div_fmas_f32 v59, v59, v62, v98
	v_div_fixup_f32 v62, v59, v51, 1.0
	s_sub_i32 s7, s16, s7
	v_pk_fma_f32 v[124:125], v[62:63], v[122:123], v[80:81] op_sel_hi:[0,1,1] neg_lo:[0,0,1] neg_hi:[0,0,1]
	s_add_i32 s7, s7, 8
	v_pk_fma_f32 v[62:63], v[62:63], v[120:121], v[56:57] op_sel_hi:[0,1,1] neg_lo:[0,0,1] neg_hi:[0,0,1]
	v_pk_mul_f32 v[124:125], v[0:1], v[124:125]
	v_add_co_u32_e32 v126, vcc, s38, v22
	v_cvt_f32_i32_e32 v51, s7
	v_pk_mul_f32 v[62:63], v[2:3], v[62:63]
	v_cvt_pk_bf16_f32 v124, v124, v125
	v_addc_co_u32_e32 v127, vcc, 0, v23, vcc
	v_cvt_pk_bf16_f32 v125, v62, v63
	global_store_dwordx2 v[126:127], v[124:125], off offset:1536
	v_lshlrev_b32_e32 v124, 16, v181
	v_and_b32_e32 v125, 0xffff0000, v181
	v_lshlrev_b32_e32 v128, 16, v99
	v_and_b32_e32 v129, 0xffff0000, v99
	v_pk_mul_f32 v[62:63], v[58:59], v[128:129] op_sel_hi:[0,1]
	v_pk_mul_f32 v[98:99], v[58:59], v[124:125] op_sel_hi:[0,1]
	v_pk_fma_f32 v[118:119], v[58:59], v[124:125], v[118:119] op_sel_hi:[0,1,1] neg_lo:[0,0,1] neg_hi:[0,0,1]
	v_pk_fma_f32 v[58:59], v[58:59], v[128:129], v[100:101] op_sel_hi:[0,1,1] neg_lo:[0,0,1] neg_hi:[0,0,1]
	v_pk_add_f32 v[120:121], v[120:121], v[58:59]
	v_div_scale_f32 v58, s[16:17], v51, v51, 1.0
	v_rcp_f32_e32 v59, v58
	v_pk_add_f32 v[118:119], v[122:123], v[118:119]
	s_max_i32 s7, s83, 8
	s_min_i32 s16, s68, s23
	v_fma_f32 v100, -v58, v59, 1.0
	v_fmac_f32_e32 v59, v100, v59
	v_div_scale_f32 v100, vcc, 1.0, v51, 1.0
	v_mul_f32_e32 v101, v100, v59
	v_fma_f32 v122, -v58, v101, v100
	v_fmac_f32_e32 v101, v122, v59
	v_fma_f32 v58, -v58, v101, v100
	s_sub_i32 s7, s16, s7
	v_div_fmas_f32 v58, v58, v59, v101
	s_add_i32 s7, s7, 8
	v_div_fixup_f32 v58, v58, v51, 1.0
	v_cvt_f32_i32_e32 v51, s7
	v_pk_fma_f32 v[100:101], v[58:59], v[118:119], v[82:83] op_sel_hi:[0,1,1] neg_lo:[0,0,1] neg_hi:[0,0,1]
	v_pk_fma_f32 v[58:59], v[58:59], v[120:121], v[72:73] op_sel_hi:[0,1,1] neg_lo:[0,0,1] neg_hi:[0,0,1]
	v_pk_mul_f32 v[100:101], v[0:1], v[100:101]
	v_pk_mul_f32 v[58:59], v[2:3], v[58:59]
	v_cvt_pk_bf16_f32 v100, v100, v101
	v_lshlrev_b32_e32 v122, 16, v180
	v_cvt_pk_bf16_f32 v101, v58, v59
	v_and_b32_e32 v123, 0xffff0000, v180
	v_lshlrev_b32_e32 v124, 16, v179
	v_and_b32_e32 v125, 0xffff0000, v179
	global_store_dwordx2 v[126:127], v[100:101], off offset:3584
	v_pk_mul_f32 v[58:59], v[54:55], v[124:125] op_sel_hi:[0,1]
	v_pk_mul_f32 v[100:101], v[54:55], v[122:123] op_sel_hi:[0,1]
	v_pk_fma_f32 v[116:117], v[54:55], v[122:123], v[116:117] op_sel_hi:[0,1,1] neg_lo:[0,0,1] neg_hi:[0,0,1]
	v_pk_fma_f32 v[102:103], v[54:55], v[124:125], v[102:103] op_sel_hi:[0,1,1] neg_lo:[0,0,1] neg_hi:[0,0,1]
	v_div_scale_f32 v54, s[16:17], v51, v51, 1.0
	v_pk_add_f32 v[120:121], v[120:121], v[102:103]
	v_rcp_f32_e32 v102, v54
	v_pk_add_f32 v[116:117], v[118:119], v[116:117]
	s_max_i32 s7, s81, 8
	s_min_i32 s16, s67, s23
	v_fma_f32 v103, -v54, v102, 1.0
	v_fmac_f32_e32 v102, v103, v102
	v_div_scale_f32 v103, vcc, 1.0, v51, 1.0
	v_mul_f32_e32 v118, v103, v102
	v_fma_f32 v119, -v54, v118, v103
	v_fmac_f32_e32 v118, v119, v102
	v_fma_f32 v54, -v54, v118, v103
	v_div_fmas_f32 v54, v54, v102, v118
	v_div_fixup_f32 v54, v54, v51, 1.0
	v_pk_fma_f32 v[102:103], v[54:55], v[116:117], v[84:85] op_sel_hi:[0,1,1] neg_lo:[0,0,1] neg_hi:[0,0,1]
	v_pk_fma_f32 v[118:119], v[54:55], v[120:121], v[76:77] op_sel_hi:[0,1,1] neg_lo:[0,0,1] neg_hi:[0,0,1]
	v_pk_mul_f32 v[118:119], v[2:3], v[118:119]
	v_pk_mul_f32 v[102:103], v[0:1], v[102:103]
	v_lshlrev_b32_e32 v122, 16, v178
	v_cvt_pk_bf16_f32 v102, v102, v103
	v_cvt_pk_bf16_f32 v103, v118, v119
	v_add_co_u32_e32 v118, vcc, s39, v22
	v_and_b32_e32 v123, 0xffff0000, v178
	s_nop 0
	v_addc_co_u32_e32 v119, vcc, 0, v23, vcc
	v_lshlrev_b32_e32 v124, 16, v55
	v_and_b32_e32 v125, 0xffff0000, v55
	s_sub_i32 s7, s16, s7
	global_store_dwordx2 v[118:119], v[102:103], off offset:1536
	v_pk_mul_f32 v[54:55], v[50:51], v[124:125] op_sel_hi:[0,1]
	v_pk_mul_f32 v[102:103], v[50:51], v[122:123] op_sel_hi:[0,1]
	v_pk_fma_f32 v[114:115], v[50:51], v[122:123], v[114:115] op_sel_hi:[0,1,1] neg_lo:[0,0,1] neg_hi:[0,0,1]
	v_pk_fma_f32 v[50:51], v[50:51], v[124:125], v[104:105] op_sel_hi:[0,1,1] neg_lo:[0,0,1] neg_hi:[0,0,1]
	s_add_i32 s7, s7, 8
	v_pk_add_f32 v[120:121], v[120:121], v[50:51]
	v_cvt_f32_i32_e32 v50, s7
	v_pk_add_f32 v[114:115], v[116:117], v[114:115]
	s_max_i32 s7, s78, 8
	v_readlane_b32 s96, v255, 13
	v_div_scale_f32 v51, s[16:17], v50, v50, 1.0
	v_rcp_f32_e32 v104, v51
	s_min_i32 s16, s66, s23
	s_sub_i32 s7, s16, s7
	s_add_i32 s7, s7, 8
	v_fma_f32 v105, -v51, v104, 1.0
	v_fmac_f32_e32 v104, v105, v104
	v_div_scale_f32 v105, vcc, 1.0, v50, 1.0
	v_mul_f32_e32 v116, v105, v104
	v_fma_f32 v117, -v51, v116, v105
	v_fmac_f32_e32 v116, v117, v104
	v_fma_f32 v51, -v51, v116, v105
	v_div_fmas_f32 v51, v51, v104, v116
	v_div_fixup_f32 v50, v51, v50, 1.0
	v_pk_fma_f32 v[104:105], v[50:51], v[114:115], v[86:87] op_sel_hi:[0,1,1] neg_lo:[0,0,1] neg_hi:[0,0,1]
	v_pk_fma_f32 v[50:51], v[50:51], v[120:121], v[78:79] op_sel_hi:[0,1,1] neg_lo:[0,0,1] neg_hi:[0,0,1]
	v_pk_mul_f32 v[104:105], v[0:1], v[104:105]
	v_pk_mul_f32 v[50:51], v[2:3], v[50:51]
	v_cvt_pk_bf16_f32 v104, v104, v105
	v_lshlrev_b32_e32 v116, 16, v177
	v_cvt_pk_bf16_f32 v105, v50, v51
	global_store_dwordx2 v[118:119], v[104:105], off offset:3584
	v_and_b32_e32 v117, 0xffff0000, v177
	v_lshlrev_b32_e32 v118, 16, v176
	v_and_b32_e32 v119, 0xffff0000, v176
	v_pk_mul_f32 v[50:51], v[44:45], v[118:119] op_sel_hi:[0,1]
	v_pk_mul_f32 v[104:105], v[44:45], v[116:117] op_sel_hi:[0,1]
	v_pk_fma_f32 v[112:113], v[44:45], v[116:117], v[112:113] op_sel_hi:[0,1,1] neg_lo:[0,0,1] neg_hi:[0,0,1]
	v_pk_fma_f32 v[106:107], v[44:45], v[118:119], v[106:107] op_sel_hi:[0,1,1] neg_lo:[0,0,1] neg_hi:[0,0,1]
	v_cvt_f32_i32_e32 v44, s7
	v_pk_add_f32 v[116:117], v[120:121], v[106:107]
	v_pk_add_f32 v[112:113], v[114:115], v[112:113]
	s_movk_i32 s7, 0x7000
	v_div_scale_f32 v106, s[16:17], v44, v44, 1.0
	v_rcp_f32_e32 v107, v106
	s_min_i32 s16, s63, s23
	v_and_b32_e32 v119, 0xffff0000, v175
	v_lshlrev_b32_e32 v120, 16, v45
	v_fma_f32 v114, -v106, v107, 1.0
	v_fmac_f32_e32 v107, v114, v107
	v_div_scale_f32 v114, vcc, 1.0, v44, 1.0
	v_mul_f32_e32 v115, v114, v107
	v_fma_f32 v118, -v106, v115, v114
	v_fmac_f32_e32 v115, v118, v107
	v_fma_f32 v106, -v106, v115, v114
	v_div_fmas_f32 v106, v106, v107, v115
	v_div_fixup_f32 v44, v106, v44, 1.0
	v_pk_fma_f32 v[106:107], v[44:45], v[112:113], v[88:89] op_sel_hi:[0,1,1] neg_lo:[0,0,1] neg_hi:[0,0,1]
	v_pk_fma_f32 v[114:115], v[44:45], v[116:117], v[74:75] op_sel_hi:[0,1,1] neg_lo:[0,0,1] neg_hi:[0,0,1]
	v_pk_mul_f32 v[114:115], v[2:3], v[114:115]
	v_pk_mul_f32 v[106:107], v[0:1], v[106:107]
	v_lshlrev_b32_e32 v118, 16, v175
	v_cvt_pk_bf16_f32 v106, v106, v107
	v_cvt_pk_bf16_f32 v107, v114, v115
	v_add_co_u32_e32 v114, vcc, s7, v22
	s_max_i32 s7, s76, 8
	s_sub_i32 s7, s16, s7
	v_addc_co_u32_e32 v115, vcc, 0, v23, vcc
	v_and_b32_e32 v121, 0xffff0000, v45
	s_add_i32 s7, s7, 8
	global_store_dwordx2 v[114:115], v[106:107], off offset:1536
	v_pk_mul_f32 v[44:45], v[40:41], v[120:121] op_sel_hi:[0,1]
	v_pk_mul_f32 v[106:107], v[40:41], v[118:119] op_sel_hi:[0,1]
	v_pk_fma_f32 v[110:111], v[40:41], v[118:119], v[110:111] op_sel_hi:[0,1,1] neg_lo:[0,0,1] neg_hi:[0,0,1]
	v_pk_fma_f32 v[108:109], v[40:41], v[120:121], v[108:109] op_sel_hi:[0,1,1] neg_lo:[0,0,1] neg_hi:[0,0,1]
	v_cvt_f32_i32_e32 v40, s7
	v_pk_add_f32 v[116:117], v[116:117], v[108:109]
	v_pk_add_f32 v[110:111], v[112:113], v[110:111]
	s_max_i32 s7, s73, 8
	v_div_scale_f32 v108, s[16:17], v40, v40, 1.0
	v_rcp_f32_e32 v109, v108
	s_min_i32 s16, s62, s23
	s_sub_i32 s7, s16, s7
	s_add_i32 s7, s7, 8
	v_fma_f32 v112, -v108, v109, 1.0
	v_fmac_f32_e32 v109, v112, v109
	v_div_scale_f32 v112, vcc, 1.0, v40, 1.0
	v_mul_f32_e32 v113, v112, v109
	v_fma_f32 v118, -v108, v113, v112
	v_fmac_f32_e32 v113, v118, v109
	v_fma_f32 v108, -v108, v113, v112
	v_div_fmas_f32 v108, v108, v109, v113
	v_div_fixup_f32 v40, v108, v40, 1.0
	v_pk_fma_f32 v[108:109], v[40:41], v[110:111], v[90:91] op_sel_hi:[0,1,1] neg_lo:[0,0,1] neg_hi:[0,0,1]
	v_pk_fma_f32 v[112:113], v[40:41], v[116:117], v[70:71] op_sel_hi:[0,1,1] neg_lo:[0,0,1] neg_hi:[0,0,1]
	v_pk_mul_f32 v[112:113], v[2:3], v[112:113]
	v_pk_mul_f32 v[108:109], v[0:1], v[108:109]
	s_movk_i32 s90, 0xff00
	v_cvt_pk_bf16_f32 v108, v108, v109
	v_cvt_pk_bf16_f32 v109, v112, v113
	global_store_dwordx2 v[114:115], v[108:109], off offset:3584
	v_lshlrev_b32_e32 v112, 16, v174
	v_and_b32_e32 v113, 0xffff0000, v174
	v_lshlrev_b32_e32 v114, 16, v41
	v_and_b32_e32 v115, 0xffff0000, v41
	v_pk_mul_f32 v[40:41], v[38:39], v[114:115] op_sel_hi:[0,1]
	v_pk_mul_f32 v[108:109], v[38:39], v[112:113] op_sel_hi:[0,1]
	v_pk_fma_f32 v[46:47], v[38:39], v[112:113], v[46:47] op_sel_hi:[0,1,1] neg_lo:[0,0,1] neg_hi:[0,0,1]
	v_pk_fma_f32 v[42:43], v[38:39], v[114:115], v[42:43] op_sel_hi:[0,1,1] neg_lo:[0,0,1] neg_hi:[0,0,1]
	v_cvt_f32_i32_e32 v38, s7
	v_pk_add_f32 v[110:111], v[110:111], v[46:47]
	v_pk_add_f32 v[42:43], v[116:117], v[42:43]
	s_max_i32 s7, s74, 8
	v_div_scale_f32 v46, s[16:17], v38, v38, 1.0
	v_rcp_f32_e32 v47, v46
	s_min_i32 s16, s21, s23
	s_sub_i32 s7, s16, s7
	v_and_b32_e32 v115, 0xffff0000, v173
	v_fma_f32 v112, -v46, v47, 1.0
	v_fmac_f32_e32 v47, v112, v47
	v_div_scale_f32 v112, vcc, 1.0, v38, 1.0
	v_mul_f32_e32 v113, v112, v47
	v_fma_f32 v114, -v46, v113, v112
	v_fmac_f32_e32 v113, v114, v47
	v_fma_f32 v46, -v46, v113, v112
	v_div_fmas_f32 v46, v46, v47, v113
	v_div_fixup_f32 v38, v46, v38, 1.0
	v_pk_fma_f32 v[46:47], v[38:39], v[110:111], v[92:93] op_sel_hi:[0,1,1] neg_lo:[0,0,1] neg_hi:[0,0,1]
	v_pk_fma_f32 v[112:113], v[38:39], v[42:43], v[64:65] op_sel_hi:[0,1,1] neg_lo:[0,0,1] neg_hi:[0,0,1]
	v_pk_mul_f32 v[112:113], v[2:3], v[112:113]
	v_pk_mul_f32 v[46:47], v[0:1], v[46:47]
	v_lshlrev_b32_e32 v114, 16, v173
	v_cvt_pk_bf16_f32 v46, v46, v47
	v_cvt_pk_bf16_f32 v47, v112, v113
	v_add_co_u32_e32 v112, vcc, s61, v22
	v_lshlrev_b32_e32 v116, 16, v39
	s_nop 0
	v_addc_co_u32_e32 v113, vcc, 0, v23, vcc
	v_and_b32_e32 v117, 0xffff0000, v39
	s_add_i32 s7, s7, 8
	global_store_dwordx2 v[112:113], v[46:47], off offset:1536
	v_pk_mul_f32 v[38:39], v[34:35], v[116:117] op_sel_hi:[0,1]
	v_pk_mul_f32 v[46:47], v[34:35], v[114:115] op_sel_hi:[0,1]
	v_pk_fma_f32 v[60:61], v[34:35], v[114:115], v[60:61] op_sel_hi:[0,1,1] neg_lo:[0,0,1] neg_hi:[0,0,1]
	v_pk_fma_f32 v[48:49], v[34:35], v[116:117], v[48:49] op_sel_hi:[0,1,1] neg_lo:[0,0,1] neg_hi:[0,0,1]
	v_cvt_f32_i32_e32 v34, s7
	v_pk_add_f32 v[48:49], v[42:43], v[48:49]
	v_pk_add_f32 v[60:61], v[110:111], v[60:61]
	s_max_i32 s7, s71, 8
	v_div_scale_f32 v42, s[16:17], v34, v34, 1.0
	v_rcp_f32_e32 v43, v42
	s_min_i32 s16, s34, s23
	s_sub_i32 s7, s16, s7
	s_add_i32 s7, s7, 8
	v_fma_f32 v110, -v42, v43, 1.0
	v_fmac_f32_e32 v43, v110, v43
	v_div_scale_f32 v110, vcc, 1.0, v34, 1.0
	v_mul_f32_e32 v111, v110, v43
	v_fma_f32 v114, -v42, v111, v110
	v_fmac_f32_e32 v111, v114, v43
	v_fma_f32 v42, -v42, v111, v110
	v_div_fmas_f32 v42, v42, v43, v111
	v_div_fixup_f32 v34, v42, v34, 1.0
	v_pk_fma_f32 v[42:43], v[34:35], v[60:61], v[94:95] op_sel_hi:[0,1,1] neg_lo:[0,0,1] neg_hi:[0,0,1]
	v_pk_fma_f32 v[110:111], v[34:35], v[48:49], v[68:69] op_sel_hi:[0,1,1] neg_lo:[0,0,1] neg_hi:[0,0,1]
	v_pk_mul_f32 v[110:111], v[2:3], v[110:111]
	v_pk_mul_f32 v[42:43], v[0:1], v[42:43]
	s_nop 0
	v_cvt_pk_bf16_f32 v42, v42, v43
	v_cvt_pk_bf16_f32 v43, v110, v111
	global_store_dwordx2 v[112:113], v[42:43], off offset:3584
	v_lshlrev_b32_e32 v110, 16, v172
	v_and_b32_e32 v111, 0xffff0000, v172
	v_lshlrev_b32_e32 v112, 16, v35
	v_and_b32_e32 v113, 0xffff0000, v35
	v_pk_mul_f32 v[34:35], v[36:37], v[112:113] op_sel_hi:[0,1]
	v_pk_mul_f32 v[42:43], v[36:37], v[110:111] op_sel_hi:[0,1]
	v_pk_fma_f32 v[66:67], v[36:37], v[110:111], v[66:67] op_sel_hi:[0,1,1] neg_lo:[0,0,1] neg_hi:[0,0,1]
	v_pk_fma_f32 v[52:53], v[36:37], v[112:113], v[52:53] op_sel_hi:[0,1,1] neg_lo:[0,0,1] neg_hi:[0,0,1]
	v_cvt_f32_i32_e32 v36, s7
	v_pk_add_f32 v[48:49], v[48:49], v[52:53]
	v_pk_add_f32 v[60:61], v[60:61], v[66:67]
	s_max_i32 s7, s69, 8
	v_div_scale_f32 v52, s[16:17], v36, v36, 1.0
	v_rcp_f32_e32 v53, v52
	s_min_i32 s16, s19, s23
	s_sub_i32 s7, s16, s7
	v_and_b32_e32 v111, 0xffff0000, v171
	v_fma_f32 v66, -v52, v53, 1.0
	v_fmac_f32_e32 v53, v66, v53
	v_div_scale_f32 v66, vcc, 1.0, v36, 1.0
	v_mul_f32_e32 v67, v66, v53
	v_fma_f32 v110, -v52, v67, v66
	v_fmac_f32_e32 v67, v110, v53
	v_fma_f32 v52, -v52, v67, v66
	v_div_fmas_f32 v52, v52, v53, v67
	v_div_fixup_f32 v36, v52, v36, 1.0
	v_pk_fma_f32 v[52:53], v[36:37], v[60:61], v[98:99] op_sel_hi:[0,1,1] neg_lo:[0,0,1] neg_hi:[0,0,1]
	v_pk_fma_f32 v[66:67], v[36:37], v[48:49], v[62:63] op_sel_hi:[0,1,1] neg_lo:[0,0,1] neg_hi:[0,0,1]
	v_pk_mul_f32 v[66:67], v[2:3], v[66:67]
	v_pk_mul_f32 v[52:53], v[0:1], v[52:53]
	v_lshlrev_b32_e32 v110, 16, v171
	v_cvt_pk_bf16_f32 v52, v52, v53
	v_cvt_pk_bf16_f32 v53, v66, v67
	v_add_co_u32_e32 v66, vcc, s94, v22
	v_lshlrev_b32_e32 v112, 16, v37
	s_nop 0
	v_addc_co_u32_e32 v67, vcc, 0, v23, vcc
	v_and_b32_e32 v113, 0xffff0000, v37
	s_add_i32 s7, s7, 8
	global_store_dwordx2 v[66:67], v[52:53], off offset:1536
	v_pk_mul_f32 v[36:37], v[30:31], v[112:113] op_sel_hi:[0,1]
	v_pk_mul_f32 v[52:53], v[30:31], v[110:111] op_sel_hi:[0,1]
	v_pk_fma_f32 v[80:81], v[30:31], v[110:111], v[80:81] op_sel_hi:[0,1,1] neg_lo:[0,0,1] neg_hi:[0,0,1]
	v_pk_fma_f32 v[56:57], v[30:31], v[112:113], v[56:57] op_sel_hi:[0,1,1] neg_lo:[0,0,1] neg_hi:[0,0,1]
	v_cvt_f32_i32_e32 v30, s7
	v_pk_add_f32 v[56:57], v[48:49], v[56:57]
	v_pk_add_f32 v[60:61], v[60:61], v[80:81]
	s_max_i32 s7, s68, 8
	v_div_scale_f32 v48, s[16:17], v30, v30, 1.0
	v_rcp_f32_e32 v49, v48
	s_min_i32 s16, s20, s23
	s_sub_i32 s7, s16, s7
	s_add_i32 s7, s7, 8
	v_fma_f32 v80, -v48, v49, 1.0
	v_fmac_f32_e32 v49, v80, v49
	v_div_scale_f32 v80, vcc, 1.0, v30, 1.0
	v_mul_f32_e32 v81, v80, v49
	v_fma_f32 v110, -v48, v81, v80
	v_fmac_f32_e32 v81, v110, v49
	v_fma_f32 v48, -v48, v81, v80
	v_div_fmas_f32 v48, v48, v49, v81
	v_div_fixup_f32 v30, v48, v30, 1.0
	v_pk_fma_f32 v[48:49], v[30:31], v[60:61], v[100:101] op_sel_hi:[0,1,1] neg_lo:[0,0,1] neg_hi:[0,0,1]
	v_pk_fma_f32 v[80:81], v[30:31], v[56:57], v[58:59] op_sel_hi:[0,1,1] neg_lo:[0,0,1] neg_hi:[0,0,1]
	v_pk_mul_f32 v[80:81], v[2:3], v[80:81]
	v_pk_mul_f32 v[48:49], v[0:1], v[48:49]
	s_nop 0
	v_cvt_pk_bf16_f32 v48, v48, v49
	v_cvt_pk_bf16_f32 v49, v80, v81
	global_store_dwordx2 v[66:67], v[48:49], off offset:3584
	v_lshlrev_b32_e32 v66, 16, v170
	v_and_b32_e32 v67, 0xffff0000, v170
	v_lshlrev_b32_e32 v80, 16, v31
	v_and_b32_e32 v81, 0xffff0000, v31
	v_pk_mul_f32 v[30:31], v[32:33], v[80:81] op_sel_hi:[0,1]
	v_pk_mul_f32 v[48:49], v[32:33], v[66:67] op_sel_hi:[0,1]
	v_pk_fma_f32 v[66:67], v[32:33], v[66:67], v[82:83] op_sel_hi:[0,1,1] neg_lo:[0,0,1] neg_hi:[0,0,1]
	v_pk_fma_f32 v[72:73], v[32:33], v[80:81], v[72:73] op_sel_hi:[0,1,1] neg_lo:[0,0,1] neg_hi:[0,0,1]
	v_cvt_f32_i32_e32 v32, s7
	v_pk_add_f32 v[66:67], v[60:61], v[66:67]
	v_pk_add_f32 v[56:57], v[56:57], v[72:73]
	s_mov_b32 s7, 0xa000
	v_div_scale_f32 v60, s[16:17], v32, v32, 1.0
	v_rcp_f32_e32 v61, v60
	s_min_i32 s16, s18, s23
	v_and_b32_e32 v81, 0xffff0000, v169
	v_lshlrev_b32_e32 v82, 16, v33
	v_fma_f32 v72, -v60, v61, 1.0
	v_fmac_f32_e32 v61, v72, v61
	v_div_scale_f32 v72, vcc, 1.0, v32, 1.0
	v_mul_f32_e32 v73, v72, v61
	v_fma_f32 v80, -v60, v73, v72
	v_fmac_f32_e32 v73, v80, v61
	v_fma_f32 v60, -v60, v73, v72
	v_div_fmas_f32 v60, v60, v61, v73
	v_div_fixup_f32 v32, v60, v32, 1.0
	v_pk_fma_f32 v[60:61], v[32:33], v[66:67], v[102:103] op_sel_hi:[0,1,1] neg_lo:[0,0,1] neg_hi:[0,0,1]
	v_pk_fma_f32 v[72:73], v[32:33], v[56:57], v[54:55] op_sel_hi:[0,1,1] neg_lo:[0,0,1] neg_hi:[0,0,1]
	v_pk_mul_f32 v[72:73], v[2:3], v[72:73]
	v_pk_mul_f32 v[60:61], v[0:1], v[60:61]
	v_lshlrev_b32_e32 v80, 16, v169
	v_cvt_pk_bf16_f32 v60, v60, v61
	v_cvt_pk_bf16_f32 v61, v72, v73
	v_add_co_u32_e32 v72, vcc, s7, v22
	s_max_i32 s7, s67, 8
	s_sub_i32 s7, s16, s7
	v_addc_co_u32_e32 v73, vcc, 0, v23, vcc
	v_and_b32_e32 v83, 0xffff0000, v33
	s_add_i32 s7, s7, 8
	global_store_dwordx2 v[72:73], v[60:61], off offset:1536
	v_pk_mul_f32 v[32:33], v[28:29], v[82:83] op_sel_hi:[0,1]
	v_pk_mul_f32 v[60:61], v[28:29], v[80:81] op_sel_hi:[0,1]
	v_pk_fma_f32 v[80:81], v[28:29], v[80:81], v[84:85] op_sel_hi:[0,1,1] neg_lo:[0,0,1] neg_hi:[0,0,1]
	v_pk_fma_f32 v[76:77], v[28:29], v[82:83], v[76:77] op_sel_hi:[0,1,1] neg_lo:[0,0,1] neg_hi:[0,0,1]
	v_cvt_f32_i32_e32 v28, s7
	v_pk_add_f32 v[76:77], v[56:57], v[76:77]
	v_pk_add_f32 v[66:67], v[66:67], v[80:81]
	s_max_i32 s7, s66, 8
	v_div_scale_f32 v56, s[16:17], v28, v28, 1.0
	v_rcp_f32_e32 v57, v56
	s_min_i32 s16, s15, s23
	s_sub_i32 s7, s16, s7
	s_add_i32 s7, s7, 8
	v_fma_f32 v80, -v56, v57, 1.0
	v_fmac_f32_e32 v57, v80, v57
	v_div_scale_f32 v80, vcc, 1.0, v28, 1.0
	v_mul_f32_e32 v81, v80, v57
	v_fma_f32 v82, -v56, v81, v80
	v_fmac_f32_e32 v81, v82, v57
	v_fma_f32 v56, -v56, v81, v80
	v_div_fmas_f32 v56, v56, v57, v81
	v_div_fixup_f32 v28, v56, v28, 1.0
	v_pk_fma_f32 v[56:57], v[28:29], v[66:67], v[104:105] op_sel_hi:[0,1,1] neg_lo:[0,0,1] neg_hi:[0,0,1]
	v_pk_fma_f32 v[80:81], v[28:29], v[76:77], v[50:51] op_sel_hi:[0,1,1] neg_lo:[0,0,1] neg_hi:[0,0,1]
	v_pk_mul_f32 v[80:81], v[2:3], v[80:81]
	v_pk_mul_f32 v[56:57], v[0:1], v[56:57]
	v_lshlrev_b32_e32 v82, 16, v167
	v_cvt_pk_bf16_f32 v56, v56, v57
	v_cvt_pk_bf16_f32 v57, v80, v81
	global_store_dwordx2 v[72:73], v[56:57], off offset:3584
	v_lshlrev_b32_e32 v72, 16, v168
	v_and_b32_e32 v73, 0xffff0000, v168
	v_lshlrev_b32_e32 v80, 16, v29
	v_and_b32_e32 v81, 0xffff0000, v29
	v_pk_mul_f32 v[28:29], v[26:27], v[80:81] op_sel_hi:[0,1]
	v_pk_mul_f32 v[56:57], v[26:27], v[72:73] op_sel_hi:[0,1]
	v_pk_fma_f32 v[72:73], v[26:27], v[72:73], v[86:87] op_sel_hi:[0,1,1] neg_lo:[0,0,1] neg_hi:[0,0,1]
	v_pk_fma_f32 v[78:79], v[26:27], v[80:81], v[78:79] op_sel_hi:[0,1,1] neg_lo:[0,0,1] neg_hi:[0,0,1]
	v_cvt_f32_i32_e32 v26, s7
	v_pk_add_f32 v[76:77], v[76:77], v[78:79]
	v_pk_add_f32 v[78:79], v[66:67], v[72:73]
	s_max_i32 s7, s63, 8
	v_div_scale_f32 v66, s[16:17], v26, v26, 1.0
	v_rcp_f32_e32 v67, v66
	s_min_i32 s16, s5, s23
	s_sub_i32 s7, s16, s7
	v_and_b32_e32 v83, 0xffff0000, v167
	v_fma_f32 v72, -v66, v67, 1.0
	v_fmac_f32_e32 v67, v72, v67
	v_div_scale_f32 v72, vcc, 1.0, v26, 1.0
	v_mul_f32_e32 v73, v72, v67
	v_fma_f32 v80, -v66, v73, v72
	v_fmac_f32_e32 v73, v80, v67
	v_fma_f32 v66, -v66, v73, v72
	v_div_fmas_f32 v66, v66, v67, v73
	v_div_fixup_f32 v26, v66, v26, 1.0
	v_pk_fma_f32 v[66:67], v[26:27], v[78:79], v[106:107] op_sel_hi:[0,1,1] neg_lo:[0,0,1] neg_hi:[0,0,1]
	v_pk_fma_f32 v[72:73], v[26:27], v[76:77], v[44:45] op_sel_hi:[0,1,1] neg_lo:[0,0,1] neg_hi:[0,0,1]
	v_pk_mul_f32 v[66:67], v[0:1], v[66:67]
	v_add_co_u32_e32 v80, vcc, s51, v22
	v_pk_mul_f32 v[72:73], v[2:3], v[72:73]
	v_cvt_pk_bf16_f32 v66, v66, v67
	s_nop 0
	v_addc_co_u32_e32 v81, vcc, 0, v23, vcc
	v_cvt_pk_bf16_f32 v67, v72, v73
	v_lshlrev_b32_e32 v84, 16, v166
	v_and_b32_e32 v85, 0xffff0000, v166
	s_add_i32 s7, s7, 8
	global_store_dwordx2 v[80:81], v[66:67], off offset:1536
	v_pk_mul_f32 v[66:67], v[24:25], v[84:85] op_sel_hi:[0,1]
	v_pk_mul_f32 v[72:73], v[24:25], v[82:83] op_sel_hi:[0,1]
	v_pk_fma_f32 v[82:83], v[24:25], v[82:83], v[88:89] op_sel_hi:[0,1,1] neg_lo:[0,0,1] neg_hi:[0,0,1]
	v_pk_fma_f32 v[74:75], v[24:25], v[84:85], v[74:75] op_sel_hi:[0,1,1] neg_lo:[0,0,1] neg_hi:[0,0,1]
	v_cvt_f32_i32_e32 v24, s7
	v_pk_add_f32 v[74:75], v[76:77], v[74:75]
	v_pk_add_f32 v[76:77], v[78:79], v[82:83]
	s_max_i32 s7, s62, 8
	v_div_scale_f32 v26, s[16:17], v24, v24, 1.0
	v_rcp_f32_e32 v78, v26
	s_min_i32 s16, s80, s23
	s_sub_i32 s7, s16, s7
	s_add_i32 s7, s7, 8
	v_fma_f32 v79, -v26, v78, 1.0
	v_fmac_f32_e32 v78, v79, v78
	v_div_scale_f32 v79, vcc, 1.0, v24, 1.0
	v_mul_f32_e32 v82, v79, v78
	v_fma_f32 v83, -v26, v82, v79
	v_fmac_f32_e32 v82, v83, v78
	v_fma_f32 v26, -v26, v82, v79
	v_div_fmas_f32 v26, v26, v78, v82
	v_div_fixup_f32 v24, v26, v24, 1.0
	v_pk_fma_f32 v[78:79], v[24:25], v[76:77], v[108:109] op_sel_hi:[0,1,1] neg_lo:[0,0,1] neg_hi:[0,0,1]
	v_pk_fma_f32 v[40:41], v[24:25], v[74:75], v[40:41] op_sel_hi:[0,1,1] neg_lo:[0,0,1] neg_hi:[0,0,1]
	v_pk_mul_f32 v[78:79], v[0:1], v[78:79]
	v_pk_mul_f32 v[40:41], v[2:3], v[40:41]
	v_cvt_pk_bf16_f32 v78, v78, v79
	s_max_i32 s5, s5, 8
	v_cvt_pk_bf16_f32 v79, v40, v41
	global_store_dwordx2 v[80:81], v[78:79], off offset:3584
	v_lshlrev_b32_e32 v40, 16, v27
	v_and_b32_e32 v41, 0xffff0000, v27
	v_lshlrev_b32_e32 v78, 16, v25
	v_and_b32_e32 v79, 0xffff0000, v25
	v_pk_mul_f32 v[24:25], v[18:19], v[78:79] op_sel_hi:[0,1]
	v_pk_mul_f32 v[26:27], v[18:19], v[40:41] op_sel_hi:[0,1]
	v_pk_fma_f32 v[40:41], v[18:19], v[40:41], v[90:91] op_sel_hi:[0,1,1] neg_lo:[0,0,1] neg_hi:[0,0,1]
	v_pk_fma_f32 v[70:71], v[18:19], v[78:79], v[70:71] op_sel_hi:[0,1,1] neg_lo:[0,0,1] neg_hi:[0,0,1]
	v_cvt_f32_i32_e32 v18, s7
	v_pk_add_f32 v[70:71], v[74:75], v[70:71]
	v_pk_add_f32 v[40:41], v[76:77], v[40:41]
	s_max_i32 s7, s21, 8
	v_div_scale_f32 v74, s[16:17], v18, v18, 1.0
	v_rcp_f32_e32 v75, v74
	s_min_i32 s16, s82, s23
	s_sub_i32 s7, s16, s7
	s_add_i32 s7, s7, 8
	v_fma_f32 v76, -v74, v75, 1.0
	v_fmac_f32_e32 v75, v76, v75
	v_div_scale_f32 v76, vcc, 1.0, v18, 1.0
	v_mul_f32_e32 v77, v76, v75
	v_fma_f32 v78, -v74, v77, v76
	v_fmac_f32_e32 v77, v78, v75
	v_fma_f32 v74, -v74, v77, v76
	v_div_fmas_f32 v74, v74, v75, v77
	v_div_fixup_f32 v18, v74, v18, 1.0
	v_pk_fma_f32 v[46:47], v[18:19], v[40:41], v[46:47] op_sel_hi:[0,1,1] neg_lo:[0,0,1] neg_hi:[0,0,1]
	v_pk_fma_f32 v[38:39], v[18:19], v[70:71], v[38:39] op_sel_hi:[0,1,1] neg_lo:[0,0,1] neg_hi:[0,0,1]
	v_pk_mul_f32 v[38:39], v[2:3], v[38:39]
	v_pk_mul_f32 v[46:47], v[0:1], v[46:47]
	v_cvt_f32_i32_e32 v18, s7
	v_cvt_pk_bf16_f32 v46, v46, v47
	v_cvt_pk_bf16_f32 v47, v38, v39
	v_add_co_u32_e32 v38, vcc, s58, v22
	v_lshlrev_b32_e32 v74, 16, v162
	s_nop 0
	v_addc_co_u32_e32 v39, vcc, 0, v23, vcc
	global_store_dwordx2 v[38:39], v[46:47], off offset:1536
	v_lshlrev_b32_e32 v46, 16, v163
	v_and_b32_e32 v47, 0xffff0000, v163
	v_and_b32_e32 v75, 0xffff0000, v162
	v_pk_fma_f32 v[46:47], v[20:21], v[46:47], v[92:93] op_sel_hi:[0,1,1] neg_lo:[0,0,1] neg_hi:[0,0,1]
	v_pk_fma_f32 v[64:65], v[20:21], v[74:75], v[64:65] op_sel_hi:[0,1,1] neg_lo:[0,0,1] neg_hi:[0,0,1]
	v_div_scale_f32 v20, s[16:17], v18, v18, 1.0
	v_pk_add_f32 v[40:41], v[40:41], v[46:47]
	v_rcp_f32_e32 v46, v20
	v_pk_add_f32 v[64:65], v[70:71], v[64:65]
	s_max_i32 s7, s34, 8
	s_min_i32 s16, s79, s23
	v_fma_f32 v47, -v20, v46, 1.0
	v_fmac_f32_e32 v46, v47, v46
	v_div_scale_f32 v47, vcc, 1.0, v18, 1.0
	v_mul_f32_e32 v70, v47, v46
	v_fma_f32 v71, -v20, v70, v47
	v_fmac_f32_e32 v70, v71, v46
	v_fma_f32 v20, -v20, v70, v47
	v_div_fmas_f32 v20, v20, v46, v70
	v_div_fixup_f32 v18, v20, v18, 1.0
	v_pk_fma_f32 v[42:43], v[18:19], v[40:41], v[42:43] op_sel_hi:[0,1,1] neg_lo:[0,0,1] neg_hi:[0,0,1]
	v_pk_fma_f32 v[34:35], v[18:19], v[64:65], v[34:35] op_sel_hi:[0,1,1] neg_lo:[0,0,1] neg_hi:[0,0,1]
	v_pk_mul_f32 v[34:35], v[2:3], v[34:35]
	v_pk_mul_f32 v[42:43], v[0:1], v[42:43]
	s_sub_i32 s7, s16, s7
	v_cvt_pk_bf16_f32 v42, v42, v43
	v_cvt_pk_bf16_f32 v43, v34, v35
	global_store_dwordx2 v[38:39], v[42:43], off offset:3584
	v_lshlrev_b32_e32 v34, 16, v165
	v_and_b32_e32 v35, 0xffff0000, v165
	v_lshlrev_b32_e32 v38, 16, v164
	v_and_b32_e32 v39, 0xffff0000, v164
	s_add_i32 s7, s7, 8
	v_pk_fma_f32 v[34:35], v[16:17], v[34:35], v[94:95] op_sel_hi:[0,1,1] neg_lo:[0,0,1] neg_hi:[0,0,1]
	v_pk_fma_f32 v[38:39], v[16:17], v[38:39], v[68:69] op_sel_hi:[0,1,1] neg_lo:[0,0,1] neg_hi:[0,0,1]
	v_cvt_f32_i32_e32 v16, s7
	v_pk_add_f32 v[34:35], v[40:41], v[34:35]
	v_pk_add_f32 v[38:39], v[64:65], v[38:39]
	s_max_i32 s7, s19, 8
	v_div_scale_f32 v18, s[16:17], v16, v16, 1.0
	v_rcp_f32_e32 v20, v18
	s_min_i32 s16, s77, s23
	s_sub_i32 s7, s16, s7
	v_and_b32_e32 v43, 0xffff0000, v160
	v_fma_f32 v40, -v18, v20, 1.0
	v_fmac_f32_e32 v20, v40, v20
	v_div_scale_f32 v40, vcc, 1.0, v16, 1.0
	v_mul_f32_e32 v41, v40, v20
	v_fma_f32 v42, -v18, v41, v40
	v_fmac_f32_e32 v41, v42, v20
	v_fma_f32 v18, -v18, v41, v40
	v_div_fmas_f32 v18, v18, v20, v41
	v_div_fixup_f32 v16, v18, v16, 1.0
	v_pk_fma_f32 v[40:41], v[16:17], v[34:35], v[52:53] op_sel_hi:[0,1,1] neg_lo:[0,0,1] neg_hi:[0,0,1]
	v_pk_fma_f32 v[36:37], v[16:17], v[38:39], v[36:37] op_sel_hi:[0,1,1] neg_lo:[0,0,1] neg_hi:[0,0,1]
	v_pk_mul_f32 v[36:37], v[2:3], v[36:37]
	v_pk_mul_f32 v[40:41], v[0:1], v[40:41]
	v_lshlrev_b32_e32 v42, 16, v160
	v_cvt_pk_bf16_f32 v40, v40, v41
	v_cvt_pk_bf16_f32 v41, v36, v37
	v_add_co_u32_e32 v36, vcc, s59, v22
	s_add_i32 s7, s7, 8
	s_nop 0
	v_addc_co_u32_e32 v37, vcc, 0, v23, vcc
	global_store_dwordx2 v[36:37], v[40:41], off offset:1536
	v_lshlrev_b32_e32 v40, 16, v161
	v_and_b32_e32 v41, 0xffff0000, v161
	v_pk_fma_f32 v[40:41], v[14:15], v[40:41], v[98:99] op_sel_hi:[0,1,1] neg_lo:[0,0,1] neg_hi:[0,0,1]
	v_pk_fma_f32 v[42:43], v[14:15], v[42:43], v[62:63] op_sel_hi:[0,1,1] neg_lo:[0,0,1] neg_hi:[0,0,1]
	v_cvt_f32_i32_e32 v14, s7
	v_pk_add_f32 v[34:35], v[34:35], v[40:41]
	s_max_i32 s7, s20, 8
	v_pk_add_f32 v[38:39], v[38:39], v[42:43]
	v_div_scale_f32 v16, s[16:17], v14, v14, 1.0
	v_rcp_f32_e32 v18, v16
	s_min_i32 s16, s75, s23
	s_sub_i32 s7, s16, s7
	s_add_i32 s7, s7, 8
	v_fma_f32 v20, -v16, v18, 1.0
	v_fmac_f32_e32 v18, v20, v18
	v_div_scale_f32 v20, vcc, 1.0, v14, 1.0
	v_mul_f32_e32 v40, v20, v18
	v_fma_f32 v41, -v16, v40, v20
	v_fmac_f32_e32 v40, v41, v18
	v_fma_f32 v16, -v16, v40, v20
	v_div_fmas_f32 v16, v16, v18, v40
	v_lshlrev_b32_e32 v20, 16, v21
	v_and_b32_e32 v21, 0xffff0000, v21
	v_lshlrev_b32_e32 v18, 16, v19
	v_and_b32_e32 v19, 0xffff0000, v19
	v_pk_fma_f32 v[20:21], v[12:13], v[20:21], v[100:101] op_sel_hi:[0,1,1] neg_lo:[0,0,1] neg_hi:[0,0,1]
	v_pk_fma_f32 v[18:19], v[12:13], v[18:19], v[58:59] op_sel_hi:[0,1,1] neg_lo:[0,0,1] neg_hi:[0,0,1]
	v_cvt_f32_i32_e32 v12, s7
	v_div_fixup_f32 v14, v16, v14, 1.0
	v_pk_fma_f32 v[40:41], v[14:15], v[34:35], v[48:49] op_sel_hi:[0,1,1] neg_lo:[0,0,1] neg_hi:[0,0,1]
	v_pk_fma_f32 v[30:31], v[14:15], v[38:39], v[30:31] op_sel_hi:[0,1,1] neg_lo:[0,0,1] neg_hi:[0,0,1]
	v_div_scale_f32 v14, s[16:17], v12, v12, 1.0
	v_rcp_f32_e32 v16, v14
	v_pk_mul_f32 v[30:31], v[2:3], v[30:31]
	v_pk_mul_f32 v[40:41], v[0:1], v[40:41]
	v_pk_add_f32 v[20:21], v[34:35], v[20:21]
	v_cvt_pk_bf16_f32 v40, v40, v41
	v_cvt_pk_bf16_f32 v41, v30, v31
	v_fma_f32 v30, -v14, v16, 1.0
	v_fmac_f32_e32 v16, v30, v16
	v_div_scale_f32 v30, vcc, 1.0, v12, 1.0
	v_mul_f32_e32 v31, v30, v16
	v_fma_f32 v34, -v14, v31, v30
	v_fmac_f32_e32 v31, v34, v16
	v_fma_f32 v14, -v14, v31, v30
	s_max_i32 s7, s18, 8
	s_min_i32 s16, s72, s23
	v_div_fmas_f32 v14, v14, v16, v31
	s_sub_i32 s7, s16, s7
	v_div_fixup_f32 v12, v14, v12, 1.0
	v_lshlrev_b32_e32 v16, 16, v17
	v_and_b32_e32 v17, 0xffff0000, v17
	v_lshlrev_b32_e32 v14, 16, v15
	v_and_b32_e32 v15, 0xffff0000, v15
	s_add_i32 s7, s7, 8
	v_pk_fma_f32 v[16:17], v[10:11], v[16:17], v[102:103] op_sel_hi:[0,1,1] neg_lo:[0,0,1] neg_hi:[0,0,1]
	v_pk_fma_f32 v[14:15], v[10:11], v[14:15], v[54:55] op_sel_hi:[0,1,1] neg_lo:[0,0,1] neg_hi:[0,0,1]
	v_cvt_f32_i32_e32 v10, s7
	v_pk_add_f32 v[18:19], v[38:39], v[18:19]
	v_pk_fma_f32 v[30:31], v[12:13], v[20:21], v[60:61] op_sel_hi:[0,1,1] neg_lo:[0,0,1] neg_hi:[0,0,1]
	v_pk_fma_f32 v[32:33], v[12:13], v[18:19], v[32:33] op_sel_hi:[0,1,1] neg_lo:[0,0,1] neg_hi:[0,0,1]
	v_div_scale_f32 v12, s[16:17], v10, v10, 1.0
	v_pk_add_f32 v[14:15], v[18:19], v[14:15]
	v_rcp_f32_e32 v18, v12
	v_pk_mul_f32 v[32:33], v[2:3], v[32:33]
	v_pk_mul_f32 v[30:31], v[0:1], v[30:31]
	global_store_dwordx2 v[36:37], v[40:41], off offset:3584
	v_cvt_pk_bf16_f32 v30, v30, v31
	v_cvt_pk_bf16_f32 v31, v32, v33
	v_add_co_u32_e32 v32, vcc, s60, v22
	v_fma_f32 v19, -v12, v18, 1.0
	s_nop 0
	v_addc_co_u32_e32 v33, vcc, 0, v23, vcc
	v_fmac_f32_e32 v18, v19, v18
	v_div_scale_f32 v19, vcc, 1.0, v10, 1.0
	v_pk_add_f32 v[16:17], v[20:21], v[16:17]
	v_mul_f32_e32 v20, v19, v18
	v_fma_f32 v21, -v12, v20, v19
	v_fmac_f32_e32 v20, v21, v18
	v_fma_f32 v12, -v12, v20, v19
	v_div_fmas_f32 v12, v12, v18, v20
	s_max_i32 s7, s15, 8
	s_min_i32 s15, s70, s23
	v_div_fixup_f32 v10, v12, v10, 1.0
	s_sub_i32 s7, s15, s7
	v_pk_fma_f32 v[18:19], v[10:11], v[16:17], v[56:57] op_sel_hi:[0,1,1] neg_lo:[0,0,1] neg_hi:[0,0,1]
	s_add_i32 s7, s7, 8
	v_pk_fma_f32 v[20:21], v[10:11], v[14:15], v[28:29] op_sel_hi:[0,1,1] neg_lo:[0,0,1] neg_hi:[0,0,1]
	v_pk_mul_f32 v[18:19], v[0:1], v[18:19]
	v_cvt_f32_i32_e32 v12, s7
	global_store_dwordx2 v[32:33], v[30:31], off offset:1536
	v_pk_mul_f32 v[20:21], v[2:3], v[20:21]
	v_cvt_pk_bf16_f32 v18, v18, v19
	v_lshlrev_b32_e32 v10, 16, v11
	v_cvt_pk_bf16_f32 v19, v20, v21
	global_store_dwordx2 v[32:33], v[18:19], off offset:3584
	v_and_b32_e32 v11, 0xffff0000, v11
	v_lshlrev_b32_e32 v18, 16, v7
	v_and_b32_e32 v19, 0xffff0000, v7
	v_pk_fma_f32 v[10:11], v[6:7], v[10:11], v[104:105] op_sel_hi:[0,1,1] neg_lo:[0,0,1] neg_hi:[0,0,1]
	v_pk_fma_f32 v[6:7], v[6:7], v[18:19], v[50:51] op_sel_hi:[0,1,1] neg_lo:[0,0,1] neg_hi:[0,0,1]
	v_pk_add_f32 v[6:7], v[14:15], v[6:7]
	v_div_scale_f32 v14, s[16:17], v12, v12, 1.0
	v_rcp_f32_e32 v15, v14
	v_pk_add_f32 v[10:11], v[16:17], v[10:11]
	s_add_i32 s7, s4, 39
	s_min_i32 s7, s7, s23
	v_fma_f32 v16, -v14, v15, 1.0
	v_fmac_f32_e32 v15, v16, v15
	v_div_scale_f32 v16, vcc, 1.0, v12, 1.0
	v_mul_f32_e32 v17, v16, v15
	v_fma_f32 v18, -v14, v17, v16
	v_fmac_f32_e32 v17, v18, v15
	v_fma_f32 v14, -v14, v17, v16
	v_div_fmas_f32 v14, v14, v15, v17
	v_div_fixup_f32 v12, v14, v12, 1.0
	v_pk_fma_f32 v[14:15], v[12:13], v[10:11], v[72:73] op_sel_hi:[0,1,1] neg_lo:[0,0,1] neg_hi:[0,0,1]
	v_pk_fma_f32 v[16:17], v[12:13], v[6:7], v[66:67] op_sel_hi:[0,1,1] neg_lo:[0,0,1] neg_hi:[0,0,1]
	v_pk_mul_f32 v[16:17], v[2:3], v[16:17]
	v_pk_mul_f32 v[14:15], v[0:1], v[14:15]
	v_lshlrev_b32_e32 v12, 16, v13
	v_cvt_pk_bf16_f32 v14, v14, v15
	v_cvt_pk_bf16_f32 v15, v16, v17
	v_add_co_u32_e32 v16, vcc, s50, v22
	v_and_b32_e32 v13, 0xffff0000, v13
	s_nop 0
	v_addc_co_u32_e32 v17, vcc, 0, v23, vcc
	global_store_dwordx2 v[16:17], v[14:15], off offset:1536
	v_lshlrev_b32_e32 v14, 16, v9
	v_and_b32_e32 v15, 0xffff0000, v9
	s_sub_i32 s5, s7, s5
	s_waitcnt vmcnt(31)
	v_pk_fma_f32 v[12:13], v[8:9], v[12:13], v[106:107] op_sel_hi:[0,1,1] neg_lo:[0,0,1] neg_hi:[0,0,1]
	v_pk_fma_f32 v[8:9], v[8:9], v[14:15], v[44:45] op_sel_hi:[0,1,1] neg_lo:[0,0,1] neg_hi:[0,0,1]
	s_add_i32 s5, s5, 8
	v_pk_add_f32 v[6:7], v[6:7], v[8:9]
	v_pk_add_f32 v[8:9], v[10:11], v[12:13]
	v_cvt_f32_i32_e32 v10, s5
	v_div_scale_f32 v11, s[16:17], v10, v10, 1.0
	v_rcp_f32_e32 v12, v11
	s_nop 0
	v_fma_f32 v13, -v11, v12, 1.0
	v_fmac_f32_e32 v12, v13, v12
	v_div_scale_f32 v13, vcc, 1.0, v10, 1.0
	v_mul_f32_e32 v14, v13, v12
	v_fma_f32 v15, -v11, v14, v13
	v_fmac_f32_e32 v14, v15, v12
	v_fma_f32 v11, -v11, v14, v13
	v_div_fmas_f32 v11, v11, v12, v14
	v_div_fixup_f32 v10, v11, v10, 1.0
	v_pk_fma_f32 v[8:9], v[10:11], v[8:9], v[26:27] op_sel_hi:[0,1,1] neg_lo:[0,0,1] neg_hi:[0,0,1]
	v_pk_fma_f32 v[6:7], v[10:11], v[6:7], v[24:25] op_sel_hi:[0,1,1] neg_lo:[0,0,1] neg_hi:[0,0,1]
	v_pk_mul_f32 v[10:11], v[2:3], v[6:7]
	v_pk_mul_f32 v[6:7], v[0:1], v[8:9]
	s_nop 0
	v_cvt_pk_bf16_f32 v6, v6, v7
	v_cvt_pk_bf16_f32 v7, v10, v11
	s_cbranch_execz .LBB0_294
	s_branch .LBB0_295
